# K-loops: ds_reads issued in MFMA consumption order with re-derived counted lgkmcnt waits (on the setprio-off-path balanced saddr loops)
# speedup vs baseline: 1.0029x; 1.0020x over previous
; #define PG8_STAGE(bufoff, gbase, voff) do { _Pragma("unroll") for (int _i = 0; _i < 2; ++_i) \
;         __builtin_amdgcn_global_load_lds((const unsigned*)((const char*)(gbase) + (voff)[_i]), (PG8_LAS unsigned*)(lds + (bufoff) + ldsw + _i * 8192), 16, 0, 0); } while (0)
; #define PG8_LDA(dst, b, h) do { _Pragma("unroll") for (int m = 0; m < 4; ++m) _Pragma("unroll") for (int k = 0; k < 2; ++k) dst[m][k] = *(const PG8_LAS bf16x8*)(lds + PG8_SA(b, h) + aoff + m * 2048 + k * 1024); } while (0)
; #define PG8_LDB(dst, b, h) do { _Pragma("unroll") for (int n = 0; n < 2; ++n) _Pragma("unroll") for (int k = 0; k < 2; ++k) dst[n][k] = *(const PG8_LAS bf16x8*)(lds + PG8_SB(b, h) + boff + n * 2048 + k * 1024); } while (0)
; #define PG8_WAIT_V(n) asm volatile("s_waitcnt vmcnt(" #n ")" ::: "memory")
; #define PG8_WAIT_L(n) asm volatile("s_waitcnt lgkmcnt(" #n ")" ::: "memory")
; #define PG8_BAR __builtin_amdgcn_s_barrier()
; #define PG8_SCHED __builtin_amdgcn_sched_barrier(0)
; template <class Epi, class Sched, bool ALIGN_EPI = false, bool SP2 = false, bool I8 = false>
; __device__ __forceinline__ void gemm_phase(PG8_LAS unsigned char* lds, const Gemm g, const Sched& S, const Epi& E) {
;     ...
;         const bool has_next = S.next(ui + 1, nxt);
;         const char* nA = has_next ? (const char*)g.A + (size_t)nxt.pm * tstep : cA; const char* nB = has_next ? (const char*)g.Bt + (size_t)nxt.pn * tstep : cB;
;         for (int t = 0; t < nt; t += 2) {
;             const bool last = (t == nt - 2);
;             const char* a1 = cA + (size_t)(t + 1) * kstep;
;             const char* a2 = last ? nA : cA + (size_t)(t + 2) * kstep; const char* b2 = last ? nB : cB + (size_t)(t + 2) * kstep;
;             const char* a3 = a2 + kstep; const char* b3 = b2 + kstep;
;             if (last && has_next) S.a_ready(nxt);
;             if constexpr (SP2) {
;             PG8_LDB(B0, 0, 0); PG8_LDB(B1, 0, 1); PG8_SCHED; PG8_LDA(At, 0, 0); PG8_STAGE(PG8_SA(1, 1), a1 + hstep, voffA);
;             PG8_WAIT_V(8); PG8_WAIT_L(0); PG8_BAR; PG8_MMA(0, 0, At, B0); PG8_MMA(0, 1, At, B1); PG8_BAR; PG8_SCHED;
;             PG8_LDA(At, 0, 1); PG8_STAGE(PG8_SB(0, 0), b2, voffB); PG8_STAGE(PG8_SB(0, 1), b2 + hstep, voffB); PG8_STAGE(PG8_SA(0, 0), a2, voffA);
;             PG8_WAIT_V(8); PG8_WAIT_L(0); PG8_BAR; PG8_MMA(1, 0, At, B0); PG8_MMA(1, 1, At, B1); PG8_BAR; PG8_SCHED;
.LBB0_207:
	s_ashr_i32 s19, s18, 31
	s_lshl_b64 s[22:23], s[18:19], 20
	s_add_u32 s22, s28, s22
	s_addc_u32 s23, s34, s23
	s_and_b64 s[24:25], s[6:7], exec
	s_cselect_b32 s19, s23, s27
	s_cselect_b32 s64, s22, s26
	s_ashr_i32 s17, s16, 31
	s_lshl_b64 s[24:25], s[16:17], 20
	s_add_u32 s24, s35, s24
	s_addc_u32 s25, s42, s25
	s_and_b64 s[40:41], s[6:7], exec
	s_cselect_b32 s17, s25, s37
	s_cselect_b32 s65, s24, s36
	s_add_u32 s26, s26, 0x80080
	s_addc_u32 s27, s27, 0
	s_add_u32 s72, s36, 0x100
	s_addc_u32 s73, s37, 0
	s_mov_b32 s76, -2
	s_add_u32 s36, s26, 0xfff80080
	s_addc_u32 s37, s27, -1
	s_add_i32 s50, 0, 0x10000
	s_cmp_eq_u32 s76, 28
	s_cselect_b32 s41, s19, s37
	s_cselect_b32 s40, s64, s36
	s_cselect_b32 s37, s17, s73
	s_cselect_b32 s36, s65, s72
	s_add_i32 s56, 0, 0x14000
	v_add_u32_e32 v136, s50, v175
	v_add_u32_e32 v172, s56, v175
	ds_read_b128 v[116:119], v136
	ds_read_b128 v[182:185], v177
	ds_read_b128 v[124:127], v136 offset:1024
	ds_read_b128 v[186:189], v177 offset:1024
	ds_read_b128 v[208:211], v177 offset:3072
	ds_read_b128 v[204:207], v177 offset:2048
	ds_read_b128 v[212:215], v177 offset:4096
	ds_read_b128 v[216:219], v177 offset:5120
	s_add_i32 m0, s44, 0xc000
	ds_read_b128 v[224:227], v177 offset:7168
	ds_read_b128 v[220:223], v177 offset:6144
	ds_read_b128 v[132:135], v136 offset:2048
	ds_read_b128 v[136:139], v136 offset:3072
	ds_read_b128 v[160:163], v172
	ds_read_b128 v[164:167], v172 offset:1024
	ds_read_b128 v[168:171], v172 offset:2048
	ds_read_b128 v[178:181], v172 offset:3072
	global_load_lds_dwordx4 v156, s[26:27]
	s_add_i32 m0, s44, 0xe000
	s_nop 0
	global_load_lds_dwordx4 v158, s[26:27]
	s_waitcnt vmcnt(8)
	s_waitcnt lgkmcnt(14)
	s_setprio 1
	s_barrier
	v_mfma_i32_16x16x64_i8 v[144:147], v[116:119], v[182:185], 0
	s_waitcnt lgkmcnt(12)
	v_mfma_i32_16x16x64_i8 v[144:147], v[124:127], v[186:189], v[144:147]
	s_waitcnt lgkmcnt(11)
	v_mfma_i32_16x16x64_i8 v[112:115], v[124:127], v[208:211], 0
	s_waitcnt lgkmcnt(10)
	v_mfma_i32_16x16x64_i8 v[112:115], v[116:119], v[204:207], v[112:115]
	s_waitcnt lgkmcnt(9)
	v_mfma_i32_16x16x64_i8 v[96:99], v[116:119], v[212:215], 0
	s_waitcnt lgkmcnt(8)
	v_mfma_i32_16x16x64_i8 v[96:99], v[124:127], v[216:219], v[96:99]
	s_waitcnt lgkmcnt(7)
	v_mfma_i32_16x16x64_i8 v[80:83], v[124:127], v[224:227], 0
	s_waitcnt lgkmcnt(6)
	v_mfma_i32_16x16x64_i8 v[80:83], v[116:119], v[220:223], v[80:83]
	s_waitcnt lgkmcnt(5)
	v_mfma_i32_16x16x64_i8 v[76:79], v[132:135], v[220:223], 0
	s_waitcnt lgkmcnt(4)
	v_mfma_i32_16x16x64_i8 v[76:79], v[136:139], v[224:227], v[76:79]
	v_mfma_i32_16x16x64_i8 v[92:95], v[136:139], v[216:219], 0
	v_mfma_i32_16x16x64_i8 v[92:95], v[132:135], v[212:215], v[92:95]
	v_mfma_i32_16x16x64_i8 v[108:111], v[132:135], v[204:207], 0
	v_mfma_i32_16x16x64_i8 v[108:111], v[136:139], v[208:211], v[108:111]
	v_mfma_i32_16x16x64_i8 v[140:143], v[136:139], v[186:189], 0
	v_mfma_i32_16x16x64_i8 v[140:143], v[132:135], v[182:185], v[140:143]
	s_waitcnt lgkmcnt(3)
	v_mfma_i32_16x16x64_i8 v[128:131], v[160:163], v[182:185], 0
	s_waitcnt lgkmcnt(2)
	v_mfma_i32_16x16x64_i8 v[128:131], v[164:167], v[186:189], v[128:131]
	v_mfma_i32_16x16x64_i8 v[104:107], v[164:167], v[208:211], 0
	v_mfma_i32_16x16x64_i8 v[104:107], v[160:163], v[204:207], v[104:107]
	v_mfma_i32_16x16x64_i8 v[88:91], v[160:163], v[212:215], 0
	v_mfma_i32_16x16x64_i8 v[88:91], v[164:167], v[216:219], v[88:91]
	v_mfma_i32_16x16x64_i8 v[72:75], v[164:167], v[224:227], 0
	v_mfma_i32_16x16x64_i8 v[72:75], v[160:163], v[220:223], v[72:75]
	s_waitcnt lgkmcnt(1)
	v_mfma_i32_16x16x64_i8 v[68:71], v[168:171], v[220:223], 0
	s_waitcnt lgkmcnt(0)
	v_mfma_i32_16x16x64_i8 v[68:71], v[178:181], v[224:227], v[68:71]
	v_mfma_i32_16x16x64_i8 v[84:87], v[178:181], v[216:219], 0
	v_mfma_i32_16x16x64_i8 v[84:87], v[168:171], v[212:215], v[84:87]
	v_mfma_i32_16x16x64_i8 v[100:103], v[168:171], v[204:207], 0
	v_mfma_i32_16x16x64_i8 v[100:103], v[178:181], v[208:211], v[100:103]
	v_mfma_i32_16x16x64_i8 v[120:123], v[178:181], v[186:189], 0
	v_mfma_i32_16x16x64_i8 v[120:123], v[168:171], v[182:185], v[120:123]
	s_barrier
	s_setprio 0
	s_add_i32 s50, s50, s43
	v_lshl_add_u64 v[172:173], s[36:37], 0, v[2:3]
	s_mov_b32 m0, s50
	ds_read_b128 v[182:185], v177 offset:16384
	ds_read_b128 v[186:189], v177 offset:17408
	ds_read_b128 v[208:211], v177 offset:19456
	ds_read_b128 v[204:207], v177 offset:18432
	ds_read_b128 v[212:215], v177 offset:20480
	ds_read_b128 v[216:219], v177 offset:21504
	ds_read_b128 v[224:227], v177 offset:23552
	ds_read_b128 v[220:223], v177 offset:22528
	global_load_lds_dwordx4 v[172:173], off
	s_add_i32 m0, s50, 0x2000
	s_add_u32 s50, s36, 0x80000
	v_lshl_add_u64 v[190:191], s[36:37], 0, v[148:149]
	s_addc_u32 s51, s37, 0
	s_add_i32 s56, s56, s43
	global_load_lds_dwordx4 v[190:191], off
	s_mov_b32 m0, s56
	v_lshl_add_u64 v[240:241], s[40:41], 0, v[150:151]
	global_load_lds_dwordx4 v2, s[50:51]
	s_add_i32 m0, s56, 0x2000
	s_nop 0
	global_load_lds_dwordx4 v148, s[50:51]
	v_lshl_add_u64 v[228:229], s[40:41], 0, v[152:153]
	s_waitcnt vmcnt(6)
	s_waitcnt lgkmcnt(7)
	s_setprio 1
	s_barrier
; #define PG8_STAGE(bufoff, gbase, voff) do { _Pragma("unroll") for (int _i = 0; _i < 2; ++_i) \
;         __builtin_amdgcn_global_load_lds((const unsigned*)((const char*)(gbase) + (voff)[_i]), (PG8_LAS unsigned*)(lds + (bufoff) + ldsw + _i * 8192), 16, 0, 0); } while (0)
; #define PG8_LDA(dst, b, h) do { _Pragma("unroll") for (int m = 0; m < 4; ++m) _Pragma("unroll") for (int k = 0; k < 2; ++k) dst[m][k] = *(const PG8_LAS bf16x8*)(lds + PG8_SA(b, h) + aoff + m * 2048 + k * 1024); } while (0)
; #define PG8_LDB(dst, b, h) do { _Pragma("unroll") for (int n = 0; n < 2; ++n) _Pragma("unroll") for (int k = 0; k < 2; ++k) dst[n][k] = *(const PG8_LAS bf16x8*)(lds + PG8_SB(b, h) + boff + n * 2048 + k * 1024); } while (0)
; #define PG8_WAIT_V(n) asm volatile("s_waitcnt vmcnt(" #n ")" ::: "memory")
; #define PG8_WAIT_L(n) asm volatile("s_waitcnt lgkmcnt(" #n ")" ::: "memory")
; #define PG8_BAR __builtin_amdgcn_s_barrier()
; #define PG8_SCHED __builtin_amdgcn_sched_barrier(0)
; template <class Epi, class Sched, bool ALIGN_EPI = false, bool SP2 = false, bool I8 = false>
; __device__ __forceinline__ void gemm_phase(PG8_LAS unsigned char* lds, const Gemm g, const Sched& S, const Epi& E) {
;     ...
;             PG8_WAIT_V(8); PG8_WAIT_L(0); PG8_BAR; PG8_MMA(1, 0, At, B0); PG8_MMA(1, 1, At, B1); PG8_BAR; PG8_SCHED;
;             PG8_LDB(B0, 1, 0); PG8_LDB(B1, 1, 1); PG8_SCHED; PG8_LDA(At, 1, 0); PG8_STAGE(PG8_SA(0, 1), a2 + hstep, voffA);
;             PG8_WAIT_V(8); PG8_WAIT_L(0); PG8_BAR; PG8_MMA(0, 0, At, B0); PG8_MMA(0, 1, At, B1); PG8_BAR; PG8_SCHED;
;             PG8_LDA(At, 1, 1); PG8_STAGE(PG8_SB(1, 0), b3, voffB); PG8_STAGE(PG8_SB(1, 1), b3 + hstep, voffB); PG8_STAGE(PG8_SA(1, 0), a3, voffA);
	v_mfma_i32_16x16x64_i8 v[64:67], v[116:119], v[182:185], 0
	s_waitcnt lgkmcnt(6)
	v_mfma_i32_16x16x64_i8 v[64:67], v[124:127], v[186:189], v[64:67]
	s_waitcnt lgkmcnt(5)
	v_mfma_i32_16x16x64_i8 v[48:51], v[124:127], v[208:211], 0
	s_waitcnt lgkmcnt(4)
	v_mfma_i32_16x16x64_i8 v[48:51], v[116:119], v[204:207], v[48:51]
	s_waitcnt lgkmcnt(3)
	v_mfma_i32_16x16x64_i8 v[32:35], v[116:119], v[212:215], 0
	s_waitcnt lgkmcnt(2)
	v_mfma_i32_16x16x64_i8 v[32:35], v[124:127], v[216:219], v[32:35]
	s_waitcnt lgkmcnt(1)
	v_mfma_i32_16x16x64_i8 v[16:19], v[124:127], v[224:227], 0
	s_waitcnt lgkmcnt(0)
	v_mfma_i32_16x16x64_i8 v[16:19], v[116:119], v[220:223], v[16:19]
	v_mfma_i32_16x16x64_i8 v[12:15], v[132:135], v[220:223], 0
	v_mfma_i32_16x16x64_i8 v[12:15], v[136:139], v[224:227], v[12:15]
	v_mfma_i32_16x16x64_i8 v[28:31], v[136:139], v[216:219], 0
	v_mfma_i32_16x16x64_i8 v[28:31], v[132:135], v[212:215], v[28:31]
	v_mfma_i32_16x16x64_i8 v[44:47], v[132:135], v[204:207], 0
	v_mfma_i32_16x16x64_i8 v[44:47], v[136:139], v[208:211], v[44:47]
	v_mfma_i32_16x16x64_i8 v[60:63], v[136:139], v[186:189], 0
	v_mfma_i32_16x16x64_i8 v[60:63], v[132:135], v[182:185], v[60:63]
	v_mfma_i32_16x16x64_i8 v[56:59], v[160:163], v[182:185], 0
	v_mfma_i32_16x16x64_i8 v[56:59], v[164:167], v[186:189], v[56:59]
	v_mfma_i32_16x16x64_i8 v[40:43], v[164:167], v[208:211], 0
	v_mfma_i32_16x16x64_i8 v[40:43], v[160:163], v[204:207], v[40:43]
	v_mfma_i32_16x16x64_i8 v[24:27], v[160:163], v[212:215], 0
	v_mfma_i32_16x16x64_i8 v[24:27], v[164:167], v[216:219], v[24:27]
	v_mfma_i32_16x16x64_i8 v[8:11], v[164:167], v[224:227], 0
	v_mfma_i32_16x16x64_i8 v[8:11], v[160:163], v[220:223], v[8:11]
	v_mfma_i32_16x16x64_i8 v[4:7], v[168:171], v[220:223], 0
	v_mfma_i32_16x16x64_i8 v[4:7], v[178:181], v[224:227], v[4:7]
	v_mfma_i32_16x16x64_i8 v[20:23], v[178:181], v[216:219], 0
	v_mfma_i32_16x16x64_i8 v[20:23], v[168:171], v[212:215], v[20:23]
	v_mfma_i32_16x16x64_i8 v[36:39], v[168:171], v[204:207], 0
	v_mfma_i32_16x16x64_i8 v[36:39], v[178:181], v[208:211], v[36:39]
	v_mfma_i32_16x16x64_i8 v[52:55], v[178:181], v[186:189], 0
	v_mfma_i32_16x16x64_i8 v[52:55], v[168:171], v[182:185], v[52:55]
	s_barrier
	s_setprio 0
	s_mov_b32 m0, s44
	s_nop 0
	global_load_lds_dwordx4 v[228:229], off
	s_mov_b32 m0, s45
	s_nop 0
	global_load_lds_dwordx4 v[240:241], off
	s_add_i32 s50, 0, 0x18000
	s_add_i32 s51, 0, 0x1c000
	v_add_u32_e32 v136, s50, v175
	v_add_u32_e32 v178, s51, v175
	ds_read_b128 v[116:119], v136
	ds_read_b128 v[182:185], v177 offset:32768
	ds_read_b128 v[124:127], v136 offset:1024
	ds_read_b128 v[186:189], v177 offset:33792
	ds_read_b128 v[208:211], v177 offset:35840
	ds_read_b128 v[204:207], v177 offset:34816
	ds_read_b128 v[212:215], v177 offset:36864
	ds_read_b128 v[216:219], v177 offset:37888
	s_add_u32 s40, s40, 0x80000
	s_addc_u32 s41, s41, 0
	s_mov_b32 m0, s46
	ds_read_b128 v[224:227], v177 offset:39936
	ds_read_b128 v[220:223], v177 offset:38912
	ds_read_b128 v[132:135], v136 offset:2048
	ds_read_b128 v[136:139], v136 offset:3072
	ds_read_b128 v[160:163], v178
	ds_read_b128 v[164:167], v178 offset:1024
	ds_read_b128 v[168:171], v178 offset:2048
	ds_read_b128 v[178:181], v178 offset:3072
	global_load_lds_dwordx4 v152, s[40:41]
	s_mov_b32 m0, s47
	s_nop 0
	global_load_lds_dwordx4 v150, s[40:41]
	s_waitcnt vmcnt(8)
	s_waitcnt lgkmcnt(14)
	s_setprio 1
	s_barrier
	v_mfma_i32_16x16x64_i8 v[144:147], v[116:119], v[182:185], v[144:147]
	s_waitcnt lgkmcnt(12)
	v_mfma_i32_16x16x64_i8 v[144:147], v[124:127], v[186:189], v[144:147]
	s_waitcnt lgkmcnt(11)
	v_mfma_i32_16x16x64_i8 v[112:115], v[124:127], v[208:211], v[112:115]
	s_waitcnt lgkmcnt(10)
	v_mfma_i32_16x16x64_i8 v[112:115], v[116:119], v[204:207], v[112:115]
	s_waitcnt lgkmcnt(9)
	v_mfma_i32_16x16x64_i8 v[96:99], v[116:119], v[212:215], v[96:99]
	s_waitcnt lgkmcnt(8)
	v_mfma_i32_16x16x64_i8 v[96:99], v[124:127], v[216:219], v[96:99]
	s_waitcnt lgkmcnt(7)
	v_mfma_i32_16x16x64_i8 v[80:83], v[124:127], v[224:227], v[80:83]
	s_waitcnt lgkmcnt(6)
	v_mfma_i32_16x16x64_i8 v[80:83], v[116:119], v[220:223], v[80:83]
	s_waitcnt lgkmcnt(5)
	v_mfma_i32_16x16x64_i8 v[76:79], v[132:135], v[220:223], v[76:79]
	s_waitcnt lgkmcnt(4)
	v_mfma_i32_16x16x64_i8 v[76:79], v[136:139], v[224:227], v[76:79]
	v_mfma_i32_16x16x64_i8 v[92:95], v[136:139], v[216:219], v[92:95]
	v_mfma_i32_16x16x64_i8 v[92:95], v[132:135], v[212:215], v[92:95]
	v_mfma_i32_16x16x64_i8 v[108:111], v[132:135], v[204:207], v[108:111]
	v_mfma_i32_16x16x64_i8 v[108:111], v[136:139], v[208:211], v[108:111]
	v_mfma_i32_16x16x64_i8 v[140:143], v[136:139], v[186:189], v[140:143]
	v_mfma_i32_16x16x64_i8 v[140:143], v[132:135], v[182:185], v[140:143]
	s_waitcnt lgkmcnt(3)
	v_mfma_i32_16x16x64_i8 v[128:131], v[160:163], v[182:185], v[128:131]
	s_waitcnt lgkmcnt(2)
	v_mfma_i32_16x16x64_i8 v[128:131], v[164:167], v[186:189], v[128:131]
	v_mfma_i32_16x16x64_i8 v[104:107], v[164:167], v[208:211], v[104:107]
	v_mfma_i32_16x16x64_i8 v[104:107], v[160:163], v[204:207], v[104:107]
	v_mfma_i32_16x16x64_i8 v[88:91], v[160:163], v[212:215], v[88:91]
	v_mfma_i32_16x16x64_i8 v[88:91], v[164:167], v[216:219], v[88:91]
	v_mfma_i32_16x16x64_i8 v[72:75], v[164:167], v[224:227], v[72:75]
	v_mfma_i32_16x16x64_i8 v[72:75], v[160:163], v[220:223], v[72:75]
	s_waitcnt lgkmcnt(1)
	v_mfma_i32_16x16x64_i8 v[68:71], v[168:171], v[220:223], v[68:71]
	s_waitcnt lgkmcnt(0)
	v_mfma_i32_16x16x64_i8 v[68:71], v[178:181], v[224:227], v[68:71]
	v_mfma_i32_16x16x64_i8 v[84:87], v[178:181], v[216:219], v[84:87]
	v_mfma_i32_16x16x64_i8 v[84:87], v[168:171], v[212:215], v[84:87]
	v_mfma_i32_16x16x64_i8 v[100:103], v[168:171], v[204:207], v[100:103]
	v_mfma_i32_16x16x64_i8 v[100:103], v[178:181], v[208:211], v[100:103]
	v_mfma_i32_16x16x64_i8 v[120:123], v[178:181], v[186:189], v[120:123]
	v_mfma_i32_16x16x64_i8 v[120:123], v[168:171], v[182:185], v[120:123]
	s_barrier
	s_setprio 0
	s_add_i32 s40, s50, s43
	v_lshl_add_u64 v[172:173], v[172:173], 0, s[84:85]
	s_mov_b32 m0, s40
	ds_read_b128 v[182:185], v177 offset:49152
	ds_read_b128 v[186:189], v177 offset:50176
	ds_read_b128 v[208:211], v177 offset:52224
	ds_read_b128 v[204:207], v177 offset:51200
	ds_read_b128 v[212:215], v177 offset:53248
	ds_read_b128 v[216:219], v177 offset:54272
	ds_read_b128 v[224:227], v177 offset:56320
	ds_read_b128 v[220:223], v177 offset:55296
	global_load_lds_dwordx4 v[172:173], off
	s_add_i32 m0, s40, 0x2000
	s_add_u32 s36, s36, 0x80080
	v_lshl_add_u64 v[172:173], v[190:191], 0, s[84:85]
	s_addc_u32 s37, s37, 0
	s_add_i32 s40, s51, s43
	global_load_lds_dwordx4 v[172:173], off
	s_mov_b32 m0, s40
	s_nop 0
	global_load_lds_dwordx4 v2, s[36:37]
	s_add_i32 m0, s40, 0x2000
	s_nop 0
	global_load_lds_dwordx4 v148, s[36:37]
	s_cmp_eq_u32 s76, 28
	s_cbranch_scc0 .Ldefer_208_peel
	v_lshl_add_u64 v[172:173], v[228:229], 0, s[84:85]
	s_mov_b32 m0, s52
	s_nop 0
	global_load_lds_dwordx4 v[172:173], off
	v_lshl_add_u64 v[172:173], v[240:241], 0, s[84:85]
	s_mov_b32 m0, s53
	s_nop 0
	global_load_lds_dwordx4 v[172:173], off
; #define PG8_STAGE(bufoff, gbase, voff) do { _Pragma("unroll") for (int _i = 0; _i < 2; ++_i) \
;         __builtin_amdgcn_global_load_lds((const unsigned*)((const char*)(gbase) + (voff)[_i]), (PG8_LAS unsigned*)(lds + (bufoff) + ldsw + _i * 8192), 16, 0, 0); } while (0)
; #define PG8_LDA(dst, b, h) do { _Pragma("unroll") for (int m = 0; m < 4; ++m) _Pragma("unroll") for (int k = 0; k < 2; ++k) dst[m][k] = *(const PG8_LAS bf16x8*)(lds + PG8_SA(b, h) + aoff + m * 2048 + k * 1024); } while (0)
; #define PG8_LDB(dst, b, h) do { _Pragma("unroll") for (int n = 0; n < 2; ++n) _Pragma("unroll") for (int k = 0; k < 2; ++k) dst[n][k] = *(const PG8_LAS bf16x8*)(lds + PG8_SB(b, h) + boff + n * 2048 + k * 1024); } while (0)
; #define PG8_WAIT_V(n) asm volatile("s_waitcnt vmcnt(" #n ")" ::: "memory")
; #define PG8_WAIT_L(n) asm volatile("s_waitcnt lgkmcnt(" #n ")" ::: "memory")
; #define PG8_BAR __builtin_amdgcn_s_barrier()
; #define PG8_SCHED __builtin_amdgcn_sched_barrier(0)
; template <class Epi, class Sched, bool ALIGN_EPI = false, bool SP2 = false, bool I8 = false>
; __device__ __forceinline__ void gemm_phase(PG8_LAS unsigned char* lds, const Gemm g, const Sched& S, const Epi& E) {
;     ...
;         for (int t = 0; t < nt; t += 2) {
;             const bool last = (t == nt - 2);
;             const char* a1 = cA + (size_t)(t + 1) * kstep;
;             const char* a2 = last ? nA : cA + (size_t)(t + 2) * kstep; const char* b2 = last ? nB : cB + (size_t)(t + 2) * kstep;
;             const char* a3 = a2 + kstep; const char* b3 = b2 + kstep;
;             if (last && has_next) S.a_ready(nxt);
;             if constexpr (SP2) {
;             PG8_LDB(B0, 0, 0); PG8_LDB(B1, 0, 1); PG8_SCHED; PG8_LDA(At, 0, 0); PG8_STAGE(PG8_SA(1, 1), a1 + hstep, voffA);
;             PG8_WAIT_V(8); PG8_WAIT_L(0); PG8_BAR; PG8_MMA(0, 0, At, B0); PG8_MMA(0, 1, At, B1); PG8_BAR; PG8_SCHED;
;     ...
;             PG8_LDA(At, 1, 1); PG8_STAGE(PG8_SB(1, 0), b3, voffB); PG8_STAGE(PG8_SB(1, 1), b3 + hstep, voffB); PG8_STAGE(PG8_SA(1, 0), a3, voffA);
;             PG8_WAIT_V(8); PG8_WAIT_L(0); PG8_BAR; PG8_MMA(1, 0, At, B0); PG8_MMA(1, 1, At, B1); PG8_BAR; PG8_SCHED;
.Ldefer_208_peel:
	s_waitcnt vmcnt(6)
	s_waitcnt lgkmcnt(7)
	s_setprio 1
	s_barrier
	v_mfma_i32_16x16x64_i8 v[64:67], v[116:119], v[182:185], v[64:67]
	s_waitcnt lgkmcnt(6)
	v_mfma_i32_16x16x64_i8 v[64:67], v[124:127], v[186:189], v[64:67]
	s_waitcnt lgkmcnt(5)
	v_mfma_i32_16x16x64_i8 v[48:51], v[124:127], v[208:211], v[48:51]
	s_waitcnt lgkmcnt(4)
	v_mfma_i32_16x16x64_i8 v[48:51], v[116:119], v[204:207], v[48:51]
	s_waitcnt lgkmcnt(3)
	v_mfma_i32_16x16x64_i8 v[32:35], v[116:119], v[212:215], v[32:35]
	s_waitcnt lgkmcnt(2)
	v_mfma_i32_16x16x64_i8 v[32:35], v[124:127], v[216:219], v[32:35]
	s_waitcnt lgkmcnt(1)
	v_mfma_i32_16x16x64_i8 v[16:19], v[124:127], v[224:227], v[16:19]
	s_waitcnt lgkmcnt(0)
	v_mfma_i32_16x16x64_i8 v[16:19], v[116:119], v[220:223], v[16:19]
	v_mfma_i32_16x16x64_i8 v[12:15], v[132:135], v[220:223], v[12:15]
	v_mfma_i32_16x16x64_i8 v[12:15], v[136:139], v[224:227], v[12:15]
	v_mfma_i32_16x16x64_i8 v[28:31], v[136:139], v[216:219], v[28:31]
	v_mfma_i32_16x16x64_i8 v[28:31], v[132:135], v[212:215], v[28:31]
	v_mfma_i32_16x16x64_i8 v[44:47], v[132:135], v[204:207], v[44:47]
	v_mfma_i32_16x16x64_i8 v[44:47], v[136:139], v[208:211], v[44:47]
	v_mfma_i32_16x16x64_i8 v[60:63], v[136:139], v[186:189], v[60:63]
	v_mfma_i32_16x16x64_i8 v[60:63], v[132:135], v[182:185], v[60:63]
	v_mfma_i32_16x16x64_i8 v[56:59], v[160:163], v[182:185], v[56:59]
	v_mfma_i32_16x16x64_i8 v[56:59], v[164:167], v[186:189], v[56:59]
	v_mfma_i32_16x16x64_i8 v[40:43], v[164:167], v[208:211], v[40:43]
	v_mfma_i32_16x16x64_i8 v[40:43], v[160:163], v[204:207], v[40:43]
	v_mfma_i32_16x16x64_i8 v[24:27], v[160:163], v[212:215], v[24:27]
	v_mfma_i32_16x16x64_i8 v[24:27], v[164:167], v[216:219], v[24:27]
	v_mfma_i32_16x16x64_i8 v[8:11], v[164:167], v[224:227], v[8:11]
	v_mfma_i32_16x16x64_i8 v[8:11], v[160:163], v[220:223], v[8:11]
	v_mfma_i32_16x16x64_i8 v[4:7], v[168:171], v[220:223], v[4:7]
	v_mfma_i32_16x16x64_i8 v[4:7], v[178:181], v[224:227], v[4:7]
	v_mfma_i32_16x16x64_i8 v[20:23], v[178:181], v[216:219], v[20:23]
	v_mfma_i32_16x16x64_i8 v[20:23], v[168:171], v[212:215], v[20:23]
	v_mfma_i32_16x16x64_i8 v[36:39], v[168:171], v[204:207], v[36:39]
	v_mfma_i32_16x16x64_i8 v[36:39], v[178:181], v[208:211], v[36:39]
	v_mfma_i32_16x16x64_i8 v[52:55], v[178:181], v[186:189], v[52:55]
	v_mfma_i32_16x16x64_i8 v[52:55], v[168:171], v[182:185], v[52:55]
	s_barrier
	s_setprio 0
	s_add_i32 s76, s76, 2
	s_add_u32 s26, s26, 0x100
	s_addc_u32 s27, s27, 0
	s_add_u32 s72, s72, 0x100
	s_addc_u32 s73, s73, 0
	s_cmp_gt_u32 s76, 29
	s_cbranch_scc1 .Lkloop_exit_0
.LBB0_208:
	s_add_u32 s36, s26, 0xfff80080
	s_addc_u32 s37, s27, -1
	s_add_i32 s50, 0, 0x10000
	s_cmp_eq_u32 s76, 28
	s_cselect_b32 s41, s19, s37
	s_cselect_b32 s40, s64, s36
	s_cselect_b32 s37, s17, s73
	s_cselect_b32 s36, s65, s72
	s_add_i32 s56, 0, 0x14000
	v_add_u32_e32 v136, s50, v175
	v_add_u32_e32 v172, s56, v175
	ds_read_b128 v[116:119], v136
	ds_read_b128 v[124:127], v136 offset:1024
	ds_read_b128 v[132:135], v136 offset:2048
	ds_read_b128 v[136:139], v136 offset:3072
	ds_read_b128 v[160:163], v172
	ds_read_b128 v[164:167], v172 offset:1024
	ds_read_b128 v[168:171], v172 offset:2048
	ds_read_b128 v[178:181], v172 offset:3072
	v_lshl_add_u64 v[172:173], v[228:229], 0, s[84:85]
	s_mov_b32 m0, s52
	s_nop 0
	global_load_lds_dwordx4 v[172:173], off
	v_lshl_add_u64 v[172:173], v[240:241], 0, s[84:85]
	s_mov_b32 m0, s53
	s_nop 0
	global_load_lds_dwordx4 v[172:173], off
	s_add_i32 m0, s44, 0xc000
	ds_read_b128 v[182:185], v177
	ds_read_b128 v[186:189], v177 offset:1024
	ds_read_b128 v[204:207], v177 offset:2048
	ds_read_b128 v[208:211], v177 offset:3072
	ds_read_b128 v[212:215], v177 offset:4096
	ds_read_b128 v[216:219], v177 offset:5120
	ds_read_b128 v[220:223], v177 offset:6144
	ds_read_b128 v[224:227], v177 offset:7168
	global_load_lds_dwordx4 v156, s[26:27]
	s_add_i32 m0, s44, 0xe000
	s_nop 0
	global_load_lds_dwordx4 v158, s[26:27]
	s_waitcnt vmcnt(8)
	s_waitcnt lgkmcnt(7)
	s_setprio 1
	s_barrier
	v_mfma_i32_16x16x64_i8 v[144:147], v[116:119], v[182:185], v[144:147]
	s_waitcnt lgkmcnt(6)
	v_mfma_i32_16x16x64_i8 v[144:147], v[124:127], v[186:189], v[144:147]
	s_waitcnt lgkmcnt(4)
	v_mfma_i32_16x16x64_i8 v[112:115], v[124:127], v[208:211], v[112:115]
	v_mfma_i32_16x16x64_i8 v[112:115], v[116:119], v[204:207], v[112:115]
	s_waitcnt lgkmcnt(3)
	v_mfma_i32_16x16x64_i8 v[96:99], v[116:119], v[212:215], v[96:99]
	s_waitcnt lgkmcnt(2)
	v_mfma_i32_16x16x64_i8 v[96:99], v[124:127], v[216:219], v[96:99]
	s_waitcnt lgkmcnt(0)
	v_mfma_i32_16x16x64_i8 v[80:83], v[124:127], v[224:227], v[80:83]
	v_mfma_i32_16x16x64_i8 v[80:83], v[116:119], v[220:223], v[80:83]
	v_mfma_i32_16x16x64_i8 v[76:79], v[132:135], v[220:223], v[76:79]
	v_mfma_i32_16x16x64_i8 v[76:79], v[136:139], v[224:227], v[76:79]
	v_mfma_i32_16x16x64_i8 v[92:95], v[136:139], v[216:219], v[92:95]
	v_mfma_i32_16x16x64_i8 v[92:95], v[132:135], v[212:215], v[92:95]
	v_mfma_i32_16x16x64_i8 v[108:111], v[132:135], v[204:207], v[108:111]
	v_mfma_i32_16x16x64_i8 v[108:111], v[136:139], v[208:211], v[108:111]
	v_mfma_i32_16x16x64_i8 v[140:143], v[136:139], v[186:189], v[140:143]
	v_mfma_i32_16x16x64_i8 v[140:143], v[132:135], v[182:185], v[140:143]
	v_mfma_i32_16x16x64_i8 v[128:131], v[160:163], v[182:185], v[128:131]
	v_mfma_i32_16x16x64_i8 v[128:131], v[164:167], v[186:189], v[128:131]
	v_mfma_i32_16x16x64_i8 v[104:107], v[164:167], v[208:211], v[104:107]
	v_mfma_i32_16x16x64_i8 v[104:107], v[160:163], v[204:207], v[104:107]
	v_mfma_i32_16x16x64_i8 v[88:91], v[160:163], v[212:215], v[88:91]
	v_mfma_i32_16x16x64_i8 v[88:91], v[164:167], v[216:219], v[88:91]
	v_mfma_i32_16x16x64_i8 v[72:75], v[164:167], v[224:227], v[72:75]
	v_mfma_i32_16x16x64_i8 v[72:75], v[160:163], v[220:223], v[72:75]
	v_mfma_i32_16x16x64_i8 v[68:71], v[168:171], v[220:223], v[68:71]
	v_mfma_i32_16x16x64_i8 v[68:71], v[178:181], v[224:227], v[68:71]
	v_mfma_i32_16x16x64_i8 v[84:87], v[178:181], v[216:219], v[84:87]
	v_mfma_i32_16x16x64_i8 v[84:87], v[168:171], v[212:215], v[84:87]
	v_mfma_i32_16x16x64_i8 v[100:103], v[168:171], v[204:207], v[100:103]
	v_mfma_i32_16x16x64_i8 v[100:103], v[178:181], v[208:211], v[100:103]
	v_mfma_i32_16x16x64_i8 v[120:123], v[178:181], v[186:189], v[120:123]
	v_mfma_i32_16x16x64_i8 v[120:123], v[168:171], v[182:185], v[120:123]
	s_barrier
; #define PG8_STAGE(bufoff, gbase, voff) do { _Pragma("unroll") for (int _i = 0; _i < 2; ++_i) \
;         __builtin_amdgcn_global_load_lds((const unsigned*)((const char*)(gbase) + (voff)[_i]), (PG8_LAS unsigned*)(lds + (bufoff) + ldsw + _i * 8192), 16, 0, 0); } while (0)
; #define PG8_LDA(dst, b, h) do { _Pragma("unroll") for (int m = 0; m < 4; ++m) _Pragma("unroll") for (int k = 0; k < 2; ++k) dst[m][k] = *(const PG8_LAS bf16x8*)(lds + PG8_SA(b, h) + aoff + m * 2048 + k * 1024); } while (0)
; #define PG8_LDB(dst, b, h) do { _Pragma("unroll") for (int n = 0; n < 2; ++n) _Pragma("unroll") for (int k = 0; k < 2; ++k) dst[n][k] = *(const PG8_LAS bf16x8*)(lds + PG8_SB(b, h) + boff + n * 2048 + k * 1024); } while (0)
; #define PG8_WAIT_V(n) asm volatile("s_waitcnt vmcnt(" #n ")" ::: "memory")
; #define PG8_WAIT_L(n) asm volatile("s_waitcnt lgkmcnt(" #n ")" ::: "memory")
; #define PG8_BAR __builtin_amdgcn_s_barrier()
; #define PG8_SCHED __builtin_amdgcn_sched_barrier(0)
; template <class Epi, class Sched, bool ALIGN_EPI = false, bool SP2 = false, bool I8 = false>
; __device__ __forceinline__ void gemm_phase(PG8_LAS unsigned char* lds, const Gemm g, const Sched& S, const Epi& E) {
;     ...
;             PG8_WAIT_V(8); PG8_WAIT_L(0); PG8_BAR; PG8_MMA(0, 0, At, B0); PG8_MMA(0, 1, At, B1); PG8_BAR; PG8_SCHED;
;             PG8_LDA(At, 0, 1); PG8_STAGE(PG8_SB(0, 0), b2, voffB); PG8_STAGE(PG8_SB(0, 1), b2 + hstep, voffB); PG8_STAGE(PG8_SA(0, 0), a2, voffA);
;             PG8_WAIT_V(8); PG8_WAIT_L(0); PG8_BAR; PG8_MMA(1, 0, At, B0); PG8_MMA(1, 1, At, B1); PG8_BAR; PG8_SCHED;
;             PG8_LDB(B0, 1, 0); PG8_LDB(B1, 1, 1); PG8_SCHED; PG8_LDA(At, 1, 0); PG8_STAGE(PG8_SA(0, 1), a2 + hstep, voffA);
	s_setprio 0
	s_add_i32 s50, s50, s43
	v_lshl_add_u64 v[172:173], s[36:37], 0, v[2:3]
	s_mov_b32 m0, s50
	ds_read_b128 v[182:185], v177 offset:16384
	ds_read_b128 v[186:189], v177 offset:17408
	ds_read_b128 v[208:211], v177 offset:19456
	ds_read_b128 v[204:207], v177 offset:18432
	ds_read_b128 v[212:215], v177 offset:20480
	ds_read_b128 v[216:219], v177 offset:21504
	ds_read_b128 v[224:227], v177 offset:23552
	ds_read_b128 v[220:223], v177 offset:22528
	global_load_lds_dwordx4 v[172:173], off
	s_add_i32 m0, s50, 0x2000
	s_add_u32 s50, s36, 0x80000
	v_lshl_add_u64 v[190:191], s[36:37], 0, v[148:149]
	s_addc_u32 s51, s37, 0
	s_add_i32 s56, s56, s43
	global_load_lds_dwordx4 v[190:191], off
	s_mov_b32 m0, s56
	v_lshl_add_u64 v[240:241], s[40:41], 0, v[150:151]
	global_load_lds_dwordx4 v2, s[50:51]
	s_add_i32 m0, s56, 0x2000
	s_nop 0
	global_load_lds_dwordx4 v148, s[50:51]
	v_lshl_add_u64 v[228:229], s[40:41], 0, v[152:153]
	s_waitcnt vmcnt(6)
	s_waitcnt lgkmcnt(7)
	s_setprio 1
	s_barrier
	v_mfma_i32_16x16x64_i8 v[64:67], v[116:119], v[182:185], v[64:67]
	s_waitcnt lgkmcnt(6)
	v_mfma_i32_16x16x64_i8 v[64:67], v[124:127], v[186:189], v[64:67]
	s_waitcnt lgkmcnt(5)
	v_mfma_i32_16x16x64_i8 v[48:51], v[124:127], v[208:211], v[48:51]
	s_waitcnt lgkmcnt(4)
	v_mfma_i32_16x16x64_i8 v[48:51], v[116:119], v[204:207], v[48:51]
	s_waitcnt lgkmcnt(3)
	v_mfma_i32_16x16x64_i8 v[32:35], v[116:119], v[212:215], v[32:35]
	s_waitcnt lgkmcnt(2)
	v_mfma_i32_16x16x64_i8 v[32:35], v[124:127], v[216:219], v[32:35]
	s_waitcnt lgkmcnt(1)
	v_mfma_i32_16x16x64_i8 v[16:19], v[124:127], v[224:227], v[16:19]
	s_waitcnt lgkmcnt(0)
	v_mfma_i32_16x16x64_i8 v[16:19], v[116:119], v[220:223], v[16:19]
	v_mfma_i32_16x16x64_i8 v[12:15], v[132:135], v[220:223], v[12:15]
	v_mfma_i32_16x16x64_i8 v[12:15], v[136:139], v[224:227], v[12:15]
	v_mfma_i32_16x16x64_i8 v[28:31], v[136:139], v[216:219], v[28:31]
	v_mfma_i32_16x16x64_i8 v[28:31], v[132:135], v[212:215], v[28:31]
	v_mfma_i32_16x16x64_i8 v[44:47], v[132:135], v[204:207], v[44:47]
	v_mfma_i32_16x16x64_i8 v[44:47], v[136:139], v[208:211], v[44:47]
	v_mfma_i32_16x16x64_i8 v[60:63], v[136:139], v[186:189], v[60:63]
	v_mfma_i32_16x16x64_i8 v[60:63], v[132:135], v[182:185], v[60:63]
	v_mfma_i32_16x16x64_i8 v[56:59], v[160:163], v[182:185], v[56:59]
	v_mfma_i32_16x16x64_i8 v[56:59], v[164:167], v[186:189], v[56:59]
	v_mfma_i32_16x16x64_i8 v[40:43], v[164:167], v[208:211], v[40:43]
	v_mfma_i32_16x16x64_i8 v[40:43], v[160:163], v[204:207], v[40:43]
	v_mfma_i32_16x16x64_i8 v[24:27], v[160:163], v[212:215], v[24:27]
	v_mfma_i32_16x16x64_i8 v[24:27], v[164:167], v[216:219], v[24:27]
	v_mfma_i32_16x16x64_i8 v[8:11], v[164:167], v[224:227], v[8:11]
	v_mfma_i32_16x16x64_i8 v[8:11], v[160:163], v[220:223], v[8:11]
	v_mfma_i32_16x16x64_i8 v[4:7], v[168:171], v[220:223], v[4:7]
	v_mfma_i32_16x16x64_i8 v[4:7], v[178:181], v[224:227], v[4:7]
	v_mfma_i32_16x16x64_i8 v[20:23], v[178:181], v[216:219], v[20:23]
	v_mfma_i32_16x16x64_i8 v[20:23], v[168:171], v[212:215], v[20:23]
	v_mfma_i32_16x16x64_i8 v[36:39], v[168:171], v[204:207], v[36:39]
	v_mfma_i32_16x16x64_i8 v[36:39], v[178:181], v[208:211], v[36:39]
	v_mfma_i32_16x16x64_i8 v[52:55], v[178:181], v[186:189], v[52:55]
	v_mfma_i32_16x16x64_i8 v[52:55], v[168:171], v[182:185], v[52:55]
	s_barrier
	s_setprio 0
	s_mov_b32 m0, s44
	s_nop 0
	global_load_lds_dwordx4 v[228:229], off
	s_mov_b32 m0, s45
	s_nop 0
	global_load_lds_dwordx4 v[240:241], off
	s_add_i32 s50, 0, 0x18000
	s_add_i32 s51, 0, 0x1c000
	v_add_u32_e32 v136, s50, v175
	v_add_u32_e32 v178, s51, v175
	ds_read_b128 v[116:119], v136
	ds_read_b128 v[182:185], v177 offset:32768
	ds_read_b128 v[124:127], v136 offset:1024
	ds_read_b128 v[186:189], v177 offset:33792
	ds_read_b128 v[208:211], v177 offset:35840
	ds_read_b128 v[204:207], v177 offset:34816
	ds_read_b128 v[212:215], v177 offset:36864
	ds_read_b128 v[216:219], v177 offset:37888
	s_add_u32 s40, s40, 0x80000
	s_addc_u32 s41, s41, 0
	s_mov_b32 m0, s46
	ds_read_b128 v[224:227], v177 offset:39936
	ds_read_b128 v[220:223], v177 offset:38912
	ds_read_b128 v[132:135], v136 offset:2048
	ds_read_b128 v[136:139], v136 offset:3072
	ds_read_b128 v[160:163], v178
	ds_read_b128 v[164:167], v178 offset:1024
	ds_read_b128 v[168:171], v178 offset:2048
	ds_read_b128 v[178:181], v178 offset:3072
	global_load_lds_dwordx4 v152, s[40:41]
	s_mov_b32 m0, s47
	s_nop 0
	global_load_lds_dwordx4 v150, s[40:41]
	s_waitcnt vmcnt(8)
	s_waitcnt lgkmcnt(14)
	s_setprio 1
	s_barrier
; #define PG8_STAGE(bufoff, gbase, voff) do { _Pragma("unroll") for (int _i = 0; _i < 2; ++_i) \
;         __builtin_amdgcn_global_load_lds((const unsigned*)((const char*)(gbase) + (voff)[_i]), (PG8_LAS unsigned*)(lds + (bufoff) + ldsw + _i * 8192), 16, 0, 0); } while (0)
; #define PG8_LDA(dst, b, h) do { _Pragma("unroll") for (int m = 0; m < 4; ++m) _Pragma("unroll") for (int k = 0; k < 2; ++k) dst[m][k] = *(const PG8_LAS bf16x8*)(lds + PG8_SA(b, h) + aoff + m * 2048 + k * 1024); } while (0)
; #define PG8_WAIT_V(n) asm volatile("s_waitcnt vmcnt(" #n ")" ::: "memory")
; #define PG8_WAIT_L(n) asm volatile("s_waitcnt lgkmcnt(" #n ")" ::: "memory")
; #define PG8_BAR __builtin_amdgcn_s_barrier()
; #define PG8_SCHED __builtin_amdgcn_sched_barrier(0)
; template <class Epi, class Sched, bool ALIGN_EPI = false, bool SP2 = false, bool I8 = false>
; __device__ __forceinline__ void gemm_phase(PG8_LAS unsigned char* lds, const Gemm g, const Sched& S, const Epi& E) {
;     ...
;             PG8_WAIT_V(8); PG8_WAIT_L(0); PG8_BAR; PG8_MMA(0, 0, At, B0); PG8_MMA(0, 1, At, B1); PG8_BAR; PG8_SCHED;
;             PG8_LDA(At, 1, 1); PG8_STAGE(PG8_SB(1, 0), b3, voffB); PG8_STAGE(PG8_SB(1, 1), b3 + hstep, voffB); PG8_STAGE(PG8_SA(1, 0), a3, voffA);
;             PG8_WAIT_V(8); PG8_WAIT_L(0); PG8_BAR; PG8_MMA(1, 0, At, B0); PG8_MMA(1, 1, At, B1); PG8_BAR; PG8_SCHED;
	v_mfma_i32_16x16x64_i8 v[144:147], v[116:119], v[182:185], v[144:147]
	s_waitcnt lgkmcnt(12)
	v_mfma_i32_16x16x64_i8 v[144:147], v[124:127], v[186:189], v[144:147]
	s_waitcnt lgkmcnt(11)
	v_mfma_i32_16x16x64_i8 v[112:115], v[124:127], v[208:211], v[112:115]
	s_waitcnt lgkmcnt(10)
	v_mfma_i32_16x16x64_i8 v[112:115], v[116:119], v[204:207], v[112:115]
	s_waitcnt lgkmcnt(9)
	v_mfma_i32_16x16x64_i8 v[96:99], v[116:119], v[212:215], v[96:99]
	s_waitcnt lgkmcnt(8)
	v_mfma_i32_16x16x64_i8 v[96:99], v[124:127], v[216:219], v[96:99]
	s_waitcnt lgkmcnt(7)
	v_mfma_i32_16x16x64_i8 v[80:83], v[124:127], v[224:227], v[80:83]
	s_waitcnt lgkmcnt(6)
	v_mfma_i32_16x16x64_i8 v[80:83], v[116:119], v[220:223], v[80:83]
	s_waitcnt lgkmcnt(5)
	v_mfma_i32_16x16x64_i8 v[76:79], v[132:135], v[220:223], v[76:79]
	s_waitcnt lgkmcnt(4)
	v_mfma_i32_16x16x64_i8 v[76:79], v[136:139], v[224:227], v[76:79]
	v_mfma_i32_16x16x64_i8 v[92:95], v[136:139], v[216:219], v[92:95]
	v_mfma_i32_16x16x64_i8 v[92:95], v[132:135], v[212:215], v[92:95]
	v_mfma_i32_16x16x64_i8 v[108:111], v[132:135], v[204:207], v[108:111]
	v_mfma_i32_16x16x64_i8 v[108:111], v[136:139], v[208:211], v[108:111]
	v_mfma_i32_16x16x64_i8 v[140:143], v[136:139], v[186:189], v[140:143]
	v_mfma_i32_16x16x64_i8 v[140:143], v[132:135], v[182:185], v[140:143]
	s_waitcnt lgkmcnt(3)
	v_mfma_i32_16x16x64_i8 v[128:131], v[160:163], v[182:185], v[128:131]
	s_waitcnt lgkmcnt(2)
	v_mfma_i32_16x16x64_i8 v[128:131], v[164:167], v[186:189], v[128:131]
	v_mfma_i32_16x16x64_i8 v[104:107], v[164:167], v[208:211], v[104:107]
	v_mfma_i32_16x16x64_i8 v[104:107], v[160:163], v[204:207], v[104:107]
	v_mfma_i32_16x16x64_i8 v[88:91], v[160:163], v[212:215], v[88:91]
	v_mfma_i32_16x16x64_i8 v[88:91], v[164:167], v[216:219], v[88:91]
	v_mfma_i32_16x16x64_i8 v[72:75], v[164:167], v[224:227], v[72:75]
	v_mfma_i32_16x16x64_i8 v[72:75], v[160:163], v[220:223], v[72:75]
	s_waitcnt lgkmcnt(1)
	v_mfma_i32_16x16x64_i8 v[68:71], v[168:171], v[220:223], v[68:71]
	s_waitcnt lgkmcnt(0)
	v_mfma_i32_16x16x64_i8 v[68:71], v[178:181], v[224:227], v[68:71]
	v_mfma_i32_16x16x64_i8 v[84:87], v[178:181], v[216:219], v[84:87]
	v_mfma_i32_16x16x64_i8 v[84:87], v[168:171], v[212:215], v[84:87]
	v_mfma_i32_16x16x64_i8 v[100:103], v[168:171], v[204:207], v[100:103]
	v_mfma_i32_16x16x64_i8 v[100:103], v[178:181], v[208:211], v[100:103]
	v_mfma_i32_16x16x64_i8 v[120:123], v[178:181], v[186:189], v[120:123]
	v_mfma_i32_16x16x64_i8 v[120:123], v[168:171], v[182:185], v[120:123]
	s_barrier
	s_setprio 0
	s_add_i32 s40, s50, s43
	v_lshl_add_u64 v[172:173], v[172:173], 0, s[84:85]
	s_mov_b32 m0, s40
	ds_read_b128 v[182:185], v177 offset:49152
	ds_read_b128 v[186:189], v177 offset:50176
	ds_read_b128 v[208:211], v177 offset:52224
	ds_read_b128 v[204:207], v177 offset:51200
	ds_read_b128 v[212:215], v177 offset:53248
	ds_read_b128 v[216:219], v177 offset:54272
	ds_read_b128 v[224:227], v177 offset:56320
	ds_read_b128 v[220:223], v177 offset:55296
	global_load_lds_dwordx4 v[172:173], off
	s_add_i32 m0, s40, 0x2000
	s_add_u32 s36, s36, 0x80080
	v_lshl_add_u64 v[172:173], v[190:191], 0, s[84:85]
	s_addc_u32 s37, s37, 0
	s_add_i32 s40, s51, s43
	global_load_lds_dwordx4 v[172:173], off
	s_mov_b32 m0, s40
	s_nop 0
	global_load_lds_dwordx4 v2, s[36:37]
	s_add_i32 m0, s40, 0x2000
	s_nop 0
	global_load_lds_dwordx4 v148, s[36:37]
	s_cmp_eq_u32 s76, 28
	s_cbranch_scc0 .Ldefer_208_body
	v_lshl_add_u64 v[172:173], v[228:229], 0, s[84:85]
	s_mov_b32 m0, s52
	s_nop 0
	global_load_lds_dwordx4 v[172:173], off
	v_lshl_add_u64 v[172:173], v[240:241], 0, s[84:85]
	s_mov_b32 m0, s53
	s_nop 0
	global_load_lds_dwordx4 v[172:173], off
.Ldefer_208_body:
	s_waitcnt vmcnt(6)
	s_waitcnt lgkmcnt(7)
	s_setprio 1
	s_barrier
	v_mfma_i32_16x16x64_i8 v[64:67], v[116:119], v[182:185], v[64:67]
	s_waitcnt lgkmcnt(6)
	v_mfma_i32_16x16x64_i8 v[64:67], v[124:127], v[186:189], v[64:67]
	s_waitcnt lgkmcnt(5)
	v_mfma_i32_16x16x64_i8 v[48:51], v[124:127], v[208:211], v[48:51]
	s_waitcnt lgkmcnt(4)
	v_mfma_i32_16x16x64_i8 v[48:51], v[116:119], v[204:207], v[48:51]
	s_waitcnt lgkmcnt(3)
	v_mfma_i32_16x16x64_i8 v[32:35], v[116:119], v[212:215], v[32:35]
	s_waitcnt lgkmcnt(2)
	v_mfma_i32_16x16x64_i8 v[32:35], v[124:127], v[216:219], v[32:35]
	s_waitcnt lgkmcnt(1)
	v_mfma_i32_16x16x64_i8 v[16:19], v[124:127], v[224:227], v[16:19]
	s_waitcnt lgkmcnt(0)
	v_mfma_i32_16x16x64_i8 v[16:19], v[116:119], v[220:223], v[16:19]
	v_mfma_i32_16x16x64_i8 v[12:15], v[132:135], v[220:223], v[12:15]
	v_mfma_i32_16x16x64_i8 v[12:15], v[136:139], v[224:227], v[12:15]
	v_mfma_i32_16x16x64_i8 v[28:31], v[136:139], v[216:219], v[28:31]
	v_mfma_i32_16x16x64_i8 v[28:31], v[132:135], v[212:215], v[28:31]
	v_mfma_i32_16x16x64_i8 v[44:47], v[132:135], v[204:207], v[44:47]
	v_mfma_i32_16x16x64_i8 v[44:47], v[136:139], v[208:211], v[44:47]
	v_mfma_i32_16x16x64_i8 v[60:63], v[136:139], v[186:189], v[60:63]
	v_mfma_i32_16x16x64_i8 v[60:63], v[132:135], v[182:185], v[60:63]
	v_mfma_i32_16x16x64_i8 v[56:59], v[160:163], v[182:185], v[56:59]
	v_mfma_i32_16x16x64_i8 v[56:59], v[164:167], v[186:189], v[56:59]
	v_mfma_i32_16x16x64_i8 v[40:43], v[164:167], v[208:211], v[40:43]
	v_mfma_i32_16x16x64_i8 v[40:43], v[160:163], v[204:207], v[40:43]
	v_mfma_i32_16x16x64_i8 v[24:27], v[160:163], v[212:215], v[24:27]
	v_mfma_i32_16x16x64_i8 v[24:27], v[164:167], v[216:219], v[24:27]
	v_mfma_i32_16x16x64_i8 v[8:11], v[164:167], v[224:227], v[8:11]
	v_mfma_i32_16x16x64_i8 v[8:11], v[160:163], v[220:223], v[8:11]
	v_mfma_i32_16x16x64_i8 v[4:7], v[168:171], v[220:223], v[4:7]
	v_mfma_i32_16x16x64_i8 v[4:7], v[178:181], v[224:227], v[4:7]
	v_mfma_i32_16x16x64_i8 v[20:23], v[178:181], v[216:219], v[20:23]
	v_mfma_i32_16x16x64_i8 v[20:23], v[168:171], v[212:215], v[20:23]
	v_mfma_i32_16x16x64_i8 v[36:39], v[168:171], v[204:207], v[36:39]
	v_mfma_i32_16x16x64_i8 v[36:39], v[178:181], v[208:211], v[36:39]
	v_mfma_i32_16x16x64_i8 v[52:55], v[178:181], v[186:189], v[52:55]
	v_mfma_i32_16x16x64_i8 v[52:55], v[168:171], v[182:185], v[52:55]
	s_barrier
	s_setprio 0
	s_add_i32 s76, s76, 2
	s_add_u32 s26, s26, 0x100
	s_addc_u32 s27, s27, 0
	s_add_u32 s72, s72, 0x100
	s_addc_u32 s73, s73, 0
	s_cmp_gt_u32 s76, 29
	s_cbranch_scc0 .LBB0_208

; #define PG8_STAGE(bufoff, gbase, voff) do { _Pragma("unroll") for (int _i = 0; _i < 2; ++_i) \
;         __builtin_amdgcn_global_load_lds((const unsigned*)((const char*)(gbase) + (voff)[_i]), (PG8_LAS unsigned*)(lds + (bufoff) + ldsw + _i * 8192), 16, 0, 0); } while (0)
; #define PG8_LDA(dst, b, h) do { _Pragma("unroll") for (int m = 0; m < 4; ++m) _Pragma("unroll") for (int k = 0; k < 2; ++k) dst[m][k] = *(const PG8_LAS bf16x8*)(lds + PG8_SA(b, h) + aoff + m * 2048 + k * 1024); } while (0)
; #define PG8_LDB(dst, b, h) do { _Pragma("unroll") for (int n = 0; n < 2; ++n) _Pragma("unroll") for (int k = 0; k < 2; ++k) dst[n][k] = *(const PG8_LAS bf16x8*)(lds + PG8_SB(b, h) + boff + n * 2048 + k * 1024); } while (0)
; #define PG8_WAIT_V(n) asm volatile("s_waitcnt vmcnt(" #n ")" ::: "memory")
; #define PG8_WAIT_L(n) asm volatile("s_waitcnt lgkmcnt(" #n ")" ::: "memory")
; #define PG8_BAR __builtin_amdgcn_s_barrier()
; #define PG8_SCHED __builtin_amdgcn_sched_barrier(0)
; template <class Epi, class Sched, bool ALIGN_EPI = false, bool SP2 = false, bool I8 = false>
; __device__ __forceinline__ void gemm_phase(PG8_LAS unsigned char* lds, const Gemm g, const Sched& S, const Epi& E) {
;     ...
;         const bool has_next = S.next(ui + 1, nxt);
;         const char* nA = has_next ? (const char*)g.A + (size_t)nxt.pm * tstep : cA; const char* nB = has_next ? (const char*)g.Bt + (size_t)nxt.pn * tstep : cB;
;         for (int t = 0; t < nt; t += 2) {
;             const bool last = (t == nt - 2);
;             const char* a1 = cA + (size_t)(t + 1) * kstep;
;             const char* a2 = last ? nA : cA + (size_t)(t + 2) * kstep; const char* b2 = last ? nB : cB + (size_t)(t + 2) * kstep;
;             const char* a3 = a2 + kstep; const char* b3 = b2 + kstep;
;             if (last && has_next) S.a_ready(nxt);
;             if constexpr (SP2) {
;             PG8_LDB(B0, 0, 0); PG8_LDB(B1, 0, 1); PG8_SCHED; PG8_LDA(At, 0, 0); PG8_STAGE(PG8_SA(1, 1), a1 + hstep, voffA);
;             PG8_WAIT_V(8); PG8_WAIT_L(0); PG8_BAR; PG8_MMA(0, 0, At, B0); PG8_MMA(0, 1, At, B1); PG8_BAR; PG8_SCHED;
;             PG8_LDA(At, 0, 1); PG8_STAGE(PG8_SB(0, 0), b2, voffB); PG8_STAGE(PG8_SB(0, 1), b2 + hstep, voffB); PG8_STAGE(PG8_SA(0, 0), a2, voffA);
;             PG8_WAIT_V(8); PG8_WAIT_L(0); PG8_BAR; PG8_MMA(1, 0, At, B0); PG8_MMA(1, 1, At, B1); PG8_BAR; PG8_SCHED;
.LBB0_229:
	s_ashr_i32 s37, s36, 31
	s_lshl_b64 s[34:35], s[36:37], 21
	s_add_u32 s40, s42, s34
	s_addc_u32 s41, s43, s35
	s_and_b64 s[34:35], s[8:9], exec
	s_cselect_b32 s11, s41, s13
	s_cselect_b32 s34, s40, s12
	s_ashr_i32 s27, s26, 31
	s_lshl_b64 s[50:51], s[26:27], 21
	s_add_u32 s54, s44, s50
	s_addc_u32 s55, s45, s51
	s_and_b64 s[50:51], s[8:9], exec
	s_cselect_b32 s27, s55, s73
	s_cselect_b32 s35, s54, s72
	s_add_u32 s12, s12, 0x100080
	s_addc_u32 s13, s13, 0
	s_add_u32 s37, s72, 0x100
	s_addc_u32 s61, s73, 0
	s_mov_b32 s97, -2
	s_add_u32 s50, s12, 0xfff00080
	s_addc_u32 s51, s13, -1
	s_add_i32 s56, 0, 0x10000
	s_cmp_eq_u32 s97, 60
	s_cselect_b32 s77, s11, s51
	s_cselect_b32 s76, s34, s50
	s_cselect_b32 s73, s27, s61
	s_cselect_b32 s72, s35, s37
	s_add_i32 s57, 0, 0x14000
	v_add_u32_e32 v156, s56, v171
	v_add_u32_e32 v168, s57, v171
	s_waitcnt vmcnt(0)
	ds_read_b128 v[112:115], v156
	ds_read_b128 v[184:187], v173
	ds_read_b128 v[120:123], v156 offset:1024
	ds_read_b128 v[188:191], v173 offset:1024
	ds_read_b128 v[208:211], v173 offset:3072
	ds_read_b128 v[204:207], v173 offset:2048
	s_waitcnt lgkmcnt(0)
	ds_read_b128 v[212:215], v173 offset:4096
	ds_read_b128 v[216:219], v173 offset:5120
	s_add_i32 m0, s47, 0xc000
	ds_read_b128 v[224:227], v173 offset:7168
	ds_read_b128 v[220:223], v173 offset:6144
	ds_read_b128 v[152:155], v156 offset:2048
	ds_read_b128 v[156:159], v156 offset:3072
	ds_read_b128 v[160:163], v168
	ds_read_b128 v[164:167], v168 offset:1024
	ds_read_b128 v[176:179], v168 offset:2048
	ds_read_b128 v[180:183], v168 offset:3072
	global_load_lds_dwordx4 v148, s[12:13]
	s_add_i32 m0, s47, 0xe000
	s_nop 0
	global_load_lds_dwordx4 v150, s[12:13]
	s_waitcnt vmcnt(8)
	s_waitcnt lgkmcnt(14)
	s_setprio 1
	s_barrier
	v_mfma_f32_16x16x32_bf16 v[136:139], v[112:115], v[184:187], 0
	s_waitcnt lgkmcnt(12)
	v_mfma_f32_16x16x32_bf16 v[136:139], v[120:123], v[188:191], v[136:139]
	s_waitcnt lgkmcnt(11)
	v_mfma_f32_16x16x32_bf16 v[116:119], v[120:123], v[208:211], 0
	s_waitcnt lgkmcnt(10)
	v_mfma_f32_16x16x32_bf16 v[116:119], v[112:115], v[204:207], v[116:119]
	s_waitcnt lgkmcnt(9)
	v_mfma_f32_16x16x32_bf16 v[96:99], v[112:115], v[212:215], 0
	s_waitcnt lgkmcnt(8)
	v_mfma_f32_16x16x32_bf16 v[96:99], v[120:123], v[216:219], v[96:99]
	s_waitcnt lgkmcnt(7)
	v_mfma_f32_16x16x32_bf16 v[80:83], v[120:123], v[224:227], 0
	s_waitcnt lgkmcnt(6)
	v_mfma_f32_16x16x32_bf16 v[80:83], v[112:115], v[220:223], v[80:83]
	s_waitcnt lgkmcnt(5)
	v_mfma_f32_16x16x32_bf16 v[76:79], v[152:155], v[220:223], 0
	s_waitcnt lgkmcnt(4)
	v_mfma_f32_16x16x32_bf16 v[76:79], v[156:159], v[224:227], v[76:79]
	v_mfma_f32_16x16x32_bf16 v[92:95], v[156:159], v[216:219], 0
	v_mfma_f32_16x16x32_bf16 v[92:95], v[152:155], v[212:215], v[92:95]
	v_mfma_f32_16x16x32_bf16 v[108:111], v[152:155], v[204:207], 0
	v_mfma_f32_16x16x32_bf16 v[108:111], v[156:159], v[208:211], v[108:111]
	v_mfma_f32_16x16x32_bf16 v[132:135], v[156:159], v[188:191], 0
	v_mfma_f32_16x16x32_bf16 v[132:135], v[152:155], v[184:187], v[132:135]
	s_waitcnt lgkmcnt(3)
	v_mfma_f32_16x16x32_bf16 v[128:131], v[160:163], v[184:187], 0
	s_waitcnt lgkmcnt(2)
	v_mfma_f32_16x16x32_bf16 v[128:131], v[164:167], v[188:191], v[128:131]
	v_mfma_f32_16x16x32_bf16 v[104:107], v[164:167], v[208:211], 0
	v_mfma_f32_16x16x32_bf16 v[104:107], v[160:163], v[204:207], v[104:107]
	v_mfma_f32_16x16x32_bf16 v[88:91], v[160:163], v[212:215], 0
	v_mfma_f32_16x16x32_bf16 v[88:91], v[164:167], v[216:219], v[88:91]
	v_mfma_f32_16x16x32_bf16 v[72:75], v[164:167], v[224:227], 0
	v_mfma_f32_16x16x32_bf16 v[72:75], v[160:163], v[220:223], v[72:75]
	s_waitcnt lgkmcnt(1)
	v_mfma_f32_16x16x32_bf16 v[68:71], v[176:179], v[220:223], 0
	s_waitcnt lgkmcnt(0)
	v_mfma_f32_16x16x32_bf16 v[68:71], v[180:183], v[224:227], v[68:71]
	v_mfma_f32_16x16x32_bf16 v[84:87], v[180:183], v[216:219], 0
	v_mfma_f32_16x16x32_bf16 v[84:87], v[176:179], v[212:215], v[84:87]
	v_mfma_f32_16x16x32_bf16 v[100:103], v[176:179], v[204:207], 0
	v_mfma_f32_16x16x32_bf16 v[100:103], v[180:183], v[208:211], v[100:103]
	v_mfma_f32_16x16x32_bf16 v[124:127], v[180:183], v[188:191], 0
	v_mfma_f32_16x16x32_bf16 v[124:127], v[176:179], v[184:187], v[124:127]
	s_barrier
	s_setprio 0
	s_add_i32 s50, s56, s46
	v_lshl_add_u64 v[168:169], s[72:73], 0, v[2:3]
	s_mov_b32 m0, s50
	ds_read_b128 v[184:187], v173 offset:16384
	ds_read_b128 v[188:191], v173 offset:17408
	ds_read_b128 v[208:211], v173 offset:19456
	ds_read_b128 v[204:207], v173 offset:18432
	ds_read_b128 v[212:215], v173 offset:20480
	ds_read_b128 v[216:219], v173 offset:21504
	ds_read_b128 v[224:227], v173 offset:23552
	ds_read_b128 v[220:223], v173 offset:22528
	global_load_lds_dwordx4 v[168:169], off
	s_add_i32 m0, s50, 0x2000
	s_add_u32 s50, s72, 0x100000
	v_lshl_add_u64 v[228:229], s[72:73], 0, v[144:145]
	s_addc_u32 s51, s73, 0
	s_add_i32 s56, s57, s46
	global_load_lds_dwordx4 v[228:229], off
	s_mov_b32 m0, s56
	v_lshl_add_u64 v[242:243], s[76:77], 0, v[142:143]
	global_load_lds_dwordx4 v2, s[50:51]
	s_add_i32 m0, s56, 0x2000
	s_nop 0
	global_load_lds_dwordx4 v144, s[50:51]
	v_lshl_add_u64 v[240:241], s[76:77], 0, v[140:141]
	s_waitcnt vmcnt(6)
	s_waitcnt lgkmcnt(7)
	s_setprio 1
	s_barrier
; #define PG8_STAGE(bufoff, gbase, voff) do { _Pragma("unroll") for (int _i = 0; _i < 2; ++_i) \
;         __builtin_amdgcn_global_load_lds((const unsigned*)((const char*)(gbase) + (voff)[_i]), (PG8_LAS unsigned*)(lds + (bufoff) + ldsw + _i * 8192), 16, 0, 0); } while (0)
; #define PG8_LDA(dst, b, h) do { _Pragma("unroll") for (int m = 0; m < 4; ++m) _Pragma("unroll") for (int k = 0; k < 2; ++k) dst[m][k] = *(const PG8_LAS bf16x8*)(lds + PG8_SA(b, h) + aoff + m * 2048 + k * 1024); } while (0)
; #define PG8_LDB(dst, b, h) do { _Pragma("unroll") for (int n = 0; n < 2; ++n) _Pragma("unroll") for (int k = 0; k < 2; ++k) dst[n][k] = *(const PG8_LAS bf16x8*)(lds + PG8_SB(b, h) + boff + n * 2048 + k * 1024); } while (0)
; #define PG8_WAIT_V(n) asm volatile("s_waitcnt vmcnt(" #n ")" ::: "memory")
; #define PG8_WAIT_L(n) asm volatile("s_waitcnt lgkmcnt(" #n ")" ::: "memory")
; #define PG8_BAR __builtin_amdgcn_s_barrier()
; #define PG8_SCHED __builtin_amdgcn_sched_barrier(0)
; template <class Epi, class Sched, bool ALIGN_EPI = false, bool SP2 = false, bool I8 = false>
; __device__ __forceinline__ void gemm_phase(PG8_LAS unsigned char* lds, const Gemm g, const Sched& S, const Epi& E) {
;     ...
;             PG8_WAIT_V(8); PG8_WAIT_L(0); PG8_BAR; PG8_MMA(1, 0, At, B0); PG8_MMA(1, 1, At, B1); PG8_BAR; PG8_SCHED;
;             PG8_LDB(B0, 1, 0); PG8_LDB(B1, 1, 1); PG8_SCHED; PG8_LDA(At, 1, 0); PG8_STAGE(PG8_SA(0, 1), a2 + hstep, voffA);
;             PG8_WAIT_V(8); PG8_WAIT_L(0); PG8_BAR; PG8_MMA(0, 0, At, B0); PG8_MMA(0, 1, At, B1); PG8_BAR; PG8_SCHED;
	v_mfma_f32_16x16x32_bf16 v[64:67], v[112:115], v[184:187], 0
	s_waitcnt lgkmcnt(6)
	v_mfma_f32_16x16x32_bf16 v[64:67], v[120:123], v[188:191], v[64:67]
	s_waitcnt lgkmcnt(5)
	v_mfma_f32_16x16x32_bf16 v[48:51], v[120:123], v[208:211], 0
	s_waitcnt lgkmcnt(4)
	v_mfma_f32_16x16x32_bf16 v[48:51], v[112:115], v[204:207], v[48:51]
	s_waitcnt lgkmcnt(3)
	v_mfma_f32_16x16x32_bf16 v[32:35], v[112:115], v[212:215], 0
	s_waitcnt lgkmcnt(2)
	v_mfma_f32_16x16x32_bf16 v[32:35], v[120:123], v[216:219], v[32:35]
	s_waitcnt lgkmcnt(1)
	v_mfma_f32_16x16x32_bf16 v[16:19], v[120:123], v[224:227], 0
	s_waitcnt lgkmcnt(0)
	v_mfma_f32_16x16x32_bf16 v[16:19], v[112:115], v[220:223], v[16:19]
	v_mfma_f32_16x16x32_bf16 v[12:15], v[152:155], v[220:223], 0
	v_mfma_f32_16x16x32_bf16 v[12:15], v[156:159], v[224:227], v[12:15]
	v_mfma_f32_16x16x32_bf16 v[28:31], v[156:159], v[216:219], 0
	v_mfma_f32_16x16x32_bf16 v[28:31], v[152:155], v[212:215], v[28:31]
	v_mfma_f32_16x16x32_bf16 v[44:47], v[152:155], v[204:207], 0
	v_mfma_f32_16x16x32_bf16 v[44:47], v[156:159], v[208:211], v[44:47]
	v_mfma_f32_16x16x32_bf16 v[60:63], v[156:159], v[188:191], 0
	v_mfma_f32_16x16x32_bf16 v[60:63], v[152:155], v[184:187], v[60:63]
	v_mfma_f32_16x16x32_bf16 v[56:59], v[160:163], v[184:187], 0
	v_mfma_f32_16x16x32_bf16 v[56:59], v[164:167], v[188:191], v[56:59]
	v_mfma_f32_16x16x32_bf16 v[40:43], v[164:167], v[208:211], 0
	v_mfma_f32_16x16x32_bf16 v[40:43], v[160:163], v[204:207], v[40:43]
	v_mfma_f32_16x16x32_bf16 v[24:27], v[160:163], v[212:215], 0
	v_mfma_f32_16x16x32_bf16 v[24:27], v[164:167], v[216:219], v[24:27]
	v_mfma_f32_16x16x32_bf16 v[8:11], v[164:167], v[224:227], 0
	v_mfma_f32_16x16x32_bf16 v[8:11], v[160:163], v[220:223], v[8:11]
	v_mfma_f32_16x16x32_bf16 v[4:7], v[176:179], v[220:223], 0
	v_mfma_f32_16x16x32_bf16 v[4:7], v[180:183], v[224:227], v[4:7]
	v_mfma_f32_16x16x32_bf16 v[20:23], v[180:183], v[216:219], 0
	v_mfma_f32_16x16x32_bf16 v[20:23], v[176:179], v[212:215], v[20:23]
	v_mfma_f32_16x16x32_bf16 v[36:39], v[176:179], v[204:207], 0
	v_mfma_f32_16x16x32_bf16 v[36:39], v[180:183], v[208:211], v[36:39]
	v_mfma_f32_16x16x32_bf16 v[52:55], v[180:183], v[188:191], 0
	v_mfma_f32_16x16x32_bf16 v[52:55], v[176:179], v[184:187], v[52:55]
	s_barrier
	s_setprio 0
	s_mov_b32 m0, s47
	s_nop 0
	global_load_lds_dwordx4 v[240:241], off
	s_mov_b32 m0, s52
	s_nop 0
	global_load_lds_dwordx4 v[242:243], off
	s_add_i32 s56, 0, 0x18000
	s_add_i32 s57, 0, 0x1c000
	v_add_u32_e32 v156, s56, v171
	v_add_u32_e32 v175, s57, v171
	ds_read_b128 v[112:115], v156
	ds_read_b128 v[184:187], v173 offset:32768
	ds_read_b128 v[120:123], v156 offset:1024
	ds_read_b128 v[188:191], v173 offset:33792
	ds_read_b128 v[208:211], v173 offset:35840
	ds_read_b128 v[204:207], v173 offset:34816
	ds_read_b128 v[212:215], v173 offset:36864
	ds_read_b128 v[216:219], v173 offset:37888
	s_add_u32 s50, s76, 0x100000
	s_addc_u32 s51, s77, 0
	s_mov_b32 m0, s53
	ds_read_b128 v[224:227], v173 offset:39936
	ds_read_b128 v[220:223], v173 offset:38912
	ds_read_b128 v[152:155], v156 offset:2048
	ds_read_b128 v[156:159], v156 offset:3072
	ds_read_b128 v[160:163], v175
	ds_read_b128 v[164:167], v175 offset:1024
	ds_read_b128 v[176:179], v175 offset:2048
	ds_read_b128 v[180:183], v175 offset:3072
	global_load_lds_dwordx4 v140, s[50:51]
	s_mov_b32 m0, s64
	s_nop 0
	global_load_lds_dwordx4 v142, s[50:51]
	s_waitcnt vmcnt(8)
	s_waitcnt lgkmcnt(14)
	s_setprio 1
	s_barrier
	v_mfma_f32_16x16x32_bf16 v[136:139], v[112:115], v[184:187], v[136:139]
	s_waitcnt lgkmcnt(12)
	v_mfma_f32_16x16x32_bf16 v[136:139], v[120:123], v[188:191], v[136:139]
	s_waitcnt lgkmcnt(11)
	v_mfma_f32_16x16x32_bf16 v[116:119], v[120:123], v[208:211], v[116:119]
	s_waitcnt lgkmcnt(10)
	v_mfma_f32_16x16x32_bf16 v[116:119], v[112:115], v[204:207], v[116:119]
	s_waitcnt lgkmcnt(9)
	v_mfma_f32_16x16x32_bf16 v[96:99], v[112:115], v[212:215], v[96:99]
	s_waitcnt lgkmcnt(8)
	v_mfma_f32_16x16x32_bf16 v[96:99], v[120:123], v[216:219], v[96:99]
	s_waitcnt lgkmcnt(7)
	v_mfma_f32_16x16x32_bf16 v[80:83], v[120:123], v[224:227], v[80:83]
	s_waitcnt lgkmcnt(6)
	v_mfma_f32_16x16x32_bf16 v[80:83], v[112:115], v[220:223], v[80:83]
	s_waitcnt lgkmcnt(5)
	v_mfma_f32_16x16x32_bf16 v[76:79], v[152:155], v[220:223], v[76:79]
	s_waitcnt lgkmcnt(4)
	v_mfma_f32_16x16x32_bf16 v[76:79], v[156:159], v[224:227], v[76:79]
	v_mfma_f32_16x16x32_bf16 v[92:95], v[156:159], v[216:219], v[92:95]
	v_mfma_f32_16x16x32_bf16 v[92:95], v[152:155], v[212:215], v[92:95]
	v_mfma_f32_16x16x32_bf16 v[108:111], v[152:155], v[204:207], v[108:111]
	v_mfma_f32_16x16x32_bf16 v[108:111], v[156:159], v[208:211], v[108:111]
	v_mfma_f32_16x16x32_bf16 v[132:135], v[156:159], v[188:191], v[132:135]
	v_mfma_f32_16x16x32_bf16 v[132:135], v[152:155], v[184:187], v[132:135]
	s_waitcnt lgkmcnt(3)
	v_mfma_f32_16x16x32_bf16 v[128:131], v[160:163], v[184:187], v[128:131]
	s_waitcnt lgkmcnt(2)
	v_mfma_f32_16x16x32_bf16 v[128:131], v[164:167], v[188:191], v[128:131]
	v_mfma_f32_16x16x32_bf16 v[104:107], v[164:167], v[208:211], v[104:107]
	v_mfma_f32_16x16x32_bf16 v[104:107], v[160:163], v[204:207], v[104:107]
	v_mfma_f32_16x16x32_bf16 v[88:91], v[160:163], v[212:215], v[88:91]
	v_mfma_f32_16x16x32_bf16 v[88:91], v[164:167], v[216:219], v[88:91]
	v_mfma_f32_16x16x32_bf16 v[72:75], v[164:167], v[224:227], v[72:75]
	v_mfma_f32_16x16x32_bf16 v[72:75], v[160:163], v[220:223], v[72:75]
	s_waitcnt lgkmcnt(1)
	v_mfma_f32_16x16x32_bf16 v[68:71], v[176:179], v[220:223], v[68:71]
	s_waitcnt lgkmcnt(0)
	v_mfma_f32_16x16x32_bf16 v[68:71], v[180:183], v[224:227], v[68:71]
	v_mfma_f32_16x16x32_bf16 v[84:87], v[180:183], v[216:219], v[84:87]
	v_mfma_f32_16x16x32_bf16 v[84:87], v[176:179], v[212:215], v[84:87]
	v_mfma_f32_16x16x32_bf16 v[100:103], v[176:179], v[204:207], v[100:103]
	v_mfma_f32_16x16x32_bf16 v[100:103], v[180:183], v[208:211], v[100:103]
	v_mfma_f32_16x16x32_bf16 v[124:127], v[180:183], v[188:191], v[124:127]
	v_mfma_f32_16x16x32_bf16 v[124:127], v[176:179], v[184:187], v[124:127]
	s_barrier
; #define PG8_STAGE(bufoff, gbase, voff) do { _Pragma("unroll") for (int _i = 0; _i < 2; ++_i) \
;         __builtin_amdgcn_global_load_lds((const unsigned*)((const char*)(gbase) + (voff)[_i]), (PG8_LAS unsigned*)(lds + (bufoff) + ldsw + _i * 8192), 16, 0, 0); } while (0)
; #define PG8_LDA(dst, b, h) do { _Pragma("unroll") for (int m = 0; m < 4; ++m) _Pragma("unroll") for (int k = 0; k < 2; ++k) dst[m][k] = *(const PG8_LAS bf16x8*)(lds + PG8_SA(b, h) + aoff + m * 2048 + k * 1024); } while (0)
; #define PG8_LDB(dst, b, h) do { _Pragma("unroll") for (int n = 0; n < 2; ++n) _Pragma("unroll") for (int k = 0; k < 2; ++k) dst[n][k] = *(const PG8_LAS bf16x8*)(lds + PG8_SB(b, h) + boff + n * 2048 + k * 1024); } while (0)
; #define PG8_WAIT_V(n) asm volatile("s_waitcnt vmcnt(" #n ")" ::: "memory")
; #define PG8_WAIT_L(n) asm volatile("s_waitcnt lgkmcnt(" #n ")" ::: "memory")
; #define PG8_BAR __builtin_amdgcn_s_barrier()
; #define PG8_SCHED __builtin_amdgcn_sched_barrier(0)
; template <class Epi, class Sched, bool ALIGN_EPI = false, bool SP2 = false, bool I8 = false>
; __device__ __forceinline__ void gemm_phase(PG8_LAS unsigned char* lds, const Gemm g, const Sched& S, const Epi& E) {
;     ...
;         for (int t = 0; t < nt; t += 2) {
;             const bool last = (t == nt - 2);
;             const char* a1 = cA + (size_t)(t + 1) * kstep;
;             const char* a2 = last ? nA : cA + (size_t)(t + 2) * kstep; const char* b2 = last ? nB : cB + (size_t)(t + 2) * kstep;
;             const char* a3 = a2 + kstep; const char* b3 = b2 + kstep;
;             if (last && has_next) S.a_ready(nxt);
;             if constexpr (SP2) {
;             PG8_LDB(B0, 0, 0); PG8_LDB(B1, 0, 1); PG8_SCHED; PG8_LDA(At, 0, 0); PG8_STAGE(PG8_SA(1, 1), a1 + hstep, voffA);
;             PG8_WAIT_V(8); PG8_WAIT_L(0); PG8_BAR; PG8_MMA(0, 0, At, B0); PG8_MMA(0, 1, At, B1); PG8_BAR; PG8_SCHED;
;     ...
;             PG8_LDA(At, 1, 1); PG8_STAGE(PG8_SB(1, 0), b3, voffB); PG8_STAGE(PG8_SB(1, 1), b3 + hstep, voffB); PG8_STAGE(PG8_SA(1, 0), a3, voffA);
;             PG8_WAIT_V(8); PG8_WAIT_L(0); PG8_BAR; PG8_MMA(1, 0, At, B0); PG8_MMA(1, 1, At, B1); PG8_BAR; PG8_SCHED;
	s_setprio 0
	s_add_i32 s50, s56, s46
	v_lshl_add_u64 v[168:169], v[168:169], 0, s[84:85]
	s_mov_b32 m0, s50
	ds_read_b128 v[184:187], v173 offset:49152
	ds_read_b128 v[188:191], v173 offset:50176
	ds_read_b128 v[208:211], v173 offset:52224
	ds_read_b128 v[204:207], v173 offset:51200
	ds_read_b128 v[212:215], v173 offset:53248
	ds_read_b128 v[216:219], v173 offset:54272
	ds_read_b128 v[224:227], v173 offset:56320
	ds_read_b128 v[220:223], v173 offset:55296
	global_load_lds_dwordx4 v[168:169], off
	s_add_i32 m0, s50, 0x2000
	s_add_u32 s50, s72, 0x100080
	v_lshl_add_u64 v[168:169], v[228:229], 0, s[84:85]
	s_addc_u32 s51, s73, 0
	s_add_i32 s56, s57, s46
	global_load_lds_dwordx4 v[168:169], off
	s_mov_b32 m0, s56
	s_nop 0
	global_load_lds_dwordx4 v2, s[50:51]
	s_add_i32 m0, s56, 0x2000
	s_nop 0
	global_load_lds_dwordx4 v144, s[50:51]
	s_cmp_eq_u32 s97, 60
	s_cbranch_scc0 .Ldefer_230_peel
	v_lshl_add_u64 v[168:169], v[240:241], 0, s[84:85]
	s_mov_b32 m0, s28
	s_nop 0
	global_load_lds_dwordx4 v[168:169], off
	v_lshl_add_u64 v[168:169], v[242:243], 0, s[84:85]
	s_mov_b32 m0, s65
	s_nop 0
	global_load_lds_dwordx4 v[168:169], off
.Ldefer_230_peel:
	s_waitcnt vmcnt(6)
	s_waitcnt lgkmcnt(7)
	s_setprio 1
	s_barrier
	v_mfma_f32_16x16x32_bf16 v[64:67], v[112:115], v[184:187], v[64:67]
	s_waitcnt lgkmcnt(6)
	v_mfma_f32_16x16x32_bf16 v[64:67], v[120:123], v[188:191], v[64:67]
	s_waitcnt lgkmcnt(5)
	v_mfma_f32_16x16x32_bf16 v[48:51], v[120:123], v[208:211], v[48:51]
	s_waitcnt lgkmcnt(4)
	v_mfma_f32_16x16x32_bf16 v[48:51], v[112:115], v[204:207], v[48:51]
	s_waitcnt lgkmcnt(3)
	v_mfma_f32_16x16x32_bf16 v[32:35], v[112:115], v[212:215], v[32:35]
	s_waitcnt lgkmcnt(2)
	v_mfma_f32_16x16x32_bf16 v[32:35], v[120:123], v[216:219], v[32:35]
	s_waitcnt lgkmcnt(1)
	v_mfma_f32_16x16x32_bf16 v[16:19], v[120:123], v[224:227], v[16:19]
	s_waitcnt lgkmcnt(0)
	v_mfma_f32_16x16x32_bf16 v[16:19], v[112:115], v[220:223], v[16:19]
	v_mfma_f32_16x16x32_bf16 v[12:15], v[152:155], v[220:223], v[12:15]
	v_mfma_f32_16x16x32_bf16 v[12:15], v[156:159], v[224:227], v[12:15]
	v_mfma_f32_16x16x32_bf16 v[28:31], v[156:159], v[216:219], v[28:31]
	v_mfma_f32_16x16x32_bf16 v[28:31], v[152:155], v[212:215], v[28:31]
	v_mfma_f32_16x16x32_bf16 v[44:47], v[152:155], v[204:207], v[44:47]
	v_mfma_f32_16x16x32_bf16 v[44:47], v[156:159], v[208:211], v[44:47]
	v_mfma_f32_16x16x32_bf16 v[60:63], v[156:159], v[188:191], v[60:63]
	v_mfma_f32_16x16x32_bf16 v[60:63], v[152:155], v[184:187], v[60:63]
	v_mfma_f32_16x16x32_bf16 v[56:59], v[160:163], v[184:187], v[56:59]
	v_mfma_f32_16x16x32_bf16 v[56:59], v[164:167], v[188:191], v[56:59]
	v_mfma_f32_16x16x32_bf16 v[40:43], v[164:167], v[208:211], v[40:43]
	v_mfma_f32_16x16x32_bf16 v[40:43], v[160:163], v[204:207], v[40:43]
	v_mfma_f32_16x16x32_bf16 v[24:27], v[160:163], v[212:215], v[24:27]
	v_mfma_f32_16x16x32_bf16 v[24:27], v[164:167], v[216:219], v[24:27]
	v_mfma_f32_16x16x32_bf16 v[8:11], v[164:167], v[224:227], v[8:11]
	v_mfma_f32_16x16x32_bf16 v[8:11], v[160:163], v[220:223], v[8:11]
	v_mfma_f32_16x16x32_bf16 v[4:7], v[176:179], v[220:223], v[4:7]
	v_mfma_f32_16x16x32_bf16 v[4:7], v[180:183], v[224:227], v[4:7]
	v_mfma_f32_16x16x32_bf16 v[20:23], v[180:183], v[216:219], v[20:23]
	v_mfma_f32_16x16x32_bf16 v[20:23], v[176:179], v[212:215], v[20:23]
	v_mfma_f32_16x16x32_bf16 v[36:39], v[176:179], v[204:207], v[36:39]
	v_mfma_f32_16x16x32_bf16 v[36:39], v[180:183], v[208:211], v[36:39]
	v_mfma_f32_16x16x32_bf16 v[52:55], v[180:183], v[188:191], v[52:55]
	v_mfma_f32_16x16x32_bf16 v[52:55], v[176:179], v[184:187], v[52:55]
	s_barrier
	s_setprio 0
	s_add_i32 s97, s97, 2
	s_add_u32 s12, s12, 0x100
	s_addc_u32 s13, s13, 0
	s_add_u32 s37, s37, 0x100
	s_addc_u32 s61, s61, 0
	s_cmp_gt_u32 s97, 61
	s_cbranch_scc1 .Lkloop_exit_1
.LBB0_230:
	s_add_u32 s50, s12, 0xfff00080
	s_addc_u32 s51, s13, -1
	s_add_i32 s56, 0, 0x10000
	s_cmp_eq_u32 s97, 60
	s_cselect_b32 s77, s11, s51
	s_cselect_b32 s76, s34, s50
	s_cselect_b32 s73, s27, s61
	s_cselect_b32 s72, s35, s37
	s_add_i32 s57, 0, 0x14000
	v_add_u32_e32 v156, s56, v171
	v_add_u32_e32 v168, s57, v171
	ds_read_b128 v[112:115], v156
	ds_read_b128 v[120:123], v156 offset:1024
	ds_read_b128 v[152:155], v156 offset:2048
	ds_read_b128 v[156:159], v156 offset:3072
	ds_read_b128 v[160:163], v168
	ds_read_b128 v[164:167], v168 offset:1024
	ds_read_b128 v[176:179], v168 offset:2048
	ds_read_b128 v[180:183], v168 offset:3072
	v_lshl_add_u64 v[168:169], v[240:241], 0, s[84:85]
	s_mov_b32 m0, s28
	s_nop 0
	global_load_lds_dwordx4 v[168:169], off
	v_lshl_add_u64 v[168:169], v[242:243], 0, s[84:85]
	s_mov_b32 m0, s65
	s_nop 0
	global_load_lds_dwordx4 v[168:169], off
	s_add_i32 m0, s47, 0xc000
	ds_read_b128 v[184:187], v173
	ds_read_b128 v[188:191], v173 offset:1024
	ds_read_b128 v[204:207], v173 offset:2048
	ds_read_b128 v[208:211], v173 offset:3072
	ds_read_b128 v[212:215], v173 offset:4096
	ds_read_b128 v[216:219], v173 offset:5120
	ds_read_b128 v[220:223], v173 offset:6144
	ds_read_b128 v[224:227], v173 offset:7168
	global_load_lds_dwordx4 v148, s[12:13]
	s_add_i32 m0, s47, 0xe000
	s_nop 0
	global_load_lds_dwordx4 v150, s[12:13]
	s_waitcnt vmcnt(8)
	s_waitcnt lgkmcnt(7)
	s_setprio 1
	s_barrier
; #define PG8_STAGE(bufoff, gbase, voff) do { _Pragma("unroll") for (int _i = 0; _i < 2; ++_i) \
;         __builtin_amdgcn_global_load_lds((const unsigned*)((const char*)(gbase) + (voff)[_i]), (PG8_LAS unsigned*)(lds + (bufoff) + ldsw + _i * 8192), 16, 0, 0); } while (0)
; #define PG8_LDA(dst, b, h) do { _Pragma("unroll") for (int m = 0; m < 4; ++m) _Pragma("unroll") for (int k = 0; k < 2; ++k) dst[m][k] = *(const PG8_LAS bf16x8*)(lds + PG8_SA(b, h) + aoff + m * 2048 + k * 1024); } while (0)
; #define PG8_WAIT_V(n) asm volatile("s_waitcnt vmcnt(" #n ")" ::: "memory")
; #define PG8_WAIT_L(n) asm volatile("s_waitcnt lgkmcnt(" #n ")" ::: "memory")
; #define PG8_BAR __builtin_amdgcn_s_barrier()
; #define PG8_SCHED __builtin_amdgcn_sched_barrier(0)
; template <class Epi, class Sched, bool ALIGN_EPI = false, bool SP2 = false, bool I8 = false>
; __device__ __forceinline__ void gemm_phase(PG8_LAS unsigned char* lds, const Gemm g, const Sched& S, const Epi& E) {
;     ...
;             PG8_WAIT_V(8); PG8_WAIT_L(0); PG8_BAR; PG8_MMA(0, 0, At, B0); PG8_MMA(0, 1, At, B1); PG8_BAR; PG8_SCHED;
;             PG8_LDA(At, 0, 1); PG8_STAGE(PG8_SB(0, 0), b2, voffB); PG8_STAGE(PG8_SB(0, 1), b2 + hstep, voffB); PG8_STAGE(PG8_SA(0, 0), a2, voffA);
;             PG8_WAIT_V(8); PG8_WAIT_L(0); PG8_BAR; PG8_MMA(1, 0, At, B0); PG8_MMA(1, 1, At, B1); PG8_BAR; PG8_SCHED;
	v_mfma_f32_16x16x32_bf16 v[136:139], v[112:115], v[184:187], v[136:139]
	s_waitcnt lgkmcnt(6)
	v_mfma_f32_16x16x32_bf16 v[136:139], v[120:123], v[188:191], v[136:139]
	s_waitcnt lgkmcnt(4)
	v_mfma_f32_16x16x32_bf16 v[116:119], v[120:123], v[208:211], v[116:119]
	v_mfma_f32_16x16x32_bf16 v[116:119], v[112:115], v[204:207], v[116:119]
	s_waitcnt lgkmcnt(3)
	v_mfma_f32_16x16x32_bf16 v[96:99], v[112:115], v[212:215], v[96:99]
	s_waitcnt lgkmcnt(2)
	v_mfma_f32_16x16x32_bf16 v[96:99], v[120:123], v[216:219], v[96:99]
	s_waitcnt lgkmcnt(0)
	v_mfma_f32_16x16x32_bf16 v[80:83], v[120:123], v[224:227], v[80:83]
	v_mfma_f32_16x16x32_bf16 v[80:83], v[112:115], v[220:223], v[80:83]
	v_mfma_f32_16x16x32_bf16 v[76:79], v[152:155], v[220:223], v[76:79]
	v_mfma_f32_16x16x32_bf16 v[76:79], v[156:159], v[224:227], v[76:79]
	v_mfma_f32_16x16x32_bf16 v[92:95], v[156:159], v[216:219], v[92:95]
	v_mfma_f32_16x16x32_bf16 v[92:95], v[152:155], v[212:215], v[92:95]
	v_mfma_f32_16x16x32_bf16 v[108:111], v[152:155], v[204:207], v[108:111]
	v_mfma_f32_16x16x32_bf16 v[108:111], v[156:159], v[208:211], v[108:111]
	v_mfma_f32_16x16x32_bf16 v[132:135], v[156:159], v[188:191], v[132:135]
	v_mfma_f32_16x16x32_bf16 v[132:135], v[152:155], v[184:187], v[132:135]
	v_mfma_f32_16x16x32_bf16 v[128:131], v[160:163], v[184:187], v[128:131]
	v_mfma_f32_16x16x32_bf16 v[128:131], v[164:167], v[188:191], v[128:131]
	v_mfma_f32_16x16x32_bf16 v[104:107], v[164:167], v[208:211], v[104:107]
	v_mfma_f32_16x16x32_bf16 v[104:107], v[160:163], v[204:207], v[104:107]
	v_mfma_f32_16x16x32_bf16 v[88:91], v[160:163], v[212:215], v[88:91]
	v_mfma_f32_16x16x32_bf16 v[88:91], v[164:167], v[216:219], v[88:91]
	v_mfma_f32_16x16x32_bf16 v[72:75], v[164:167], v[224:227], v[72:75]
	v_mfma_f32_16x16x32_bf16 v[72:75], v[160:163], v[220:223], v[72:75]
	v_mfma_f32_16x16x32_bf16 v[68:71], v[176:179], v[220:223], v[68:71]
	v_mfma_f32_16x16x32_bf16 v[68:71], v[180:183], v[224:227], v[68:71]
	v_mfma_f32_16x16x32_bf16 v[84:87], v[180:183], v[216:219], v[84:87]
	v_mfma_f32_16x16x32_bf16 v[84:87], v[176:179], v[212:215], v[84:87]
	v_mfma_f32_16x16x32_bf16 v[100:103], v[176:179], v[204:207], v[100:103]
	v_mfma_f32_16x16x32_bf16 v[100:103], v[180:183], v[208:211], v[100:103]
	v_mfma_f32_16x16x32_bf16 v[124:127], v[180:183], v[188:191], v[124:127]
	v_mfma_f32_16x16x32_bf16 v[124:127], v[176:179], v[184:187], v[124:127]
	s_barrier
	s_setprio 0
	s_add_i32 s50, s56, s46
	v_lshl_add_u64 v[168:169], s[72:73], 0, v[2:3]
	s_mov_b32 m0, s50
	ds_read_b128 v[184:187], v173 offset:16384
	ds_read_b128 v[188:191], v173 offset:17408
	ds_read_b128 v[208:211], v173 offset:19456
	ds_read_b128 v[204:207], v173 offset:18432
	ds_read_b128 v[212:215], v173 offset:20480
	ds_read_b128 v[216:219], v173 offset:21504
	ds_read_b128 v[224:227], v173 offset:23552
	ds_read_b128 v[220:223], v173 offset:22528
	global_load_lds_dwordx4 v[168:169], off
	s_add_i32 m0, s50, 0x2000
	s_add_u32 s50, s72, 0x100000
	v_lshl_add_u64 v[228:229], s[72:73], 0, v[144:145]
	s_addc_u32 s51, s73, 0
	s_add_i32 s56, s57, s46
	global_load_lds_dwordx4 v[228:229], off
	s_mov_b32 m0, s56
	v_lshl_add_u64 v[242:243], s[76:77], 0, v[142:143]
	global_load_lds_dwordx4 v2, s[50:51]
	s_add_i32 m0, s56, 0x2000
	s_nop 0
	global_load_lds_dwordx4 v144, s[50:51]
	v_lshl_add_u64 v[240:241], s[76:77], 0, v[140:141]
	s_waitcnt vmcnt(6)
	s_waitcnt lgkmcnt(7)
	s_setprio 1
	s_barrier
	v_mfma_f32_16x16x32_bf16 v[64:67], v[112:115], v[184:187], v[64:67]
	s_waitcnt lgkmcnt(6)
	v_mfma_f32_16x16x32_bf16 v[64:67], v[120:123], v[188:191], v[64:67]
	s_waitcnt lgkmcnt(5)
	v_mfma_f32_16x16x32_bf16 v[48:51], v[120:123], v[208:211], v[48:51]
	s_waitcnt lgkmcnt(4)
	v_mfma_f32_16x16x32_bf16 v[48:51], v[112:115], v[204:207], v[48:51]
	s_waitcnt lgkmcnt(3)
	v_mfma_f32_16x16x32_bf16 v[32:35], v[112:115], v[212:215], v[32:35]
	s_waitcnt lgkmcnt(2)
	v_mfma_f32_16x16x32_bf16 v[32:35], v[120:123], v[216:219], v[32:35]
	s_waitcnt lgkmcnt(1)
	v_mfma_f32_16x16x32_bf16 v[16:19], v[120:123], v[224:227], v[16:19]
	s_waitcnt lgkmcnt(0)
	v_mfma_f32_16x16x32_bf16 v[16:19], v[112:115], v[220:223], v[16:19]
	v_mfma_f32_16x16x32_bf16 v[12:15], v[152:155], v[220:223], v[12:15]
	v_mfma_f32_16x16x32_bf16 v[12:15], v[156:159], v[224:227], v[12:15]
	v_mfma_f32_16x16x32_bf16 v[28:31], v[156:159], v[216:219], v[28:31]
	v_mfma_f32_16x16x32_bf16 v[28:31], v[152:155], v[212:215], v[28:31]
	v_mfma_f32_16x16x32_bf16 v[44:47], v[152:155], v[204:207], v[44:47]
	v_mfma_f32_16x16x32_bf16 v[44:47], v[156:159], v[208:211], v[44:47]
	v_mfma_f32_16x16x32_bf16 v[60:63], v[156:159], v[188:191], v[60:63]
	v_mfma_f32_16x16x32_bf16 v[60:63], v[152:155], v[184:187], v[60:63]
	v_mfma_f32_16x16x32_bf16 v[56:59], v[160:163], v[184:187], v[56:59]
	v_mfma_f32_16x16x32_bf16 v[56:59], v[164:167], v[188:191], v[56:59]
	v_mfma_f32_16x16x32_bf16 v[40:43], v[164:167], v[208:211], v[40:43]
	v_mfma_f32_16x16x32_bf16 v[40:43], v[160:163], v[204:207], v[40:43]
	v_mfma_f32_16x16x32_bf16 v[24:27], v[160:163], v[212:215], v[24:27]
	v_mfma_f32_16x16x32_bf16 v[24:27], v[164:167], v[216:219], v[24:27]
	v_mfma_f32_16x16x32_bf16 v[8:11], v[164:167], v[224:227], v[8:11]
	v_mfma_f32_16x16x32_bf16 v[8:11], v[160:163], v[220:223], v[8:11]
	v_mfma_f32_16x16x32_bf16 v[4:7], v[176:179], v[220:223], v[4:7]
	v_mfma_f32_16x16x32_bf16 v[4:7], v[180:183], v[224:227], v[4:7]
	v_mfma_f32_16x16x32_bf16 v[20:23], v[180:183], v[216:219], v[20:23]
	v_mfma_f32_16x16x32_bf16 v[20:23], v[176:179], v[212:215], v[20:23]
	v_mfma_f32_16x16x32_bf16 v[36:39], v[176:179], v[204:207], v[36:39]
	v_mfma_f32_16x16x32_bf16 v[36:39], v[180:183], v[208:211], v[36:39]
	v_mfma_f32_16x16x32_bf16 v[52:55], v[180:183], v[188:191], v[52:55]
	v_mfma_f32_16x16x32_bf16 v[52:55], v[176:179], v[184:187], v[52:55]
	s_barrier
; #define PG8_STAGE(bufoff, gbase, voff) do { _Pragma("unroll") for (int _i = 0; _i < 2; ++_i) \
;         __builtin_amdgcn_global_load_lds((const unsigned*)((const char*)(gbase) + (voff)[_i]), (PG8_LAS unsigned*)(lds + (bufoff) + ldsw + _i * 8192), 16, 0, 0); } while (0)
; #define PG8_LDA(dst, b, h) do { _Pragma("unroll") for (int m = 0; m < 4; ++m) _Pragma("unroll") for (int k = 0; k < 2; ++k) dst[m][k] = *(const PG8_LAS bf16x8*)(lds + PG8_SA(b, h) + aoff + m * 2048 + k * 1024); } while (0)
; #define PG8_LDB(dst, b, h) do { _Pragma("unroll") for (int n = 0; n < 2; ++n) _Pragma("unroll") for (int k = 0; k < 2; ++k) dst[n][k] = *(const PG8_LAS bf16x8*)(lds + PG8_SB(b, h) + boff + n * 2048 + k * 1024); } while (0)
; #define PG8_WAIT_V(n) asm volatile("s_waitcnt vmcnt(" #n ")" ::: "memory")
; #define PG8_WAIT_L(n) asm volatile("s_waitcnt lgkmcnt(" #n ")" ::: "memory")
; #define PG8_BAR __builtin_amdgcn_s_barrier()
; #define PG8_SCHED __builtin_amdgcn_sched_barrier(0)
; template <class Epi, class Sched, bool ALIGN_EPI = false, bool SP2 = false, bool I8 = false>
; __device__ __forceinline__ void gemm_phase(PG8_LAS unsigned char* lds, const Gemm g, const Sched& S, const Epi& E) {
;     ...
;             PG8_LDB(B0, 1, 0); PG8_LDB(B1, 1, 1); PG8_SCHED; PG8_LDA(At, 1, 0); PG8_STAGE(PG8_SA(0, 1), a2 + hstep, voffA);
;             PG8_WAIT_V(8); PG8_WAIT_L(0); PG8_BAR; PG8_MMA(0, 0, At, B0); PG8_MMA(0, 1, At, B1); PG8_BAR; PG8_SCHED;
;             PG8_LDA(At, 1, 1); PG8_STAGE(PG8_SB(1, 0), b3, voffB); PG8_STAGE(PG8_SB(1, 1), b3 + hstep, voffB); PG8_STAGE(PG8_SA(1, 0), a3, voffA);
	s_setprio 0
	s_mov_b32 m0, s47
	s_nop 0
	global_load_lds_dwordx4 v[240:241], off
	s_mov_b32 m0, s52
	s_nop 0
	global_load_lds_dwordx4 v[242:243], off
	s_add_i32 s56, 0, 0x18000
	s_add_i32 s57, 0, 0x1c000
	v_add_u32_e32 v156, s56, v171
	v_add_u32_e32 v175, s57, v171
	ds_read_b128 v[112:115], v156
	ds_read_b128 v[184:187], v173 offset:32768
	ds_read_b128 v[120:123], v156 offset:1024
	ds_read_b128 v[188:191], v173 offset:33792
	ds_read_b128 v[208:211], v173 offset:35840
	ds_read_b128 v[204:207], v173 offset:34816
	ds_read_b128 v[212:215], v173 offset:36864
	ds_read_b128 v[216:219], v173 offset:37888
	s_add_u32 s50, s76, 0x100000
	s_addc_u32 s51, s77, 0
	s_mov_b32 m0, s53
	ds_read_b128 v[224:227], v173 offset:39936
	ds_read_b128 v[220:223], v173 offset:38912
	ds_read_b128 v[152:155], v156 offset:2048
	ds_read_b128 v[156:159], v156 offset:3072
	ds_read_b128 v[160:163], v175
	ds_read_b128 v[164:167], v175 offset:1024
	ds_read_b128 v[176:179], v175 offset:2048
	ds_read_b128 v[180:183], v175 offset:3072
	global_load_lds_dwordx4 v140, s[50:51]
	s_mov_b32 m0, s64
	s_nop 0
	global_load_lds_dwordx4 v142, s[50:51]
	s_waitcnt vmcnt(8)
	s_waitcnt lgkmcnt(14)
	s_setprio 1
	s_barrier
	v_mfma_f32_16x16x32_bf16 v[136:139], v[112:115], v[184:187], v[136:139]
	s_waitcnt lgkmcnt(12)
	v_mfma_f32_16x16x32_bf16 v[136:139], v[120:123], v[188:191], v[136:139]
	s_waitcnt lgkmcnt(11)
	v_mfma_f32_16x16x32_bf16 v[116:119], v[120:123], v[208:211], v[116:119]
	s_waitcnt lgkmcnt(10)
	v_mfma_f32_16x16x32_bf16 v[116:119], v[112:115], v[204:207], v[116:119]
	s_waitcnt lgkmcnt(9)
	v_mfma_f32_16x16x32_bf16 v[96:99], v[112:115], v[212:215], v[96:99]
	s_waitcnt lgkmcnt(8)
	v_mfma_f32_16x16x32_bf16 v[96:99], v[120:123], v[216:219], v[96:99]
	s_waitcnt lgkmcnt(7)
	v_mfma_f32_16x16x32_bf16 v[80:83], v[120:123], v[224:227], v[80:83]
	s_waitcnt lgkmcnt(6)
	v_mfma_f32_16x16x32_bf16 v[80:83], v[112:115], v[220:223], v[80:83]
	s_waitcnt lgkmcnt(5)
	v_mfma_f32_16x16x32_bf16 v[76:79], v[152:155], v[220:223], v[76:79]
	s_waitcnt lgkmcnt(4)
	v_mfma_f32_16x16x32_bf16 v[76:79], v[156:159], v[224:227], v[76:79]
	v_mfma_f32_16x16x32_bf16 v[92:95], v[156:159], v[216:219], v[92:95]
	v_mfma_f32_16x16x32_bf16 v[92:95], v[152:155], v[212:215], v[92:95]
	v_mfma_f32_16x16x32_bf16 v[108:111], v[152:155], v[204:207], v[108:111]
	v_mfma_f32_16x16x32_bf16 v[108:111], v[156:159], v[208:211], v[108:111]
	v_mfma_f32_16x16x32_bf16 v[132:135], v[156:159], v[188:191], v[132:135]
	v_mfma_f32_16x16x32_bf16 v[132:135], v[152:155], v[184:187], v[132:135]
	s_waitcnt lgkmcnt(3)
	v_mfma_f32_16x16x32_bf16 v[128:131], v[160:163], v[184:187], v[128:131]
	s_waitcnt lgkmcnt(2)
	v_mfma_f32_16x16x32_bf16 v[128:131], v[164:167], v[188:191], v[128:131]
	v_mfma_f32_16x16x32_bf16 v[104:107], v[164:167], v[208:211], v[104:107]
	v_mfma_f32_16x16x32_bf16 v[104:107], v[160:163], v[204:207], v[104:107]
	v_mfma_f32_16x16x32_bf16 v[88:91], v[160:163], v[212:215], v[88:91]
	v_mfma_f32_16x16x32_bf16 v[88:91], v[164:167], v[216:219], v[88:91]
	v_mfma_f32_16x16x32_bf16 v[72:75], v[164:167], v[224:227], v[72:75]
	v_mfma_f32_16x16x32_bf16 v[72:75], v[160:163], v[220:223], v[72:75]
	s_waitcnt lgkmcnt(1)
	v_mfma_f32_16x16x32_bf16 v[68:71], v[176:179], v[220:223], v[68:71]
	s_waitcnt lgkmcnt(0)
	v_mfma_f32_16x16x32_bf16 v[68:71], v[180:183], v[224:227], v[68:71]
	v_mfma_f32_16x16x32_bf16 v[84:87], v[180:183], v[216:219], v[84:87]
	v_mfma_f32_16x16x32_bf16 v[84:87], v[176:179], v[212:215], v[84:87]
	v_mfma_f32_16x16x32_bf16 v[100:103], v[176:179], v[204:207], v[100:103]
	v_mfma_f32_16x16x32_bf16 v[100:103], v[180:183], v[208:211], v[100:103]
	v_mfma_f32_16x16x32_bf16 v[124:127], v[180:183], v[188:191], v[124:127]
	v_mfma_f32_16x16x32_bf16 v[124:127], v[176:179], v[184:187], v[124:127]
	s_barrier
	s_setprio 0
	s_add_i32 s50, s56, s46
	v_lshl_add_u64 v[168:169], v[168:169], 0, s[84:85]
	s_mov_b32 m0, s50
	ds_read_b128 v[184:187], v173 offset:49152
	ds_read_b128 v[188:191], v173 offset:50176
	ds_read_b128 v[208:211], v173 offset:52224
	ds_read_b128 v[204:207], v173 offset:51200
	ds_read_b128 v[212:215], v173 offset:53248
	ds_read_b128 v[216:219], v173 offset:54272
	ds_read_b128 v[224:227], v173 offset:56320
	ds_read_b128 v[220:223], v173 offset:55296
	global_load_lds_dwordx4 v[168:169], off
	s_add_i32 m0, s50, 0x2000
	s_add_u32 s50, s72, 0x100080
	v_lshl_add_u64 v[168:169], v[228:229], 0, s[84:85]
	s_addc_u32 s51, s73, 0
	s_add_i32 s56, s57, s46
	global_load_lds_dwordx4 v[168:169], off
	s_mov_b32 m0, s56
	s_nop 0
	global_load_lds_dwordx4 v2, s[50:51]
	s_add_i32 m0, s56, 0x2000
	s_nop 0
	global_load_lds_dwordx4 v144, s[50:51]
	s_cmp_eq_u32 s97, 60
	s_cbranch_scc0 .Ldefer_230_body
	v_lshl_add_u64 v[168:169], v[240:241], 0, s[84:85]
	s_mov_b32 m0, s28
	s_nop 0
	global_load_lds_dwordx4 v[168:169], off
	v_lshl_add_u64 v[168:169], v[242:243], 0, s[84:85]
	s_mov_b32 m0, s65
	s_nop 0
	global_load_lds_dwordx4 v[168:169], off
; #define PG8_STAGE(bufoff, gbase, voff) do { _Pragma("unroll") for (int _i = 0; _i < 2; ++_i) \
;         __builtin_amdgcn_global_load_lds((const unsigned*)((const char*)(gbase) + (voff)[_i]), (PG8_LAS unsigned*)(lds + (bufoff) + ldsw + _i * 8192), 16, 0, 0); } while (0)
; #define PG8_LDA(dst, b, h) do { _Pragma("unroll") for (int m = 0; m < 4; ++m) _Pragma("unroll") for (int k = 0; k < 2; ++k) dst[m][k] = *(const PG8_LAS bf16x8*)(lds + PG8_SA(b, h) + aoff + m * 2048 + k * 1024); } while (0)
; #define PG8_WAIT_V(n) asm volatile("s_waitcnt vmcnt(" #n ")" ::: "memory")
; #define PG8_WAIT_L(n) asm volatile("s_waitcnt lgkmcnt(" #n ")" ::: "memory")
; #define PG8_BAR __builtin_amdgcn_s_barrier()
; #define PG8_SCHED __builtin_amdgcn_sched_barrier(0)
; template <class Epi, class Sched, bool ALIGN_EPI = false, bool SP2 = false, bool I8 = false>
; __device__ __forceinline__ void gemm_phase(PG8_LAS unsigned char* lds, const Gemm g, const Sched& S, const Epi& E) {
;     ...
;             PG8_LDA(At, 1, 1); PG8_STAGE(PG8_SB(1, 0), b3, voffB); PG8_STAGE(PG8_SB(1, 1), b3 + hstep, voffB); PG8_STAGE(PG8_SA(1, 0), a3, voffA);
;             PG8_WAIT_V(8); PG8_WAIT_L(0); PG8_BAR; PG8_MMA(1, 0, At, B0); PG8_MMA(1, 1, At, B1); PG8_BAR; PG8_SCHED;
.Ldefer_230_body:
	s_waitcnt vmcnt(6)
	s_waitcnt lgkmcnt(7)
	s_setprio 1
	s_barrier
	v_mfma_f32_16x16x32_bf16 v[64:67], v[112:115], v[184:187], v[64:67]
	s_waitcnt lgkmcnt(6)
	v_mfma_f32_16x16x32_bf16 v[64:67], v[120:123], v[188:191], v[64:67]
	s_waitcnt lgkmcnt(5)
	v_mfma_f32_16x16x32_bf16 v[48:51], v[120:123], v[208:211], v[48:51]
	s_waitcnt lgkmcnt(4)
	v_mfma_f32_16x16x32_bf16 v[48:51], v[112:115], v[204:207], v[48:51]
	s_waitcnt lgkmcnt(3)
	v_mfma_f32_16x16x32_bf16 v[32:35], v[112:115], v[212:215], v[32:35]
	s_waitcnt lgkmcnt(2)
	v_mfma_f32_16x16x32_bf16 v[32:35], v[120:123], v[216:219], v[32:35]
	s_waitcnt lgkmcnt(1)
	v_mfma_f32_16x16x32_bf16 v[16:19], v[120:123], v[224:227], v[16:19]
	s_waitcnt lgkmcnt(0)
	v_mfma_f32_16x16x32_bf16 v[16:19], v[112:115], v[220:223], v[16:19]
	v_mfma_f32_16x16x32_bf16 v[12:15], v[152:155], v[220:223], v[12:15]
	v_mfma_f32_16x16x32_bf16 v[12:15], v[156:159], v[224:227], v[12:15]
	v_mfma_f32_16x16x32_bf16 v[28:31], v[156:159], v[216:219], v[28:31]
	v_mfma_f32_16x16x32_bf16 v[28:31], v[152:155], v[212:215], v[28:31]
	v_mfma_f32_16x16x32_bf16 v[44:47], v[152:155], v[204:207], v[44:47]
	v_mfma_f32_16x16x32_bf16 v[44:47], v[156:159], v[208:211], v[44:47]
	v_mfma_f32_16x16x32_bf16 v[60:63], v[156:159], v[188:191], v[60:63]
	v_mfma_f32_16x16x32_bf16 v[60:63], v[152:155], v[184:187], v[60:63]
	v_mfma_f32_16x16x32_bf16 v[56:59], v[160:163], v[184:187], v[56:59]
	v_mfma_f32_16x16x32_bf16 v[56:59], v[164:167], v[188:191], v[56:59]
	v_mfma_f32_16x16x32_bf16 v[40:43], v[164:167], v[208:211], v[40:43]
	v_mfma_f32_16x16x32_bf16 v[40:43], v[160:163], v[204:207], v[40:43]
	v_mfma_f32_16x16x32_bf16 v[24:27], v[160:163], v[212:215], v[24:27]
	v_mfma_f32_16x16x32_bf16 v[24:27], v[164:167], v[216:219], v[24:27]
	v_mfma_f32_16x16x32_bf16 v[8:11], v[164:167], v[224:227], v[8:11]
	v_mfma_f32_16x16x32_bf16 v[8:11], v[160:163], v[220:223], v[8:11]
	v_mfma_f32_16x16x32_bf16 v[4:7], v[176:179], v[220:223], v[4:7]
	v_mfma_f32_16x16x32_bf16 v[4:7], v[180:183], v[224:227], v[4:7]
	v_mfma_f32_16x16x32_bf16 v[20:23], v[180:183], v[216:219], v[20:23]
	v_mfma_f32_16x16x32_bf16 v[20:23], v[176:179], v[212:215], v[20:23]
	v_mfma_f32_16x16x32_bf16 v[36:39], v[176:179], v[204:207], v[36:39]
	v_mfma_f32_16x16x32_bf16 v[36:39], v[180:183], v[208:211], v[36:39]
	v_mfma_f32_16x16x32_bf16 v[52:55], v[180:183], v[188:191], v[52:55]
	v_mfma_f32_16x16x32_bf16 v[52:55], v[176:179], v[184:187], v[52:55]
	s_barrier
	s_setprio 0
	s_add_i32 s97, s97, 2
	s_add_u32 s12, s12, 0x100
	s_addc_u32 s13, s13, 0
	s_add_u32 s37, s37, 0x100
	s_addc_u32 s61, s61, 0
	s_cmp_gt_u32 s97, 61
	s_cbranch_scc0 .LBB0_230

; #define PG8_STAGE(bufoff, gbase, voff) do { _Pragma("unroll") for (int _i = 0; _i < 2; ++_i) \
;         __builtin_amdgcn_global_load_lds((const unsigned*)((const char*)(gbase) + (voff)[_i]), (PG8_LAS unsigned*)(lds + (bufoff) + ldsw + _i * 8192), 16, 0, 0); } while (0)
; #define PG8_LDA(dst, b, h) do { _Pragma("unroll") for (int m = 0; m < 4; ++m) _Pragma("unroll") for (int k = 0; k < 2; ++k) dst[m][k] = *(const PG8_LAS bf16x8*)(lds + PG8_SA(b, h) + aoff + m * 2048 + k * 1024); } while (0)
; #define PG8_LDB(dst, b, h) do { _Pragma("unroll") for (int n = 0; n < 2; ++n) _Pragma("unroll") for (int k = 0; k < 2; ++k) dst[n][k] = *(const PG8_LAS bf16x8*)(lds + PG8_SB(b, h) + boff + n * 2048 + k * 1024); } while (0)
; #define PG8_WAIT_V(n) asm volatile("s_waitcnt vmcnt(" #n ")" ::: "memory")
; #define PG8_WAIT_L(n) asm volatile("s_waitcnt lgkmcnt(" #n ")" ::: "memory")
; #define PG8_BAR __builtin_amdgcn_s_barrier()
; #define PG8_SCHED __builtin_amdgcn_sched_barrier(0)
; template <class Epi, class Sched, bool ALIGN_EPI = false, bool SP2 = false, bool I8 = false>
; __device__ __forceinline__ void gemm_phase(PG8_LAS unsigned char* lds, const Gemm g, const Sched& S, const Epi& E) {
;     ...
;         const bool has_next = S.next(ui + 1, nxt);
;         const char* nA = has_next ? (const char*)g.A + (size_t)nxt.pm * tstep : cA; const char* nB = has_next ? (const char*)g.Bt + (size_t)nxt.pn * tstep : cB;
;         for (int t = 0; t < nt; t += 2) {
;             const bool last = (t == nt - 2);
;             const char* a1 = cA + (size_t)(t + 1) * kstep;
;             const char* a2 = last ? nA : cA + (size_t)(t + 2) * kstep; const char* b2 = last ? nB : cB + (size_t)(t + 2) * kstep;
;             const char* a3 = a2 + kstep; const char* b3 = b2 + kstep;
;             if (last && has_next) S.a_ready(nxt);
;             if constexpr (SP2) {
;             PG8_LDB(B0, 0, 0); PG8_LDB(B1, 0, 1); PG8_SCHED; PG8_LDA(At, 0, 0); PG8_STAGE(PG8_SA(1, 1), a1 + hstep, voffA);
;             PG8_WAIT_V(8); PG8_WAIT_L(0); PG8_BAR; PG8_MMA(0, 0, At, B0); PG8_MMA(0, 1, At, B1); PG8_BAR; PG8_SCHED;
;             PG8_LDA(At, 0, 1); PG8_STAGE(PG8_SB(0, 0), b2, voffB); PG8_STAGE(PG8_SB(0, 1), b2 + hstep, voffB); PG8_STAGE(PG8_SA(0, 0), a2, voffA);
;             PG8_WAIT_V(8); PG8_WAIT_L(0); PG8_BAR; PG8_MMA(1, 0, At, B0); PG8_MMA(1, 1, At, B1); PG8_BAR; PG8_SCHED;
.LBB0_1455:
	s_ashr_i32 s17, s16, 31
	s_lshl_b64 s[20:21], s[16:17], 21
	s_add_u32 s20, s28, s20
	s_addc_u32 s21, s34, s21
	s_and_b64 s[22:23], s[8:9], exec
	s_cselect_b32 s17, s21, s25
	s_cselect_b32 s51, s20, s24
	s_ashr_i32 s19, s18, 31
	s_lshl_b64 s[22:23], s[18:19], 21
	s_add_u32 s22, s35, s22
	s_addc_u32 s23, s39, s23
	s_and_b64 s[36:37], s[8:9], exec
	s_cselect_b32 s19, s23, s27
	s_cselect_b32 s52, s22, s26
	s_add_u32 s24, s24, 0x100080
	s_addc_u32 s25, s25, 0
	s_add_u32 s53, s26, 0x100
	s_addc_u32 s54, s27, 0
	s_mov_b32 s55, -2
	s_waitcnt vmcnt(0)
	s_add_u32 s26, s24, 0xfff00080
	s_addc_u32 s27, s25, -1
	s_add_i32 s56, 0, 0x10000
	s_cmp_eq_u32 s55, 60
	s_cselect_b32 s37, s17, s27
	s_cselect_b32 s36, s51, s26
	s_cselect_b32 s27, s19, s54
	s_cselect_b32 s26, s52, s53
	s_add_i32 s58, 0, 0x14000
	v_add_u32_e32 v144, s56, v240
	v_add_u32_e32 v160, s58, v240
	ds_read_b128 v[124:127], v144
	ds_read_b128 v[164:167], v242
	ds_read_b128 v[128:131], v144 offset:1024
	ds_read_b128 v[168:171], v242 offset:1024
	ds_read_b128 v[176:179], v242 offset:3072
	ds_read_b128 v[172:175], v242 offset:2048
	ds_read_b128 v[180:183], v242 offset:4096
	ds_read_b128 v[184:187], v242 offset:5120
	s_add_i32 m0, s41, 0xc000
	ds_read_b128 v[214:217], v242 offset:7168
	ds_read_b128 v[188:191], v242 offset:6144
	ds_read_b128 v[132:135], v144 offset:2048
	ds_read_b128 v[144:147], v144 offset:3072
	ds_read_b128 v[148:151], v160
	ds_read_b128 v[152:155], v160 offset:1024
	ds_read_b128 v[156:159], v160 offset:2048
	ds_read_b128 v[160:163], v160 offset:3072
	global_load_lds_dwordx4 v210, s[24:25]
	s_add_i32 m0, s41, 0xe000
	s_nop 0
	global_load_lds_dwordx4 v212, s[24:25]
	s_waitcnt vmcnt(8)
	s_waitcnt lgkmcnt(14)
	s_setprio 1
	s_barrier
	v_mfma_f32_16x16x32_bf16 v[140:143], v[124:127], v[164:167], 0
	s_waitcnt lgkmcnt(12)
	v_mfma_f32_16x16x32_bf16 v[140:143], v[128:131], v[168:171], v[140:143]
	s_waitcnt lgkmcnt(11)
	v_mfma_f32_16x16x32_bf16 v[112:115], v[128:131], v[176:179], 0
	s_waitcnt lgkmcnt(10)
	v_mfma_f32_16x16x32_bf16 v[112:115], v[124:127], v[172:175], v[112:115]
	s_waitcnt lgkmcnt(9)
	v_mfma_f32_16x16x32_bf16 v[96:99], v[124:127], v[180:183], 0
	s_waitcnt lgkmcnt(8)
	v_mfma_f32_16x16x32_bf16 v[96:99], v[128:131], v[184:187], v[96:99]
	s_waitcnt lgkmcnt(7)
	v_mfma_f32_16x16x32_bf16 v[80:83], v[128:131], v[214:217], 0
	s_waitcnt lgkmcnt(6)
	v_mfma_f32_16x16x32_bf16 v[80:83], v[124:127], v[188:191], v[80:83]
	s_waitcnt lgkmcnt(5)
	v_mfma_f32_16x16x32_bf16 v[76:79], v[132:135], v[188:191], 0
	s_waitcnt lgkmcnt(4)
	v_mfma_f32_16x16x32_bf16 v[76:79], v[144:147], v[214:217], v[76:79]
	v_mfma_f32_16x16x32_bf16 v[92:95], v[144:147], v[184:187], 0
	v_mfma_f32_16x16x32_bf16 v[92:95], v[132:135], v[180:183], v[92:95]
	v_mfma_f32_16x16x32_bf16 v[108:111], v[132:135], v[172:175], 0
	v_mfma_f32_16x16x32_bf16 v[108:111], v[144:147], v[176:179], v[108:111]
	v_mfma_f32_16x16x32_bf16 v[136:139], v[144:147], v[168:171], 0
	v_mfma_f32_16x16x32_bf16 v[136:139], v[132:135], v[164:167], v[136:139]
	s_waitcnt lgkmcnt(3)
	v_mfma_f32_16x16x32_bf16 v[120:123], v[148:151], v[164:167], 0
	s_waitcnt lgkmcnt(2)
	v_mfma_f32_16x16x32_bf16 v[120:123], v[152:155], v[168:171], v[120:123]
	v_mfma_f32_16x16x32_bf16 v[104:107], v[152:155], v[176:179], 0
	v_mfma_f32_16x16x32_bf16 v[104:107], v[148:151], v[172:175], v[104:107]
	v_mfma_f32_16x16x32_bf16 v[88:91], v[148:151], v[180:183], 0
	v_mfma_f32_16x16x32_bf16 v[88:91], v[152:155], v[184:187], v[88:91]
	v_mfma_f32_16x16x32_bf16 v[72:75], v[152:155], v[214:217], 0
	v_mfma_f32_16x16x32_bf16 v[72:75], v[148:151], v[188:191], v[72:75]
	s_waitcnt lgkmcnt(1)
	v_mfma_f32_16x16x32_bf16 v[68:71], v[156:159], v[188:191], 0
	s_waitcnt lgkmcnt(0)
	v_mfma_f32_16x16x32_bf16 v[68:71], v[160:163], v[214:217], v[68:71]
	v_mfma_f32_16x16x32_bf16 v[84:87], v[160:163], v[184:187], 0
	v_mfma_f32_16x16x32_bf16 v[84:87], v[156:159], v[180:183], v[84:87]
	v_mfma_f32_16x16x32_bf16 v[100:103], v[156:159], v[172:175], 0
	v_mfma_f32_16x16x32_bf16 v[100:103], v[160:163], v[176:179], v[100:103]
	v_mfma_f32_16x16x32_bf16 v[116:119], v[160:163], v[168:171], 0
	v_mfma_f32_16x16x32_bf16 v[116:119], v[156:159], v[164:167], v[116:119]
	s_barrier
	s_setprio 0
	s_add_i32 s56, s56, s40
	v_lshl_add_u64 v[218:219], s[26:27], 0, v[2:3]
	s_mov_b32 m0, s56
	ds_read_b128 v[164:167], v242 offset:16384
	ds_read_b128 v[168:171], v242 offset:17408
	ds_read_b128 v[176:179], v242 offset:19456
	ds_read_b128 v[172:175], v242 offset:18432
	ds_read_b128 v[180:183], v242 offset:20480
	ds_read_b128 v[184:187], v242 offset:21504
	ds_read_b128 v[214:217], v242 offset:23552
	ds_read_b128 v[188:191], v242 offset:22528
	global_load_lds_dwordx4 v[218:219], off
	s_add_i32 m0, s56, 0x2000
	s_add_u32 s56, s26, 0x100000
	v_lshl_add_u64 v[220:221], s[26:27], 0, v[204:205]
	s_addc_u32 s57, s27, 0
	s_add_i32 s58, s58, s40
	global_load_lds_dwordx4 v[220:221], off
	s_mov_b32 m0, s58
	v_lshl_add_u64 v[224:225], s[36:37], 0, v[206:207]
	global_load_lds_dwordx4 v2, s[56:57]
	s_add_i32 m0, s58, 0x2000
	s_nop 0
	global_load_lds_dwordx4 v204, s[56:57]
	v_lshl_add_u64 v[222:223], s[36:37], 0, v[208:209]
	s_waitcnt vmcnt(6)
	s_waitcnt lgkmcnt(7)
	s_setprio 1
	s_barrier
; #define PG8_STAGE(bufoff, gbase, voff) do { _Pragma("unroll") for (int _i = 0; _i < 2; ++_i) \
;         __builtin_amdgcn_global_load_lds((const unsigned*)((const char*)(gbase) + (voff)[_i]), (PG8_LAS unsigned*)(lds + (bufoff) + ldsw + _i * 8192), 16, 0, 0); } while (0)
; #define PG8_LDA(dst, b, h) do { _Pragma("unroll") for (int m = 0; m < 4; ++m) _Pragma("unroll") for (int k = 0; k < 2; ++k) dst[m][k] = *(const PG8_LAS bf16x8*)(lds + PG8_SA(b, h) + aoff + m * 2048 + k * 1024); } while (0)
; #define PG8_LDB(dst, b, h) do { _Pragma("unroll") for (int n = 0; n < 2; ++n) _Pragma("unroll") for (int k = 0; k < 2; ++k) dst[n][k] = *(const PG8_LAS bf16x8*)(lds + PG8_SB(b, h) + boff + n * 2048 + k * 1024); } while (0)
; #define PG8_WAIT_V(n) asm volatile("s_waitcnt vmcnt(" #n ")" ::: "memory")
; #define PG8_WAIT_L(n) asm volatile("s_waitcnt lgkmcnt(" #n ")" ::: "memory")
; #define PG8_BAR __builtin_amdgcn_s_barrier()
; #define PG8_SCHED __builtin_amdgcn_sched_barrier(0)
; template <class Epi, class Sched, bool ALIGN_EPI = false, bool SP2 = false, bool I8 = false>
; __device__ __forceinline__ void gemm_phase(PG8_LAS unsigned char* lds, const Gemm g, const Sched& S, const Epi& E) {
;     ...
;             PG8_WAIT_V(8); PG8_WAIT_L(0); PG8_BAR; PG8_MMA(1, 0, At, B0); PG8_MMA(1, 1, At, B1); PG8_BAR; PG8_SCHED;
;             PG8_LDB(B0, 1, 0); PG8_LDB(B1, 1, 1); PG8_SCHED; PG8_LDA(At, 1, 0); PG8_STAGE(PG8_SA(0, 1), a2 + hstep, voffA);
;             PG8_WAIT_V(8); PG8_WAIT_L(0); PG8_BAR; PG8_MMA(0, 0, At, B0); PG8_MMA(0, 1, At, B1); PG8_BAR; PG8_SCHED;
;             PG8_LDA(At, 1, 1); PG8_STAGE(PG8_SB(1, 0), b3, voffB); PG8_STAGE(PG8_SB(1, 1), b3 + hstep, voffB); PG8_STAGE(PG8_SA(1, 0), a3, voffA);
	v_mfma_f32_16x16x32_bf16 v[64:67], v[124:127], v[164:167], 0
	s_waitcnt lgkmcnt(6)
	v_mfma_f32_16x16x32_bf16 v[64:67], v[128:131], v[168:171], v[64:67]
	s_waitcnt lgkmcnt(5)
	v_mfma_f32_16x16x32_bf16 v[48:51], v[128:131], v[176:179], 0
	s_waitcnt lgkmcnt(4)
	v_mfma_f32_16x16x32_bf16 v[48:51], v[124:127], v[172:175], v[48:51]
	s_waitcnt lgkmcnt(3)
	v_mfma_f32_16x16x32_bf16 v[32:35], v[124:127], v[180:183], 0
	s_waitcnt lgkmcnt(2)
	v_mfma_f32_16x16x32_bf16 v[32:35], v[128:131], v[184:187], v[32:35]
	s_waitcnt lgkmcnt(1)
	v_mfma_f32_16x16x32_bf16 v[16:19], v[128:131], v[214:217], 0
	s_waitcnt lgkmcnt(0)
	v_mfma_f32_16x16x32_bf16 v[16:19], v[124:127], v[188:191], v[16:19]
	v_mfma_f32_16x16x32_bf16 v[12:15], v[132:135], v[188:191], 0
	v_mfma_f32_16x16x32_bf16 v[12:15], v[144:147], v[214:217], v[12:15]
	v_mfma_f32_16x16x32_bf16 v[28:31], v[144:147], v[184:187], 0
	v_mfma_f32_16x16x32_bf16 v[28:31], v[132:135], v[180:183], v[28:31]
	v_mfma_f32_16x16x32_bf16 v[44:47], v[132:135], v[172:175], 0
	v_mfma_f32_16x16x32_bf16 v[44:47], v[144:147], v[176:179], v[44:47]
	v_mfma_f32_16x16x32_bf16 v[60:63], v[144:147], v[168:171], 0
	v_mfma_f32_16x16x32_bf16 v[60:63], v[132:135], v[164:167], v[60:63]
	v_mfma_f32_16x16x32_bf16 v[56:59], v[148:151], v[164:167], 0
	v_mfma_f32_16x16x32_bf16 v[56:59], v[152:155], v[168:171], v[56:59]
	v_mfma_f32_16x16x32_bf16 v[40:43], v[152:155], v[176:179], 0
	v_mfma_f32_16x16x32_bf16 v[40:43], v[148:151], v[172:175], v[40:43]
	v_mfma_f32_16x16x32_bf16 v[24:27], v[148:151], v[180:183], 0
	v_mfma_f32_16x16x32_bf16 v[24:27], v[152:155], v[184:187], v[24:27]
	v_mfma_f32_16x16x32_bf16 v[8:11], v[152:155], v[214:217], 0
	v_mfma_f32_16x16x32_bf16 v[8:11], v[148:151], v[188:191], v[8:11]
	v_mfma_f32_16x16x32_bf16 v[4:7], v[156:159], v[188:191], 0
	v_mfma_f32_16x16x32_bf16 v[4:7], v[160:163], v[214:217], v[4:7]
	v_mfma_f32_16x16x32_bf16 v[20:23], v[160:163], v[184:187], 0
	v_mfma_f32_16x16x32_bf16 v[20:23], v[156:159], v[180:183], v[20:23]
	v_mfma_f32_16x16x32_bf16 v[36:39], v[156:159], v[172:175], 0
	v_mfma_f32_16x16x32_bf16 v[36:39], v[160:163], v[176:179], v[36:39]
	v_mfma_f32_16x16x32_bf16 v[52:55], v[160:163], v[168:171], 0
	v_mfma_f32_16x16x32_bf16 v[52:55], v[156:159], v[164:167], v[52:55]
	s_barrier
	s_setprio 0
	s_mov_b32 m0, s41
	s_nop 0
	global_load_lds_dwordx4 v[222:223], off
	s_mov_b32 m0, s42
	s_nop 0
	global_load_lds_dwordx4 v[224:225], off
	s_add_i32 s56, 0, 0x18000
	s_add_i32 s57, 0, 0x1c000
	v_add_u32_e32 v144, s56, v240
	v_add_u32_e32 v160, s57, v240
	ds_read_b128 v[124:127], v144
	ds_read_b128 v[164:167], v242 offset:32768
	ds_read_b128 v[128:131], v144 offset:1024
	ds_read_b128 v[168:171], v242 offset:33792
	ds_read_b128 v[176:179], v242 offset:35840
	ds_read_b128 v[172:175], v242 offset:34816
	ds_read_b128 v[180:183], v242 offset:36864
	ds_read_b128 v[184:187], v242 offset:37888
	s_add_u32 s36, s36, 0x100000
	s_addc_u32 s37, s37, 0
	s_mov_b32 m0, s43
	ds_read_b128 v[214:217], v242 offset:39936
	ds_read_b128 v[188:191], v242 offset:38912
	ds_read_b128 v[132:135], v144 offset:2048
	ds_read_b128 v[144:147], v144 offset:3072
	ds_read_b128 v[148:151], v160
	ds_read_b128 v[152:155], v160 offset:1024
	ds_read_b128 v[156:159], v160 offset:2048
	ds_read_b128 v[160:163], v160 offset:3072
	global_load_lds_dwordx4 v208, s[36:37]
	s_mov_b32 m0, s44
	s_nop 0
	global_load_lds_dwordx4 v206, s[36:37]
	s_waitcnt vmcnt(8)
	s_waitcnt lgkmcnt(14)
	s_setprio 1
	s_barrier
	v_mfma_f32_16x16x32_bf16 v[140:143], v[124:127], v[164:167], v[140:143]
	s_waitcnt lgkmcnt(12)
	v_mfma_f32_16x16x32_bf16 v[140:143], v[128:131], v[168:171], v[140:143]
	s_waitcnt lgkmcnt(11)
	v_mfma_f32_16x16x32_bf16 v[112:115], v[128:131], v[176:179], v[112:115]
	s_waitcnt lgkmcnt(10)
	v_mfma_f32_16x16x32_bf16 v[112:115], v[124:127], v[172:175], v[112:115]
	s_waitcnt lgkmcnt(9)
	v_mfma_f32_16x16x32_bf16 v[96:99], v[124:127], v[180:183], v[96:99]
	s_waitcnt lgkmcnt(8)
	v_mfma_f32_16x16x32_bf16 v[96:99], v[128:131], v[184:187], v[96:99]
	s_waitcnt lgkmcnt(7)
	v_mfma_f32_16x16x32_bf16 v[80:83], v[128:131], v[214:217], v[80:83]
	s_waitcnt lgkmcnt(6)
	v_mfma_f32_16x16x32_bf16 v[80:83], v[124:127], v[188:191], v[80:83]
	s_waitcnt lgkmcnt(5)
	v_mfma_f32_16x16x32_bf16 v[76:79], v[132:135], v[188:191], v[76:79]
	s_waitcnt lgkmcnt(4)
	v_mfma_f32_16x16x32_bf16 v[76:79], v[144:147], v[214:217], v[76:79]
	v_mfma_f32_16x16x32_bf16 v[92:95], v[144:147], v[184:187], v[92:95]
	v_mfma_f32_16x16x32_bf16 v[92:95], v[132:135], v[180:183], v[92:95]
	v_mfma_f32_16x16x32_bf16 v[108:111], v[132:135], v[172:175], v[108:111]
	v_mfma_f32_16x16x32_bf16 v[108:111], v[144:147], v[176:179], v[108:111]
	v_mfma_f32_16x16x32_bf16 v[136:139], v[144:147], v[168:171], v[136:139]
	v_mfma_f32_16x16x32_bf16 v[136:139], v[132:135], v[164:167], v[136:139]
	s_waitcnt lgkmcnt(3)
	v_mfma_f32_16x16x32_bf16 v[120:123], v[148:151], v[164:167], v[120:123]
	s_waitcnt lgkmcnt(2)
	v_mfma_f32_16x16x32_bf16 v[120:123], v[152:155], v[168:171], v[120:123]
	v_mfma_f32_16x16x32_bf16 v[104:107], v[152:155], v[176:179], v[104:107]
	v_mfma_f32_16x16x32_bf16 v[104:107], v[148:151], v[172:175], v[104:107]
	v_mfma_f32_16x16x32_bf16 v[88:91], v[148:151], v[180:183], v[88:91]
	v_mfma_f32_16x16x32_bf16 v[88:91], v[152:155], v[184:187], v[88:91]
	v_mfma_f32_16x16x32_bf16 v[72:75], v[152:155], v[214:217], v[72:75]
	v_mfma_f32_16x16x32_bf16 v[72:75], v[148:151], v[188:191], v[72:75]
	s_waitcnt lgkmcnt(1)
	v_mfma_f32_16x16x32_bf16 v[68:71], v[156:159], v[188:191], v[68:71]
	s_waitcnt lgkmcnt(0)
	v_mfma_f32_16x16x32_bf16 v[68:71], v[160:163], v[214:217], v[68:71]
	v_mfma_f32_16x16x32_bf16 v[84:87], v[160:163], v[184:187], v[84:87]
	v_mfma_f32_16x16x32_bf16 v[84:87], v[156:159], v[180:183], v[84:87]
	v_mfma_f32_16x16x32_bf16 v[100:103], v[156:159], v[172:175], v[100:103]
	v_mfma_f32_16x16x32_bf16 v[100:103], v[160:163], v[176:179], v[100:103]
	v_mfma_f32_16x16x32_bf16 v[116:119], v[160:163], v[168:171], v[116:119]
	v_mfma_f32_16x16x32_bf16 v[116:119], v[156:159], v[164:167], v[116:119]
	s_barrier
; #define PG8_STAGE(bufoff, gbase, voff) do { _Pragma("unroll") for (int _i = 0; _i < 2; ++_i) \
;         __builtin_amdgcn_global_load_lds((const unsigned*)((const char*)(gbase) + (voff)[_i]), (PG8_LAS unsigned*)(lds + (bufoff) + ldsw + _i * 8192), 16, 0, 0); } while (0)
; #define PG8_LDA(dst, b, h) do { _Pragma("unroll") for (int m = 0; m < 4; ++m) _Pragma("unroll") for (int k = 0; k < 2; ++k) dst[m][k] = *(const PG8_LAS bf16x8*)(lds + PG8_SA(b, h) + aoff + m * 2048 + k * 1024); } while (0)
; #define PG8_LDB(dst, b, h) do { _Pragma("unroll") for (int n = 0; n < 2; ++n) _Pragma("unroll") for (int k = 0; k < 2; ++k) dst[n][k] = *(const PG8_LAS bf16x8*)(lds + PG8_SB(b, h) + boff + n * 2048 + k * 1024); } while (0)
; #define PG8_WAIT_V(n) asm volatile("s_waitcnt vmcnt(" #n ")" ::: "memory")
; template <class Epi, class Sched, bool ALIGN_EPI = false, bool SP2 = false, bool I8 = false>
; __device__ __forceinline__ void gemm_phase(PG8_LAS unsigned char* lds, const Gemm g, const Sched& S, const Epi& E) {
;     ...
;         for (int t = 0; t < nt; t += 2) {
;             const bool last = (t == nt - 2);
;             const char* a1 = cA + (size_t)(t + 1) * kstep;
;             const char* a2 = last ? nA : cA + (size_t)(t + 2) * kstep; const char* b2 = last ? nB : cB + (size_t)(t + 2) * kstep;
;             const char* a3 = a2 + kstep; const char* b3 = b2 + kstep;
;             if (last && has_next) S.a_ready(nxt);
;             if constexpr (SP2) {
;             PG8_LDB(B0, 0, 0); PG8_LDB(B1, 0, 1); PG8_SCHED; PG8_LDA(At, 0, 0); PG8_STAGE(PG8_SA(1, 1), a1 + hstep, voffA);
;             PG8_WAIT_V(8); PG8_WAIT_L(0); PG8_BAR; PG8_MMA(0, 0, At, B0); PG8_MMA(0, 1, At, B1); PG8_BAR; PG8_SCHED;
;             PG8_LDA(At, 0, 1); PG8_STAGE(PG8_SB(0, 0), b2, voffB); PG8_STAGE(PG8_SB(0, 1), b2 + hstep, voffB); PG8_STAGE(PG8_SA(0, 0), a2, voffA);
;             PG8_WAIT_V(8); PG8_WAIT_L(0); PG8_BAR; PG8_MMA(1, 0, At, B0); PG8_MMA(1, 1, At, B1); PG8_BAR; PG8_SCHED;
;             PG8_LDB(B0, 1, 0); PG8_LDB(B1, 1, 1); PG8_SCHED; PG8_LDA(At, 1, 0); PG8_STAGE(PG8_SA(0, 1), a2 + hstep, voffA);
;             PG8_WAIT_V(8); PG8_WAIT_L(0); PG8_BAR; PG8_MMA(0, 0, At, B0); PG8_MMA(0, 1, At, B1); PG8_BAR; PG8_SCHED;
;             PG8_LDA(At, 1, 1); PG8_STAGE(PG8_SB(1, 0), b3, voffB); PG8_STAGE(PG8_SB(1, 1), b3 + hstep, voffB); PG8_STAGE(PG8_SA(1, 0), a3, voffA);
	s_setprio 0
	s_add_i32 s36, s56, s40
	v_lshl_add_u64 v[218:219], v[218:219], 0, s[84:85]
	s_mov_b32 m0, s36
	ds_read_b128 v[164:167], v242 offset:49152
	ds_read_b128 v[168:171], v242 offset:50176
	ds_read_b128 v[176:179], v242 offset:52224
	ds_read_b128 v[172:175], v242 offset:51200
	ds_read_b128 v[180:183], v242 offset:53248
	ds_read_b128 v[184:187], v242 offset:54272
	ds_read_b128 v[214:217], v242 offset:56320
	ds_read_b128 v[188:191], v242 offset:55296
	global_load_lds_dwordx4 v[218:219], off
	s_add_i32 m0, s36, 0x2000
	s_add_u32 s26, s26, 0x100080
	v_lshl_add_u64 v[218:219], v[220:221], 0, s[84:85]
	s_addc_u32 s27, s27, 0
	s_add_i32 s36, s57, s40
	global_load_lds_dwordx4 v[218:219], off
	s_mov_b32 m0, s36
	s_nop 0
	global_load_lds_dwordx4 v2, s[26:27]
	s_add_i32 m0, s36, 0x2000
	s_nop 0
	global_load_lds_dwordx4 v204, s[26:27]
	s_cmp_eq_u32 s55, 60
	s_cbranch_scc0 .Ldefer_1456_peel
	v_lshl_add_u64 v[218:219], v[222:223], 0, s[84:85]
	s_mov_b32 m0, s45
	s_nop 0
	global_load_lds_dwordx4 v[218:219], off
	v_lshl_add_u64 v[218:219], v[224:225], 0, s[84:85]
	s_mov_b32 m0, s46
	s_nop 0
	global_load_lds_dwordx4 v[218:219], off
.Ldefer_1456_peel:
	s_waitcnt vmcnt(6)
	s_waitcnt lgkmcnt(7)
	s_setprio 1
	s_barrier
	v_mfma_f32_16x16x32_bf16 v[64:67], v[124:127], v[164:167], v[64:67]
	s_waitcnt lgkmcnt(6)
	v_mfma_f32_16x16x32_bf16 v[64:67], v[128:131], v[168:171], v[64:67]
	s_waitcnt lgkmcnt(5)
	v_mfma_f32_16x16x32_bf16 v[48:51], v[128:131], v[176:179], v[48:51]
	s_waitcnt lgkmcnt(4)
	v_mfma_f32_16x16x32_bf16 v[48:51], v[124:127], v[172:175], v[48:51]
	s_waitcnt lgkmcnt(3)
	v_mfma_f32_16x16x32_bf16 v[32:35], v[124:127], v[180:183], v[32:35]
	s_waitcnt lgkmcnt(2)
	v_mfma_f32_16x16x32_bf16 v[32:35], v[128:131], v[184:187], v[32:35]
	s_waitcnt lgkmcnt(1)
	v_mfma_f32_16x16x32_bf16 v[16:19], v[128:131], v[214:217], v[16:19]
	s_waitcnt lgkmcnt(0)
	v_mfma_f32_16x16x32_bf16 v[16:19], v[124:127], v[188:191], v[16:19]
	v_mfma_f32_16x16x32_bf16 v[12:15], v[132:135], v[188:191], v[12:15]
	v_mfma_f32_16x16x32_bf16 v[12:15], v[144:147], v[214:217], v[12:15]
	v_mfma_f32_16x16x32_bf16 v[28:31], v[144:147], v[184:187], v[28:31]
	v_mfma_f32_16x16x32_bf16 v[28:31], v[132:135], v[180:183], v[28:31]
	v_mfma_f32_16x16x32_bf16 v[44:47], v[132:135], v[172:175], v[44:47]
	v_mfma_f32_16x16x32_bf16 v[44:47], v[144:147], v[176:179], v[44:47]
	v_mfma_f32_16x16x32_bf16 v[60:63], v[144:147], v[168:171], v[60:63]
	v_mfma_f32_16x16x32_bf16 v[60:63], v[132:135], v[164:167], v[60:63]
	v_mfma_f32_16x16x32_bf16 v[56:59], v[148:151], v[164:167], v[56:59]
	v_mfma_f32_16x16x32_bf16 v[56:59], v[152:155], v[168:171], v[56:59]
	v_mfma_f32_16x16x32_bf16 v[40:43], v[152:155], v[176:179], v[40:43]
	v_mfma_f32_16x16x32_bf16 v[40:43], v[148:151], v[172:175], v[40:43]
	v_mfma_f32_16x16x32_bf16 v[24:27], v[148:151], v[180:183], v[24:27]
	v_mfma_f32_16x16x32_bf16 v[24:27], v[152:155], v[184:187], v[24:27]
	v_mfma_f32_16x16x32_bf16 v[8:11], v[152:155], v[214:217], v[8:11]
	v_mfma_f32_16x16x32_bf16 v[8:11], v[148:151], v[188:191], v[8:11]
	v_mfma_f32_16x16x32_bf16 v[4:7], v[156:159], v[188:191], v[4:7]
	v_mfma_f32_16x16x32_bf16 v[4:7], v[160:163], v[214:217], v[4:7]
	v_mfma_f32_16x16x32_bf16 v[20:23], v[160:163], v[184:187], v[20:23]
	v_mfma_f32_16x16x32_bf16 v[20:23], v[156:159], v[180:183], v[20:23]
	v_mfma_f32_16x16x32_bf16 v[36:39], v[156:159], v[172:175], v[36:39]
	v_mfma_f32_16x16x32_bf16 v[36:39], v[160:163], v[176:179], v[36:39]
	v_mfma_f32_16x16x32_bf16 v[52:55], v[160:163], v[168:171], v[52:55]
	v_mfma_f32_16x16x32_bf16 v[52:55], v[156:159], v[164:167], v[52:55]
	s_barrier
	s_setprio 0
	s_add_i32 s55, s55, 2
	s_add_u32 s24, s24, 0x100
	s_addc_u32 s25, s25, 0
	s_add_u32 s53, s53, 0x100
	s_addc_u32 s54, s54, 0
	s_cmp_gt_u32 s55, 61
	s_cbranch_scc1 .Lkloop_exit_2
.LBB0_1456:
	s_add_u32 s26, s24, 0xfff00080
	s_addc_u32 s27, s25, -1
	s_add_i32 s56, 0, 0x10000
	s_cmp_eq_u32 s55, 60
	s_cselect_b32 s37, s17, s27
	s_cselect_b32 s36, s51, s26
	s_cselect_b32 s27, s19, s54
	s_cselect_b32 s26, s52, s53
	s_add_i32 s58, 0, 0x14000
	v_add_u32_e32 v144, s56, v240
	v_add_u32_e32 v160, s58, v240
	ds_read_b128 v[124:127], v144
	ds_read_b128 v[164:167], v242
	ds_read_b128 v[128:131], v144 offset:1024
	ds_read_b128 v[168:171], v242 offset:1024
	ds_read_b128 v[176:179], v242 offset:3072
	ds_read_b128 v[172:175], v242 offset:2048
	ds_read_b128 v[180:183], v242 offset:4096
	ds_read_b128 v[184:187], v242 offset:5120
	v_lshl_add_u64 v[218:219], v[222:223], 0, s[84:85]
	s_mov_b32 m0, s45
	s_nop 0
	global_load_lds_dwordx4 v[218:219], off
	v_lshl_add_u64 v[218:219], v[224:225], 0, s[84:85]
	s_mov_b32 m0, s46
	s_nop 0
	global_load_lds_dwordx4 v[218:219], off
	s_add_i32 m0, s41, 0xc000
	ds_read_b128 v[214:217], v242 offset:7168
	ds_read_b128 v[188:191], v242 offset:6144
	ds_read_b128 v[132:135], v144 offset:2048
	ds_read_b128 v[144:147], v144 offset:3072
	ds_read_b128 v[148:151], v160
	ds_read_b128 v[152:155], v160 offset:1024
	ds_read_b128 v[156:159], v160 offset:2048
	ds_read_b128 v[160:163], v160 offset:3072
	global_load_lds_dwordx4 v210, s[24:25]
	s_add_i32 m0, s41, 0xe000
	s_nop 0
	global_load_lds_dwordx4 v212, s[24:25]
	s_waitcnt vmcnt(8)
	s_waitcnt lgkmcnt(14)
	s_setprio 1
	s_barrier
; #define PG8_STAGE(bufoff, gbase, voff) do { _Pragma("unroll") for (int _i = 0; _i < 2; ++_i) \
;         __builtin_amdgcn_global_load_lds((const unsigned*)((const char*)(gbase) + (voff)[_i]), (PG8_LAS unsigned*)(lds + (bufoff) + ldsw + _i * 8192), 16, 0, 0); } while (0)
; #define PG8_LDA(dst, b, h) do { _Pragma("unroll") for (int m = 0; m < 4; ++m) _Pragma("unroll") for (int k = 0; k < 2; ++k) dst[m][k] = *(const PG8_LAS bf16x8*)(lds + PG8_SA(b, h) + aoff + m * 2048 + k * 1024); } while (0)
; #define PG8_LDB(dst, b, h) do { _Pragma("unroll") for (int n = 0; n < 2; ++n) _Pragma("unroll") for (int k = 0; k < 2; ++k) dst[n][k] = *(const PG8_LAS bf16x8*)(lds + PG8_SB(b, h) + boff + n * 2048 + k * 1024); } while (0)
; #define PG8_WAIT_V(n) asm volatile("s_waitcnt vmcnt(" #n ")" ::: "memory")
; #define PG8_WAIT_L(n) asm volatile("s_waitcnt lgkmcnt(" #n ")" ::: "memory")
; #define PG8_BAR __builtin_amdgcn_s_barrier()
; #define PG8_SCHED __builtin_amdgcn_sched_barrier(0)
; template <class Epi, class Sched, bool ALIGN_EPI = false, bool SP2 = false, bool I8 = false>
; __device__ __forceinline__ void gemm_phase(PG8_LAS unsigned char* lds, const Gemm g, const Sched& S, const Epi& E) {
;     ...
;             PG8_LDB(B0, 0, 0); PG8_LDB(B1, 0, 1); PG8_SCHED; PG8_LDA(At, 0, 0); PG8_STAGE(PG8_SA(1, 1), a1 + hstep, voffA);
;             PG8_WAIT_V(8); PG8_WAIT_L(0); PG8_BAR; PG8_MMA(0, 0, At, B0); PG8_MMA(0, 1, At, B1); PG8_BAR; PG8_SCHED;
;             PG8_LDA(At, 0, 1); PG8_STAGE(PG8_SB(0, 0), b2, voffB); PG8_STAGE(PG8_SB(0, 1), b2 + hstep, voffB); PG8_STAGE(PG8_SA(0, 0), a2, voffA);
;             PG8_WAIT_V(8); PG8_WAIT_L(0); PG8_BAR; PG8_MMA(1, 0, At, B0); PG8_MMA(1, 1, At, B1); PG8_BAR; PG8_SCHED;
;             PG8_LDB(B0, 1, 0); PG8_LDB(B1, 1, 1); PG8_SCHED; PG8_LDA(At, 1, 0); PG8_STAGE(PG8_SA(0, 1), a2 + hstep, voffA);
;             PG8_WAIT_V(8); PG8_WAIT_L(0); PG8_BAR; PG8_MMA(0, 0, At, B0); PG8_MMA(0, 1, At, B1); PG8_BAR; PG8_SCHED;
	v_mfma_f32_16x16x32_bf16 v[140:143], v[124:127], v[164:167], v[140:143]
	s_waitcnt lgkmcnt(12)
	v_mfma_f32_16x16x32_bf16 v[140:143], v[128:131], v[168:171], v[140:143]
	s_waitcnt lgkmcnt(11)
	v_mfma_f32_16x16x32_bf16 v[112:115], v[128:131], v[176:179], v[112:115]
	s_waitcnt lgkmcnt(10)
	v_mfma_f32_16x16x32_bf16 v[112:115], v[124:127], v[172:175], v[112:115]
	s_waitcnt lgkmcnt(9)
	v_mfma_f32_16x16x32_bf16 v[96:99], v[124:127], v[180:183], v[96:99]
	s_waitcnt lgkmcnt(8)
	v_mfma_f32_16x16x32_bf16 v[96:99], v[128:131], v[184:187], v[96:99]
	s_waitcnt lgkmcnt(7)
	v_mfma_f32_16x16x32_bf16 v[80:83], v[128:131], v[214:217], v[80:83]
	s_waitcnt lgkmcnt(6)
	v_mfma_f32_16x16x32_bf16 v[80:83], v[124:127], v[188:191], v[80:83]
	s_waitcnt lgkmcnt(5)
	v_mfma_f32_16x16x32_bf16 v[76:79], v[132:135], v[188:191], v[76:79]
	s_waitcnt lgkmcnt(4)
	v_mfma_f32_16x16x32_bf16 v[76:79], v[144:147], v[214:217], v[76:79]
	v_mfma_f32_16x16x32_bf16 v[92:95], v[144:147], v[184:187], v[92:95]
	v_mfma_f32_16x16x32_bf16 v[92:95], v[132:135], v[180:183], v[92:95]
	v_mfma_f32_16x16x32_bf16 v[108:111], v[132:135], v[172:175], v[108:111]
	v_mfma_f32_16x16x32_bf16 v[108:111], v[144:147], v[176:179], v[108:111]
	v_mfma_f32_16x16x32_bf16 v[136:139], v[144:147], v[168:171], v[136:139]
	v_mfma_f32_16x16x32_bf16 v[136:139], v[132:135], v[164:167], v[136:139]
	s_waitcnt lgkmcnt(3)
	v_mfma_f32_16x16x32_bf16 v[120:123], v[148:151], v[164:167], v[120:123]
	s_waitcnt lgkmcnt(2)
	v_mfma_f32_16x16x32_bf16 v[120:123], v[152:155], v[168:171], v[120:123]
	v_mfma_f32_16x16x32_bf16 v[104:107], v[152:155], v[176:179], v[104:107]
	v_mfma_f32_16x16x32_bf16 v[104:107], v[148:151], v[172:175], v[104:107]
	v_mfma_f32_16x16x32_bf16 v[88:91], v[148:151], v[180:183], v[88:91]
	v_mfma_f32_16x16x32_bf16 v[88:91], v[152:155], v[184:187], v[88:91]
	v_mfma_f32_16x16x32_bf16 v[72:75], v[152:155], v[214:217], v[72:75]
	v_mfma_f32_16x16x32_bf16 v[72:75], v[148:151], v[188:191], v[72:75]
	s_waitcnt lgkmcnt(1)
	v_mfma_f32_16x16x32_bf16 v[68:71], v[156:159], v[188:191], v[68:71]
	s_waitcnt lgkmcnt(0)
	v_mfma_f32_16x16x32_bf16 v[68:71], v[160:163], v[214:217], v[68:71]
	v_mfma_f32_16x16x32_bf16 v[84:87], v[160:163], v[184:187], v[84:87]
	v_mfma_f32_16x16x32_bf16 v[84:87], v[156:159], v[180:183], v[84:87]
	v_mfma_f32_16x16x32_bf16 v[100:103], v[156:159], v[172:175], v[100:103]
	v_mfma_f32_16x16x32_bf16 v[100:103], v[160:163], v[176:179], v[100:103]
	v_mfma_f32_16x16x32_bf16 v[116:119], v[160:163], v[168:171], v[116:119]
	v_mfma_f32_16x16x32_bf16 v[116:119], v[156:159], v[164:167], v[116:119]
	s_barrier
	s_setprio 0
	s_add_i32 s56, s56, s40
	v_lshl_add_u64 v[218:219], s[26:27], 0, v[2:3]
	s_mov_b32 m0, s56
	ds_read_b128 v[164:167], v242 offset:16384
	ds_read_b128 v[168:171], v242 offset:17408
	ds_read_b128 v[176:179], v242 offset:19456
	ds_read_b128 v[172:175], v242 offset:18432
	ds_read_b128 v[180:183], v242 offset:20480
	ds_read_b128 v[184:187], v242 offset:21504
	ds_read_b128 v[214:217], v242 offset:23552
	ds_read_b128 v[188:191], v242 offset:22528
	global_load_lds_dwordx4 v[218:219], off
	s_add_i32 m0, s56, 0x2000
	s_add_u32 s56, s26, 0x100000
	v_lshl_add_u64 v[220:221], s[26:27], 0, v[204:205]
	s_addc_u32 s57, s27, 0
	s_add_i32 s58, s58, s40
	global_load_lds_dwordx4 v[220:221], off
	s_mov_b32 m0, s58
	v_lshl_add_u64 v[224:225], s[36:37], 0, v[206:207]
	global_load_lds_dwordx4 v2, s[56:57]
	s_add_i32 m0, s58, 0x2000
	s_nop 0
	global_load_lds_dwordx4 v204, s[56:57]
	v_lshl_add_u64 v[222:223], s[36:37], 0, v[208:209]
	s_waitcnt vmcnt(6)
	s_waitcnt lgkmcnt(7)
	s_setprio 1
	s_barrier
	v_mfma_f32_16x16x32_bf16 v[64:67], v[124:127], v[164:167], v[64:67]
	s_waitcnt lgkmcnt(6)
	v_mfma_f32_16x16x32_bf16 v[64:67], v[128:131], v[168:171], v[64:67]
	s_waitcnt lgkmcnt(5)
	v_mfma_f32_16x16x32_bf16 v[48:51], v[128:131], v[176:179], v[48:51]
	s_waitcnt lgkmcnt(4)
	v_mfma_f32_16x16x32_bf16 v[48:51], v[124:127], v[172:175], v[48:51]
	s_waitcnt lgkmcnt(3)
	v_mfma_f32_16x16x32_bf16 v[32:35], v[124:127], v[180:183], v[32:35]
	s_waitcnt lgkmcnt(2)
	v_mfma_f32_16x16x32_bf16 v[32:35], v[128:131], v[184:187], v[32:35]
	s_waitcnt lgkmcnt(1)
	v_mfma_f32_16x16x32_bf16 v[16:19], v[128:131], v[214:217], v[16:19]
	s_waitcnt lgkmcnt(0)
	v_mfma_f32_16x16x32_bf16 v[16:19], v[124:127], v[188:191], v[16:19]
	v_mfma_f32_16x16x32_bf16 v[12:15], v[132:135], v[188:191], v[12:15]
	v_mfma_f32_16x16x32_bf16 v[12:15], v[144:147], v[214:217], v[12:15]
	v_mfma_f32_16x16x32_bf16 v[28:31], v[144:147], v[184:187], v[28:31]
	v_mfma_f32_16x16x32_bf16 v[28:31], v[132:135], v[180:183], v[28:31]
	v_mfma_f32_16x16x32_bf16 v[44:47], v[132:135], v[172:175], v[44:47]
	v_mfma_f32_16x16x32_bf16 v[44:47], v[144:147], v[176:179], v[44:47]
	v_mfma_f32_16x16x32_bf16 v[60:63], v[144:147], v[168:171], v[60:63]
	v_mfma_f32_16x16x32_bf16 v[60:63], v[132:135], v[164:167], v[60:63]
	v_mfma_f32_16x16x32_bf16 v[56:59], v[148:151], v[164:167], v[56:59]
	v_mfma_f32_16x16x32_bf16 v[56:59], v[152:155], v[168:171], v[56:59]
	v_mfma_f32_16x16x32_bf16 v[40:43], v[152:155], v[176:179], v[40:43]
	v_mfma_f32_16x16x32_bf16 v[40:43], v[148:151], v[172:175], v[40:43]
	v_mfma_f32_16x16x32_bf16 v[24:27], v[148:151], v[180:183], v[24:27]
	v_mfma_f32_16x16x32_bf16 v[24:27], v[152:155], v[184:187], v[24:27]
	v_mfma_f32_16x16x32_bf16 v[8:11], v[152:155], v[214:217], v[8:11]
	v_mfma_f32_16x16x32_bf16 v[8:11], v[148:151], v[188:191], v[8:11]
	v_mfma_f32_16x16x32_bf16 v[4:7], v[156:159], v[188:191], v[4:7]
	v_mfma_f32_16x16x32_bf16 v[4:7], v[160:163], v[214:217], v[4:7]
	v_mfma_f32_16x16x32_bf16 v[20:23], v[160:163], v[184:187], v[20:23]
	v_mfma_f32_16x16x32_bf16 v[20:23], v[156:159], v[180:183], v[20:23]
	v_mfma_f32_16x16x32_bf16 v[36:39], v[156:159], v[172:175], v[36:39]
	v_mfma_f32_16x16x32_bf16 v[36:39], v[160:163], v[176:179], v[36:39]
	v_mfma_f32_16x16x32_bf16 v[52:55], v[160:163], v[168:171], v[52:55]
	v_mfma_f32_16x16x32_bf16 v[52:55], v[156:159], v[164:167], v[52:55]
	s_barrier
; #define PG8_STAGE(bufoff, gbase, voff) do { _Pragma("unroll") for (int _i = 0; _i < 2; ++_i) \
;         __builtin_amdgcn_global_load_lds((const unsigned*)((const char*)(gbase) + (voff)[_i]), (PG8_LAS unsigned*)(lds + (bufoff) + ldsw + _i * 8192), 16, 0, 0); } while (0)
; #define PG8_LDA(dst, b, h) do { _Pragma("unroll") for (int m = 0; m < 4; ++m) _Pragma("unroll") for (int k = 0; k < 2; ++k) dst[m][k] = *(const PG8_LAS bf16x8*)(lds + PG8_SA(b, h) + aoff + m * 2048 + k * 1024); } while (0)
; #define PG8_WAIT_V(n) asm volatile("s_waitcnt vmcnt(" #n ")" ::: "memory")
; #define PG8_WAIT_L(n) asm volatile("s_waitcnt lgkmcnt(" #n ")" ::: "memory")
; #define PG8_BAR __builtin_amdgcn_s_barrier()
; #define PG8_SCHED __builtin_amdgcn_sched_barrier(0)
; template <class Epi, class Sched, bool ALIGN_EPI = false, bool SP2 = false, bool I8 = false>
; __device__ __forceinline__ void gemm_phase(PG8_LAS unsigned char* lds, const Gemm g, const Sched& S, const Epi& E) {
;     ...
;             PG8_WAIT_V(8); PG8_WAIT_L(0); PG8_BAR; PG8_MMA(0, 0, At, B0); PG8_MMA(0, 1, At, B1); PG8_BAR; PG8_SCHED;
;             PG8_LDA(At, 1, 1); PG8_STAGE(PG8_SB(1, 0), b3, voffB); PG8_STAGE(PG8_SB(1, 1), b3 + hstep, voffB); PG8_STAGE(PG8_SA(1, 0), a3, voffA);
;             PG8_WAIT_V(8); PG8_WAIT_L(0); PG8_BAR; PG8_MMA(1, 0, At, B0); PG8_MMA(1, 1, At, B1); PG8_BAR; PG8_SCHED;
	s_setprio 0
	s_mov_b32 m0, s41
	s_nop 0
	global_load_lds_dwordx4 v[222:223], off
	s_mov_b32 m0, s42
	s_nop 0
	global_load_lds_dwordx4 v[224:225], off
	s_add_i32 s56, 0, 0x18000
	s_add_i32 s57, 0, 0x1c000
	v_add_u32_e32 v144, s56, v240
	v_add_u32_e32 v160, s57, v240
	ds_read_b128 v[124:127], v144
	ds_read_b128 v[164:167], v242 offset:32768
	ds_read_b128 v[128:131], v144 offset:1024
	ds_read_b128 v[168:171], v242 offset:33792
	ds_read_b128 v[176:179], v242 offset:35840
	ds_read_b128 v[172:175], v242 offset:34816
	ds_read_b128 v[180:183], v242 offset:36864
	ds_read_b128 v[184:187], v242 offset:37888
	s_add_u32 s36, s36, 0x100000
	s_addc_u32 s37, s37, 0
	s_mov_b32 m0, s43
	ds_read_b128 v[214:217], v242 offset:39936
	ds_read_b128 v[188:191], v242 offset:38912
	ds_read_b128 v[132:135], v144 offset:2048
	ds_read_b128 v[144:147], v144 offset:3072
	ds_read_b128 v[148:151], v160
	ds_read_b128 v[152:155], v160 offset:1024
	ds_read_b128 v[156:159], v160 offset:2048
	ds_read_b128 v[160:163], v160 offset:3072
	global_load_lds_dwordx4 v208, s[36:37]
	s_mov_b32 m0, s44
	s_nop 0
	global_load_lds_dwordx4 v206, s[36:37]
	s_waitcnt vmcnt(8)
	s_waitcnt lgkmcnt(14)
	s_setprio 1
	s_barrier
	v_mfma_f32_16x16x32_bf16 v[140:143], v[124:127], v[164:167], v[140:143]
	s_waitcnt lgkmcnt(12)
	v_mfma_f32_16x16x32_bf16 v[140:143], v[128:131], v[168:171], v[140:143]
	s_waitcnt lgkmcnt(11)
	v_mfma_f32_16x16x32_bf16 v[112:115], v[128:131], v[176:179], v[112:115]
	s_waitcnt lgkmcnt(10)
	v_mfma_f32_16x16x32_bf16 v[112:115], v[124:127], v[172:175], v[112:115]
	s_waitcnt lgkmcnt(9)
	v_mfma_f32_16x16x32_bf16 v[96:99], v[124:127], v[180:183], v[96:99]
	s_waitcnt lgkmcnt(8)
	v_mfma_f32_16x16x32_bf16 v[96:99], v[128:131], v[184:187], v[96:99]
	s_waitcnt lgkmcnt(7)
	v_mfma_f32_16x16x32_bf16 v[80:83], v[128:131], v[214:217], v[80:83]
	s_waitcnt lgkmcnt(6)
	v_mfma_f32_16x16x32_bf16 v[80:83], v[124:127], v[188:191], v[80:83]
	s_waitcnt lgkmcnt(5)
	v_mfma_f32_16x16x32_bf16 v[76:79], v[132:135], v[188:191], v[76:79]
	s_waitcnt lgkmcnt(4)
	v_mfma_f32_16x16x32_bf16 v[76:79], v[144:147], v[214:217], v[76:79]
	v_mfma_f32_16x16x32_bf16 v[92:95], v[144:147], v[184:187], v[92:95]
	v_mfma_f32_16x16x32_bf16 v[92:95], v[132:135], v[180:183], v[92:95]
	v_mfma_f32_16x16x32_bf16 v[108:111], v[132:135], v[172:175], v[108:111]
	v_mfma_f32_16x16x32_bf16 v[108:111], v[144:147], v[176:179], v[108:111]
	v_mfma_f32_16x16x32_bf16 v[136:139], v[144:147], v[168:171], v[136:139]
	v_mfma_f32_16x16x32_bf16 v[136:139], v[132:135], v[164:167], v[136:139]
	s_waitcnt lgkmcnt(3)
	v_mfma_f32_16x16x32_bf16 v[120:123], v[148:151], v[164:167], v[120:123]
	s_waitcnt lgkmcnt(2)
	v_mfma_f32_16x16x32_bf16 v[120:123], v[152:155], v[168:171], v[120:123]
	v_mfma_f32_16x16x32_bf16 v[104:107], v[152:155], v[176:179], v[104:107]
	v_mfma_f32_16x16x32_bf16 v[104:107], v[148:151], v[172:175], v[104:107]
	v_mfma_f32_16x16x32_bf16 v[88:91], v[148:151], v[180:183], v[88:91]
	v_mfma_f32_16x16x32_bf16 v[88:91], v[152:155], v[184:187], v[88:91]
	v_mfma_f32_16x16x32_bf16 v[72:75], v[152:155], v[214:217], v[72:75]
	v_mfma_f32_16x16x32_bf16 v[72:75], v[148:151], v[188:191], v[72:75]
	s_waitcnt lgkmcnt(1)
	v_mfma_f32_16x16x32_bf16 v[68:71], v[156:159], v[188:191], v[68:71]
	s_waitcnt lgkmcnt(0)
	v_mfma_f32_16x16x32_bf16 v[68:71], v[160:163], v[214:217], v[68:71]
	v_mfma_f32_16x16x32_bf16 v[84:87], v[160:163], v[184:187], v[84:87]
	v_mfma_f32_16x16x32_bf16 v[84:87], v[156:159], v[180:183], v[84:87]
	v_mfma_f32_16x16x32_bf16 v[100:103], v[156:159], v[172:175], v[100:103]
	v_mfma_f32_16x16x32_bf16 v[100:103], v[160:163], v[176:179], v[100:103]
	v_mfma_f32_16x16x32_bf16 v[116:119], v[160:163], v[168:171], v[116:119]
	v_mfma_f32_16x16x32_bf16 v[116:119], v[156:159], v[164:167], v[116:119]
	s_barrier
	s_setprio 0
	s_add_i32 s36, s56, s40
	v_lshl_add_u64 v[218:219], v[218:219], 0, s[84:85]
	s_mov_b32 m0, s36
	ds_read_b128 v[164:167], v242 offset:49152
	ds_read_b128 v[168:171], v242 offset:50176
	ds_read_b128 v[176:179], v242 offset:52224
	ds_read_b128 v[172:175], v242 offset:51200
	ds_read_b128 v[180:183], v242 offset:53248
	ds_read_b128 v[184:187], v242 offset:54272
	ds_read_b128 v[214:217], v242 offset:56320
	ds_read_b128 v[188:191], v242 offset:55296
	global_load_lds_dwordx4 v[218:219], off
	s_add_i32 m0, s36, 0x2000
	s_add_u32 s26, s26, 0x100080
	v_lshl_add_u64 v[218:219], v[220:221], 0, s[84:85]
	s_addc_u32 s27, s27, 0
	s_add_i32 s36, s57, s40
	global_load_lds_dwordx4 v[218:219], off
	s_mov_b32 m0, s36
	s_nop 0
	global_load_lds_dwordx4 v2, s[26:27]
	s_add_i32 m0, s36, 0x2000
	s_nop 0
	global_load_lds_dwordx4 v204, s[26:27]
	s_cmp_eq_u32 s55, 60
	s_cbranch_scc0 .Ldefer_1456_body
	v_lshl_add_u64 v[218:219], v[222:223], 0, s[84:85]
	s_mov_b32 m0, s45
	s_nop 0
	global_load_lds_dwordx4 v[218:219], off
	v_lshl_add_u64 v[218:219], v[224:225], 0, s[84:85]
	s_mov_b32 m0, s46
	s_nop 0
	global_load_lds_dwordx4 v[218:219], off
; #define PG8_STAGE(bufoff, gbase, voff) do { _Pragma("unroll") for (int _i = 0; _i < 2; ++_i) \
;         __builtin_amdgcn_global_load_lds((const unsigned*)((const char*)(gbase) + (voff)[_i]), (PG8_LAS unsigned*)(lds + (bufoff) + ldsw + _i * 8192), 16, 0, 0); } while (0)
; #define PG8_LDA(dst, b, h) do { _Pragma("unroll") for (int m = 0; m < 4; ++m) _Pragma("unroll") for (int k = 0; k < 2; ++k) dst[m][k] = *(const PG8_LAS bf16x8*)(lds + PG8_SA(b, h) + aoff + m * 2048 + k * 1024); } while (0)
; #define PG8_WAIT_V(n) asm volatile("s_waitcnt vmcnt(" #n ")" ::: "memory")
; #define PG8_WAIT_L(n) asm volatile("s_waitcnt lgkmcnt(" #n ")" ::: "memory")
; #define PG8_BAR __builtin_amdgcn_s_barrier()
; #define PG8_SCHED __builtin_amdgcn_sched_barrier(0)
; template <class Epi, class Sched, bool ALIGN_EPI = false, bool SP2 = false, bool I8 = false>
; __device__ __forceinline__ void gemm_phase(PG8_LAS unsigned char* lds, const Gemm g, const Sched& S, const Epi& E) {
;     ...
;         for (int t = 0; t < nt; t += 2) {
;     ...
;             PG8_LDA(At, 1, 1); PG8_STAGE(PG8_SB(1, 0), b3, voffB); PG8_STAGE(PG8_SB(1, 1), b3 + hstep, voffB); PG8_STAGE(PG8_SA(1, 0), a3, voffA);
;             PG8_WAIT_V(8); PG8_WAIT_L(0); PG8_BAR; PG8_MMA(1, 0, At, B0); PG8_MMA(1, 1, At, B1); PG8_BAR; PG8_SCHED;
.Ldefer_1456_body:
	s_waitcnt vmcnt(6)
	s_waitcnt lgkmcnt(7)
	s_setprio 1
	s_barrier
	v_mfma_f32_16x16x32_bf16 v[64:67], v[124:127], v[164:167], v[64:67]
	s_waitcnt lgkmcnt(6)
	v_mfma_f32_16x16x32_bf16 v[64:67], v[128:131], v[168:171], v[64:67]
	s_waitcnt lgkmcnt(5)
	v_mfma_f32_16x16x32_bf16 v[48:51], v[128:131], v[176:179], v[48:51]
	s_waitcnt lgkmcnt(4)
	v_mfma_f32_16x16x32_bf16 v[48:51], v[124:127], v[172:175], v[48:51]
	s_waitcnt lgkmcnt(3)
	v_mfma_f32_16x16x32_bf16 v[32:35], v[124:127], v[180:183], v[32:35]
	s_waitcnt lgkmcnt(2)
	v_mfma_f32_16x16x32_bf16 v[32:35], v[128:131], v[184:187], v[32:35]
	s_waitcnt lgkmcnt(1)
	v_mfma_f32_16x16x32_bf16 v[16:19], v[128:131], v[214:217], v[16:19]
	s_waitcnt lgkmcnt(0)
	v_mfma_f32_16x16x32_bf16 v[16:19], v[124:127], v[188:191], v[16:19]
	v_mfma_f32_16x16x32_bf16 v[12:15], v[132:135], v[188:191], v[12:15]
	v_mfma_f32_16x16x32_bf16 v[12:15], v[144:147], v[214:217], v[12:15]
	v_mfma_f32_16x16x32_bf16 v[28:31], v[144:147], v[184:187], v[28:31]
	v_mfma_f32_16x16x32_bf16 v[28:31], v[132:135], v[180:183], v[28:31]
	v_mfma_f32_16x16x32_bf16 v[44:47], v[132:135], v[172:175], v[44:47]
	v_mfma_f32_16x16x32_bf16 v[44:47], v[144:147], v[176:179], v[44:47]
	v_mfma_f32_16x16x32_bf16 v[60:63], v[144:147], v[168:171], v[60:63]
	v_mfma_f32_16x16x32_bf16 v[60:63], v[132:135], v[164:167], v[60:63]
	v_mfma_f32_16x16x32_bf16 v[56:59], v[148:151], v[164:167], v[56:59]
	v_mfma_f32_16x16x32_bf16 v[56:59], v[152:155], v[168:171], v[56:59]
	v_mfma_f32_16x16x32_bf16 v[40:43], v[152:155], v[176:179], v[40:43]
	v_mfma_f32_16x16x32_bf16 v[40:43], v[148:151], v[172:175], v[40:43]
	v_mfma_f32_16x16x32_bf16 v[24:27], v[148:151], v[180:183], v[24:27]
	v_mfma_f32_16x16x32_bf16 v[24:27], v[152:155], v[184:187], v[24:27]
	v_mfma_f32_16x16x32_bf16 v[8:11], v[152:155], v[214:217], v[8:11]
	v_mfma_f32_16x16x32_bf16 v[8:11], v[148:151], v[188:191], v[8:11]
	v_mfma_f32_16x16x32_bf16 v[4:7], v[156:159], v[188:191], v[4:7]
	v_mfma_f32_16x16x32_bf16 v[4:7], v[160:163], v[214:217], v[4:7]
	v_mfma_f32_16x16x32_bf16 v[20:23], v[160:163], v[184:187], v[20:23]
	v_mfma_f32_16x16x32_bf16 v[20:23], v[156:159], v[180:183], v[20:23]
	v_mfma_f32_16x16x32_bf16 v[36:39], v[156:159], v[172:175], v[36:39]
	v_mfma_f32_16x16x32_bf16 v[36:39], v[160:163], v[176:179], v[36:39]
	v_mfma_f32_16x16x32_bf16 v[52:55], v[160:163], v[168:171], v[52:55]
	v_mfma_f32_16x16x32_bf16 v[52:55], v[156:159], v[164:167], v[52:55]
	s_barrier
	s_setprio 0
	s_add_i32 s55, s55, 2
	s_add_u32 s24, s24, 0x100
	s_addc_u32 s25, s25, 0
	s_add_u32 s53, s53, 0x100
	s_addc_u32 s54, s54, 0
	s_cmp_gt_u32 s55, 61
	s_cbranch_scc0 .LBB0_1456

; #define PG8_STAGE(bufoff, gbase, voff) do { _Pragma("unroll") for (int _i = 0; _i < 2; ++_i) \
;         __builtin_amdgcn_global_load_lds((const unsigned*)((const char*)(gbase) + (voff)[_i]), (PG8_LAS unsigned*)(lds + (bufoff) + ldsw + _i * 8192), 16, 0, 0); } while (0)
; #define PG8_LDA(dst, b, h) do { _Pragma("unroll") for (int m = 0; m < 4; ++m) _Pragma("unroll") for (int k = 0; k < 2; ++k) dst[m][k] = *(const PG8_LAS bf16x8*)(lds + PG8_SA(b, h) + aoff + m * 2048 + k * 1024); } while (0)
; #define PG8_LDB(dst, b, h) do { _Pragma("unroll") for (int n = 0; n < 2; ++n) _Pragma("unroll") for (int k = 0; k < 2; ++k) dst[n][k] = *(const PG8_LAS bf16x8*)(lds + PG8_SB(b, h) + boff + n * 2048 + k * 1024); } while (0)
; #define PG8_WAIT_V(n) asm volatile("s_waitcnt vmcnt(" #n ")" ::: "memory")
; #define PG8_WAIT_L(n) asm volatile("s_waitcnt lgkmcnt(" #n ")" ::: "memory")
; #define PG8_BAR __builtin_amdgcn_s_barrier()
; #define PG8_SCHED __builtin_amdgcn_sched_barrier(0)
; template <class Epi, class Sched, bool ALIGN_EPI = false, bool SP2 = false, bool I8 = false>
; __device__ __forceinline__ void gemm_phase(PG8_LAS unsigned char* lds, const Gemm g, const Sched& S, const Epi& E) {
;     ...
;         const bool has_next = S.next(ui + 1, nxt);
;         const char* nA = has_next ? (const char*)g.A + (size_t)nxt.pm * tstep : cA; const char* nB = has_next ? (const char*)g.Bt + (size_t)nxt.pn * tstep : cB;
;         for (int t = 0; t < nt; t += 2) {
;             const bool last = (t == nt - 2);
;             const char* a1 = cA + (size_t)(t + 1) * kstep;
;             const char* a2 = last ? nA : cA + (size_t)(t + 2) * kstep; const char* b2 = last ? nB : cB + (size_t)(t + 2) * kstep;
;             const char* a3 = a2 + kstep; const char* b3 = b2 + kstep;
;             if (last && has_next) S.a_ready(nxt);
;             if constexpr (SP2) {
;             PG8_LDB(B0, 0, 0); PG8_LDB(B1, 0, 1); PG8_SCHED; PG8_LDA(At, 0, 0); PG8_STAGE(PG8_SA(1, 1), a1 + hstep, voffA);
;             PG8_WAIT_V(8); PG8_WAIT_L(0); PG8_BAR; PG8_MMA(0, 0, At, B0); PG8_MMA(0, 1, At, B1); PG8_BAR; PG8_SCHED;
;             PG8_LDA(At, 0, 1); PG8_STAGE(PG8_SB(0, 0), b2, voffB); PG8_STAGE(PG8_SB(0, 1), b2 + hstep, voffB); PG8_STAGE(PG8_SA(0, 0), a2, voffA);
;             PG8_WAIT_V(8); PG8_WAIT_L(0); PG8_BAR; PG8_MMA(1, 0, At, B0); PG8_MMA(1, 1, At, B1); PG8_BAR; PG8_SCHED;
.LBB0_1590:
	s_ashr_i32 s25, s24, 31
	s_lshl_b64 s[26:27], s[24:25], 20
	s_add_u32 s26, s28, s26
	s_addc_u32 s27, s42, s27
	s_and_b64 s[36:37], s[10:11], exec
	s_cselect_b32 s25, s27, s41
	s_cselect_b32 s57, s26, s40
	s_ashr_i32 s23, s22, 31
	s_lshl_b64 s[36:37], s[22:23], 20
	s_add_u32 s36, s43, s36
	s_addc_u32 s37, s46, s37
	s_and_b64 s[48:49], s[10:11], exec
	s_cselect_b32 s23, s37, s45
	s_cselect_b32 s58, s36, s44
	s_add_u32 s40, s40, 0x80080
	s_addc_u32 s41, s41, 0
	s_add_u32 s59, s44, 0x100
	s_addc_u32 s60, s45, 0
	s_mov_b32 s61, -2
	s_add_u32 s44, s40, 0xfff80080
	s_addc_u32 s45, s41, -1
	s_add_i32 s64, 0, 0x10000
	s_cmp_eq_u32 s61, 28
	s_cselect_b32 s49, s25, s45
	s_cselect_b32 s48, s57, s44
	s_cselect_b32 s45, s23, s60
	s_cselect_b32 s44, s58, s59
	s_add_i32 s67, 0, 0x14000
	v_add_u32_e32 v144, s64, v167
	v_add_u32_e32 v158, s67, v167
	ds_read_b128 v[36:39], v144
	ds_read_b128 v[184:187], v171
	ds_read_b128 v[44:47], v144 offset:1024
	ds_read_b128 v[188:191], v171 offset:1024
	ds_read_b128 v[208:211], v171 offset:3072
	ds_read_b128 v[204:207], v171 offset:2048
	ds_read_b128 v[212:215], v171 offset:4096
	ds_read_b128 v[216:219], v171 offset:5120
	s_add_i32 m0, s50, 0xc000
	ds_read_b128 v[224:227], v171 offset:7168
	ds_read_b128 v[220:223], v171 offset:6144
	ds_read_b128 v[140:143], v144 offset:2048
	ds_read_b128 v[144:147], v144 offset:3072
	ds_read_b128 v[160:163], v158
	ds_read_b128 v[172:175], v158 offset:1024
	ds_read_b128 v[176:179], v158 offset:2048
	ds_read_b128 v[180:183], v158 offset:3072
	global_load_lds_dwordx4 v154, s[40:41]
	s_add_i32 m0, s50, 0xe000
	s_nop 0
	global_load_lds_dwordx4 v156, s[40:41]
	s_waitcnt vmcnt(8)
	s_waitcnt lgkmcnt(14)
	s_setprio 1
	s_barrier
	v_mfma_i32_16x16x64_i8 v[136:139], v[36:39], v[184:187], 0
	s_waitcnt lgkmcnt(12)
	v_mfma_i32_16x16x64_i8 v[136:139], v[44:47], v[188:191], v[136:139]
	s_waitcnt lgkmcnt(11)
	v_mfma_i32_16x16x64_i8 v[120:123], v[44:47], v[208:211], 0
	s_waitcnt lgkmcnt(10)
	v_mfma_i32_16x16x64_i8 v[120:123], v[36:39], v[204:207], v[120:123]
	s_waitcnt lgkmcnt(9)
	v_mfma_i32_16x16x64_i8 v[104:107], v[36:39], v[212:215], 0
	s_waitcnt lgkmcnt(8)
	v_mfma_i32_16x16x64_i8 v[104:107], v[44:47], v[216:219], v[104:107]
	s_waitcnt lgkmcnt(7)
	v_mfma_i32_16x16x64_i8 v[88:91], v[44:47], v[224:227], 0
	s_waitcnt lgkmcnt(6)
	v_mfma_i32_16x16x64_i8 v[88:91], v[36:39], v[220:223], v[88:91]
	s_waitcnt lgkmcnt(5)
	v_mfma_i32_16x16x64_i8 v[80:83], v[140:143], v[220:223], 0
	s_waitcnt lgkmcnt(4)
	v_mfma_i32_16x16x64_i8 v[80:83], v[144:147], v[224:227], v[80:83]
	v_mfma_i32_16x16x64_i8 v[96:99], v[144:147], v[216:219], 0
	v_mfma_i32_16x16x64_i8 v[96:99], v[140:143], v[212:215], v[96:99]
	v_mfma_i32_16x16x64_i8 v[112:115], v[140:143], v[204:207], 0
	v_mfma_i32_16x16x64_i8 v[112:115], v[144:147], v[208:211], v[112:115]
	v_mfma_i32_16x16x64_i8 v[128:131], v[144:147], v[188:191], 0
	v_mfma_i32_16x16x64_i8 v[128:131], v[140:143], v[184:187], v[128:131]
	s_waitcnt lgkmcnt(3)
	v_mfma_i32_16x16x64_i8 v[132:135], v[160:163], v[184:187], 0
	s_waitcnt lgkmcnt(2)
	v_mfma_i32_16x16x64_i8 v[132:135], v[172:175], v[188:191], v[132:135]
	v_mfma_i32_16x16x64_i8 v[116:119], v[172:175], v[208:211], 0
	v_mfma_i32_16x16x64_i8 v[116:119], v[160:163], v[204:207], v[116:119]
	v_mfma_i32_16x16x64_i8 v[100:103], v[160:163], v[212:215], 0
	v_mfma_i32_16x16x64_i8 v[100:103], v[172:175], v[216:219], v[100:103]
	v_mfma_i32_16x16x64_i8 v[84:87], v[172:175], v[224:227], 0
	v_mfma_i32_16x16x64_i8 v[84:87], v[160:163], v[220:223], v[84:87]
	s_waitcnt lgkmcnt(1)
	v_mfma_i32_16x16x64_i8 v[76:79], v[176:179], v[220:223], 0
	s_waitcnt lgkmcnt(0)
	v_mfma_i32_16x16x64_i8 v[76:79], v[180:183], v[224:227], v[76:79]
	v_mfma_i32_16x16x64_i8 v[92:95], v[180:183], v[216:219], 0
	v_mfma_i32_16x16x64_i8 v[92:95], v[176:179], v[212:215], v[92:95]
	v_mfma_i32_16x16x64_i8 v[108:111], v[176:179], v[204:207], 0
	v_mfma_i32_16x16x64_i8 v[108:111], v[180:183], v[208:211], v[108:111]
	v_mfma_i32_16x16x64_i8 v[124:127], v[180:183], v[188:191], 0
	v_mfma_i32_16x16x64_i8 v[124:127], v[176:179], v[184:187], v[124:127]
	s_barrier
	s_setprio 0
	s_add_i32 s64, s64, s47
	v_lshl_add_u64 v[164:165], s[44:45], 0, v[2:3]
	s_mov_b32 m0, s64
	ds_read_b128 v[184:187], v171 offset:16384
	ds_read_b128 v[188:191], v171 offset:17408
	ds_read_b128 v[208:211], v171 offset:19456
	ds_read_b128 v[204:207], v171 offset:18432
	ds_read_b128 v[212:215], v171 offset:20480
	ds_read_b128 v[216:219], v171 offset:21504
	ds_read_b128 v[224:227], v171 offset:23552
	ds_read_b128 v[220:223], v171 offset:22528
	global_load_lds_dwordx4 v[164:165], off
	s_add_i32 m0, s64, 0x2000
	s_add_u32 s64, s44, 0x80000
	v_lshl_add_u64 v[228:229], s[44:45], 0, v[148:149]
	s_addc_u32 s65, s45, 0
	s_add_i32 s67, s67, s47
	global_load_lds_dwordx4 v[228:229], off
	s_mov_b32 m0, s67
	v_lshl_add_u64 v[242:243], s[48:49], 0, v[150:151]
	global_load_lds_dwordx4 v2, s[64:65]
	s_add_i32 m0, s67, 0x2000
	s_nop 0
	global_load_lds_dwordx4 v148, s[64:65]
	v_lshl_add_u64 v[240:241], s[48:49], 0, v[152:153]
	s_waitcnt vmcnt(6)
	s_waitcnt lgkmcnt(7)
	s_setprio 1
	s_barrier
; #define PG8_STAGE(bufoff, gbase, voff) do { _Pragma("unroll") for (int _i = 0; _i < 2; ++_i) \
;         __builtin_amdgcn_global_load_lds((const unsigned*)((const char*)(gbase) + (voff)[_i]), (PG8_LAS unsigned*)(lds + (bufoff) + ldsw + _i * 8192), 16, 0, 0); } while (0)
; #define PG8_LDA(dst, b, h) do { _Pragma("unroll") for (int m = 0; m < 4; ++m) _Pragma("unroll") for (int k = 0; k < 2; ++k) dst[m][k] = *(const PG8_LAS bf16x8*)(lds + PG8_SA(b, h) + aoff + m * 2048 + k * 1024); } while (0)
; #define PG8_LDB(dst, b, h) do { _Pragma("unroll") for (int n = 0; n < 2; ++n) _Pragma("unroll") for (int k = 0; k < 2; ++k) dst[n][k] = *(const PG8_LAS bf16x8*)(lds + PG8_SB(b, h) + boff + n * 2048 + k * 1024); } while (0)
; #define PG8_WAIT_V(n) asm volatile("s_waitcnt vmcnt(" #n ")" ::: "memory")
; #define PG8_WAIT_L(n) asm volatile("s_waitcnt lgkmcnt(" #n ")" ::: "memory")
; #define PG8_BAR __builtin_amdgcn_s_barrier()
; #define PG8_SCHED __builtin_amdgcn_sched_barrier(0)
; template <class Epi, class Sched, bool ALIGN_EPI = false, bool SP2 = false, bool I8 = false>
; __device__ __forceinline__ void gemm_phase(PG8_LAS unsigned char* lds, const Gemm g, const Sched& S, const Epi& E) {
;     ...
;             PG8_WAIT_V(8); PG8_WAIT_L(0); PG8_BAR; PG8_MMA(1, 0, At, B0); PG8_MMA(1, 1, At, B1); PG8_BAR; PG8_SCHED;
;             PG8_LDB(B0, 1, 0); PG8_LDB(B1, 1, 1); PG8_SCHED; PG8_LDA(At, 1, 0); PG8_STAGE(PG8_SA(0, 1), a2 + hstep, voffA);
;             PG8_WAIT_V(8); PG8_WAIT_L(0); PG8_BAR; PG8_MMA(0, 0, At, B0); PG8_MMA(0, 1, At, B1); PG8_BAR; PG8_SCHED;
;             PG8_LDA(At, 1, 1); PG8_STAGE(PG8_SB(1, 0), b3, voffB); PG8_STAGE(PG8_SB(1, 1), b3 + hstep, voffB); PG8_STAGE(PG8_SA(1, 0), a3, voffA);
;             PG8_WAIT_V(8); PG8_WAIT_L(0); PG8_BAR; PG8_MMA(1, 0, At, B0); PG8_MMA(1, 1, At, B1); PG8_BAR; PG8_SCHED;
	v_mfma_i32_16x16x64_i8 v[72:75], v[36:39], v[184:187], 0
	s_waitcnt lgkmcnt(6)
	v_mfma_i32_16x16x64_i8 v[72:75], v[44:47], v[188:191], v[72:75]
	s_waitcnt lgkmcnt(5)
	v_mfma_i32_16x16x64_i8 v[56:59], v[44:47], v[208:211], 0
	s_waitcnt lgkmcnt(4)
	v_mfma_i32_16x16x64_i8 v[56:59], v[36:39], v[204:207], v[56:59]
	s_waitcnt lgkmcnt(3)
	v_mfma_i32_16x16x64_i8 v[32:35], v[36:39], v[212:215], 0
	s_waitcnt lgkmcnt(2)
	v_mfma_i32_16x16x64_i8 v[32:35], v[44:47], v[216:219], v[32:35]
	s_waitcnt lgkmcnt(1)
	v_mfma_i32_16x16x64_i8 v[16:19], v[44:47], v[224:227], 0
	s_waitcnt lgkmcnt(0)
	v_mfma_i32_16x16x64_i8 v[16:19], v[36:39], v[220:223], v[16:19]
	v_mfma_i32_16x16x64_i8 v[8:11], v[140:143], v[220:223], 0
	v_mfma_i32_16x16x64_i8 v[8:11], v[144:147], v[224:227], v[8:11]
	v_mfma_i32_16x16x64_i8 v[24:27], v[144:147], v[216:219], 0
	v_mfma_i32_16x16x64_i8 v[24:27], v[140:143], v[212:215], v[24:27]
	v_mfma_i32_16x16x64_i8 v[48:51], v[140:143], v[204:207], 0
	v_mfma_i32_16x16x64_i8 v[48:51], v[144:147], v[208:211], v[48:51]
	v_mfma_i32_16x16x64_i8 v[64:67], v[144:147], v[188:191], 0
	v_mfma_i32_16x16x64_i8 v[64:67], v[140:143], v[184:187], v[64:67]
	v_mfma_i32_16x16x64_i8 v[36:39], v[160:163], v[184:187], 0
	v_mfma_i32_16x16x64_i8 v[36:39], v[172:175], v[188:191], v[36:39]
	v_mfma_i32_16x16x64_i8 v[52:55], v[172:175], v[208:211], 0
	v_mfma_i32_16x16x64_i8 v[52:55], v[160:163], v[204:207], v[52:55]
	v_mfma_i32_16x16x64_i8 v[28:31], v[160:163], v[212:215], 0
	v_mfma_i32_16x16x64_i8 v[28:31], v[172:175], v[216:219], v[28:31]
	v_mfma_i32_16x16x64_i8 v[12:15], v[172:175], v[224:227], 0
	v_mfma_i32_16x16x64_i8 v[12:15], v[160:163], v[220:223], v[12:15]
	v_mfma_i32_16x16x64_i8 v[4:7], v[176:179], v[220:223], 0
	v_mfma_i32_16x16x64_i8 v[4:7], v[180:183], v[224:227], v[4:7]
	v_mfma_i32_16x16x64_i8 v[20:23], v[180:183], v[216:219], 0
	v_mfma_i32_16x16x64_i8 v[20:23], v[176:179], v[212:215], v[20:23]
	v_mfma_i32_16x16x64_i8 v[40:43], v[176:179], v[204:207], 0
	v_mfma_i32_16x16x64_i8 v[40:43], v[180:183], v[208:211], v[40:43]
	v_mfma_i32_16x16x64_i8 v[44:47], v[180:183], v[188:191], 0
	v_mfma_i32_16x16x64_i8 v[44:47], v[176:179], v[184:187], v[44:47]
	s_barrier
	s_setprio 0
	s_mov_b32 m0, s50
	s_nop 0
	global_load_lds_dwordx4 v[240:241], off
	s_mov_b32 m0, s51
	s_nop 0
	global_load_lds_dwordx4 v[242:243], off
	s_add_i32 s64, 0, 0x18000
	s_add_i32 s65, 0, 0x1c000
	v_add_u32_e32 v144, s64, v167
	v_add_u32_e32 v158, s65, v167
	ds_read_b128 v[60:63], v144
	ds_read_b128 v[184:187], v171 offset:32768
	ds_read_b128 v[68:71], v144 offset:1024
	ds_read_b128 v[188:191], v171 offset:33792
	ds_read_b128 v[208:211], v171 offset:35840
	ds_read_b128 v[204:207], v171 offset:34816
	ds_read_b128 v[212:215], v171 offset:36864
	ds_read_b128 v[216:219], v171 offset:37888
	s_add_u32 s48, s48, 0x80000
	s_addc_u32 s49, s49, 0
	s_mov_b32 m0, s52
	ds_read_b128 v[224:227], v171 offset:39936
	ds_read_b128 v[220:223], v171 offset:38912
	ds_read_b128 v[140:143], v144 offset:2048
	ds_read_b128 v[144:147], v144 offset:3072
	ds_read_b128 v[160:163], v158
	ds_read_b128 v[172:175], v158 offset:1024
	ds_read_b128 v[176:179], v158 offset:2048
	ds_read_b128 v[180:183], v158 offset:3072
	global_load_lds_dwordx4 v152, s[48:49]
	s_mov_b32 m0, s53
	s_nop 0
	global_load_lds_dwordx4 v150, s[48:49]
	s_waitcnt vmcnt(8)
	s_waitcnt lgkmcnt(14)
	s_setprio 1
	s_barrier
	v_mfma_i32_16x16x64_i8 v[136:139], v[60:63], v[184:187], v[136:139]
	s_waitcnt lgkmcnt(12)
	v_mfma_i32_16x16x64_i8 v[136:139], v[68:71], v[188:191], v[136:139]
	s_waitcnt lgkmcnt(11)
	v_mfma_i32_16x16x64_i8 v[120:123], v[68:71], v[208:211], v[120:123]
	s_waitcnt lgkmcnt(10)
	v_mfma_i32_16x16x64_i8 v[120:123], v[60:63], v[204:207], v[120:123]
	s_waitcnt lgkmcnt(9)
	v_mfma_i32_16x16x64_i8 v[104:107], v[60:63], v[212:215], v[104:107]
	s_waitcnt lgkmcnt(8)
	v_mfma_i32_16x16x64_i8 v[104:107], v[68:71], v[216:219], v[104:107]
	s_waitcnt lgkmcnt(7)
	v_mfma_i32_16x16x64_i8 v[88:91], v[68:71], v[224:227], v[88:91]
	s_waitcnt lgkmcnt(6)
	v_mfma_i32_16x16x64_i8 v[88:91], v[60:63], v[220:223], v[88:91]
	s_waitcnt lgkmcnt(5)
	v_mfma_i32_16x16x64_i8 v[80:83], v[140:143], v[220:223], v[80:83]
	s_waitcnt lgkmcnt(4)
	v_mfma_i32_16x16x64_i8 v[80:83], v[144:147], v[224:227], v[80:83]
	v_mfma_i32_16x16x64_i8 v[96:99], v[144:147], v[216:219], v[96:99]
	v_mfma_i32_16x16x64_i8 v[96:99], v[140:143], v[212:215], v[96:99]
	v_mfma_i32_16x16x64_i8 v[112:115], v[140:143], v[204:207], v[112:115]
	v_mfma_i32_16x16x64_i8 v[112:115], v[144:147], v[208:211], v[112:115]
	v_mfma_i32_16x16x64_i8 v[128:131], v[144:147], v[188:191], v[128:131]
	v_mfma_i32_16x16x64_i8 v[128:131], v[140:143], v[184:187], v[128:131]
	s_waitcnt lgkmcnt(3)
	v_mfma_i32_16x16x64_i8 v[132:135], v[160:163], v[184:187], v[132:135]
	s_waitcnt lgkmcnt(2)
	v_mfma_i32_16x16x64_i8 v[132:135], v[172:175], v[188:191], v[132:135]
	v_mfma_i32_16x16x64_i8 v[116:119], v[172:175], v[208:211], v[116:119]
	v_mfma_i32_16x16x64_i8 v[116:119], v[160:163], v[204:207], v[116:119]
	v_mfma_i32_16x16x64_i8 v[100:103], v[160:163], v[212:215], v[100:103]
	v_mfma_i32_16x16x64_i8 v[100:103], v[172:175], v[216:219], v[100:103]
	v_mfma_i32_16x16x64_i8 v[84:87], v[172:175], v[224:227], v[84:87]
	v_mfma_i32_16x16x64_i8 v[84:87], v[160:163], v[220:223], v[84:87]
	s_waitcnt lgkmcnt(1)
	v_mfma_i32_16x16x64_i8 v[76:79], v[176:179], v[220:223], v[76:79]
	s_waitcnt lgkmcnt(0)
	v_mfma_i32_16x16x64_i8 v[76:79], v[180:183], v[224:227], v[76:79]
	v_mfma_i32_16x16x64_i8 v[92:95], v[180:183], v[216:219], v[92:95]
	v_mfma_i32_16x16x64_i8 v[92:95], v[176:179], v[212:215], v[92:95]
	v_mfma_i32_16x16x64_i8 v[108:111], v[176:179], v[204:207], v[108:111]
	v_mfma_i32_16x16x64_i8 v[108:111], v[180:183], v[208:211], v[108:111]
	v_mfma_i32_16x16x64_i8 v[124:127], v[180:183], v[188:191], v[124:127]
	v_mfma_i32_16x16x64_i8 v[124:127], v[176:179], v[184:187], v[124:127]
	s_barrier
	s_setprio 0
	s_add_i32 s48, s64, s47
	v_lshl_add_u64 v[164:165], v[164:165], 0, s[84:85]
	s_mov_b32 m0, s48
	ds_read_b128 v[184:187], v171 offset:49152
	ds_read_b128 v[188:191], v171 offset:50176
	ds_read_b128 v[208:211], v171 offset:52224
	ds_read_b128 v[204:207], v171 offset:51200
	ds_read_b128 v[212:215], v171 offset:53248
	ds_read_b128 v[216:219], v171 offset:54272
	ds_read_b128 v[224:227], v171 offset:56320
	ds_read_b128 v[220:223], v171 offset:55296
	global_load_lds_dwordx4 v[164:165], off
	s_add_i32 m0, s48, 0x2000
	s_add_u32 s44, s44, 0x80080
	v_lshl_add_u64 v[164:165], v[228:229], 0, s[84:85]
	s_addc_u32 s45, s45, 0
	s_add_i32 s48, s65, s47
	global_load_lds_dwordx4 v[164:165], off
	s_mov_b32 m0, s48
	s_nop 0
	global_load_lds_dwordx4 v2, s[44:45]
	s_add_i32 m0, s48, 0x2000
	s_nop 0
	global_load_lds_dwordx4 v148, s[44:45]
	s_cmp_eq_u32 s61, 28
	s_cbranch_scc0 .Ldefer_1591_peel
	v_lshl_add_u64 v[164:165], v[240:241], 0, s[84:85]
	s_mov_b32 m0, s54
	s_nop 0
	global_load_lds_dwordx4 v[164:165], off
	v_lshl_add_u64 v[164:165], v[242:243], 0, s[84:85]
	s_mov_b32 m0, s55
	s_nop 0
	global_load_lds_dwordx4 v[164:165], off
; #define PG8_STAGE(bufoff, gbase, voff) do { _Pragma("unroll") for (int _i = 0; _i < 2; ++_i) \
;         __builtin_amdgcn_global_load_lds((const unsigned*)((const char*)(gbase) + (voff)[_i]), (PG8_LAS unsigned*)(lds + (bufoff) + ldsw + _i * 8192), 16, 0, 0); } while (0)
; #define PG8_LDA(dst, b, h) do { _Pragma("unroll") for (int m = 0; m < 4; ++m) _Pragma("unroll") for (int k = 0; k < 2; ++k) dst[m][k] = *(const PG8_LAS bf16x8*)(lds + PG8_SA(b, h) + aoff + m * 2048 + k * 1024); } while (0)
; #define PG8_LDB(dst, b, h) do { _Pragma("unroll") for (int n = 0; n < 2; ++n) _Pragma("unroll") for (int k = 0; k < 2; ++k) dst[n][k] = *(const PG8_LAS bf16x8*)(lds + PG8_SB(b, h) + boff + n * 2048 + k * 1024); } while (0)
; #define PG8_WAIT_V(n) asm volatile("s_waitcnt vmcnt(" #n ")" ::: "memory")
; #define PG8_WAIT_L(n) asm volatile("s_waitcnt lgkmcnt(" #n ")" ::: "memory")
; #define PG8_BAR __builtin_amdgcn_s_barrier()
; #define PG8_SCHED __builtin_amdgcn_sched_barrier(0)
; template <class Epi, class Sched, bool ALIGN_EPI = false, bool SP2 = false, bool I8 = false>
; __device__ __forceinline__ void gemm_phase(PG8_LAS unsigned char* lds, const Gemm g, const Sched& S, const Epi& E) {
;     ...
;         for (int t = 0; t < nt; t += 2) {
;             const bool last = (t == nt - 2);
;             const char* a1 = cA + (size_t)(t + 1) * kstep;
;             const char* a2 = last ? nA : cA + (size_t)(t + 2) * kstep; const char* b2 = last ? nB : cB + (size_t)(t + 2) * kstep;
;             const char* a3 = a2 + kstep; const char* b3 = b2 + kstep;
;             if (last && has_next) S.a_ready(nxt);
;             if constexpr (SP2) {
;             PG8_LDB(B0, 0, 0); PG8_LDB(B1, 0, 1); PG8_SCHED; PG8_LDA(At, 0, 0); PG8_STAGE(PG8_SA(1, 1), a1 + hstep, voffA);
;             PG8_WAIT_V(8); PG8_WAIT_L(0); PG8_BAR; PG8_MMA(0, 0, At, B0); PG8_MMA(0, 1, At, B1); PG8_BAR; PG8_SCHED;
;     ...
;             PG8_LDA(At, 1, 1); PG8_STAGE(PG8_SB(1, 0), b3, voffB); PG8_STAGE(PG8_SB(1, 1), b3 + hstep, voffB); PG8_STAGE(PG8_SA(1, 0), a3, voffA);
;             PG8_WAIT_V(8); PG8_WAIT_L(0); PG8_BAR; PG8_MMA(1, 0, At, B0); PG8_MMA(1, 1, At, B1); PG8_BAR; PG8_SCHED;
.Ldefer_1591_peel:
	s_waitcnt vmcnt(6)
	s_waitcnt lgkmcnt(7)
	s_setprio 1
	s_barrier
	v_mfma_i32_16x16x64_i8 v[72:75], v[60:63], v[184:187], v[72:75]
	s_waitcnt lgkmcnt(6)
	v_mfma_i32_16x16x64_i8 v[72:75], v[68:71], v[188:191], v[72:75]
	s_waitcnt lgkmcnt(5)
	v_mfma_i32_16x16x64_i8 v[56:59], v[68:71], v[208:211], v[56:59]
	s_waitcnt lgkmcnt(4)
	v_mfma_i32_16x16x64_i8 v[56:59], v[60:63], v[204:207], v[56:59]
	s_waitcnt lgkmcnt(3)
	v_mfma_i32_16x16x64_i8 v[32:35], v[60:63], v[212:215], v[32:35]
	s_waitcnt lgkmcnt(2)
	v_mfma_i32_16x16x64_i8 v[32:35], v[68:71], v[216:219], v[32:35]
	s_waitcnt lgkmcnt(1)
	v_mfma_i32_16x16x64_i8 v[16:19], v[68:71], v[224:227], v[16:19]
	s_waitcnt lgkmcnt(0)
	v_mfma_i32_16x16x64_i8 v[16:19], v[60:63], v[220:223], v[16:19]
	v_mfma_i32_16x16x64_i8 v[8:11], v[140:143], v[220:223], v[8:11]
	v_mfma_i32_16x16x64_i8 v[8:11], v[144:147], v[224:227], v[8:11]
	v_mfma_i32_16x16x64_i8 v[24:27], v[144:147], v[216:219], v[24:27]
	v_mfma_i32_16x16x64_i8 v[24:27], v[140:143], v[212:215], v[24:27]
	v_mfma_i32_16x16x64_i8 v[48:51], v[140:143], v[204:207], v[48:51]
	v_mfma_i32_16x16x64_i8 v[48:51], v[144:147], v[208:211], v[48:51]
	v_mfma_i32_16x16x64_i8 v[64:67], v[144:147], v[188:191], v[64:67]
	v_mfma_i32_16x16x64_i8 v[64:67], v[140:143], v[184:187], v[64:67]
	v_mfma_i32_16x16x64_i8 v[36:39], v[160:163], v[184:187], v[36:39]
	v_mfma_i32_16x16x64_i8 v[68:71], v[172:175], v[188:191], v[36:39]
	v_mfma_i32_16x16x64_i8 v[36:39], v[172:175], v[208:211], v[52:55]
	v_mfma_i32_16x16x64_i8 v[52:55], v[160:163], v[204:207], v[36:39]
	v_mfma_i32_16x16x64_i8 v[28:31], v[160:163], v[212:215], v[28:31]
	v_mfma_i32_16x16x64_i8 v[28:31], v[172:175], v[216:219], v[28:31]
	v_mfma_i32_16x16x64_i8 v[12:15], v[172:175], v[224:227], v[12:15]
	v_mfma_i32_16x16x64_i8 v[12:15], v[160:163], v[220:223], v[12:15]
	v_mfma_i32_16x16x64_i8 v[4:7], v[176:179], v[220:223], v[4:7]
	v_mfma_i32_16x16x64_i8 v[4:7], v[180:183], v[224:227], v[4:7]
	v_mfma_i32_16x16x64_i8 v[20:23], v[180:183], v[216:219], v[20:23]
	v_mfma_i32_16x16x64_i8 v[20:23], v[176:179], v[212:215], v[20:23]
	v_mfma_i32_16x16x64_i8 v[36:39], v[176:179], v[204:207], v[40:43]
	v_mfma_i32_16x16x64_i8 v[40:43], v[180:183], v[208:211], v[36:39]
	v_mfma_i32_16x16x64_i8 v[36:39], v[180:183], v[188:191], v[44:47]
	v_mfma_i32_16x16x64_i8 v[60:63], v[176:179], v[184:187], v[36:39]
	s_barrier
	s_setprio 0
	s_add_i32 s61, s61, 2
	s_add_u32 s40, s40, 0x100
	s_addc_u32 s41, s41, 0
	s_add_u32 s59, s59, 0x100
	s_addc_u32 s60, s60, 0
	s_cmp_gt_u32 s61, 29
	s_cbranch_scc1 .Lkloop_exit_3
.LBB0_1591:
	s_add_u32 s44, s40, 0xfff80080
	s_addc_u32 s45, s41, -1
	s_add_i32 s64, 0, 0x10000
	s_cmp_eq_u32 s61, 28
	s_cselect_b32 s49, s25, s45
	s_cselect_b32 s48, s57, s44
	s_cselect_b32 s45, s23, s60
	s_cselect_b32 s44, s58, s59
	s_add_i32 s67, 0, 0x14000
	v_add_u32_e32 v144, s64, v167
	v_add_u32_e32 v158, s67, v167
	ds_read_b128 v[36:39], v144
	ds_read_b128 v[184:187], v171
	ds_read_b128 v[44:47], v144 offset:1024
	ds_read_b128 v[188:191], v171 offset:1024
	ds_read_b128 v[208:211], v171 offset:3072
	ds_read_b128 v[204:207], v171 offset:2048
	ds_read_b128 v[212:215], v171 offset:4096
	ds_read_b128 v[216:219], v171 offset:5120
	v_lshl_add_u64 v[164:165], v[240:241], 0, s[84:85]
	s_mov_b32 m0, s54
	s_nop 0
	global_load_lds_dwordx4 v[164:165], off
	v_lshl_add_u64 v[164:165], v[242:243], 0, s[84:85]
	s_mov_b32 m0, s55
	s_nop 0
	global_load_lds_dwordx4 v[164:165], off
	s_add_i32 m0, s50, 0xc000
	ds_read_b128 v[224:227], v171 offset:7168
	ds_read_b128 v[220:223], v171 offset:6144
	ds_read_b128 v[140:143], v144 offset:2048
	ds_read_b128 v[144:147], v144 offset:3072
	ds_read_b128 v[160:163], v158
	ds_read_b128 v[172:175], v158 offset:1024
	ds_read_b128 v[176:179], v158 offset:2048
	ds_read_b128 v[180:183], v158 offset:3072
	global_load_lds_dwordx4 v154, s[40:41]
	s_add_i32 m0, s50, 0xe000
	s_nop 0
	global_load_lds_dwordx4 v156, s[40:41]
	s_waitcnt vmcnt(8)
	s_waitcnt lgkmcnt(14)
	s_setprio 1
	s_barrier
	v_mfma_i32_16x16x64_i8 v[136:139], v[36:39], v[184:187], v[136:139]
	s_waitcnt lgkmcnt(12)
	v_mfma_i32_16x16x64_i8 v[136:139], v[44:47], v[188:191], v[136:139]
	s_waitcnt lgkmcnt(11)
	v_mfma_i32_16x16x64_i8 v[120:123], v[44:47], v[208:211], v[120:123]
	s_waitcnt lgkmcnt(10)
	v_mfma_i32_16x16x64_i8 v[120:123], v[36:39], v[204:207], v[120:123]
	s_waitcnt lgkmcnt(9)
	v_mfma_i32_16x16x64_i8 v[104:107], v[36:39], v[212:215], v[104:107]
	s_waitcnt lgkmcnt(8)
	v_mfma_i32_16x16x64_i8 v[104:107], v[44:47], v[216:219], v[104:107]
	s_waitcnt lgkmcnt(7)
	v_mfma_i32_16x16x64_i8 v[88:91], v[44:47], v[224:227], v[88:91]
	s_waitcnt lgkmcnt(6)
	v_mfma_i32_16x16x64_i8 v[88:91], v[36:39], v[220:223], v[88:91]
	s_waitcnt lgkmcnt(5)
	v_mfma_i32_16x16x64_i8 v[80:83], v[140:143], v[220:223], v[80:83]
	s_waitcnt lgkmcnt(4)
	v_mfma_i32_16x16x64_i8 v[80:83], v[144:147], v[224:227], v[80:83]
	v_mfma_i32_16x16x64_i8 v[96:99], v[144:147], v[216:219], v[96:99]
	v_mfma_i32_16x16x64_i8 v[96:99], v[140:143], v[212:215], v[96:99]
	v_mfma_i32_16x16x64_i8 v[112:115], v[140:143], v[204:207], v[112:115]
	v_mfma_i32_16x16x64_i8 v[112:115], v[144:147], v[208:211], v[112:115]
	v_mfma_i32_16x16x64_i8 v[128:131], v[144:147], v[188:191], v[128:131]
	v_mfma_i32_16x16x64_i8 v[128:131], v[140:143], v[184:187], v[128:131]
	s_waitcnt lgkmcnt(3)
	v_mfma_i32_16x16x64_i8 v[132:135], v[160:163], v[184:187], v[132:135]
	s_waitcnt lgkmcnt(2)
	v_mfma_i32_16x16x64_i8 v[132:135], v[172:175], v[188:191], v[132:135]
	v_mfma_i32_16x16x64_i8 v[116:119], v[172:175], v[208:211], v[116:119]
	v_mfma_i32_16x16x64_i8 v[116:119], v[160:163], v[204:207], v[116:119]
	v_mfma_i32_16x16x64_i8 v[100:103], v[160:163], v[212:215], v[100:103]
	v_mfma_i32_16x16x64_i8 v[100:103], v[172:175], v[216:219], v[100:103]
	v_mfma_i32_16x16x64_i8 v[84:87], v[172:175], v[224:227], v[84:87]
	v_mfma_i32_16x16x64_i8 v[84:87], v[160:163], v[220:223], v[84:87]
	s_waitcnt lgkmcnt(1)
	v_mfma_i32_16x16x64_i8 v[76:79], v[176:179], v[220:223], v[76:79]
	s_waitcnt lgkmcnt(0)
	v_mfma_i32_16x16x64_i8 v[76:79], v[180:183], v[224:227], v[76:79]
	v_mfma_i32_16x16x64_i8 v[92:95], v[180:183], v[216:219], v[92:95]
	v_mfma_i32_16x16x64_i8 v[92:95], v[176:179], v[212:215], v[92:95]
	v_mfma_i32_16x16x64_i8 v[108:111], v[176:179], v[204:207], v[108:111]
	v_mfma_i32_16x16x64_i8 v[108:111], v[180:183], v[208:211], v[108:111]
	v_mfma_i32_16x16x64_i8 v[124:127], v[180:183], v[188:191], v[124:127]
	v_mfma_i32_16x16x64_i8 v[124:127], v[176:179], v[184:187], v[124:127]
	s_barrier
; #define PG8_STAGE(bufoff, gbase, voff) do { _Pragma("unroll") for (int _i = 0; _i < 2; ++_i) \
;         __builtin_amdgcn_global_load_lds((const unsigned*)((const char*)(gbase) + (voff)[_i]), (PG8_LAS unsigned*)(lds + (bufoff) + ldsw + _i * 8192), 16, 0, 0); } while (0)
; #define PG8_LDA(dst, b, h) do { _Pragma("unroll") for (int m = 0; m < 4; ++m) _Pragma("unroll") for (int k = 0; k < 2; ++k) dst[m][k] = *(const PG8_LAS bf16x8*)(lds + PG8_SA(b, h) + aoff + m * 2048 + k * 1024); } while (0)
; #define PG8_LDB(dst, b, h) do { _Pragma("unroll") for (int n = 0; n < 2; ++n) _Pragma("unroll") for (int k = 0; k < 2; ++k) dst[n][k] = *(const PG8_LAS bf16x8*)(lds + PG8_SB(b, h) + boff + n * 2048 + k * 1024); } while (0)
; #define PG8_WAIT_V(n) asm volatile("s_waitcnt vmcnt(" #n ")" ::: "memory")
; #define PG8_WAIT_L(n) asm volatile("s_waitcnt lgkmcnt(" #n ")" ::: "memory")
; #define PG8_BAR __builtin_amdgcn_s_barrier()
; #define PG8_SCHED __builtin_amdgcn_sched_barrier(0)
; template <class Epi, class Sched, bool ALIGN_EPI = false, bool SP2 = false, bool I8 = false>
; __device__ __forceinline__ void gemm_phase(PG8_LAS unsigned char* lds, const Gemm g, const Sched& S, const Epi& E) {
;     ...
;             PG8_LDA(At, 0, 1); PG8_STAGE(PG8_SB(0, 0), b2, voffB); PG8_STAGE(PG8_SB(0, 1), b2 + hstep, voffB); PG8_STAGE(PG8_SA(0, 0), a2, voffA);
;             PG8_WAIT_V(8); PG8_WAIT_L(0); PG8_BAR; PG8_MMA(1, 0, At, B0); PG8_MMA(1, 1, At, B1); PG8_BAR; PG8_SCHED;
;             PG8_LDB(B0, 1, 0); PG8_LDB(B1, 1, 1); PG8_SCHED; PG8_LDA(At, 1, 0); PG8_STAGE(PG8_SA(0, 1), a2 + hstep, voffA);
;             PG8_WAIT_V(8); PG8_WAIT_L(0); PG8_BAR; PG8_MMA(0, 0, At, B0); PG8_MMA(0, 1, At, B1); PG8_BAR; PG8_SCHED;
;             PG8_LDA(At, 1, 1); PG8_STAGE(PG8_SB(1, 0), b3, voffB); PG8_STAGE(PG8_SB(1, 1), b3 + hstep, voffB); PG8_STAGE(PG8_SA(1, 0), a3, voffA);
	s_setprio 0
	s_add_i32 s64, s64, s47
	v_lshl_add_u64 v[164:165], s[44:45], 0, v[2:3]
	s_mov_b32 m0, s64
	ds_read_b128 v[184:187], v171 offset:16384
	ds_read_b128 v[188:191], v171 offset:17408
	ds_read_b128 v[208:211], v171 offset:19456
	ds_read_b128 v[204:207], v171 offset:18432
	ds_read_b128 v[212:215], v171 offset:20480
	ds_read_b128 v[216:219], v171 offset:21504
	ds_read_b128 v[224:227], v171 offset:23552
	ds_read_b128 v[220:223], v171 offset:22528
	global_load_lds_dwordx4 v[164:165], off
	s_add_i32 m0, s64, 0x2000
	s_add_u32 s64, s44, 0x80000
	v_lshl_add_u64 v[228:229], s[44:45], 0, v[148:149]
	s_addc_u32 s65, s45, 0
	s_add_i32 s67, s67, s47
	global_load_lds_dwordx4 v[228:229], off
	s_mov_b32 m0, s67
	v_lshl_add_u64 v[242:243], s[48:49], 0, v[150:151]
	global_load_lds_dwordx4 v2, s[64:65]
	s_add_i32 m0, s67, 0x2000
	s_nop 0
	global_load_lds_dwordx4 v148, s[64:65]
	v_lshl_add_u64 v[240:241], s[48:49], 0, v[152:153]
	s_waitcnt vmcnt(6)
	s_waitcnt lgkmcnt(7)
	s_setprio 1
	s_barrier
	v_mfma_i32_16x16x64_i8 v[72:75], v[36:39], v[184:187], v[72:75]
	s_waitcnt lgkmcnt(6)
	v_mfma_i32_16x16x64_i8 v[72:75], v[44:47], v[188:191], v[72:75]
	s_waitcnt lgkmcnt(5)
	v_mfma_i32_16x16x64_i8 v[56:59], v[44:47], v[208:211], v[56:59]
	s_waitcnt lgkmcnt(4)
	v_mfma_i32_16x16x64_i8 v[56:59], v[36:39], v[204:207], v[56:59]
	s_waitcnt lgkmcnt(3)
	v_mfma_i32_16x16x64_i8 v[32:35], v[36:39], v[212:215], v[32:35]
	s_waitcnt lgkmcnt(2)
	v_mfma_i32_16x16x64_i8 v[32:35], v[44:47], v[216:219], v[32:35]
	s_waitcnt lgkmcnt(1)
	v_mfma_i32_16x16x64_i8 v[16:19], v[44:47], v[224:227], v[16:19]
	s_waitcnt lgkmcnt(0)
	v_mfma_i32_16x16x64_i8 v[16:19], v[36:39], v[220:223], v[16:19]
	v_mfma_i32_16x16x64_i8 v[8:11], v[140:143], v[220:223], v[8:11]
	v_mfma_i32_16x16x64_i8 v[8:11], v[144:147], v[224:227], v[8:11]
	v_mfma_i32_16x16x64_i8 v[24:27], v[144:147], v[216:219], v[24:27]
	v_mfma_i32_16x16x64_i8 v[24:27], v[140:143], v[212:215], v[24:27]
	v_mfma_i32_16x16x64_i8 v[48:51], v[140:143], v[204:207], v[48:51]
	v_mfma_i32_16x16x64_i8 v[48:51], v[144:147], v[208:211], v[48:51]
	v_mfma_i32_16x16x64_i8 v[64:67], v[144:147], v[188:191], v[64:67]
	v_mfma_i32_16x16x64_i8 v[64:67], v[140:143], v[184:187], v[64:67]
	v_mfma_i32_16x16x64_i8 v[36:39], v[160:163], v[184:187], v[68:71]
	v_mfma_i32_16x16x64_i8 v[36:39], v[172:175], v[188:191], v[36:39]
	v_mfma_i32_16x16x64_i8 v[52:55], v[172:175], v[208:211], v[52:55]
	v_mfma_i32_16x16x64_i8 v[52:55], v[160:163], v[204:207], v[52:55]
	v_mfma_i32_16x16x64_i8 v[28:31], v[160:163], v[212:215], v[28:31]
	v_mfma_i32_16x16x64_i8 v[28:31], v[172:175], v[216:219], v[28:31]
	v_mfma_i32_16x16x64_i8 v[12:15], v[172:175], v[224:227], v[12:15]
	v_mfma_i32_16x16x64_i8 v[12:15], v[160:163], v[220:223], v[12:15]
	v_mfma_i32_16x16x64_i8 v[4:7], v[176:179], v[220:223], v[4:7]
	v_mfma_i32_16x16x64_i8 v[4:7], v[180:183], v[224:227], v[4:7]
	v_mfma_i32_16x16x64_i8 v[20:23], v[180:183], v[216:219], v[20:23]
	v_mfma_i32_16x16x64_i8 v[20:23], v[176:179], v[212:215], v[20:23]
	v_mfma_i32_16x16x64_i8 v[40:43], v[176:179], v[204:207], v[40:43]
	v_mfma_i32_16x16x64_i8 v[40:43], v[180:183], v[208:211], v[40:43]
	v_mfma_i32_16x16x64_i8 v[44:47], v[180:183], v[188:191], v[60:63]
	v_mfma_i32_16x16x64_i8 v[44:47], v[176:179], v[184:187], v[44:47]
	s_barrier
	s_setprio 0
	s_mov_b32 m0, s50
	s_nop 0
	global_load_lds_dwordx4 v[240:241], off
	s_mov_b32 m0, s51
	s_nop 0
	global_load_lds_dwordx4 v[242:243], off
	s_add_i32 s64, 0, 0x18000
	s_add_i32 s65, 0, 0x1c000
	v_add_u32_e32 v144, s64, v167
	v_add_u32_e32 v158, s65, v167
	ds_read_b128 v[60:63], v144
	ds_read_b128 v[184:187], v171 offset:32768
	ds_read_b128 v[68:71], v144 offset:1024
	ds_read_b128 v[188:191], v171 offset:33792
	ds_read_b128 v[208:211], v171 offset:35840
	ds_read_b128 v[204:207], v171 offset:34816
	ds_read_b128 v[212:215], v171 offset:36864
	ds_read_b128 v[216:219], v171 offset:37888
	s_add_u32 s48, s48, 0x80000
	s_addc_u32 s49, s49, 0
	s_mov_b32 m0, s52
	ds_read_b128 v[224:227], v171 offset:39936
	ds_read_b128 v[220:223], v171 offset:38912
	ds_read_b128 v[140:143], v144 offset:2048
	ds_read_b128 v[144:147], v144 offset:3072
	ds_read_b128 v[160:163], v158
	ds_read_b128 v[172:175], v158 offset:1024
	ds_read_b128 v[176:179], v158 offset:2048
	ds_read_b128 v[180:183], v158 offset:3072
	global_load_lds_dwordx4 v152, s[48:49]
	s_mov_b32 m0, s53
	s_nop 0
	global_load_lds_dwordx4 v150, s[48:49]
	s_waitcnt vmcnt(8)
	s_waitcnt lgkmcnt(14)
	s_setprio 1
	s_barrier
; #define PG8_STAGE(bufoff, gbase, voff) do { _Pragma("unroll") for (int _i = 0; _i < 2; ++_i) \
;         __builtin_amdgcn_global_load_lds((const unsigned*)((const char*)(gbase) + (voff)[_i]), (PG8_LAS unsigned*)(lds + (bufoff) + ldsw + _i * 8192), 16, 0, 0); } while (0)
; #define PG8_LDA(dst, b, h) do { _Pragma("unroll") for (int m = 0; m < 4; ++m) _Pragma("unroll") for (int k = 0; k < 2; ++k) dst[m][k] = *(const PG8_LAS bf16x8*)(lds + PG8_SA(b, h) + aoff + m * 2048 + k * 1024); } while (0)
; #define PG8_WAIT_V(n) asm volatile("s_waitcnt vmcnt(" #n ")" ::: "memory")
; #define PG8_WAIT_L(n) asm volatile("s_waitcnt lgkmcnt(" #n ")" ::: "memory")
; #define PG8_BAR __builtin_amdgcn_s_barrier()
; #define PG8_SCHED __builtin_amdgcn_sched_barrier(0)
; template <class Epi, class Sched, bool ALIGN_EPI = false, bool SP2 = false, bool I8 = false>
; __device__ __forceinline__ void gemm_phase(PG8_LAS unsigned char* lds, const Gemm g, const Sched& S, const Epi& E) {
;     ...
;         for (int t = 0; t < nt; t += 2) {
;     ...
;             PG8_WAIT_V(8); PG8_WAIT_L(0); PG8_BAR; PG8_MMA(0, 0, At, B0); PG8_MMA(0, 1, At, B1); PG8_BAR; PG8_SCHED;
;             PG8_LDA(At, 1, 1); PG8_STAGE(PG8_SB(1, 0), b3, voffB); PG8_STAGE(PG8_SB(1, 1), b3 + hstep, voffB); PG8_STAGE(PG8_SA(1, 0), a3, voffA);
;             PG8_WAIT_V(8); PG8_WAIT_L(0); PG8_BAR; PG8_MMA(1, 0, At, B0); PG8_MMA(1, 1, At, B1); PG8_BAR; PG8_SCHED;
	v_mfma_i32_16x16x64_i8 v[136:139], v[60:63], v[184:187], v[136:139]
	s_waitcnt lgkmcnt(12)
	v_mfma_i32_16x16x64_i8 v[136:139], v[68:71], v[188:191], v[136:139]
	s_waitcnt lgkmcnt(11)
	v_mfma_i32_16x16x64_i8 v[120:123], v[68:71], v[208:211], v[120:123]
	s_waitcnt lgkmcnt(10)
	v_mfma_i32_16x16x64_i8 v[120:123], v[60:63], v[204:207], v[120:123]
	s_waitcnt lgkmcnt(9)
	v_mfma_i32_16x16x64_i8 v[104:107], v[60:63], v[212:215], v[104:107]
	s_waitcnt lgkmcnt(8)
	v_mfma_i32_16x16x64_i8 v[104:107], v[68:71], v[216:219], v[104:107]
	s_waitcnt lgkmcnt(7)
	v_mfma_i32_16x16x64_i8 v[88:91], v[68:71], v[224:227], v[88:91]
	s_waitcnt lgkmcnt(6)
	v_mfma_i32_16x16x64_i8 v[88:91], v[60:63], v[220:223], v[88:91]
	s_waitcnt lgkmcnt(5)
	v_mfma_i32_16x16x64_i8 v[80:83], v[140:143], v[220:223], v[80:83]
	s_waitcnt lgkmcnt(4)
	v_mfma_i32_16x16x64_i8 v[80:83], v[144:147], v[224:227], v[80:83]
	v_mfma_i32_16x16x64_i8 v[96:99], v[144:147], v[216:219], v[96:99]
	v_mfma_i32_16x16x64_i8 v[96:99], v[140:143], v[212:215], v[96:99]
	v_mfma_i32_16x16x64_i8 v[112:115], v[140:143], v[204:207], v[112:115]
	v_mfma_i32_16x16x64_i8 v[112:115], v[144:147], v[208:211], v[112:115]
	v_mfma_i32_16x16x64_i8 v[128:131], v[144:147], v[188:191], v[128:131]
	v_mfma_i32_16x16x64_i8 v[128:131], v[140:143], v[184:187], v[128:131]
	s_waitcnt lgkmcnt(3)
	v_mfma_i32_16x16x64_i8 v[132:135], v[160:163], v[184:187], v[132:135]
	s_waitcnt lgkmcnt(2)
	v_mfma_i32_16x16x64_i8 v[132:135], v[172:175], v[188:191], v[132:135]
	v_mfma_i32_16x16x64_i8 v[116:119], v[172:175], v[208:211], v[116:119]
	v_mfma_i32_16x16x64_i8 v[116:119], v[160:163], v[204:207], v[116:119]
	v_mfma_i32_16x16x64_i8 v[100:103], v[160:163], v[212:215], v[100:103]
	v_mfma_i32_16x16x64_i8 v[100:103], v[172:175], v[216:219], v[100:103]
	v_mfma_i32_16x16x64_i8 v[84:87], v[172:175], v[224:227], v[84:87]
	v_mfma_i32_16x16x64_i8 v[84:87], v[160:163], v[220:223], v[84:87]
	s_waitcnt lgkmcnt(1)
	v_mfma_i32_16x16x64_i8 v[76:79], v[176:179], v[220:223], v[76:79]
	s_waitcnt lgkmcnt(0)
	v_mfma_i32_16x16x64_i8 v[76:79], v[180:183], v[224:227], v[76:79]
	v_mfma_i32_16x16x64_i8 v[92:95], v[180:183], v[216:219], v[92:95]
	v_mfma_i32_16x16x64_i8 v[92:95], v[176:179], v[212:215], v[92:95]
	v_mfma_i32_16x16x64_i8 v[108:111], v[176:179], v[204:207], v[108:111]
	v_mfma_i32_16x16x64_i8 v[108:111], v[180:183], v[208:211], v[108:111]
	v_mfma_i32_16x16x64_i8 v[124:127], v[180:183], v[188:191], v[124:127]
	v_mfma_i32_16x16x64_i8 v[124:127], v[176:179], v[184:187], v[124:127]
	s_barrier
	s_setprio 0
	s_add_i32 s48, s64, s47
	v_lshl_add_u64 v[164:165], v[164:165], 0, s[84:85]
	s_mov_b32 m0, s48
	ds_read_b128 v[184:187], v171 offset:49152
	ds_read_b128 v[188:191], v171 offset:50176
	ds_read_b128 v[208:211], v171 offset:52224
	ds_read_b128 v[204:207], v171 offset:51200
	ds_read_b128 v[212:215], v171 offset:53248
	ds_read_b128 v[216:219], v171 offset:54272
	ds_read_b128 v[224:227], v171 offset:56320
	ds_read_b128 v[220:223], v171 offset:55296
	global_load_lds_dwordx4 v[164:165], off
	s_add_i32 m0, s48, 0x2000
	s_add_u32 s44, s44, 0x80080
	v_lshl_add_u64 v[164:165], v[228:229], 0, s[84:85]
	s_addc_u32 s45, s45, 0
	s_add_i32 s48, s65, s47
	global_load_lds_dwordx4 v[164:165], off
	s_mov_b32 m0, s48
	s_nop 0
	global_load_lds_dwordx4 v2, s[44:45]
	s_add_i32 m0, s48, 0x2000
	s_nop 0
	global_load_lds_dwordx4 v148, s[44:45]
	s_cmp_eq_u32 s61, 28
	s_cbranch_scc0 .Ldefer_1591_body
	v_lshl_add_u64 v[164:165], v[240:241], 0, s[84:85]
	s_mov_b32 m0, s54
	s_nop 0
	global_load_lds_dwordx4 v[164:165], off
	v_lshl_add_u64 v[164:165], v[242:243], 0, s[84:85]
	s_mov_b32 m0, s55
	s_nop 0
	global_load_lds_dwordx4 v[164:165], off
.Ldefer_1591_body:
	s_waitcnt vmcnt(6)
	s_waitcnt lgkmcnt(7)
	s_setprio 1
	s_barrier
	v_mfma_i32_16x16x64_i8 v[72:75], v[60:63], v[184:187], v[72:75]
	s_waitcnt lgkmcnt(6)
	v_mfma_i32_16x16x64_i8 v[72:75], v[68:71], v[188:191], v[72:75]
	s_waitcnt lgkmcnt(5)
	v_mfma_i32_16x16x64_i8 v[56:59], v[68:71], v[208:211], v[56:59]
	s_waitcnt lgkmcnt(4)
	v_mfma_i32_16x16x64_i8 v[56:59], v[60:63], v[204:207], v[56:59]
	s_waitcnt lgkmcnt(3)
	v_mfma_i32_16x16x64_i8 v[32:35], v[60:63], v[212:215], v[32:35]
	s_waitcnt lgkmcnt(2)
	v_mfma_i32_16x16x64_i8 v[32:35], v[68:71], v[216:219], v[32:35]
	s_waitcnt lgkmcnt(1)
	v_mfma_i32_16x16x64_i8 v[16:19], v[68:71], v[224:227], v[16:19]
	s_waitcnt lgkmcnt(0)
	v_mfma_i32_16x16x64_i8 v[16:19], v[60:63], v[220:223], v[16:19]
	v_mfma_i32_16x16x64_i8 v[8:11], v[140:143], v[220:223], v[8:11]
	v_mfma_i32_16x16x64_i8 v[8:11], v[144:147], v[224:227], v[8:11]
	v_mfma_i32_16x16x64_i8 v[24:27], v[144:147], v[216:219], v[24:27]
	v_mfma_i32_16x16x64_i8 v[24:27], v[140:143], v[212:215], v[24:27]
	v_mfma_i32_16x16x64_i8 v[48:51], v[140:143], v[204:207], v[48:51]
	v_mfma_i32_16x16x64_i8 v[48:51], v[144:147], v[208:211], v[48:51]
	v_mfma_i32_16x16x64_i8 v[64:67], v[144:147], v[188:191], v[64:67]
	v_mfma_i32_16x16x64_i8 v[64:67], v[140:143], v[184:187], v[64:67]
	v_mfma_i32_16x16x64_i8 v[36:39], v[160:163], v[184:187], v[36:39]
	v_mfma_i32_16x16x64_i8 v[68:71], v[172:175], v[188:191], v[36:39]
	v_mfma_i32_16x16x64_i8 v[36:39], v[172:175], v[208:211], v[52:55]
	v_mfma_i32_16x16x64_i8 v[52:55], v[160:163], v[204:207], v[36:39]
	v_mfma_i32_16x16x64_i8 v[28:31], v[160:163], v[212:215], v[28:31]
	v_mfma_i32_16x16x64_i8 v[28:31], v[172:175], v[216:219], v[28:31]
	v_mfma_i32_16x16x64_i8 v[12:15], v[172:175], v[224:227], v[12:15]
	v_mfma_i32_16x16x64_i8 v[12:15], v[160:163], v[220:223], v[12:15]
	v_mfma_i32_16x16x64_i8 v[4:7], v[176:179], v[220:223], v[4:7]
	v_mfma_i32_16x16x64_i8 v[4:7], v[180:183], v[224:227], v[4:7]
	v_mfma_i32_16x16x64_i8 v[20:23], v[180:183], v[216:219], v[20:23]
	v_mfma_i32_16x16x64_i8 v[20:23], v[176:179], v[212:215], v[20:23]
	v_mfma_i32_16x16x64_i8 v[36:39], v[176:179], v[204:207], v[40:43]
	v_mfma_i32_16x16x64_i8 v[40:43], v[180:183], v[208:211], v[36:39]
	v_mfma_i32_16x16x64_i8 v[36:39], v[180:183], v[188:191], v[44:47]
	v_mfma_i32_16x16x64_i8 v[60:63], v[176:179], v[184:187], v[36:39]
	s_barrier
	s_setprio 0
	s_add_i32 s61, s61, 2
	s_add_u32 s40, s40, 0x100
	s_addc_u32 s41, s41, 0
	s_add_u32 s59, s59, 0x100
	s_addc_u32 s60, s60, 0
	s_cmp_gt_u32 s61, 29
	s_cbranch_scc0 .LBB0_1591

; #define PG8_STAGE(bufoff, gbase, voff) do { _Pragma("unroll") for (int _i = 0; _i < 2; ++_i) \
;         __builtin_amdgcn_global_load_lds((const unsigned*)((const char*)(gbase) + (voff)[_i]), (PG8_LAS unsigned*)(lds + (bufoff) + ldsw + _i * 8192), 16, 0, 0); } while (0)
; #define PG8_LDA(dst, b, h) do { _Pragma("unroll") for (int m = 0; m < 4; ++m) _Pragma("unroll") for (int k = 0; k < 2; ++k) dst[m][k] = *(const PG8_LAS bf16x8*)(lds + PG8_SA(b, h) + aoff + m * 2048 + k * 1024); } while (0)
; #define PG8_LDB(dst, b, h) do { _Pragma("unroll") for (int n = 0; n < 2; ++n) _Pragma("unroll") for (int k = 0; k < 2; ++k) dst[n][k] = *(const PG8_LAS bf16x8*)(lds + PG8_SB(b, h) + boff + n * 2048 + k * 1024); } while (0)
; #define PG8_WAIT_V(n) asm volatile("s_waitcnt vmcnt(" #n ")" ::: "memory")
; #define PG8_WAIT_L(n) asm volatile("s_waitcnt lgkmcnt(" #n ")" ::: "memory")
; #define PG8_BAR __builtin_amdgcn_s_barrier()
; #define PG8_SCHED __builtin_amdgcn_sched_barrier(0)
; template <class Epi, class Sched, bool ALIGN_EPI = false, bool SP2 = false, bool I8 = false>
; __device__ __forceinline__ void gemm_phase(PG8_LAS unsigned char* lds, const Gemm g, const Sched& S, const Epi& E) {
;     ...
;         for (int t = 0; t < nt; t += 2) {
;             const bool last = (t == nt - 2);
;             const char* a1 = cA + (size_t)(t + 1) * kstep;
;             const char* a2 = last ? nA : cA + (size_t)(t + 2) * kstep; const char* b2 = last ? nB : cB + (size_t)(t + 2) * kstep;
;             const char* a3 = a2 + kstep; const char* b3 = b2 + kstep;
;             if (last && has_next) S.a_ready(nxt);
;             if constexpr (SP2) {
;             PG8_LDB(B0, 0, 0); PG8_LDB(B1, 0, 1); PG8_SCHED; PG8_LDA(At, 0, 0); PG8_STAGE(PG8_SA(1, 1), a1 + hstep, voffA);
;             PG8_WAIT_V(8); PG8_WAIT_L(0); PG8_BAR; PG8_MMA(0, 0, At, B0); PG8_MMA(0, 1, At, B1); PG8_BAR; PG8_SCHED;
;     ...
; #pragma unroll
;         for (int a = 0; a < 2; ++a)
; #pragma unroll
;             for (int b = 0; b < 2; ++b)
; #pragma unroll
;                 for (int m = 0; m < 4; ++m)
; #pragma unroll
;                     for (int n = 0; n < 2; ++n) acc[a][b][m][n] = (acc_t){0, 0, 0, 0};
.LBB0_1621:
	v_mov_b32_e32 v127, 0
	s_andn2_b64 vcc, exec, s[26:27]
	v_mov_b32_e32 v126, v127
	v_mov_b32_e32 v125, v127
	v_mov_b32_e32 v124, v127
	v_mov_b32_e32 v131, v127
	v_mov_b32_e32 v130, v127
	v_mov_b32_e32 v129, v127
	v_mov_b32_e32 v128, v127
	v_mov_b32_e32 v115, v127
	v_mov_b32_e32 v114, v127
	v_mov_b32_e32 v113, v127
	v_mov_b32_e32 v112, v127
	v_mov_b32_e32 v111, v127
	v_mov_b32_e32 v110, v127
	v_mov_b32_e32 v109, v127
	v_mov_b32_e32 v108, v127
	v_mov_b32_e32 v99, v127
	v_mov_b32_e32 v98, v127
	v_mov_b32_e32 v97, v127
	v_mov_b32_e32 v96, v127
	v_mov_b32_e32 v95, v127
	v_mov_b32_e32 v94, v127
	v_mov_b32_e32 v93, v127
	v_mov_b32_e32 v92, v127
	v_mov_b32_e32 v83, v127
	v_mov_b32_e32 v82, v127
	v_mov_b32_e32 v81, v127
	v_mov_b32_e32 v80, v127
	v_mov_b32_e32 v79, v127
	v_mov_b32_e32 v78, v127
	v_mov_b32_e32 v77, v127
	v_mov_b32_e32 v76, v127
	v_mov_b32_e32 v123, v127
	v_mov_b32_e32 v122, v127
	v_mov_b32_e32 v121, v127
	v_mov_b32_e32 v120, v127
	v_mov_b32_e32 v119, v127
	v_mov_b32_e32 v118, v127
	v_mov_b32_e32 v117, v127
	v_mov_b32_e32 v116, v127
	v_mov_b32_e32 v107, v127
	v_mov_b32_e32 v106, v127
	v_mov_b32_e32 v105, v127
	v_mov_b32_e32 v104, v127
	v_mov_b32_e32 v103, v127
	v_mov_b32_e32 v102, v127
	v_mov_b32_e32 v101, v127
	v_mov_b32_e32 v100, v127
	v_mov_b32_e32 v91, v127
	v_mov_b32_e32 v90, v127
	v_mov_b32_e32 v89, v127
	v_mov_b32_e32 v88, v127
	v_mov_b32_e32 v87, v127
	v_mov_b32_e32 v86, v127
	v_mov_b32_e32 v85, v127
	v_mov_b32_e32 v84, v127
	v_mov_b32_e32 v75, v127
	v_mov_b32_e32 v74, v127
	v_mov_b32_e32 v73, v127
	v_mov_b32_e32 v72, v127
	v_mov_b32_e32 v71, v127
	v_mov_b32_e32 v70, v127
	v_mov_b32_e32 v69, v127
	v_mov_b32_e32 v68, v127
	v_mov_b32_e32 v67, v127
	v_mov_b32_e32 v66, v127
	v_mov_b32_e32 v65, v127
	v_mov_b32_e32 v64, v127
	v_mov_b32_e32 v63, v127
	v_mov_b32_e32 v62, v127
	v_mov_b32_e32 v61, v127
	v_mov_b32_e32 v60, v127
	v_mov_b32_e32 v51, v127
	v_mov_b32_e32 v50, v127
	v_mov_b32_e32 v49, v127
	v_mov_b32_e32 v48, v127
	v_mov_b32_e32 v47, v127
	v_mov_b32_e32 v46, v127
	v_mov_b32_e32 v45, v127
	v_mov_b32_e32 v44, v127
	v_mov_b32_e32 v35, v127
	v_mov_b32_e32 v34, v127
	v_mov_b32_e32 v33, v127
	v_mov_b32_e32 v32, v127
	v_mov_b32_e32 v31, v127
	v_mov_b32_e32 v30, v127
	v_mov_b32_e32 v29, v127
	v_mov_b32_e32 v28, v127
	v_mov_b32_e32 v19, v127
	v_mov_b32_e32 v18, v127
	v_mov_b32_e32 v17, v127
	v_mov_b32_e32 v16, v127
	v_mov_b32_e32 v15, v127
	v_mov_b32_e32 v14, v127
	v_mov_b32_e32 v13, v127
	v_mov_b32_e32 v12, v127
	v_mov_b32_e32 v59, v127
	v_mov_b32_e32 v58, v127
	v_mov_b32_e32 v57, v127
	v_mov_b32_e32 v56, v127
	v_mov_b32_e32 v55, v127
	v_mov_b32_e32 v54, v127
	v_mov_b32_e32 v53, v127
	v_mov_b32_e32 v52, v127
	v_mov_b32_e32 v43, v127
	v_mov_b32_e32 v42, v127
	v_mov_b32_e32 v41, v127
	v_mov_b32_e32 v40, v127
	v_mov_b32_e32 v39, v127
	v_mov_b32_e32 v38, v127
	v_mov_b32_e32 v37, v127
	v_mov_b32_e32 v36, v127
	v_mov_b32_e32 v27, v127
	v_mov_b32_e32 v26, v127
	v_mov_b32_e32 v25, v127
	v_mov_b32_e32 v24, v127
	v_mov_b32_e32 v23, v127
	v_mov_b32_e32 v22, v127
	v_mov_b32_e32 v21, v127
	v_mov_b32_e32 v20, v127
	v_mov_b32_e32 v11, v127
	v_mov_b32_e32 v10, v127
	v_mov_b32_e32 v9, v127
	v_mov_b32_e32 v8, v127
	v_mov_b32_e32 v7, v127
	v_mov_b32_e32 v6, v127
	v_mov_b32_e32 v5, v127
	v_mov_b32_e32 v4, v127
	s_cbranch_vccnz .LBB0_1625
	s_add_u32 s44, s44, 0x80
	s_addc_u32 s45, s45, 0
	s_add_u32 s65, s48, 0x100
	s_addc_u32 s67, s49, 0
	s_mov_b32 s48, 0
	s_add_i32 s72, s48, 2
	s_add_u32 s73, s44, 0x80
	s_addc_u32 s49, s45, 0
	s_add_i32 s86, 0, 0x10000
	s_cmp_eq_u32 s57, s48
	s_cselect_b32 s49, s13, s49
	s_cselect_b32 s48, s12, s73
	s_cselect_b32 s77, s41, s67
	s_cselect_b32 s76, s40, s65
	s_add_i32 s73, 0, 0x14000
	v_add_u32_e32 v158, s86, v143
	v_add_u32_e32 v174, s73, v143
	ds_read_b128 v[146:149], v158
	ds_read_b128 v[178:181], v145
	ds_read_b128 v[150:153], v158 offset:1024
	ds_read_b128 v[182:185], v145 offset:1024
	ds_read_b128 v[204:207], v145 offset:3072
	ds_read_b128 v[186:189], v145 offset:2048
	ds_read_b128 v[208:211], v145 offset:4096
	ds_read_b128 v[212:215], v145 offset:5120
	v_lshl_add_u64 v[190:191], s[44:45], 0, v[138:139]
	s_add_i32 m0, s47, 0xc000
	ds_read_b128 v[220:223], v145 offset:7168
	ds_read_b128 v[216:219], v145 offset:6144
	ds_read_b128 v[154:157], v158 offset:2048
	ds_read_b128 v[158:161], v158 offset:3072
	ds_read_b128 v[162:165], v174
	ds_read_b128 v[166:169], v174 offset:1024
	ds_read_b128 v[170:173], v174 offset:2048
	ds_read_b128 v[174:177], v174 offset:3072
	global_load_lds_dwordx4 v[190:191], off
	v_lshl_add_u64 v[190:191], s[44:45], 0, v[140:141]
	s_add_i32 m0, s47, 0xe000
	s_nop 0
	global_load_lds_dwordx4 v[190:191], off
	s_waitcnt vmcnt(8)
	s_waitcnt lgkmcnt(14)
	s_setprio 1
	s_barrier
; #define PG8_STAGE(bufoff, gbase, voff) do { _Pragma("unroll") for (int _i = 0; _i < 2; ++_i) \
;         __builtin_amdgcn_global_load_lds((const unsigned*)((const char*)(gbase) + (voff)[_i]), (PG8_LAS unsigned*)(lds + (bufoff) + ldsw + _i * 8192), 16, 0, 0); } while (0)
; #define PG8_LDA(dst, b, h) do { _Pragma("unroll") for (int m = 0; m < 4; ++m) _Pragma("unroll") for (int k = 0; k < 2; ++k) dst[m][k] = *(const PG8_LAS bf16x8*)(lds + PG8_SA(b, h) + aoff + m * 2048 + k * 1024); } while (0)
; #define PG8_LDB(dst, b, h) do { _Pragma("unroll") for (int n = 0; n < 2; ++n) _Pragma("unroll") for (int k = 0; k < 2; ++k) dst[n][k] = *(const PG8_LAS bf16x8*)(lds + PG8_SB(b, h) + boff + n * 2048 + k * 1024); } while (0)
; #define PG8_WAIT_V(n) asm volatile("s_waitcnt vmcnt(" #n ")" ::: "memory")
; #define PG8_WAIT_L(n) asm volatile("s_waitcnt lgkmcnt(" #n ")" ::: "memory")
; #define PG8_BAR __builtin_amdgcn_s_barrier()
; #define PG8_SCHED __builtin_amdgcn_sched_barrier(0)
; template <class Epi, class Sched, bool ALIGN_EPI = false, bool SP2 = false, bool I8 = false>
; __device__ __forceinline__ void gemm_phase(PG8_LAS unsigned char* lds, const Gemm g, const Sched& S, const Epi& E) {
;     ...
;             PG8_LDB(B0, 0, 0); PG8_LDB(B1, 0, 1); PG8_SCHED; PG8_LDA(At, 0, 0); PG8_STAGE(PG8_SA(1, 1), a1 + hstep, voffA);
;             PG8_WAIT_V(8); PG8_WAIT_L(0); PG8_BAR; PG8_MMA(0, 0, At, B0); PG8_MMA(0, 1, At, B1); PG8_BAR; PG8_SCHED;
;             PG8_LDA(At, 0, 1); PG8_STAGE(PG8_SB(0, 0), b2, voffB); PG8_STAGE(PG8_SB(0, 1), b2 + hstep, voffB); PG8_STAGE(PG8_SA(0, 0), a2, voffA);
;             PG8_WAIT_V(8); PG8_WAIT_L(0); PG8_BAR; PG8_MMA(1, 0, At, B0); PG8_MMA(1, 1, At, B1); PG8_BAR; PG8_SCHED;
	v_mfma_f32_16x16x32_bf16 v[124:127], v[146:149], v[178:181], 0
	s_waitcnt lgkmcnt(12)
	v_mfma_f32_16x16x32_bf16 v[124:127], v[150:153], v[182:185], v[124:127]
	s_waitcnt lgkmcnt(11)
	v_mfma_f32_16x16x32_bf16 v[112:115], v[150:153], v[204:207], 0
	s_waitcnt lgkmcnt(10)
	v_mfma_f32_16x16x32_bf16 v[112:115], v[146:149], v[186:189], v[112:115]
	s_waitcnt lgkmcnt(9)
	v_mfma_f32_16x16x32_bf16 v[96:99], v[146:149], v[208:211], 0
	s_waitcnt lgkmcnt(8)
	v_mfma_f32_16x16x32_bf16 v[96:99], v[150:153], v[212:215], v[96:99]
	s_waitcnt lgkmcnt(7)
	v_mfma_f32_16x16x32_bf16 v[80:83], v[150:153], v[220:223], 0
	s_waitcnt lgkmcnt(6)
	v_mfma_f32_16x16x32_bf16 v[80:83], v[146:149], v[216:219], v[80:83]
	s_waitcnt lgkmcnt(5)
	v_mfma_f32_16x16x32_bf16 v[76:79], v[154:157], v[216:219], 0
	s_waitcnt lgkmcnt(4)
	v_mfma_f32_16x16x32_bf16 v[76:79], v[158:161], v[220:223], v[76:79]
	v_mfma_f32_16x16x32_bf16 v[92:95], v[158:161], v[212:215], 0
	v_mfma_f32_16x16x32_bf16 v[92:95], v[154:157], v[208:211], v[92:95]
	v_mfma_f32_16x16x32_bf16 v[108:111], v[154:157], v[186:189], 0
	v_mfma_f32_16x16x32_bf16 v[108:111], v[158:161], v[204:207], v[108:111]
	v_mfma_f32_16x16x32_bf16 v[128:131], v[158:161], v[182:185], 0
	v_mfma_f32_16x16x32_bf16 v[128:131], v[154:157], v[178:181], v[128:131]
	s_waitcnt lgkmcnt(3)
	v_mfma_f32_16x16x32_bf16 v[120:123], v[162:165], v[178:181], 0
	s_waitcnt lgkmcnt(2)
	v_mfma_f32_16x16x32_bf16 v[120:123], v[166:169], v[182:185], v[120:123]
	v_mfma_f32_16x16x32_bf16 v[104:107], v[166:169], v[204:207], 0
	v_mfma_f32_16x16x32_bf16 v[104:107], v[162:165], v[186:189], v[104:107]
	v_mfma_f32_16x16x32_bf16 v[88:91], v[162:165], v[208:211], 0
	v_mfma_f32_16x16x32_bf16 v[88:91], v[166:169], v[212:215], v[88:91]
	v_mfma_f32_16x16x32_bf16 v[72:75], v[166:169], v[220:223], 0
	v_mfma_f32_16x16x32_bf16 v[72:75], v[162:165], v[216:219], v[72:75]
	s_waitcnt lgkmcnt(1)
	v_mfma_f32_16x16x32_bf16 v[68:71], v[170:173], v[216:219], 0
	s_waitcnt lgkmcnt(0)
	v_mfma_f32_16x16x32_bf16 v[68:71], v[174:177], v[220:223], v[68:71]
	v_mfma_f32_16x16x32_bf16 v[84:87], v[174:177], v[212:215], 0
	v_mfma_f32_16x16x32_bf16 v[84:87], v[170:173], v[208:211], v[84:87]
	v_mfma_f32_16x16x32_bf16 v[100:103], v[170:173], v[186:189], 0
	v_mfma_f32_16x16x32_bf16 v[100:103], v[174:177], v[204:207], v[100:103]
	v_mfma_f32_16x16x32_bf16 v[116:119], v[174:177], v[182:185], 0
	v_mfma_f32_16x16x32_bf16 v[116:119], v[170:173], v[178:181], v[116:119]
	s_barrier
	s_setprio 0
	s_add_i32 s86, s86, s28
	v_lshl_add_u64 v[190:191], s[76:77], 0, v[2:3]
	s_mov_b32 m0, s86
	ds_read_b128 v[178:181], v145 offset:16384
	ds_read_b128 v[182:185], v145 offset:17408
	ds_read_b128 v[204:207], v145 offset:19456
	ds_read_b128 v[186:189], v145 offset:18432
	ds_read_b128 v[208:211], v145 offset:20480
	ds_read_b128 v[212:215], v145 offset:21504
	ds_read_b128 v[220:223], v145 offset:23552
	ds_read_b128 v[216:219], v145 offset:22528
	global_load_lds_dwordx4 v[190:191], off
	s_add_i32 m0, s86, 0x2000
	v_lshl_add_u64 v[224:225], s[76:77], 0, v[136:137]
	s_add_u32 s76, s76, s18
	s_addc_u32 s77, s77, s19
	s_add_i32 s73, s73, s28
	global_load_lds_dwordx4 v[224:225], off
	v_lshl_add_u64 v[226:227], s[76:77], 0, v[2:3]
	s_mov_b32 m0, s73
	v_lshl_add_u64 v[228:229], s[76:77], 0, v[136:137]
	global_load_lds_dwordx4 v[226:227], off
	s_add_i32 m0, s73, 0x2000
	v_lshl_add_u64 v[240:241], s[48:49], 0, v[132:133]
	global_load_lds_dwordx4 v[228:229], off
	v_lshl_add_u64 v[242:243], s[48:49], 0, v[134:135]
	s_waitcnt vmcnt(6)
	s_waitcnt lgkmcnt(7)
	s_setprio 1
	s_barrier
	v_mfma_f32_16x16x32_bf16 v[64:67], v[146:149], v[178:181], 0
	s_waitcnt lgkmcnt(6)
	v_mfma_f32_16x16x32_bf16 v[64:67], v[150:153], v[182:185], v[64:67]
	s_waitcnt lgkmcnt(5)
	v_mfma_f32_16x16x32_bf16 v[48:51], v[150:153], v[204:207], 0
	s_waitcnt lgkmcnt(4)
	v_mfma_f32_16x16x32_bf16 v[48:51], v[146:149], v[186:189], v[48:51]
	s_waitcnt lgkmcnt(3)
	v_mfma_f32_16x16x32_bf16 v[32:35], v[146:149], v[208:211], 0
	s_waitcnt lgkmcnt(2)
	v_mfma_f32_16x16x32_bf16 v[32:35], v[150:153], v[212:215], v[32:35]
	s_waitcnt lgkmcnt(1)
	v_mfma_f32_16x16x32_bf16 v[16:19], v[150:153], v[220:223], 0
	s_waitcnt lgkmcnt(0)
	v_mfma_f32_16x16x32_bf16 v[16:19], v[146:149], v[216:219], v[16:19]
	v_mfma_f32_16x16x32_bf16 v[12:15], v[154:157], v[216:219], 0
	v_mfma_f32_16x16x32_bf16 v[12:15], v[158:161], v[220:223], v[12:15]
	v_mfma_f32_16x16x32_bf16 v[28:31], v[158:161], v[212:215], 0
	v_mfma_f32_16x16x32_bf16 v[28:31], v[154:157], v[208:211], v[28:31]
	v_mfma_f32_16x16x32_bf16 v[44:47], v[154:157], v[186:189], 0
	v_mfma_f32_16x16x32_bf16 v[44:47], v[158:161], v[204:207], v[44:47]
	v_mfma_f32_16x16x32_bf16 v[60:63], v[158:161], v[182:185], 0
	v_mfma_f32_16x16x32_bf16 v[60:63], v[154:157], v[178:181], v[60:63]
	v_mfma_f32_16x16x32_bf16 v[56:59], v[162:165], v[178:181], 0
	v_mfma_f32_16x16x32_bf16 v[56:59], v[166:169], v[182:185], v[56:59]
	v_mfma_f32_16x16x32_bf16 v[40:43], v[166:169], v[204:207], 0
	v_mfma_f32_16x16x32_bf16 v[40:43], v[162:165], v[186:189], v[40:43]
	v_mfma_f32_16x16x32_bf16 v[24:27], v[162:165], v[208:211], 0
	v_mfma_f32_16x16x32_bf16 v[24:27], v[166:169], v[212:215], v[24:27]
	v_mfma_f32_16x16x32_bf16 v[8:11], v[166:169], v[220:223], 0
	v_mfma_f32_16x16x32_bf16 v[8:11], v[162:165], v[216:219], v[8:11]
	v_mfma_f32_16x16x32_bf16 v[4:7], v[170:173], v[216:219], 0
	v_mfma_f32_16x16x32_bf16 v[4:7], v[174:177], v[220:223], v[4:7]
	v_mfma_f32_16x16x32_bf16 v[20:23], v[174:177], v[212:215], 0
	v_mfma_f32_16x16x32_bf16 v[20:23], v[170:173], v[208:211], v[20:23]
	v_mfma_f32_16x16x32_bf16 v[36:39], v[170:173], v[186:189], 0
	v_mfma_f32_16x16x32_bf16 v[36:39], v[174:177], v[204:207], v[36:39]
	v_mfma_f32_16x16x32_bf16 v[52:55], v[174:177], v[182:185], 0
	v_mfma_f32_16x16x32_bf16 v[52:55], v[170:173], v[178:181], v[52:55]
	s_barrier
; #define PG8_STAGE(bufoff, gbase, voff) do { _Pragma("unroll") for (int _i = 0; _i < 2; ++_i) \
;         __builtin_amdgcn_global_load_lds((const unsigned*)((const char*)(gbase) + (voff)[_i]), (PG8_LAS unsigned*)(lds + (bufoff) + ldsw + _i * 8192), 16, 0, 0); } while (0)
; #define PG8_LDA(dst, b, h) do { _Pragma("unroll") for (int m = 0; m < 4; ++m) _Pragma("unroll") for (int k = 0; k < 2; ++k) dst[m][k] = *(const PG8_LAS bf16x8*)(lds + PG8_SA(b, h) + aoff + m * 2048 + k * 1024); } while (0)
; #define PG8_LDB(dst, b, h) do { _Pragma("unroll") for (int n = 0; n < 2; ++n) _Pragma("unroll") for (int k = 0; k < 2; ++k) dst[n][k] = *(const PG8_LAS bf16x8*)(lds + PG8_SB(b, h) + boff + n * 2048 + k * 1024); } while (0)
; #define PG8_WAIT_V(n) asm volatile("s_waitcnt vmcnt(" #n ")" ::: "memory")
; #define PG8_WAIT_L(n) asm volatile("s_waitcnt lgkmcnt(" #n ")" ::: "memory")
; #define PG8_BAR __builtin_amdgcn_s_barrier()
; #define PG8_SCHED __builtin_amdgcn_sched_barrier(0)
; template <class Epi, class Sched, bool ALIGN_EPI = false, bool SP2 = false, bool I8 = false>
; __device__ __forceinline__ void gemm_phase(PG8_LAS unsigned char* lds, const Gemm g, const Sched& S, const Epi& E) {
;     ...
;             PG8_LDB(B0, 1, 0); PG8_LDB(B1, 1, 1); PG8_SCHED; PG8_LDA(At, 1, 0); PG8_STAGE(PG8_SA(0, 1), a2 + hstep, voffA);
;             PG8_WAIT_V(8); PG8_WAIT_L(0); PG8_BAR; PG8_MMA(0, 0, At, B0); PG8_MMA(0, 1, At, B1); PG8_BAR; PG8_SCHED;
;             PG8_LDA(At, 1, 1); PG8_STAGE(PG8_SB(1, 0), b3, voffB); PG8_STAGE(PG8_SB(1, 1), b3 + hstep, voffB); PG8_STAGE(PG8_SA(1, 0), a3, voffA);
;             PG8_WAIT_V(8); PG8_WAIT_L(0); PG8_BAR; PG8_MMA(1, 0, At, B0); PG8_MMA(1, 1, At, B1); PG8_BAR; PG8_SCHED;
	s_setprio 0
	s_mov_b32 m0, s47
	s_nop 0
	global_load_lds_dwordx4 v[240:241], off
	s_mov_b32 m0, s50
	s_nop 0
	global_load_lds_dwordx4 v[242:243], off
	s_add_i32 s73, 0, 0x18000
	s_add_i32 s76, 0, 0x1c000
	v_add_u32_e32 v158, s73, v143
	v_add_u32_e32 v174, s76, v143
	ds_read_b128 v[146:149], v158
	ds_read_b128 v[178:181], v145 offset:32768
	ds_read_b128 v[150:153], v158 offset:1024
	ds_read_b128 v[182:185], v145 offset:33792
	ds_read_b128 v[204:207], v145 offset:35840
	ds_read_b128 v[186:189], v145 offset:34816
	ds_read_b128 v[208:211], v145 offset:36864
	ds_read_b128 v[212:215], v145 offset:37888
	s_add_u32 s48, s48, s18
	s_addc_u32 s49, s49, s19
	s_mov_b32 m0, s51
	ds_read_b128 v[220:223], v145 offset:39936
	ds_read_b128 v[216:219], v145 offset:38912
	ds_read_b128 v[154:157], v158 offset:2048
	ds_read_b128 v[158:161], v158 offset:3072
	ds_read_b128 v[162:165], v174
	ds_read_b128 v[166:169], v174 offset:1024
	ds_read_b128 v[170:173], v174 offset:2048
	ds_read_b128 v[174:177], v174 offset:3072
	global_load_lds_dwordx4 v132, s[48:49]
	s_mov_b32 m0, s52
	s_nop 0
	global_load_lds_dwordx4 v134, s[48:49]
	s_waitcnt vmcnt(8)
	s_waitcnt lgkmcnt(14)
	s_setprio 1
	s_barrier
	v_mfma_f32_16x16x32_bf16 v[124:127], v[146:149], v[178:181], v[124:127]
	s_waitcnt lgkmcnt(12)
	v_mfma_f32_16x16x32_bf16 v[124:127], v[150:153], v[182:185], v[124:127]
	s_waitcnt lgkmcnt(11)
	v_mfma_f32_16x16x32_bf16 v[112:115], v[150:153], v[204:207], v[112:115]
	s_waitcnt lgkmcnt(10)
	v_mfma_f32_16x16x32_bf16 v[112:115], v[146:149], v[186:189], v[112:115]
	s_waitcnt lgkmcnt(9)
	v_mfma_f32_16x16x32_bf16 v[96:99], v[146:149], v[208:211], v[96:99]
	s_waitcnt lgkmcnt(8)
	v_mfma_f32_16x16x32_bf16 v[96:99], v[150:153], v[212:215], v[96:99]
	s_waitcnt lgkmcnt(7)
	v_mfma_f32_16x16x32_bf16 v[80:83], v[150:153], v[220:223], v[80:83]
	s_waitcnt lgkmcnt(6)
	v_mfma_f32_16x16x32_bf16 v[80:83], v[146:149], v[216:219], v[80:83]
	s_waitcnt lgkmcnt(5)
	v_mfma_f32_16x16x32_bf16 v[76:79], v[154:157], v[216:219], v[76:79]
	s_waitcnt lgkmcnt(4)
	v_mfma_f32_16x16x32_bf16 v[76:79], v[158:161], v[220:223], v[76:79]
	v_mfma_f32_16x16x32_bf16 v[92:95], v[158:161], v[212:215], v[92:95]
	v_mfma_f32_16x16x32_bf16 v[92:95], v[154:157], v[208:211], v[92:95]
	v_mfma_f32_16x16x32_bf16 v[108:111], v[154:157], v[186:189], v[108:111]
	v_mfma_f32_16x16x32_bf16 v[108:111], v[158:161], v[204:207], v[108:111]
	v_mfma_f32_16x16x32_bf16 v[128:131], v[158:161], v[182:185], v[128:131]
	v_mfma_f32_16x16x32_bf16 v[128:131], v[154:157], v[178:181], v[128:131]
	s_waitcnt lgkmcnt(3)
	v_mfma_f32_16x16x32_bf16 v[120:123], v[162:165], v[178:181], v[120:123]
	s_waitcnt lgkmcnt(2)
	v_mfma_f32_16x16x32_bf16 v[120:123], v[166:169], v[182:185], v[120:123]
	v_mfma_f32_16x16x32_bf16 v[104:107], v[166:169], v[204:207], v[104:107]
	v_mfma_f32_16x16x32_bf16 v[104:107], v[162:165], v[186:189], v[104:107]
	v_mfma_f32_16x16x32_bf16 v[88:91], v[162:165], v[208:211], v[88:91]
	v_mfma_f32_16x16x32_bf16 v[88:91], v[166:169], v[212:215], v[88:91]
	v_mfma_f32_16x16x32_bf16 v[72:75], v[166:169], v[220:223], v[72:75]
	v_mfma_f32_16x16x32_bf16 v[72:75], v[162:165], v[216:219], v[72:75]
	s_waitcnt lgkmcnt(1)
	v_mfma_f32_16x16x32_bf16 v[68:71], v[170:173], v[216:219], v[68:71]
	s_waitcnt lgkmcnt(0)
	v_mfma_f32_16x16x32_bf16 v[68:71], v[174:177], v[220:223], v[68:71]
	v_mfma_f32_16x16x32_bf16 v[84:87], v[174:177], v[212:215], v[84:87]
	v_mfma_f32_16x16x32_bf16 v[84:87], v[170:173], v[208:211], v[84:87]
	v_mfma_f32_16x16x32_bf16 v[100:103], v[170:173], v[186:189], v[100:103]
	v_mfma_f32_16x16x32_bf16 v[100:103], v[174:177], v[204:207], v[100:103]
	v_mfma_f32_16x16x32_bf16 v[116:119], v[174:177], v[182:185], v[116:119]
	v_mfma_f32_16x16x32_bf16 v[116:119], v[170:173], v[178:181], v[116:119]
	s_barrier
	s_setprio 0
	s_add_i32 s48, s73, s28
	v_lshl_add_u64 v[190:191], v[190:191], 0, s[84:85]
	s_mov_b32 m0, s48
	ds_read_b128 v[178:181], v145 offset:49152
	ds_read_b128 v[182:185], v145 offset:50176
	ds_read_b128 v[204:207], v145 offset:52224
	ds_read_b128 v[186:189], v145 offset:51200
	ds_read_b128 v[208:211], v145 offset:53248
	ds_read_b128 v[212:215], v145 offset:54272
	ds_read_b128 v[220:223], v145 offset:56320
	ds_read_b128 v[216:219], v145 offset:55296
	global_load_lds_dwordx4 v[190:191], off
	v_lshl_add_u64 v[190:191], v[224:225], 0, s[84:85]
	s_add_i32 m0, s48, 0x2000
	s_add_i32 s48, s76, s28
	global_load_lds_dwordx4 v[190:191], off
	v_lshl_add_u64 v[190:191], v[226:227], 0, s[84:85]
	s_mov_b32 m0, s48
	s_nop 0
	global_load_lds_dwordx4 v[190:191], off
	v_lshl_add_u64 v[190:191], v[228:229], 0, s[84:85]
	s_add_i32 m0, s48, 0x2000
	s_nop 0
	global_load_lds_dwordx4 v[190:191], off
	v_lshl_add_u64 v[190:191], v[240:241], 0, s[84:85]
	s_mov_b32 m0, s55
	s_nop 0
	global_load_lds_dwordx4 v[190:191], off
	v_lshl_add_u64 v[190:191], v[242:243], 0, s[84:85]
	s_mov_b32 m0, s56
	s_nop 0
	global_load_lds_dwordx4 v[190:191], off
	s_waitcnt vmcnt(8)
	s_waitcnt lgkmcnt(7)
	s_setprio 1
	s_barrier
; #define PG8_STAGE(bufoff, gbase, voff) do { _Pragma("unroll") for (int _i = 0; _i < 2; ++_i) \
;         __builtin_amdgcn_global_load_lds((const unsigned*)((const char*)(gbase) + (voff)[_i]), (PG8_LAS unsigned*)(lds + (bufoff) + ldsw + _i * 8192), 16, 0, 0); } while (0)
; #define PG8_LDA(dst, b, h) do { _Pragma("unroll") for (int m = 0; m < 4; ++m) _Pragma("unroll") for (int k = 0; k < 2; ++k) dst[m][k] = *(const PG8_LAS bf16x8*)(lds + PG8_SA(b, h) + aoff + m * 2048 + k * 1024); } while (0)
; #define PG8_LDB(dst, b, h) do { _Pragma("unroll") for (int n = 0; n < 2; ++n) _Pragma("unroll") for (int k = 0; k < 2; ++k) dst[n][k] = *(const PG8_LAS bf16x8*)(lds + PG8_SB(b, h) + boff + n * 2048 + k * 1024); } while (0)
; #define PG8_WAIT_V(n) asm volatile("s_waitcnt vmcnt(" #n ")" ::: "memory")
; #define PG8_WAIT_L(n) asm volatile("s_waitcnt lgkmcnt(" #n ")" ::: "memory")
; #define PG8_BAR __builtin_amdgcn_s_barrier()
; #define PG8_SCHED __builtin_amdgcn_sched_barrier(0)
; template <class Epi, class Sched, bool ALIGN_EPI = false, bool SP2 = false, bool I8 = false>
; __device__ __forceinline__ void gemm_phase(PG8_LAS unsigned char* lds, const Gemm g, const Sched& S, const Epi& E) {
;     ...
;         for (int t = 0; t < nt; t += 2) {
;             const bool last = (t == nt - 2);
;             const char* a1 = cA + (size_t)(t + 1) * kstep;
;             const char* a2 = last ? nA : cA + (size_t)(t + 2) * kstep; const char* b2 = last ? nB : cB + (size_t)(t + 2) * kstep;
;             const char* a3 = a2 + kstep; const char* b3 = b2 + kstep;
;             if (last && has_next) S.a_ready(nxt);
;             if constexpr (SP2) {
;             PG8_LDB(B0, 0, 0); PG8_LDB(B1, 0, 1); PG8_SCHED; PG8_LDA(At, 0, 0); PG8_STAGE(PG8_SA(1, 1), a1 + hstep, voffA);
;             PG8_WAIT_V(8); PG8_WAIT_L(0); PG8_BAR; PG8_MMA(0, 0, At, B0); PG8_MMA(0, 1, At, B1); PG8_BAR; PG8_SCHED;
;     ...
;             PG8_LDA(At, 1, 1); PG8_STAGE(PG8_SB(1, 0), b3, voffB); PG8_STAGE(PG8_SB(1, 1), b3 + hstep, voffB); PG8_STAGE(PG8_SA(1, 0), a3, voffA);
;             PG8_WAIT_V(8); PG8_WAIT_L(0); PG8_BAR; PG8_MMA(1, 0, At, B0); PG8_MMA(1, 1, At, B1); PG8_BAR; PG8_SCHED;
	v_mfma_f32_16x16x32_bf16 v[64:67], v[146:149], v[178:181], v[64:67]
	s_waitcnt lgkmcnt(6)
	v_mfma_f32_16x16x32_bf16 v[64:67], v[150:153], v[182:185], v[64:67]
	s_waitcnt lgkmcnt(5)
	v_mfma_f32_16x16x32_bf16 v[48:51], v[150:153], v[204:207], v[48:51]
	s_waitcnt lgkmcnt(4)
	v_mfma_f32_16x16x32_bf16 v[48:51], v[146:149], v[186:189], v[48:51]
	s_waitcnt lgkmcnt(3)
	v_mfma_f32_16x16x32_bf16 v[32:35], v[146:149], v[208:211], v[32:35]
	s_waitcnt lgkmcnt(2)
	v_mfma_f32_16x16x32_bf16 v[32:35], v[150:153], v[212:215], v[32:35]
	s_waitcnt lgkmcnt(1)
	v_mfma_f32_16x16x32_bf16 v[16:19], v[150:153], v[220:223], v[16:19]
	s_waitcnt lgkmcnt(0)
	v_mfma_f32_16x16x32_bf16 v[16:19], v[146:149], v[216:219], v[16:19]
	v_mfma_f32_16x16x32_bf16 v[12:15], v[154:157], v[216:219], v[12:15]
	v_mfma_f32_16x16x32_bf16 v[12:15], v[158:161], v[220:223], v[12:15]
	v_mfma_f32_16x16x32_bf16 v[28:31], v[158:161], v[212:215], v[28:31]
	v_mfma_f32_16x16x32_bf16 v[28:31], v[154:157], v[208:211], v[28:31]
	v_mfma_f32_16x16x32_bf16 v[44:47], v[154:157], v[186:189], v[44:47]
	v_mfma_f32_16x16x32_bf16 v[44:47], v[158:161], v[204:207], v[44:47]
	v_mfma_f32_16x16x32_bf16 v[60:63], v[158:161], v[182:185], v[60:63]
	v_mfma_f32_16x16x32_bf16 v[60:63], v[154:157], v[178:181], v[60:63]
	v_mfma_f32_16x16x32_bf16 v[56:59], v[162:165], v[178:181], v[56:59]
	v_mfma_f32_16x16x32_bf16 v[56:59], v[166:169], v[182:185], v[56:59]
	v_mfma_f32_16x16x32_bf16 v[40:43], v[166:169], v[204:207], v[40:43]
	v_mfma_f32_16x16x32_bf16 v[40:43], v[162:165], v[186:189], v[40:43]
	v_mfma_f32_16x16x32_bf16 v[24:27], v[162:165], v[208:211], v[24:27]
	v_mfma_f32_16x16x32_bf16 v[24:27], v[166:169], v[212:215], v[24:27]
	v_mfma_f32_16x16x32_bf16 v[8:11], v[166:169], v[220:223], v[8:11]
	v_mfma_f32_16x16x32_bf16 v[8:11], v[162:165], v[216:219], v[8:11]
	v_mfma_f32_16x16x32_bf16 v[4:7], v[170:173], v[216:219], v[4:7]
	v_mfma_f32_16x16x32_bf16 v[4:7], v[174:177], v[220:223], v[4:7]
	v_mfma_f32_16x16x32_bf16 v[20:23], v[174:177], v[212:215], v[20:23]
	v_mfma_f32_16x16x32_bf16 v[20:23], v[170:173], v[208:211], v[20:23]
	v_mfma_f32_16x16x32_bf16 v[36:39], v[170:173], v[186:189], v[36:39]
	v_mfma_f32_16x16x32_bf16 v[36:39], v[174:177], v[204:207], v[36:39]
	v_mfma_f32_16x16x32_bf16 v[52:55], v[174:177], v[182:185], v[52:55]
	v_mfma_f32_16x16x32_bf16 v[52:55], v[170:173], v[178:181], v[52:55]
	s_barrier
	s_setprio 0
	s_add_u32 s44, s44, 0x100
	s_addc_u32 s45, s45, 0
	s_add_u32 s65, s65, 0x100
	s_addc_u32 s67, s67, 0
	s_cmp_ge_i32 s72, s53
	s_mov_b32 s48, s72
	s_cbranch_scc1 .Lkloop_exit_4
.LBB0_1623:
	s_add_i32 s72, s48, 2
	s_add_u32 s73, s44, 0x80
	s_addc_u32 s49, s45, 0
	s_add_i32 s86, 0, 0x10000
	s_cmp_eq_u32 s57, s48
	s_cselect_b32 s49, s13, s49
	s_cselect_b32 s48, s12, s73
	s_cselect_b32 s77, s41, s67
	s_cselect_b32 s76, s40, s65
	s_add_i32 s73, 0, 0x14000
	v_add_u32_e32 v158, s86, v143
	v_add_u32_e32 v174, s73, v143
	ds_read_b128 v[146:149], v158
	ds_read_b128 v[178:181], v145
	ds_read_b128 v[150:153], v158 offset:1024
	ds_read_b128 v[182:185], v145 offset:1024
	ds_read_b128 v[204:207], v145 offset:3072
	ds_read_b128 v[186:189], v145 offset:2048
	ds_read_b128 v[208:211], v145 offset:4096
	ds_read_b128 v[212:215], v145 offset:5120
	v_lshl_add_u64 v[190:191], s[44:45], 0, v[138:139]
	s_add_i32 m0, s47, 0xc000
	ds_read_b128 v[220:223], v145 offset:7168
	ds_read_b128 v[216:219], v145 offset:6144
	ds_read_b128 v[154:157], v158 offset:2048
	ds_read_b128 v[158:161], v158 offset:3072
	ds_read_b128 v[162:165], v174
	ds_read_b128 v[166:169], v174 offset:1024
	ds_read_b128 v[170:173], v174 offset:2048
	ds_read_b128 v[174:177], v174 offset:3072
	global_load_lds_dwordx4 v[190:191], off
	v_lshl_add_u64 v[190:191], s[44:45], 0, v[140:141]
	s_add_i32 m0, s47, 0xe000
	s_nop 0
	global_load_lds_dwordx4 v[190:191], off
	s_waitcnt vmcnt(8)
	s_waitcnt lgkmcnt(14)
	s_setprio 1
	s_barrier
	v_mfma_f32_16x16x32_bf16 v[124:127], v[146:149], v[178:181], v[124:127]
	s_waitcnt lgkmcnt(12)
	v_mfma_f32_16x16x32_bf16 v[124:127], v[150:153], v[182:185], v[124:127]
	s_waitcnt lgkmcnt(11)
	v_mfma_f32_16x16x32_bf16 v[112:115], v[150:153], v[204:207], v[112:115]
	s_waitcnt lgkmcnt(10)
	v_mfma_f32_16x16x32_bf16 v[112:115], v[146:149], v[186:189], v[112:115]
	s_waitcnt lgkmcnt(9)
	v_mfma_f32_16x16x32_bf16 v[96:99], v[146:149], v[208:211], v[96:99]
	s_waitcnt lgkmcnt(8)
	v_mfma_f32_16x16x32_bf16 v[96:99], v[150:153], v[212:215], v[96:99]
	s_waitcnt lgkmcnt(7)
	v_mfma_f32_16x16x32_bf16 v[80:83], v[150:153], v[220:223], v[80:83]
	s_waitcnt lgkmcnt(6)
	v_mfma_f32_16x16x32_bf16 v[80:83], v[146:149], v[216:219], v[80:83]
	s_waitcnt lgkmcnt(5)
	v_mfma_f32_16x16x32_bf16 v[76:79], v[154:157], v[216:219], v[76:79]
	s_waitcnt lgkmcnt(4)
	v_mfma_f32_16x16x32_bf16 v[76:79], v[158:161], v[220:223], v[76:79]
	v_mfma_f32_16x16x32_bf16 v[92:95], v[158:161], v[212:215], v[92:95]
	v_mfma_f32_16x16x32_bf16 v[92:95], v[154:157], v[208:211], v[92:95]
	v_mfma_f32_16x16x32_bf16 v[108:111], v[154:157], v[186:189], v[108:111]
	v_mfma_f32_16x16x32_bf16 v[108:111], v[158:161], v[204:207], v[108:111]
	v_mfma_f32_16x16x32_bf16 v[128:131], v[158:161], v[182:185], v[128:131]
	v_mfma_f32_16x16x32_bf16 v[128:131], v[154:157], v[178:181], v[128:131]
	s_waitcnt lgkmcnt(3)
	v_mfma_f32_16x16x32_bf16 v[120:123], v[162:165], v[178:181], v[120:123]
	s_waitcnt lgkmcnt(2)
	v_mfma_f32_16x16x32_bf16 v[120:123], v[166:169], v[182:185], v[120:123]
	v_mfma_f32_16x16x32_bf16 v[104:107], v[166:169], v[204:207], v[104:107]
	v_mfma_f32_16x16x32_bf16 v[104:107], v[162:165], v[186:189], v[104:107]
	v_mfma_f32_16x16x32_bf16 v[88:91], v[162:165], v[208:211], v[88:91]
	v_mfma_f32_16x16x32_bf16 v[88:91], v[166:169], v[212:215], v[88:91]
	v_mfma_f32_16x16x32_bf16 v[72:75], v[166:169], v[220:223], v[72:75]
	v_mfma_f32_16x16x32_bf16 v[72:75], v[162:165], v[216:219], v[72:75]
	s_waitcnt lgkmcnt(1)
	v_mfma_f32_16x16x32_bf16 v[68:71], v[170:173], v[216:219], v[68:71]
	s_waitcnt lgkmcnt(0)
	v_mfma_f32_16x16x32_bf16 v[68:71], v[174:177], v[220:223], v[68:71]
	v_mfma_f32_16x16x32_bf16 v[84:87], v[174:177], v[212:215], v[84:87]
	v_mfma_f32_16x16x32_bf16 v[84:87], v[170:173], v[208:211], v[84:87]
	v_mfma_f32_16x16x32_bf16 v[100:103], v[170:173], v[186:189], v[100:103]
	v_mfma_f32_16x16x32_bf16 v[100:103], v[174:177], v[204:207], v[100:103]
	v_mfma_f32_16x16x32_bf16 v[116:119], v[174:177], v[182:185], v[116:119]
	v_mfma_f32_16x16x32_bf16 v[116:119], v[170:173], v[178:181], v[116:119]
	s_barrier
; #define PG8_STAGE(bufoff, gbase, voff) do { _Pragma("unroll") for (int _i = 0; _i < 2; ++_i) \
;         __builtin_amdgcn_global_load_lds((const unsigned*)((const char*)(gbase) + (voff)[_i]), (PG8_LAS unsigned*)(lds + (bufoff) + ldsw + _i * 8192), 16, 0, 0); } while (0)
; #define PG8_LDA(dst, b, h) do { _Pragma("unroll") for (int m = 0; m < 4; ++m) _Pragma("unroll") for (int k = 0; k < 2; ++k) dst[m][k] = *(const PG8_LAS bf16x8*)(lds + PG8_SA(b, h) + aoff + m * 2048 + k * 1024); } while (0)
; #define PG8_LDB(dst, b, h) do { _Pragma("unroll") for (int n = 0; n < 2; ++n) _Pragma("unroll") for (int k = 0; k < 2; ++k) dst[n][k] = *(const PG8_LAS bf16x8*)(lds + PG8_SB(b, h) + boff + n * 2048 + k * 1024); } while (0)
; #define PG8_WAIT_V(n) asm volatile("s_waitcnt vmcnt(" #n ")" ::: "memory")
; #define PG8_WAIT_L(n) asm volatile("s_waitcnt lgkmcnt(" #n ")" ::: "memory")
; #define PG8_BAR __builtin_amdgcn_s_barrier()
; #define PG8_SCHED __builtin_amdgcn_sched_barrier(0)
; template <class Epi, class Sched, bool ALIGN_EPI = false, bool SP2 = false, bool I8 = false>
; __device__ __forceinline__ void gemm_phase(PG8_LAS unsigned char* lds, const Gemm g, const Sched& S, const Epi& E) {
;     ...
;             PG8_LDA(At, 0, 1); PG8_STAGE(PG8_SB(0, 0), b2, voffB); PG8_STAGE(PG8_SB(0, 1), b2 + hstep, voffB); PG8_STAGE(PG8_SA(0, 0), a2, voffA);
;             PG8_WAIT_V(8); PG8_WAIT_L(0); PG8_BAR; PG8_MMA(1, 0, At, B0); PG8_MMA(1, 1, At, B1); PG8_BAR; PG8_SCHED;
;             PG8_LDB(B0, 1, 0); PG8_LDB(B1, 1, 1); PG8_SCHED; PG8_LDA(At, 1, 0); PG8_STAGE(PG8_SA(0, 1), a2 + hstep, voffA);
;             PG8_WAIT_V(8); PG8_WAIT_L(0); PG8_BAR; PG8_MMA(0, 0, At, B0); PG8_MMA(0, 1, At, B1); PG8_BAR; PG8_SCHED;
;             PG8_LDA(At, 1, 1); PG8_STAGE(PG8_SB(1, 0), b3, voffB); PG8_STAGE(PG8_SB(1, 1), b3 + hstep, voffB); PG8_STAGE(PG8_SA(1, 0), a3, voffA);
	s_setprio 0
	s_add_i32 s86, s86, s28
	v_lshl_add_u64 v[190:191], s[76:77], 0, v[2:3]
	s_mov_b32 m0, s86
	ds_read_b128 v[178:181], v145 offset:16384
	ds_read_b128 v[182:185], v145 offset:17408
	ds_read_b128 v[204:207], v145 offset:19456
	ds_read_b128 v[186:189], v145 offset:18432
	ds_read_b128 v[208:211], v145 offset:20480
	ds_read_b128 v[212:215], v145 offset:21504
	ds_read_b128 v[220:223], v145 offset:23552
	ds_read_b128 v[216:219], v145 offset:22528
	global_load_lds_dwordx4 v[190:191], off
	s_add_i32 m0, s86, 0x2000
	v_lshl_add_u64 v[224:225], s[76:77], 0, v[136:137]
	s_add_u32 s76, s76, s18
	s_addc_u32 s77, s77, s19
	s_add_i32 s73, s73, s28
	global_load_lds_dwordx4 v[224:225], off
	v_lshl_add_u64 v[226:227], s[76:77], 0, v[2:3]
	s_mov_b32 m0, s73
	v_lshl_add_u64 v[228:229], s[76:77], 0, v[136:137]
	global_load_lds_dwordx4 v[226:227], off
	s_add_i32 m0, s73, 0x2000
	v_lshl_add_u64 v[240:241], s[48:49], 0, v[132:133]
	global_load_lds_dwordx4 v[228:229], off
	v_lshl_add_u64 v[242:243], s[48:49], 0, v[134:135]
	s_waitcnt vmcnt(6)
	s_waitcnt lgkmcnt(7)
	s_setprio 1
	s_barrier
	v_mfma_f32_16x16x32_bf16 v[64:67], v[146:149], v[178:181], v[64:67]
	s_waitcnt lgkmcnt(6)
	v_mfma_f32_16x16x32_bf16 v[64:67], v[150:153], v[182:185], v[64:67]
	s_waitcnt lgkmcnt(5)
	v_mfma_f32_16x16x32_bf16 v[48:51], v[150:153], v[204:207], v[48:51]
	s_waitcnt lgkmcnt(4)
	v_mfma_f32_16x16x32_bf16 v[48:51], v[146:149], v[186:189], v[48:51]
	s_waitcnt lgkmcnt(3)
	v_mfma_f32_16x16x32_bf16 v[32:35], v[146:149], v[208:211], v[32:35]
	s_waitcnt lgkmcnt(2)
	v_mfma_f32_16x16x32_bf16 v[32:35], v[150:153], v[212:215], v[32:35]
	s_waitcnt lgkmcnt(1)
	v_mfma_f32_16x16x32_bf16 v[16:19], v[150:153], v[220:223], v[16:19]
	s_waitcnt lgkmcnt(0)
	v_mfma_f32_16x16x32_bf16 v[16:19], v[146:149], v[216:219], v[16:19]
	v_mfma_f32_16x16x32_bf16 v[12:15], v[154:157], v[216:219], v[12:15]
	v_mfma_f32_16x16x32_bf16 v[12:15], v[158:161], v[220:223], v[12:15]
	v_mfma_f32_16x16x32_bf16 v[28:31], v[158:161], v[212:215], v[28:31]
	v_mfma_f32_16x16x32_bf16 v[28:31], v[154:157], v[208:211], v[28:31]
	v_mfma_f32_16x16x32_bf16 v[44:47], v[154:157], v[186:189], v[44:47]
	v_mfma_f32_16x16x32_bf16 v[44:47], v[158:161], v[204:207], v[44:47]
	v_mfma_f32_16x16x32_bf16 v[60:63], v[158:161], v[182:185], v[60:63]
	v_mfma_f32_16x16x32_bf16 v[60:63], v[154:157], v[178:181], v[60:63]
	v_mfma_f32_16x16x32_bf16 v[56:59], v[162:165], v[178:181], v[56:59]
	v_mfma_f32_16x16x32_bf16 v[56:59], v[166:169], v[182:185], v[56:59]
	v_mfma_f32_16x16x32_bf16 v[40:43], v[166:169], v[204:207], v[40:43]
	v_mfma_f32_16x16x32_bf16 v[40:43], v[162:165], v[186:189], v[40:43]
	v_mfma_f32_16x16x32_bf16 v[24:27], v[162:165], v[208:211], v[24:27]
	v_mfma_f32_16x16x32_bf16 v[24:27], v[166:169], v[212:215], v[24:27]
	v_mfma_f32_16x16x32_bf16 v[8:11], v[166:169], v[220:223], v[8:11]
	v_mfma_f32_16x16x32_bf16 v[8:11], v[162:165], v[216:219], v[8:11]
	v_mfma_f32_16x16x32_bf16 v[4:7], v[170:173], v[216:219], v[4:7]
	v_mfma_f32_16x16x32_bf16 v[4:7], v[174:177], v[220:223], v[4:7]
	v_mfma_f32_16x16x32_bf16 v[20:23], v[174:177], v[212:215], v[20:23]
	v_mfma_f32_16x16x32_bf16 v[20:23], v[170:173], v[208:211], v[20:23]
	v_mfma_f32_16x16x32_bf16 v[36:39], v[170:173], v[186:189], v[36:39]
	v_mfma_f32_16x16x32_bf16 v[36:39], v[174:177], v[204:207], v[36:39]
	v_mfma_f32_16x16x32_bf16 v[52:55], v[174:177], v[182:185], v[52:55]
	v_mfma_f32_16x16x32_bf16 v[52:55], v[170:173], v[178:181], v[52:55]
	s_barrier
	s_setprio 0
	s_mov_b32 m0, s47
	s_nop 0
	global_load_lds_dwordx4 v[240:241], off
	s_mov_b32 m0, s50
	s_nop 0
	global_load_lds_dwordx4 v[242:243], off
	s_add_i32 s73, 0, 0x18000
	s_add_i32 s76, 0, 0x1c000
	v_add_u32_e32 v158, s73, v143
	v_add_u32_e32 v174, s76, v143
	ds_read_b128 v[146:149], v158
	ds_read_b128 v[178:181], v145 offset:32768
	ds_read_b128 v[150:153], v158 offset:1024
	ds_read_b128 v[182:185], v145 offset:33792
	ds_read_b128 v[204:207], v145 offset:35840
	ds_read_b128 v[186:189], v145 offset:34816
	ds_read_b128 v[208:211], v145 offset:36864
	ds_read_b128 v[212:215], v145 offset:37888
	s_add_u32 s48, s48, s18
	s_addc_u32 s49, s49, s19
	s_mov_b32 m0, s51
	ds_read_b128 v[220:223], v145 offset:39936
	ds_read_b128 v[216:219], v145 offset:38912
	ds_read_b128 v[154:157], v158 offset:2048
	ds_read_b128 v[158:161], v158 offset:3072
	ds_read_b128 v[162:165], v174
	ds_read_b128 v[166:169], v174 offset:1024
	ds_read_b128 v[170:173], v174 offset:2048
	ds_read_b128 v[174:177], v174 offset:3072
	global_load_lds_dwordx4 v132, s[48:49]
	s_mov_b32 m0, s52
	s_nop 0
	global_load_lds_dwordx4 v134, s[48:49]
	s_waitcnt vmcnt(8)
	s_waitcnt lgkmcnt(14)
	s_setprio 1
	s_barrier
; #define PG8_STAGE(bufoff, gbase, voff) do { _Pragma("unroll") for (int _i = 0; _i < 2; ++_i) \
;         __builtin_amdgcn_global_load_lds((const unsigned*)((const char*)(gbase) + (voff)[_i]), (PG8_LAS unsigned*)(lds + (bufoff) + ldsw + _i * 8192), 16, 0, 0); } while (0)
; #define PG8_LDA(dst, b, h) do { _Pragma("unroll") for (int m = 0; m < 4; ++m) _Pragma("unroll") for (int k = 0; k < 2; ++k) dst[m][k] = *(const PG8_LAS bf16x8*)(lds + PG8_SA(b, h) + aoff + m * 2048 + k * 1024); } while (0)
; #define PG8_WAIT_V(n) asm volatile("s_waitcnt vmcnt(" #n ")" ::: "memory")
; #define PG8_WAIT_L(n) asm volatile("s_waitcnt lgkmcnt(" #n ")" ::: "memory")
; #define PG8_BAR __builtin_amdgcn_s_barrier()
; #define PG8_SCHED __builtin_amdgcn_sched_barrier(0)
; template <class Epi, class Sched, bool ALIGN_EPI = false, bool SP2 = false, bool I8 = false>
; __device__ __forceinline__ void gemm_phase(PG8_LAS unsigned char* lds, const Gemm g, const Sched& S, const Epi& E) {
;     ...
;         for (int t = 0; t < nt; t += 2) {
;     ...
;             PG8_WAIT_V(8); PG8_WAIT_L(0); PG8_BAR; PG8_MMA(0, 0, At, B0); PG8_MMA(0, 1, At, B1); PG8_BAR; PG8_SCHED;
;             PG8_LDA(At, 1, 1); PG8_STAGE(PG8_SB(1, 0), b3, voffB); PG8_STAGE(PG8_SB(1, 1), b3 + hstep, voffB); PG8_STAGE(PG8_SA(1, 0), a3, voffA);
;             PG8_WAIT_V(8); PG8_WAIT_L(0); PG8_BAR; PG8_MMA(1, 0, At, B0); PG8_MMA(1, 1, At, B1); PG8_BAR; PG8_SCHED;
	v_mfma_f32_16x16x32_bf16 v[124:127], v[146:149], v[178:181], v[124:127]
	s_waitcnt lgkmcnt(12)
	v_mfma_f32_16x16x32_bf16 v[124:127], v[150:153], v[182:185], v[124:127]
	s_waitcnt lgkmcnt(11)
	v_mfma_f32_16x16x32_bf16 v[112:115], v[150:153], v[204:207], v[112:115]
	s_waitcnt lgkmcnt(10)
	v_mfma_f32_16x16x32_bf16 v[112:115], v[146:149], v[186:189], v[112:115]
	s_waitcnt lgkmcnt(9)
	v_mfma_f32_16x16x32_bf16 v[96:99], v[146:149], v[208:211], v[96:99]
	s_waitcnt lgkmcnt(8)
	v_mfma_f32_16x16x32_bf16 v[96:99], v[150:153], v[212:215], v[96:99]
	s_waitcnt lgkmcnt(7)
	v_mfma_f32_16x16x32_bf16 v[80:83], v[150:153], v[220:223], v[80:83]
	s_waitcnt lgkmcnt(6)
	v_mfma_f32_16x16x32_bf16 v[80:83], v[146:149], v[216:219], v[80:83]
	s_waitcnt lgkmcnt(5)
	v_mfma_f32_16x16x32_bf16 v[76:79], v[154:157], v[216:219], v[76:79]
	s_waitcnt lgkmcnt(4)
	v_mfma_f32_16x16x32_bf16 v[76:79], v[158:161], v[220:223], v[76:79]
	v_mfma_f32_16x16x32_bf16 v[92:95], v[158:161], v[212:215], v[92:95]
	v_mfma_f32_16x16x32_bf16 v[92:95], v[154:157], v[208:211], v[92:95]
	v_mfma_f32_16x16x32_bf16 v[108:111], v[154:157], v[186:189], v[108:111]
	v_mfma_f32_16x16x32_bf16 v[108:111], v[158:161], v[204:207], v[108:111]
	v_mfma_f32_16x16x32_bf16 v[128:131], v[158:161], v[182:185], v[128:131]
	v_mfma_f32_16x16x32_bf16 v[128:131], v[154:157], v[178:181], v[128:131]
	s_waitcnt lgkmcnt(3)
	v_mfma_f32_16x16x32_bf16 v[120:123], v[162:165], v[178:181], v[120:123]
	s_waitcnt lgkmcnt(2)
	v_mfma_f32_16x16x32_bf16 v[120:123], v[166:169], v[182:185], v[120:123]
	v_mfma_f32_16x16x32_bf16 v[104:107], v[166:169], v[204:207], v[104:107]
	v_mfma_f32_16x16x32_bf16 v[104:107], v[162:165], v[186:189], v[104:107]
	v_mfma_f32_16x16x32_bf16 v[88:91], v[162:165], v[208:211], v[88:91]
	v_mfma_f32_16x16x32_bf16 v[88:91], v[166:169], v[212:215], v[88:91]
	v_mfma_f32_16x16x32_bf16 v[72:75], v[166:169], v[220:223], v[72:75]
	v_mfma_f32_16x16x32_bf16 v[72:75], v[162:165], v[216:219], v[72:75]
	s_waitcnt lgkmcnt(1)
	v_mfma_f32_16x16x32_bf16 v[68:71], v[170:173], v[216:219], v[68:71]
	s_waitcnt lgkmcnt(0)
	v_mfma_f32_16x16x32_bf16 v[68:71], v[174:177], v[220:223], v[68:71]
	v_mfma_f32_16x16x32_bf16 v[84:87], v[174:177], v[212:215], v[84:87]
	v_mfma_f32_16x16x32_bf16 v[84:87], v[170:173], v[208:211], v[84:87]
	v_mfma_f32_16x16x32_bf16 v[100:103], v[170:173], v[186:189], v[100:103]
	v_mfma_f32_16x16x32_bf16 v[100:103], v[174:177], v[204:207], v[100:103]
	v_mfma_f32_16x16x32_bf16 v[116:119], v[174:177], v[182:185], v[116:119]
	v_mfma_f32_16x16x32_bf16 v[116:119], v[170:173], v[178:181], v[116:119]
	s_barrier
	s_setprio 0
	s_add_i32 s48, s73, s28
	v_lshl_add_u64 v[190:191], v[190:191], 0, s[84:85]
	s_mov_b32 m0, s48
	ds_read_b128 v[178:181], v145 offset:49152
	ds_read_b128 v[182:185], v145 offset:50176
	ds_read_b128 v[204:207], v145 offset:52224
	ds_read_b128 v[186:189], v145 offset:51200
	ds_read_b128 v[208:211], v145 offset:53248
	ds_read_b128 v[212:215], v145 offset:54272
	ds_read_b128 v[220:223], v145 offset:56320
	ds_read_b128 v[216:219], v145 offset:55296
	global_load_lds_dwordx4 v[190:191], off
	v_lshl_add_u64 v[190:191], v[224:225], 0, s[84:85]
	s_add_i32 m0, s48, 0x2000
	s_add_i32 s48, s76, s28
	global_load_lds_dwordx4 v[190:191], off
	v_lshl_add_u64 v[190:191], v[226:227], 0, s[84:85]
	s_mov_b32 m0, s48
	s_nop 0
	global_load_lds_dwordx4 v[190:191], off
	v_lshl_add_u64 v[190:191], v[228:229], 0, s[84:85]
	s_add_i32 m0, s48, 0x2000
	s_nop 0
	global_load_lds_dwordx4 v[190:191], off
	v_lshl_add_u64 v[190:191], v[240:241], 0, s[84:85]
	s_mov_b32 m0, s55
	s_nop 0
	global_load_lds_dwordx4 v[190:191], off
	v_lshl_add_u64 v[190:191], v[242:243], 0, s[84:85]
	s_mov_b32 m0, s56
	s_nop 0
	global_load_lds_dwordx4 v[190:191], off
	s_waitcnt vmcnt(8)
	s_waitcnt lgkmcnt(7)
	s_setprio 1
	s_barrier
	v_mfma_f32_16x16x32_bf16 v[64:67], v[146:149], v[178:181], v[64:67]
	s_waitcnt lgkmcnt(6)
	v_mfma_f32_16x16x32_bf16 v[64:67], v[150:153], v[182:185], v[64:67]
	s_waitcnt lgkmcnt(5)
	v_mfma_f32_16x16x32_bf16 v[48:51], v[150:153], v[204:207], v[48:51]
	s_waitcnt lgkmcnt(4)
	v_mfma_f32_16x16x32_bf16 v[48:51], v[146:149], v[186:189], v[48:51]
	s_waitcnt lgkmcnt(3)
	v_mfma_f32_16x16x32_bf16 v[32:35], v[146:149], v[208:211], v[32:35]
	s_waitcnt lgkmcnt(2)
	v_mfma_f32_16x16x32_bf16 v[32:35], v[150:153], v[212:215], v[32:35]
	s_waitcnt lgkmcnt(1)
	v_mfma_f32_16x16x32_bf16 v[16:19], v[150:153], v[220:223], v[16:19]
	s_waitcnt lgkmcnt(0)
	v_mfma_f32_16x16x32_bf16 v[16:19], v[146:149], v[216:219], v[16:19]
	v_mfma_f32_16x16x32_bf16 v[12:15], v[154:157], v[216:219], v[12:15]
	v_mfma_f32_16x16x32_bf16 v[12:15], v[158:161], v[220:223], v[12:15]
	v_mfma_f32_16x16x32_bf16 v[28:31], v[158:161], v[212:215], v[28:31]
	v_mfma_f32_16x16x32_bf16 v[28:31], v[154:157], v[208:211], v[28:31]
	v_mfma_f32_16x16x32_bf16 v[44:47], v[154:157], v[186:189], v[44:47]
	v_mfma_f32_16x16x32_bf16 v[44:47], v[158:161], v[204:207], v[44:47]
	v_mfma_f32_16x16x32_bf16 v[60:63], v[158:161], v[182:185], v[60:63]
	v_mfma_f32_16x16x32_bf16 v[60:63], v[154:157], v[178:181], v[60:63]
	v_mfma_f32_16x16x32_bf16 v[56:59], v[162:165], v[178:181], v[56:59]
	v_mfma_f32_16x16x32_bf16 v[56:59], v[166:169], v[182:185], v[56:59]
	v_mfma_f32_16x16x32_bf16 v[40:43], v[166:169], v[204:207], v[40:43]
	v_mfma_f32_16x16x32_bf16 v[40:43], v[162:165], v[186:189], v[40:43]
	v_mfma_f32_16x16x32_bf16 v[24:27], v[162:165], v[208:211], v[24:27]
	v_mfma_f32_16x16x32_bf16 v[24:27], v[166:169], v[212:215], v[24:27]
	v_mfma_f32_16x16x32_bf16 v[8:11], v[166:169], v[220:223], v[8:11]
	v_mfma_f32_16x16x32_bf16 v[8:11], v[162:165], v[216:219], v[8:11]
	v_mfma_f32_16x16x32_bf16 v[4:7], v[170:173], v[216:219], v[4:7]
	v_mfma_f32_16x16x32_bf16 v[4:7], v[174:177], v[220:223], v[4:7]
	v_mfma_f32_16x16x32_bf16 v[20:23], v[174:177], v[212:215], v[20:23]
	v_mfma_f32_16x16x32_bf16 v[20:23], v[170:173], v[208:211], v[20:23]
	v_mfma_f32_16x16x32_bf16 v[36:39], v[170:173], v[186:189], v[36:39]
	v_mfma_f32_16x16x32_bf16 v[36:39], v[174:177], v[204:207], v[36:39]
	v_mfma_f32_16x16x32_bf16 v[52:55], v[174:177], v[182:185], v[52:55]
	v_mfma_f32_16x16x32_bf16 v[52:55], v[170:173], v[178:181], v[52:55]
	s_barrier
	s_setprio 0
	s_add_u32 s44, s44, 0x100
	s_addc_u32 s45, s45, 0
	s_add_u32 s65, s65, 0x100
	s_addc_u32 s67, s67, 0
	s_cmp_ge_i32 s72, s53
	s_mov_b32 s48, s72
	s_cbranch_scc0 .LBB0_1623

; #define PG8_STAGE(bufoff, gbase, voff) do { _Pragma("unroll") for (int _i = 0; _i < 2; ++_i) \
;         __builtin_amdgcn_global_load_lds((const unsigned*)((const char*)(gbase) + (voff)[_i]), (PG8_LAS unsigned*)(lds + (bufoff) + ldsw + _i * 8192), 16, 0, 0); } while (0)
; #define PG8_LDA(dst, b, h) do { _Pragma("unroll") for (int m = 0; m < 4; ++m) _Pragma("unroll") for (int k = 0; k < 2; ++k) dst[m][k] = *(const PG8_LAS bf16x8*)(lds + PG8_SA(b, h) + aoff + m * 2048 + k * 1024); } while (0)
; #define PG8_LDB(dst, b, h) do { _Pragma("unroll") for (int n = 0; n < 2; ++n) _Pragma("unroll") for (int k = 0; k < 2; ++k) dst[n][k] = *(const PG8_LAS bf16x8*)(lds + PG8_SB(b, h) + boff + n * 2048 + k * 1024); } while (0)
; #define PG8_WAIT_V(n) asm volatile("s_waitcnt vmcnt(" #n ")" ::: "memory")
; #define PG8_WAIT_L(n) asm volatile("s_waitcnt lgkmcnt(" #n ")" ::: "memory")
; #define PG8_BAR __builtin_amdgcn_s_barrier()
; #define PG8_SCHED __builtin_amdgcn_sched_barrier(0)
; template <class Epi, class Sched, bool ALIGN_EPI = false, bool SP2 = false, bool I8 = false>
; __device__ __forceinline__ void gemm_phase(PG8_LAS unsigned char* lds, const Gemm g, const Sched& S, const Epi& E) {
;     ...
;         for (int t = 0; t < nt; t += 2) {
;             const bool last = (t == nt - 2);
;             const char* a1 = cA + (size_t)(t + 1) * kstep;
;             const char* a2 = last ? nA : cA + (size_t)(t + 2) * kstep; const char* b2 = last ? nB : cB + (size_t)(t + 2) * kstep;
;             const char* a3 = a2 + kstep; const char* b3 = b2 + kstep;
;             if (last && has_next) S.a_ready(nxt);
;             if constexpr (SP2) {
;             PG8_LDB(B0, 0, 0); PG8_LDB(B1, 0, 1); PG8_SCHED; PG8_LDA(At, 0, 0); PG8_STAGE(PG8_SA(1, 1), a1 + hstep, voffA);
;             PG8_WAIT_V(8); PG8_WAIT_L(0); PG8_BAR; PG8_MMA(0, 0, At, B0); PG8_MMA(0, 1, At, B1); PG8_BAR; PG8_SCHED;
;             PG8_LDA(At, 0, 1); PG8_STAGE(PG8_SB(0, 0), b2, voffB); PG8_STAGE(PG8_SB(0, 1), b2 + hstep, voffB); PG8_STAGE(PG8_SA(0, 0), a2, voffA);
;             PG8_WAIT_V(8); PG8_WAIT_L(0); PG8_BAR; PG8_MMA(1, 0, At, B0); PG8_MMA(1, 1, At, B1); PG8_BAR; PG8_SCHED;
.LBB0_1699:
	s_add_u32 s53, s24, 0x100
	s_addc_u32 s54, s25, 0
	s_mov_b32 s55, -2
	s_add_u32 s24, s22, 0x100
	s_addc_u32 s25, s23, 0
	s_add_i32 s56, 0, 0x10000
	s_cmpk_eq_i32 s55, 0xa8
	s_cselect_b32 s37, s13, s25
	s_cselect_b32 s36, s12, s24
	s_cselect_b32 s27, s21, s54
	s_cselect_b32 s26, s20, s53
	s_add_i32 s57, 0, 0x14000
	v_add_u32_e32 v144, s56, v240
	v_add_u32_e32 v160, s57, v240
	ds_read_b128 v[124:127], v144
	ds_read_b128 v[164:167], v242
	ds_read_b128 v[128:131], v144 offset:1024
	ds_read_b128 v[168:171], v242 offset:1024
	ds_read_b128 v[176:179], v242 offset:3072
	ds_read_b128 v[172:175], v242 offset:2048
	ds_read_b128 v[180:183], v242 offset:4096
	ds_read_b128 v[184:187], v242 offset:5120
	v_lshl_add_u64 v[218:219], s[22:23], 0, v[210:211]
	s_add_i32 m0, s42, 0xc000
	ds_read_b128 v[214:217], v242 offset:7168
	ds_read_b128 v[188:191], v242 offset:6144
	ds_read_b128 v[132:135], v144 offset:2048
	ds_read_b128 v[144:147], v144 offset:3072
	ds_read_b128 v[148:151], v160
	ds_read_b128 v[152:155], v160 offset:1024
	ds_read_b128 v[156:159], v160 offset:2048
	ds_read_b128 v[160:163], v160 offset:3072
	global_load_lds_dwordx4 v[218:219], off
	v_lshl_add_u64 v[218:219], s[22:23], 0, v[212:213]
	s_add_i32 m0, s42, 0xe000
	s_nop 0
	global_load_lds_dwordx4 v[218:219], off
	s_waitcnt vmcnt(8)
	s_waitcnt lgkmcnt(14)
	s_setprio 1
	s_barrier
	v_mfma_f32_16x16x32_bf16 v[140:143], v[124:127], v[164:167], 0
	s_waitcnt lgkmcnt(12)
	v_mfma_f32_16x16x32_bf16 v[140:143], v[128:131], v[168:171], v[140:143]
	s_waitcnt lgkmcnt(11)
	v_mfma_f32_16x16x32_bf16 v[112:115], v[128:131], v[176:179], 0
	s_waitcnt lgkmcnt(10)
	v_mfma_f32_16x16x32_bf16 v[112:115], v[124:127], v[172:175], v[112:115]
	s_waitcnt lgkmcnt(9)
	v_mfma_f32_16x16x32_bf16 v[96:99], v[124:127], v[180:183], 0
	s_waitcnt lgkmcnt(8)
	v_mfma_f32_16x16x32_bf16 v[96:99], v[128:131], v[184:187], v[96:99]
	s_waitcnt lgkmcnt(7)
	v_mfma_f32_16x16x32_bf16 v[80:83], v[128:131], v[214:217], 0
	s_waitcnt lgkmcnt(6)
	v_mfma_f32_16x16x32_bf16 v[80:83], v[124:127], v[188:191], v[80:83]
	s_waitcnt lgkmcnt(5)
	v_mfma_f32_16x16x32_bf16 v[76:79], v[132:135], v[188:191], 0
	s_waitcnt lgkmcnt(4)
	v_mfma_f32_16x16x32_bf16 v[76:79], v[144:147], v[214:217], v[76:79]
	v_mfma_f32_16x16x32_bf16 v[92:95], v[144:147], v[184:187], 0
	v_mfma_f32_16x16x32_bf16 v[92:95], v[132:135], v[180:183], v[92:95]
	v_mfma_f32_16x16x32_bf16 v[108:111], v[132:135], v[172:175], 0
	v_mfma_f32_16x16x32_bf16 v[108:111], v[144:147], v[176:179], v[108:111]
	v_mfma_f32_16x16x32_bf16 v[136:139], v[144:147], v[168:171], 0
	v_mfma_f32_16x16x32_bf16 v[136:139], v[132:135], v[164:167], v[136:139]
	s_waitcnt lgkmcnt(3)
	v_mfma_f32_16x16x32_bf16 v[120:123], v[148:151], v[164:167], 0
	s_waitcnt lgkmcnt(2)
	v_mfma_f32_16x16x32_bf16 v[120:123], v[152:155], v[168:171], v[120:123]
	v_mfma_f32_16x16x32_bf16 v[104:107], v[152:155], v[176:179], 0
	v_mfma_f32_16x16x32_bf16 v[104:107], v[148:151], v[172:175], v[104:107]
	v_mfma_f32_16x16x32_bf16 v[88:91], v[148:151], v[180:183], 0
	v_mfma_f32_16x16x32_bf16 v[88:91], v[152:155], v[184:187], v[88:91]
	v_mfma_f32_16x16x32_bf16 v[72:75], v[152:155], v[214:217], 0
	v_mfma_f32_16x16x32_bf16 v[72:75], v[148:151], v[188:191], v[72:75]
	s_waitcnt lgkmcnt(1)
	v_mfma_f32_16x16x32_bf16 v[68:71], v[156:159], v[188:191], 0
	s_waitcnt lgkmcnt(0)
	v_mfma_f32_16x16x32_bf16 v[68:71], v[160:163], v[214:217], v[68:71]
	v_mfma_f32_16x16x32_bf16 v[84:87], v[160:163], v[184:187], 0
	v_mfma_f32_16x16x32_bf16 v[84:87], v[156:159], v[180:183], v[84:87]
	v_mfma_f32_16x16x32_bf16 v[100:103], v[156:159], v[172:175], 0
	v_mfma_f32_16x16x32_bf16 v[100:103], v[160:163], v[176:179], v[100:103]
	v_mfma_f32_16x16x32_bf16 v[116:119], v[160:163], v[168:171], 0
	v_mfma_f32_16x16x32_bf16 v[116:119], v[156:159], v[164:167], v[116:119]
	s_barrier
	s_setprio 0
	s_add_i32 s22, s56, s41
	v_lshl_add_u64 v[218:219], s[26:27], 0, v[2:3]
	s_mov_b32 m0, s22
	ds_read_b128 v[164:167], v242 offset:16384
	ds_read_b128 v[168:171], v242 offset:17408
	ds_read_b128 v[176:179], v242 offset:19456
	ds_read_b128 v[172:175], v242 offset:18432
	ds_read_b128 v[180:183], v242 offset:20480
	ds_read_b128 v[184:187], v242 offset:21504
	ds_read_b128 v[214:217], v242 offset:23552
	ds_read_b128 v[188:191], v242 offset:22528
	global_load_lds_dwordx4 v[218:219], off
	s_add_i32 m0, s22, 0x2000
	s_add_u32 s22, s26, 0x2b0000
	v_lshl_add_u64 v[220:221], s[26:27], 0, v[204:205]
	s_addc_u32 s23, s27, 0
	s_add_i32 s56, s57, s41
	global_load_lds_dwordx4 v[220:221], off
	s_mov_b32 m0, s56
	v_lshl_add_u64 v[224:225], s[36:37], 0, v[206:207]
	global_load_lds_dwordx4 v2, s[22:23]
	s_add_i32 m0, s56, 0x2000
	s_nop 0
	global_load_lds_dwordx4 v204, s[22:23]
	v_lshl_add_u64 v[222:223], s[36:37], 0, v[208:209]
	s_waitcnt vmcnt(6)
	s_waitcnt lgkmcnt(7)
	s_setprio 1
	s_barrier
; #define PG8_STAGE(bufoff, gbase, voff) do { _Pragma("unroll") for (int _i = 0; _i < 2; ++_i) \
;         __builtin_amdgcn_global_load_lds((const unsigned*)((const char*)(gbase) + (voff)[_i]), (PG8_LAS unsigned*)(lds + (bufoff) + ldsw + _i * 8192), 16, 0, 0); } while (0)
; #define PG8_LDA(dst, b, h) do { _Pragma("unroll") for (int m = 0; m < 4; ++m) _Pragma("unroll") for (int k = 0; k < 2; ++k) dst[m][k] = *(const PG8_LAS bf16x8*)(lds + PG8_SA(b, h) + aoff + m * 2048 + k * 1024); } while (0)
; #define PG8_LDB(dst, b, h) do { _Pragma("unroll") for (int n = 0; n < 2; ++n) _Pragma("unroll") for (int k = 0; k < 2; ++k) dst[n][k] = *(const PG8_LAS bf16x8*)(lds + PG8_SB(b, h) + boff + n * 2048 + k * 1024); } while (0)
; #define PG8_WAIT_V(n) asm volatile("s_waitcnt vmcnt(" #n ")" ::: "memory")
; #define PG8_WAIT_L(n) asm volatile("s_waitcnt lgkmcnt(" #n ")" ::: "memory")
; #define PG8_BAR __builtin_amdgcn_s_barrier()
; #define PG8_SCHED __builtin_amdgcn_sched_barrier(0)
; template <class Epi, class Sched, bool ALIGN_EPI = false, bool SP2 = false, bool I8 = false>
; __device__ __forceinline__ void gemm_phase(PG8_LAS unsigned char* lds, const Gemm g, const Sched& S, const Epi& E) {
;     ...
;             PG8_WAIT_V(8); PG8_WAIT_L(0); PG8_BAR; PG8_MMA(1, 0, At, B0); PG8_MMA(1, 1, At, B1); PG8_BAR; PG8_SCHED;
;             PG8_LDB(B0, 1, 0); PG8_LDB(B1, 1, 1); PG8_SCHED; PG8_LDA(At, 1, 0); PG8_STAGE(PG8_SA(0, 1), a2 + hstep, voffA);
;             PG8_WAIT_V(8); PG8_WAIT_L(0); PG8_BAR; PG8_MMA(0, 0, At, B0); PG8_MMA(0, 1, At, B1); PG8_BAR; PG8_SCHED;
;             PG8_LDA(At, 1, 1); PG8_STAGE(PG8_SB(1, 0), b3, voffB); PG8_STAGE(PG8_SB(1, 1), b3 + hstep, voffB); PG8_STAGE(PG8_SA(1, 0), a3, voffA);
	v_mfma_f32_16x16x32_bf16 v[64:67], v[124:127], v[164:167], 0
	s_waitcnt lgkmcnt(6)
	v_mfma_f32_16x16x32_bf16 v[64:67], v[128:131], v[168:171], v[64:67]
	s_waitcnt lgkmcnt(5)
	v_mfma_f32_16x16x32_bf16 v[48:51], v[128:131], v[176:179], 0
	s_waitcnt lgkmcnt(4)
	v_mfma_f32_16x16x32_bf16 v[48:51], v[124:127], v[172:175], v[48:51]
	s_waitcnt lgkmcnt(3)
	v_mfma_f32_16x16x32_bf16 v[32:35], v[124:127], v[180:183], 0
	s_waitcnt lgkmcnt(2)
	v_mfma_f32_16x16x32_bf16 v[32:35], v[128:131], v[184:187], v[32:35]
	s_waitcnt lgkmcnt(1)
	v_mfma_f32_16x16x32_bf16 v[16:19], v[128:131], v[214:217], 0
	s_waitcnt lgkmcnt(0)
	v_mfma_f32_16x16x32_bf16 v[16:19], v[124:127], v[188:191], v[16:19]
	v_mfma_f32_16x16x32_bf16 v[12:15], v[132:135], v[188:191], 0
	v_mfma_f32_16x16x32_bf16 v[12:15], v[144:147], v[214:217], v[12:15]
	v_mfma_f32_16x16x32_bf16 v[28:31], v[144:147], v[184:187], 0
	v_mfma_f32_16x16x32_bf16 v[28:31], v[132:135], v[180:183], v[28:31]
	v_mfma_f32_16x16x32_bf16 v[44:47], v[132:135], v[172:175], 0
	v_mfma_f32_16x16x32_bf16 v[44:47], v[144:147], v[176:179], v[44:47]
	v_mfma_f32_16x16x32_bf16 v[60:63], v[144:147], v[168:171], 0
	v_mfma_f32_16x16x32_bf16 v[60:63], v[132:135], v[164:167], v[60:63]
	v_mfma_f32_16x16x32_bf16 v[56:59], v[148:151], v[164:167], 0
	v_mfma_f32_16x16x32_bf16 v[56:59], v[152:155], v[168:171], v[56:59]
	v_mfma_f32_16x16x32_bf16 v[40:43], v[152:155], v[176:179], 0
	v_mfma_f32_16x16x32_bf16 v[40:43], v[148:151], v[172:175], v[40:43]
	v_mfma_f32_16x16x32_bf16 v[24:27], v[148:151], v[180:183], 0
	v_mfma_f32_16x16x32_bf16 v[24:27], v[152:155], v[184:187], v[24:27]
	v_mfma_f32_16x16x32_bf16 v[8:11], v[152:155], v[214:217], 0
	v_mfma_f32_16x16x32_bf16 v[8:11], v[148:151], v[188:191], v[8:11]
	v_mfma_f32_16x16x32_bf16 v[4:7], v[156:159], v[188:191], 0
	v_mfma_f32_16x16x32_bf16 v[4:7], v[160:163], v[214:217], v[4:7]
	v_mfma_f32_16x16x32_bf16 v[20:23], v[160:163], v[184:187], 0
	v_mfma_f32_16x16x32_bf16 v[20:23], v[156:159], v[180:183], v[20:23]
	v_mfma_f32_16x16x32_bf16 v[36:39], v[156:159], v[172:175], 0
	v_mfma_f32_16x16x32_bf16 v[36:39], v[160:163], v[176:179], v[36:39]
	v_mfma_f32_16x16x32_bf16 v[52:55], v[160:163], v[168:171], 0
	v_mfma_f32_16x16x32_bf16 v[52:55], v[156:159], v[164:167], v[52:55]
	s_barrier
	s_setprio 0
	s_mov_b32 m0, s42
	s_nop 0
	global_load_lds_dwordx4 v[222:223], off
	s_mov_b32 m0, s43
	s_nop 0
	global_load_lds_dwordx4 v[224:225], off
	s_add_i32 s56, 0, 0x18000
	s_add_i32 s57, 0, 0x1c000
	v_add_u32_e32 v144, s56, v240
	v_add_u32_e32 v160, s57, v240
	ds_read_b128 v[124:127], v144
	ds_read_b128 v[164:167], v242 offset:32768
	ds_read_b128 v[128:131], v144 offset:1024
	ds_read_b128 v[168:171], v242 offset:33792
	ds_read_b128 v[176:179], v242 offset:35840
	ds_read_b128 v[172:175], v242 offset:34816
	ds_read_b128 v[180:183], v242 offset:36864
	ds_read_b128 v[184:187], v242 offset:37888
	s_add_u32 s22, s36, 0x2b0000
	s_addc_u32 s23, s37, 0
	s_mov_b32 m0, s44
	ds_read_b128 v[214:217], v242 offset:39936
	ds_read_b128 v[188:191], v242 offset:38912
	ds_read_b128 v[132:135], v144 offset:2048
	ds_read_b128 v[144:147], v144 offset:3072
	ds_read_b128 v[148:151], v160
	ds_read_b128 v[152:155], v160 offset:1024
	ds_read_b128 v[156:159], v160 offset:2048
	ds_read_b128 v[160:163], v160 offset:3072
	global_load_lds_dwordx4 v208, s[22:23]
	s_mov_b32 m0, s45
	s_nop 0
	global_load_lds_dwordx4 v206, s[22:23]
	s_waitcnt vmcnt(8)
	s_waitcnt lgkmcnt(14)
	s_setprio 1
	s_barrier
	v_mfma_f32_16x16x32_bf16 v[140:143], v[124:127], v[164:167], v[140:143]
	s_waitcnt lgkmcnt(12)
	v_mfma_f32_16x16x32_bf16 v[140:143], v[128:131], v[168:171], v[140:143]
	s_waitcnt lgkmcnt(11)
	v_mfma_f32_16x16x32_bf16 v[112:115], v[128:131], v[176:179], v[112:115]
	s_waitcnt lgkmcnt(10)
	v_mfma_f32_16x16x32_bf16 v[112:115], v[124:127], v[172:175], v[112:115]
	s_waitcnt lgkmcnt(9)
	v_mfma_f32_16x16x32_bf16 v[96:99], v[124:127], v[180:183], v[96:99]
	s_waitcnt lgkmcnt(8)
	v_mfma_f32_16x16x32_bf16 v[96:99], v[128:131], v[184:187], v[96:99]
	s_waitcnt lgkmcnt(7)
	v_mfma_f32_16x16x32_bf16 v[80:83], v[128:131], v[214:217], v[80:83]
	s_waitcnt lgkmcnt(6)
	v_mfma_f32_16x16x32_bf16 v[80:83], v[124:127], v[188:191], v[80:83]
	s_waitcnt lgkmcnt(5)
	v_mfma_f32_16x16x32_bf16 v[76:79], v[132:135], v[188:191], v[76:79]
	s_waitcnt lgkmcnt(4)
	v_mfma_f32_16x16x32_bf16 v[76:79], v[144:147], v[214:217], v[76:79]
	v_mfma_f32_16x16x32_bf16 v[92:95], v[144:147], v[184:187], v[92:95]
	v_mfma_f32_16x16x32_bf16 v[92:95], v[132:135], v[180:183], v[92:95]
	v_mfma_f32_16x16x32_bf16 v[108:111], v[132:135], v[172:175], v[108:111]
	v_mfma_f32_16x16x32_bf16 v[108:111], v[144:147], v[176:179], v[108:111]
	v_mfma_f32_16x16x32_bf16 v[136:139], v[144:147], v[168:171], v[136:139]
	v_mfma_f32_16x16x32_bf16 v[136:139], v[132:135], v[164:167], v[136:139]
	s_waitcnt lgkmcnt(3)
	v_mfma_f32_16x16x32_bf16 v[120:123], v[148:151], v[164:167], v[120:123]
	s_waitcnt lgkmcnt(2)
	v_mfma_f32_16x16x32_bf16 v[120:123], v[152:155], v[168:171], v[120:123]
	v_mfma_f32_16x16x32_bf16 v[104:107], v[152:155], v[176:179], v[104:107]
	v_mfma_f32_16x16x32_bf16 v[104:107], v[148:151], v[172:175], v[104:107]
	v_mfma_f32_16x16x32_bf16 v[88:91], v[148:151], v[180:183], v[88:91]
	v_mfma_f32_16x16x32_bf16 v[88:91], v[152:155], v[184:187], v[88:91]
	v_mfma_f32_16x16x32_bf16 v[72:75], v[152:155], v[214:217], v[72:75]
	v_mfma_f32_16x16x32_bf16 v[72:75], v[148:151], v[188:191], v[72:75]
	s_waitcnt lgkmcnt(1)
	v_mfma_f32_16x16x32_bf16 v[68:71], v[156:159], v[188:191], v[68:71]
	s_waitcnt lgkmcnt(0)
	v_mfma_f32_16x16x32_bf16 v[68:71], v[160:163], v[214:217], v[68:71]
	v_mfma_f32_16x16x32_bf16 v[84:87], v[160:163], v[184:187], v[84:87]
	v_mfma_f32_16x16x32_bf16 v[84:87], v[156:159], v[180:183], v[84:87]
	v_mfma_f32_16x16x32_bf16 v[100:103], v[156:159], v[172:175], v[100:103]
	v_mfma_f32_16x16x32_bf16 v[100:103], v[160:163], v[176:179], v[100:103]
	v_mfma_f32_16x16x32_bf16 v[116:119], v[160:163], v[168:171], v[116:119]
	v_mfma_f32_16x16x32_bf16 v[116:119], v[156:159], v[164:167], v[116:119]
	s_barrier
; #define PG8_STAGE(bufoff, gbase, voff) do { _Pragma("unroll") for (int _i = 0; _i < 2; ++_i) \
;         __builtin_amdgcn_global_load_lds((const unsigned*)((const char*)(gbase) + (voff)[_i]), (PG8_LAS unsigned*)(lds + (bufoff) + ldsw + _i * 8192), 16, 0, 0); } while (0)
; #define PG8_LDA(dst, b, h) do { _Pragma("unroll") for (int m = 0; m < 4; ++m) _Pragma("unroll") for (int k = 0; k < 2; ++k) dst[m][k] = *(const PG8_LAS bf16x8*)(lds + PG8_SA(b, h) + aoff + m * 2048 + k * 1024); } while (0)
; #define PG8_WAIT_V(n) asm volatile("s_waitcnt vmcnt(" #n ")" ::: "memory")
; #define PG8_WAIT_L(n) asm volatile("s_waitcnt lgkmcnt(" #n ")" ::: "memory")
; #define PG8_BAR __builtin_amdgcn_s_barrier()
; template <class Epi, class Sched, bool ALIGN_EPI = false, bool SP2 = false, bool I8 = false>
; __device__ __forceinline__ void gemm_phase(PG8_LAS unsigned char* lds, const Gemm g, const Sched& S, const Epi& E) {
;     ...
;         for (int t = 0; t < nt; t += 2) {
;             const bool last = (t == nt - 2);
;             const char* a1 = cA + (size_t)(t + 1) * kstep;
;             const char* a2 = last ? nA : cA + (size_t)(t + 2) * kstep; const char* b2 = last ? nB : cB + (size_t)(t + 2) * kstep;
;             const char* a3 = a2 + kstep; const char* b3 = b2 + kstep;
;             if (last && has_next) S.a_ready(nxt);
;             if constexpr (SP2) {
;             PG8_LDB(B0, 0, 0); PG8_LDB(B1, 0, 1); PG8_SCHED; PG8_LDA(At, 0, 0); PG8_STAGE(PG8_SA(1, 1), a1 + hstep, voffA);
;             PG8_WAIT_V(8); PG8_WAIT_L(0); PG8_BAR; PG8_MMA(0, 0, At, B0); PG8_MMA(0, 1, At, B1); PG8_BAR; PG8_SCHED;
;             PG8_LDA(At, 0, 1); PG8_STAGE(PG8_SB(0, 0), b2, voffB); PG8_STAGE(PG8_SB(0, 1), b2 + hstep, voffB); PG8_STAGE(PG8_SA(0, 0), a2, voffA);
;             PG8_WAIT_V(8); PG8_WAIT_L(0); PG8_BAR; PG8_MMA(1, 0, At, B0); PG8_MMA(1, 1, At, B1); PG8_BAR; PG8_SCHED;
;             PG8_LDB(B0, 1, 0); PG8_LDB(B1, 1, 1); PG8_SCHED; PG8_LDA(At, 1, 0); PG8_STAGE(PG8_SA(0, 1), a2 + hstep, voffA);
;             PG8_WAIT_V(8); PG8_WAIT_L(0); PG8_BAR; PG8_MMA(0, 0, At, B0); PG8_MMA(0, 1, At, B1); PG8_BAR; PG8_SCHED;
;             PG8_LDA(At, 1, 1); PG8_STAGE(PG8_SB(1, 0), b3, voffB); PG8_STAGE(PG8_SB(1, 1), b3 + hstep, voffB); PG8_STAGE(PG8_SA(1, 0), a3, voffA);
;             PG8_WAIT_V(8); PG8_WAIT_L(0); PG8_BAR; PG8_MMA(1, 0, At, B0); PG8_MMA(1, 1, At, B1); PG8_BAR; PG8_SCHED;
	s_setprio 0
	s_add_i32 s22, s56, s41
	v_lshl_add_u64 v[218:219], v[218:219], 0, s[84:85]
	s_mov_b32 m0, s22
	ds_read_b128 v[164:167], v242 offset:49152
	ds_read_b128 v[168:171], v242 offset:50176
	ds_read_b128 v[176:179], v242 offset:52224
	ds_read_b128 v[172:175], v242 offset:51200
	ds_read_b128 v[180:183], v242 offset:53248
	ds_read_b128 v[184:187], v242 offset:54272
	ds_read_b128 v[214:217], v242 offset:56320
	ds_read_b128 v[188:191], v242 offset:55296
	global_load_lds_dwordx4 v[218:219], off
	s_add_i32 m0, s22, 0x2000
	s_add_u32 s22, s26, 0x2b0080
	v_lshl_add_u64 v[218:219], v[220:221], 0, s[84:85]
	s_addc_u32 s23, s27, 0
	s_add_i32 s26, s57, s41
	global_load_lds_dwordx4 v[218:219], off
	s_mov_b32 m0, s26
	s_nop 0
	global_load_lds_dwordx4 v2, s[22:23]
	s_add_i32 m0, s26, 0x2000
	s_nop 0
	global_load_lds_dwordx4 v204, s[22:23]
	s_cmpk_eq_i32 s55, 0xa8
	s_cbranch_scc0 .Ldefer_1700_peel
	v_lshl_add_u64 v[218:219], v[222:223], 0, s[84:85]
	s_mov_b32 m0, s46
	s_nop 0
	global_load_lds_dwordx4 v[218:219], off
	v_lshl_add_u64 v[218:219], v[224:225], 0, s[84:85]
	s_mov_b32 m0, s47
	s_nop 0
	global_load_lds_dwordx4 v[218:219], off
.Ldefer_1700_peel:
	s_waitcnt vmcnt(6)
	s_waitcnt lgkmcnt(7)
	s_setprio 1
	s_barrier
	v_mfma_f32_16x16x32_bf16 v[64:67], v[124:127], v[164:167], v[64:67]
	s_waitcnt lgkmcnt(6)
	v_mfma_f32_16x16x32_bf16 v[64:67], v[128:131], v[168:171], v[64:67]
	s_waitcnt lgkmcnt(5)
	v_mfma_f32_16x16x32_bf16 v[48:51], v[128:131], v[176:179], v[48:51]
	s_waitcnt lgkmcnt(4)
	v_mfma_f32_16x16x32_bf16 v[48:51], v[124:127], v[172:175], v[48:51]
	s_waitcnt lgkmcnt(3)
	v_mfma_f32_16x16x32_bf16 v[32:35], v[124:127], v[180:183], v[32:35]
	s_waitcnt lgkmcnt(2)
	v_mfma_f32_16x16x32_bf16 v[32:35], v[128:131], v[184:187], v[32:35]
	s_waitcnt lgkmcnt(1)
	v_mfma_f32_16x16x32_bf16 v[16:19], v[128:131], v[214:217], v[16:19]
	s_waitcnt lgkmcnt(0)
	v_mfma_f32_16x16x32_bf16 v[16:19], v[124:127], v[188:191], v[16:19]
	v_mfma_f32_16x16x32_bf16 v[12:15], v[132:135], v[188:191], v[12:15]
	v_mfma_f32_16x16x32_bf16 v[12:15], v[144:147], v[214:217], v[12:15]
	v_mfma_f32_16x16x32_bf16 v[28:31], v[144:147], v[184:187], v[28:31]
	v_mfma_f32_16x16x32_bf16 v[28:31], v[132:135], v[180:183], v[28:31]
	v_mfma_f32_16x16x32_bf16 v[44:47], v[132:135], v[172:175], v[44:47]
	v_mfma_f32_16x16x32_bf16 v[44:47], v[144:147], v[176:179], v[44:47]
	v_mfma_f32_16x16x32_bf16 v[60:63], v[144:147], v[168:171], v[60:63]
	v_mfma_f32_16x16x32_bf16 v[60:63], v[132:135], v[164:167], v[60:63]
	v_mfma_f32_16x16x32_bf16 v[56:59], v[148:151], v[164:167], v[56:59]
	v_mfma_f32_16x16x32_bf16 v[56:59], v[152:155], v[168:171], v[56:59]
	v_mfma_f32_16x16x32_bf16 v[40:43], v[152:155], v[176:179], v[40:43]
	v_mfma_f32_16x16x32_bf16 v[40:43], v[148:151], v[172:175], v[40:43]
	v_mfma_f32_16x16x32_bf16 v[24:27], v[148:151], v[180:183], v[24:27]
	v_mfma_f32_16x16x32_bf16 v[24:27], v[152:155], v[184:187], v[24:27]
	v_mfma_f32_16x16x32_bf16 v[8:11], v[152:155], v[214:217], v[8:11]
	v_mfma_f32_16x16x32_bf16 v[8:11], v[148:151], v[188:191], v[8:11]
	v_mfma_f32_16x16x32_bf16 v[4:7], v[156:159], v[188:191], v[4:7]
	v_mfma_f32_16x16x32_bf16 v[4:7], v[160:163], v[214:217], v[4:7]
	v_mfma_f32_16x16x32_bf16 v[20:23], v[160:163], v[184:187], v[20:23]
	v_mfma_f32_16x16x32_bf16 v[20:23], v[156:159], v[180:183], v[20:23]
	v_mfma_f32_16x16x32_bf16 v[36:39], v[156:159], v[172:175], v[36:39]
	v_mfma_f32_16x16x32_bf16 v[36:39], v[160:163], v[176:179], v[36:39]
	v_mfma_f32_16x16x32_bf16 v[52:55], v[160:163], v[168:171], v[52:55]
	v_mfma_f32_16x16x32_bf16 v[52:55], v[156:159], v[164:167], v[52:55]
	s_barrier
	s_setprio 0
	s_add_i32 s55, s55, 2
	s_add_u32 s53, s53, 0x100
	s_addc_u32 s54, s54, 0
	s_cmpk_gt_u32 s55, 0xa9
	s_mov_b64 s[22:23], s[24:25]
	s_cbranch_scc1 .Lkloop_exit_5
.LBB0_1700:
	s_add_u32 s24, s22, 0x100
	s_addc_u32 s25, s23, 0
	s_add_i32 s56, 0, 0x10000
	s_cmpk_eq_i32 s55, 0xa8
	s_cselect_b32 s37, s13, s25
	s_cselect_b32 s36, s12, s24
	s_cselect_b32 s27, s21, s54
	s_cselect_b32 s26, s20, s53
	s_add_i32 s57, 0, 0x14000
	v_add_u32_e32 v144, s56, v240
	v_add_u32_e32 v160, s57, v240
	ds_read_b128 v[124:127], v144
	ds_read_b128 v[164:167], v242
	ds_read_b128 v[128:131], v144 offset:1024
	ds_read_b128 v[168:171], v242 offset:1024
	ds_read_b128 v[176:179], v242 offset:3072
	ds_read_b128 v[172:175], v242 offset:2048
	ds_read_b128 v[180:183], v242 offset:4096
	ds_read_b128 v[184:187], v242 offset:5120
	v_lshl_add_u64 v[218:219], v[222:223], 0, s[84:85]
	s_mov_b32 m0, s46
	s_nop 0
	global_load_lds_dwordx4 v[218:219], off
	v_lshl_add_u64 v[218:219], v[224:225], 0, s[84:85]
	s_mov_b32 m0, s47
	s_nop 0
	global_load_lds_dwordx4 v[218:219], off
	v_lshl_add_u64 v[218:219], s[22:23], 0, v[210:211]
	s_add_i32 m0, s42, 0xc000
	ds_read_b128 v[214:217], v242 offset:7168
	ds_read_b128 v[188:191], v242 offset:6144
	ds_read_b128 v[132:135], v144 offset:2048
	ds_read_b128 v[144:147], v144 offset:3072
	ds_read_b128 v[148:151], v160
	ds_read_b128 v[152:155], v160 offset:1024
	ds_read_b128 v[156:159], v160 offset:2048
	ds_read_b128 v[160:163], v160 offset:3072
	global_load_lds_dwordx4 v[218:219], off
	v_lshl_add_u64 v[218:219], s[22:23], 0, v[212:213]
	s_add_i32 m0, s42, 0xe000
	s_nop 0
	global_load_lds_dwordx4 v[218:219], off
	s_waitcnt vmcnt(8)
	s_waitcnt lgkmcnt(14)
	s_setprio 1
	s_barrier
; #define PG8_STAGE(bufoff, gbase, voff) do { _Pragma("unroll") for (int _i = 0; _i < 2; ++_i) \
;         __builtin_amdgcn_global_load_lds((const unsigned*)((const char*)(gbase) + (voff)[_i]), (PG8_LAS unsigned*)(lds + (bufoff) + ldsw + _i * 8192), 16, 0, 0); } while (0)
; #define PG8_LDA(dst, b, h) do { _Pragma("unroll") for (int m = 0; m < 4; ++m) _Pragma("unroll") for (int k = 0; k < 2; ++k) dst[m][k] = *(const PG8_LAS bf16x8*)(lds + PG8_SA(b, h) + aoff + m * 2048 + k * 1024); } while (0)
; #define PG8_LDB(dst, b, h) do { _Pragma("unroll") for (int n = 0; n < 2; ++n) _Pragma("unroll") for (int k = 0; k < 2; ++k) dst[n][k] = *(const PG8_LAS bf16x8*)(lds + PG8_SB(b, h) + boff + n * 2048 + k * 1024); } while (0)
; #define PG8_WAIT_V(n) asm volatile("s_waitcnt vmcnt(" #n ")" ::: "memory")
; #define PG8_WAIT_L(n) asm volatile("s_waitcnt lgkmcnt(" #n ")" ::: "memory")
; #define PG8_BAR __builtin_amdgcn_s_barrier()
; #define PG8_SCHED __builtin_amdgcn_sched_barrier(0)
; template <class Epi, class Sched, bool ALIGN_EPI = false, bool SP2 = false, bool I8 = false>
; __device__ __forceinline__ void gemm_phase(PG8_LAS unsigned char* lds, const Gemm g, const Sched& S, const Epi& E) {
;     ...
;             if constexpr (SP2) {
;             PG8_LDB(B0, 0, 0); PG8_LDB(B1, 0, 1); PG8_SCHED; PG8_LDA(At, 0, 0); PG8_STAGE(PG8_SA(1, 1), a1 + hstep, voffA);
;             PG8_WAIT_V(8); PG8_WAIT_L(0); PG8_BAR; PG8_MMA(0, 0, At, B0); PG8_MMA(0, 1, At, B1); PG8_BAR; PG8_SCHED;
;             PG8_LDA(At, 0, 1); PG8_STAGE(PG8_SB(0, 0), b2, voffB); PG8_STAGE(PG8_SB(0, 1), b2 + hstep, voffB); PG8_STAGE(PG8_SA(0, 0), a2, voffA);
;             PG8_WAIT_V(8); PG8_WAIT_L(0); PG8_BAR; PG8_MMA(1, 0, At, B0); PG8_MMA(1, 1, At, B1); PG8_BAR; PG8_SCHED;
;             PG8_LDB(B0, 1, 0); PG8_LDB(B1, 1, 1); PG8_SCHED; PG8_LDA(At, 1, 0); PG8_STAGE(PG8_SA(0, 1), a2 + hstep, voffA);
;             PG8_WAIT_V(8); PG8_WAIT_L(0); PG8_BAR; PG8_MMA(0, 0, At, B0); PG8_MMA(0, 1, At, B1); PG8_BAR; PG8_SCHED;
;             PG8_LDA(At, 1, 1); PG8_STAGE(PG8_SB(1, 0), b3, voffB); PG8_STAGE(PG8_SB(1, 1), b3 + hstep, voffB); PG8_STAGE(PG8_SA(1, 0), a3, voffA);
;             PG8_WAIT_V(8); PG8_WAIT_L(0); PG8_BAR; PG8_MMA(1, 0, At, B0); PG8_MMA(1, 1, At, B1); PG8_BAR; PG8_SCHED;
	v_mfma_f32_16x16x32_bf16 v[140:143], v[124:127], v[164:167], v[140:143]
	s_waitcnt lgkmcnt(12)
	v_mfma_f32_16x16x32_bf16 v[140:143], v[128:131], v[168:171], v[140:143]
	s_waitcnt lgkmcnt(11)
	v_mfma_f32_16x16x32_bf16 v[112:115], v[128:131], v[176:179], v[112:115]
	s_waitcnt lgkmcnt(10)
	v_mfma_f32_16x16x32_bf16 v[112:115], v[124:127], v[172:175], v[112:115]
	s_waitcnt lgkmcnt(9)
	v_mfma_f32_16x16x32_bf16 v[96:99], v[124:127], v[180:183], v[96:99]
	s_waitcnt lgkmcnt(8)
	v_mfma_f32_16x16x32_bf16 v[96:99], v[128:131], v[184:187], v[96:99]
	s_waitcnt lgkmcnt(7)
	v_mfma_f32_16x16x32_bf16 v[80:83], v[128:131], v[214:217], v[80:83]
	s_waitcnt lgkmcnt(6)
	v_mfma_f32_16x16x32_bf16 v[80:83], v[124:127], v[188:191], v[80:83]
	s_waitcnt lgkmcnt(5)
	v_mfma_f32_16x16x32_bf16 v[76:79], v[132:135], v[188:191], v[76:79]
	s_waitcnt lgkmcnt(4)
	v_mfma_f32_16x16x32_bf16 v[76:79], v[144:147], v[214:217], v[76:79]
	v_mfma_f32_16x16x32_bf16 v[92:95], v[144:147], v[184:187], v[92:95]
	v_mfma_f32_16x16x32_bf16 v[92:95], v[132:135], v[180:183], v[92:95]
	v_mfma_f32_16x16x32_bf16 v[108:111], v[132:135], v[172:175], v[108:111]
	v_mfma_f32_16x16x32_bf16 v[108:111], v[144:147], v[176:179], v[108:111]
	v_mfma_f32_16x16x32_bf16 v[136:139], v[144:147], v[168:171], v[136:139]
	v_mfma_f32_16x16x32_bf16 v[136:139], v[132:135], v[164:167], v[136:139]
	s_waitcnt lgkmcnt(3)
	v_mfma_f32_16x16x32_bf16 v[120:123], v[148:151], v[164:167], v[120:123]
	s_waitcnt lgkmcnt(2)
	v_mfma_f32_16x16x32_bf16 v[120:123], v[152:155], v[168:171], v[120:123]
	v_mfma_f32_16x16x32_bf16 v[104:107], v[152:155], v[176:179], v[104:107]
	v_mfma_f32_16x16x32_bf16 v[104:107], v[148:151], v[172:175], v[104:107]
	v_mfma_f32_16x16x32_bf16 v[88:91], v[148:151], v[180:183], v[88:91]
	v_mfma_f32_16x16x32_bf16 v[88:91], v[152:155], v[184:187], v[88:91]
	v_mfma_f32_16x16x32_bf16 v[72:75], v[152:155], v[214:217], v[72:75]
	v_mfma_f32_16x16x32_bf16 v[72:75], v[148:151], v[188:191], v[72:75]
	s_waitcnt lgkmcnt(1)
	v_mfma_f32_16x16x32_bf16 v[68:71], v[156:159], v[188:191], v[68:71]
	s_waitcnt lgkmcnt(0)
	v_mfma_f32_16x16x32_bf16 v[68:71], v[160:163], v[214:217], v[68:71]
	v_mfma_f32_16x16x32_bf16 v[84:87], v[160:163], v[184:187], v[84:87]
	v_mfma_f32_16x16x32_bf16 v[84:87], v[156:159], v[180:183], v[84:87]
	v_mfma_f32_16x16x32_bf16 v[100:103], v[156:159], v[172:175], v[100:103]
	v_mfma_f32_16x16x32_bf16 v[100:103], v[160:163], v[176:179], v[100:103]
	v_mfma_f32_16x16x32_bf16 v[116:119], v[160:163], v[168:171], v[116:119]
	v_mfma_f32_16x16x32_bf16 v[116:119], v[156:159], v[164:167], v[116:119]
	s_barrier
	s_setprio 0
	s_add_i32 s22, s56, s41
	v_lshl_add_u64 v[218:219], s[26:27], 0, v[2:3]
	s_mov_b32 m0, s22
	ds_read_b128 v[164:167], v242 offset:16384
	ds_read_b128 v[168:171], v242 offset:17408
	ds_read_b128 v[176:179], v242 offset:19456
	ds_read_b128 v[172:175], v242 offset:18432
	ds_read_b128 v[180:183], v242 offset:20480
	ds_read_b128 v[184:187], v242 offset:21504
	ds_read_b128 v[214:217], v242 offset:23552
	ds_read_b128 v[188:191], v242 offset:22528
	global_load_lds_dwordx4 v[218:219], off
	s_add_i32 m0, s22, 0x2000
	s_add_u32 s22, s26, 0x2b0000
	v_lshl_add_u64 v[220:221], s[26:27], 0, v[204:205]
	s_addc_u32 s23, s27, 0
	s_add_i32 s56, s57, s41
	global_load_lds_dwordx4 v[220:221], off
	s_mov_b32 m0, s56
	v_lshl_add_u64 v[224:225], s[36:37], 0, v[206:207]
	global_load_lds_dwordx4 v2, s[22:23]
	s_add_i32 m0, s56, 0x2000
	s_nop 0
	global_load_lds_dwordx4 v204, s[22:23]
	v_lshl_add_u64 v[222:223], s[36:37], 0, v[208:209]
	s_waitcnt vmcnt(6)
	s_waitcnt lgkmcnt(7)
	s_setprio 1
	s_barrier
	v_mfma_f32_16x16x32_bf16 v[64:67], v[124:127], v[164:167], v[64:67]
	s_waitcnt lgkmcnt(6)
	v_mfma_f32_16x16x32_bf16 v[64:67], v[128:131], v[168:171], v[64:67]
	s_waitcnt lgkmcnt(5)
	v_mfma_f32_16x16x32_bf16 v[48:51], v[128:131], v[176:179], v[48:51]
	s_waitcnt lgkmcnt(4)
	v_mfma_f32_16x16x32_bf16 v[48:51], v[124:127], v[172:175], v[48:51]
	s_waitcnt lgkmcnt(3)
	v_mfma_f32_16x16x32_bf16 v[32:35], v[124:127], v[180:183], v[32:35]
	s_waitcnt lgkmcnt(2)
	v_mfma_f32_16x16x32_bf16 v[32:35], v[128:131], v[184:187], v[32:35]
	s_waitcnt lgkmcnt(1)
	v_mfma_f32_16x16x32_bf16 v[16:19], v[128:131], v[214:217], v[16:19]
	s_waitcnt lgkmcnt(0)
	v_mfma_f32_16x16x32_bf16 v[16:19], v[124:127], v[188:191], v[16:19]
	v_mfma_f32_16x16x32_bf16 v[12:15], v[132:135], v[188:191], v[12:15]
	v_mfma_f32_16x16x32_bf16 v[12:15], v[144:147], v[214:217], v[12:15]
	v_mfma_f32_16x16x32_bf16 v[28:31], v[144:147], v[184:187], v[28:31]
	v_mfma_f32_16x16x32_bf16 v[28:31], v[132:135], v[180:183], v[28:31]
	v_mfma_f32_16x16x32_bf16 v[44:47], v[132:135], v[172:175], v[44:47]
	v_mfma_f32_16x16x32_bf16 v[44:47], v[144:147], v[176:179], v[44:47]
	v_mfma_f32_16x16x32_bf16 v[60:63], v[144:147], v[168:171], v[60:63]
	v_mfma_f32_16x16x32_bf16 v[60:63], v[132:135], v[164:167], v[60:63]
	v_mfma_f32_16x16x32_bf16 v[56:59], v[148:151], v[164:167], v[56:59]
	v_mfma_f32_16x16x32_bf16 v[56:59], v[152:155], v[168:171], v[56:59]
	v_mfma_f32_16x16x32_bf16 v[40:43], v[152:155], v[176:179], v[40:43]
	v_mfma_f32_16x16x32_bf16 v[40:43], v[148:151], v[172:175], v[40:43]
	v_mfma_f32_16x16x32_bf16 v[24:27], v[148:151], v[180:183], v[24:27]
	v_mfma_f32_16x16x32_bf16 v[24:27], v[152:155], v[184:187], v[24:27]
	v_mfma_f32_16x16x32_bf16 v[8:11], v[152:155], v[214:217], v[8:11]
	v_mfma_f32_16x16x32_bf16 v[8:11], v[148:151], v[188:191], v[8:11]
	v_mfma_f32_16x16x32_bf16 v[4:7], v[156:159], v[188:191], v[4:7]
	v_mfma_f32_16x16x32_bf16 v[4:7], v[160:163], v[214:217], v[4:7]
	v_mfma_f32_16x16x32_bf16 v[20:23], v[160:163], v[184:187], v[20:23]
	v_mfma_f32_16x16x32_bf16 v[20:23], v[156:159], v[180:183], v[20:23]
	v_mfma_f32_16x16x32_bf16 v[36:39], v[156:159], v[172:175], v[36:39]
	v_mfma_f32_16x16x32_bf16 v[36:39], v[160:163], v[176:179], v[36:39]
	v_mfma_f32_16x16x32_bf16 v[52:55], v[160:163], v[168:171], v[52:55]
	v_mfma_f32_16x16x32_bf16 v[52:55], v[156:159], v[164:167], v[52:55]
	s_barrier
; #define PG8_STAGE(bufoff, gbase, voff) do { _Pragma("unroll") for (int _i = 0; _i < 2; ++_i) \
;         __builtin_amdgcn_global_load_lds((const unsigned*)((const char*)(gbase) + (voff)[_i]), (PG8_LAS unsigned*)(lds + (bufoff) + ldsw + _i * 8192), 16, 0, 0); } while (0)
; #define PG8_LDA(dst, b, h) do { _Pragma("unroll") for (int m = 0; m < 4; ++m) _Pragma("unroll") for (int k = 0; k < 2; ++k) dst[m][k] = *(const PG8_LAS bf16x8*)(lds + PG8_SA(b, h) + aoff + m * 2048 + k * 1024); } while (0)
; #define PG8_LDB(dst, b, h) do { _Pragma("unroll") for (int n = 0; n < 2; ++n) _Pragma("unroll") for (int k = 0; k < 2; ++k) dst[n][k] = *(const PG8_LAS bf16x8*)(lds + PG8_SB(b, h) + boff + n * 2048 + k * 1024); } while (0)
; #define PG8_WAIT_V(n) asm volatile("s_waitcnt vmcnt(" #n ")" ::: "memory")
; #define PG8_WAIT_L(n) asm volatile("s_waitcnt lgkmcnt(" #n ")" ::: "memory")
; #define PG8_BAR __builtin_amdgcn_s_barrier()
; #define PG8_SCHED __builtin_amdgcn_sched_barrier(0)
; template <class Epi, class Sched, bool ALIGN_EPI = false, bool SP2 = false, bool I8 = false>
; __device__ __forceinline__ void gemm_phase(PG8_LAS unsigned char* lds, const Gemm g, const Sched& S, const Epi& E) {
;     ...
;             if constexpr (SP2) {
;             PG8_LDB(B0, 0, 0); PG8_LDB(B1, 0, 1); PG8_SCHED; PG8_LDA(At, 0, 0); PG8_STAGE(PG8_SA(1, 1), a1 + hstep, voffA);
;             PG8_WAIT_V(8); PG8_WAIT_L(0); PG8_BAR; PG8_MMA(0, 0, At, B0); PG8_MMA(0, 1, At, B1); PG8_BAR; PG8_SCHED;
;             PG8_LDA(At, 0, 1); PG8_STAGE(PG8_SB(0, 0), b2, voffB); PG8_STAGE(PG8_SB(0, 1), b2 + hstep, voffB); PG8_STAGE(PG8_SA(0, 0), a2, voffA);
;             PG8_WAIT_V(8); PG8_WAIT_L(0); PG8_BAR; PG8_MMA(1, 0, At, B0); PG8_MMA(1, 1, At, B1); PG8_BAR; PG8_SCHED;
;             PG8_LDB(B0, 1, 0); PG8_LDB(B1, 1, 1); PG8_SCHED; PG8_LDA(At, 1, 0); PG8_STAGE(PG8_SA(0, 1), a2 + hstep, voffA);
;             PG8_WAIT_V(8); PG8_WAIT_L(0); PG8_BAR; PG8_MMA(0, 0, At, B0); PG8_MMA(0, 1, At, B1); PG8_BAR; PG8_SCHED;
;             PG8_LDA(At, 1, 1); PG8_STAGE(PG8_SB(1, 0), b3, voffB); PG8_STAGE(PG8_SB(1, 1), b3 + hstep, voffB); PG8_STAGE(PG8_SA(1, 0), a3, voffA);
;             PG8_WAIT_V(8); PG8_WAIT_L(0); PG8_BAR; PG8_MMA(1, 0, At, B0); PG8_MMA(1, 1, At, B1); PG8_BAR; PG8_SCHED;
	s_setprio 0
	s_mov_b32 m0, s42
	s_nop 0
	global_load_lds_dwordx4 v[222:223], off
	s_mov_b32 m0, s43
	s_nop 0
	global_load_lds_dwordx4 v[224:225], off
	s_add_i32 s56, 0, 0x18000
	s_add_i32 s57, 0, 0x1c000
	v_add_u32_e32 v144, s56, v240
	v_add_u32_e32 v160, s57, v240
	ds_read_b128 v[124:127], v144
	ds_read_b128 v[164:167], v242 offset:32768
	ds_read_b128 v[128:131], v144 offset:1024
	ds_read_b128 v[168:171], v242 offset:33792
	ds_read_b128 v[176:179], v242 offset:35840
	ds_read_b128 v[172:175], v242 offset:34816
	ds_read_b128 v[180:183], v242 offset:36864
	ds_read_b128 v[184:187], v242 offset:37888
	s_add_u32 s22, s36, 0x2b0000
	s_addc_u32 s23, s37, 0
	s_mov_b32 m0, s44
	ds_read_b128 v[214:217], v242 offset:39936
	ds_read_b128 v[188:191], v242 offset:38912
	ds_read_b128 v[132:135], v144 offset:2048
	ds_read_b128 v[144:147], v144 offset:3072
	ds_read_b128 v[148:151], v160
	ds_read_b128 v[152:155], v160 offset:1024
	ds_read_b128 v[156:159], v160 offset:2048
	ds_read_b128 v[160:163], v160 offset:3072
	global_load_lds_dwordx4 v208, s[22:23]
	s_mov_b32 m0, s45
	s_nop 0
	global_load_lds_dwordx4 v206, s[22:23]
	s_waitcnt vmcnt(8)
	s_waitcnt lgkmcnt(14)
	s_setprio 1
	s_barrier
	v_mfma_f32_16x16x32_bf16 v[140:143], v[124:127], v[164:167], v[140:143]
	s_waitcnt lgkmcnt(12)
	v_mfma_f32_16x16x32_bf16 v[140:143], v[128:131], v[168:171], v[140:143]
	s_waitcnt lgkmcnt(11)
	v_mfma_f32_16x16x32_bf16 v[112:115], v[128:131], v[176:179], v[112:115]
	s_waitcnt lgkmcnt(10)
	v_mfma_f32_16x16x32_bf16 v[112:115], v[124:127], v[172:175], v[112:115]
	s_waitcnt lgkmcnt(9)
	v_mfma_f32_16x16x32_bf16 v[96:99], v[124:127], v[180:183], v[96:99]
	s_waitcnt lgkmcnt(8)
	v_mfma_f32_16x16x32_bf16 v[96:99], v[128:131], v[184:187], v[96:99]
	s_waitcnt lgkmcnt(7)
	v_mfma_f32_16x16x32_bf16 v[80:83], v[128:131], v[214:217], v[80:83]
	s_waitcnt lgkmcnt(6)
	v_mfma_f32_16x16x32_bf16 v[80:83], v[124:127], v[188:191], v[80:83]
	s_waitcnt lgkmcnt(5)
	v_mfma_f32_16x16x32_bf16 v[76:79], v[132:135], v[188:191], v[76:79]
	s_waitcnt lgkmcnt(4)
	v_mfma_f32_16x16x32_bf16 v[76:79], v[144:147], v[214:217], v[76:79]
	v_mfma_f32_16x16x32_bf16 v[92:95], v[144:147], v[184:187], v[92:95]
	v_mfma_f32_16x16x32_bf16 v[92:95], v[132:135], v[180:183], v[92:95]
	v_mfma_f32_16x16x32_bf16 v[108:111], v[132:135], v[172:175], v[108:111]
	v_mfma_f32_16x16x32_bf16 v[108:111], v[144:147], v[176:179], v[108:111]
	v_mfma_f32_16x16x32_bf16 v[136:139], v[144:147], v[168:171], v[136:139]
	v_mfma_f32_16x16x32_bf16 v[136:139], v[132:135], v[164:167], v[136:139]
	s_waitcnt lgkmcnt(3)
	v_mfma_f32_16x16x32_bf16 v[120:123], v[148:151], v[164:167], v[120:123]
	s_waitcnt lgkmcnt(2)
	v_mfma_f32_16x16x32_bf16 v[120:123], v[152:155], v[168:171], v[120:123]
	v_mfma_f32_16x16x32_bf16 v[104:107], v[152:155], v[176:179], v[104:107]
	v_mfma_f32_16x16x32_bf16 v[104:107], v[148:151], v[172:175], v[104:107]
	v_mfma_f32_16x16x32_bf16 v[88:91], v[148:151], v[180:183], v[88:91]
	v_mfma_f32_16x16x32_bf16 v[88:91], v[152:155], v[184:187], v[88:91]
	v_mfma_f32_16x16x32_bf16 v[72:75], v[152:155], v[214:217], v[72:75]
	v_mfma_f32_16x16x32_bf16 v[72:75], v[148:151], v[188:191], v[72:75]
	s_waitcnt lgkmcnt(1)
	v_mfma_f32_16x16x32_bf16 v[68:71], v[156:159], v[188:191], v[68:71]
	s_waitcnt lgkmcnt(0)
	v_mfma_f32_16x16x32_bf16 v[68:71], v[160:163], v[214:217], v[68:71]
	v_mfma_f32_16x16x32_bf16 v[84:87], v[160:163], v[184:187], v[84:87]
	v_mfma_f32_16x16x32_bf16 v[84:87], v[156:159], v[180:183], v[84:87]
	v_mfma_f32_16x16x32_bf16 v[100:103], v[156:159], v[172:175], v[100:103]
	v_mfma_f32_16x16x32_bf16 v[100:103], v[160:163], v[176:179], v[100:103]
	v_mfma_f32_16x16x32_bf16 v[116:119], v[160:163], v[168:171], v[116:119]
	v_mfma_f32_16x16x32_bf16 v[116:119], v[156:159], v[164:167], v[116:119]
	s_barrier
	s_setprio 0
	s_add_i32 s22, s56, s41
	v_lshl_add_u64 v[218:219], v[218:219], 0, s[84:85]
	s_mov_b32 m0, s22
	ds_read_b128 v[164:167], v242 offset:49152
	ds_read_b128 v[168:171], v242 offset:50176
	ds_read_b128 v[176:179], v242 offset:52224
	ds_read_b128 v[172:175], v242 offset:51200
	ds_read_b128 v[180:183], v242 offset:53248
	ds_read_b128 v[184:187], v242 offset:54272
	ds_read_b128 v[214:217], v242 offset:56320
	ds_read_b128 v[188:191], v242 offset:55296
	global_load_lds_dwordx4 v[218:219], off
	s_add_i32 m0, s22, 0x2000
	s_add_u32 s22, s26, 0x2b0080
	v_lshl_add_u64 v[218:219], v[220:221], 0, s[84:85]
	s_addc_u32 s23, s27, 0
	s_add_i32 s26, s57, s41
	global_load_lds_dwordx4 v[218:219], off
	s_mov_b32 m0, s26
	s_nop 0
	global_load_lds_dwordx4 v2, s[22:23]
	s_add_i32 m0, s26, 0x2000
	s_nop 0
	global_load_lds_dwordx4 v204, s[22:23]
	s_cmpk_eq_i32 s55, 0xa8
	s_cbranch_scc0 .Ldefer_1700_body
	v_lshl_add_u64 v[218:219], v[222:223], 0, s[84:85]
	s_mov_b32 m0, s46
	s_nop 0
	global_load_lds_dwordx4 v[218:219], off
	v_lshl_add_u64 v[218:219], v[224:225], 0, s[84:85]
	s_mov_b32 m0, s47
	s_nop 0
	global_load_lds_dwordx4 v[218:219], off
; #define PG8_STAGE(bufoff, gbase, voff) do { _Pragma("unroll") for (int _i = 0; _i < 2; ++_i) \
;         __builtin_amdgcn_global_load_lds((const unsigned*)((const char*)(gbase) + (voff)[_i]), (PG8_LAS unsigned*)(lds + (bufoff) + ldsw + _i * 8192), 16, 0, 0); } while (0)
; #define PG8_LDA(dst, b, h) do { _Pragma("unroll") for (int m = 0; m < 4; ++m) _Pragma("unroll") for (int k = 0; k < 2; ++k) dst[m][k] = *(const PG8_LAS bf16x8*)(lds + PG8_SA(b, h) + aoff + m * 2048 + k * 1024); } while (0)
; #define PG8_LDB(dst, b, h) do { _Pragma("unroll") for (int n = 0; n < 2; ++n) _Pragma("unroll") for (int k = 0; k < 2; ++k) dst[n][k] = *(const PG8_LAS bf16x8*)(lds + PG8_SB(b, h) + boff + n * 2048 + k * 1024); } while (0)
; #define PG8_WAIT_V(n) asm volatile("s_waitcnt vmcnt(" #n ")" ::: "memory")
; #define PG8_WAIT_L(n) asm volatile("s_waitcnt lgkmcnt(" #n ")" ::: "memory")
; #define PG8_BAR __builtin_amdgcn_s_barrier()
; #define PG8_SCHED __builtin_amdgcn_sched_barrier(0)
; template <class Epi, class Sched, bool ALIGN_EPI = false, bool SP2 = false, bool I8 = false>
; __device__ __forceinline__ void gemm_phase(PG8_LAS unsigned char* lds, const Gemm g, const Sched& S, const Epi& E) {
;     ...
;             PG8_WAIT_V(8); PG8_WAIT_L(0); PG8_BAR; PG8_MMA(0, 0, At, B0); PG8_MMA(0, 1, At, B1); PG8_BAR; PG8_SCHED;
;             PG8_LDA(At, 0, 1); PG8_STAGE(PG8_SB(0, 0), b2, voffB); PG8_STAGE(PG8_SB(0, 1), b2 + hstep, voffB); PG8_STAGE(PG8_SA(0, 0), a2, voffA);
;             PG8_WAIT_V(8); PG8_WAIT_L(0); PG8_BAR; PG8_MMA(1, 0, At, B0); PG8_MMA(1, 1, At, B1); PG8_BAR; PG8_SCHED;
;             PG8_LDB(B0, 1, 0); PG8_LDB(B1, 1, 1); PG8_SCHED; PG8_LDA(At, 1, 0); PG8_STAGE(PG8_SA(0, 1), a2 + hstep, voffA);
;             PG8_WAIT_V(8); PG8_WAIT_L(0); PG8_BAR; PG8_MMA(0, 0, At, B0); PG8_MMA(0, 1, At, B1); PG8_BAR; PG8_SCHED;
;             PG8_LDA(At, 1, 1); PG8_STAGE(PG8_SB(1, 0), b3, voffB); PG8_STAGE(PG8_SB(1, 1), b3 + hstep, voffB); PG8_STAGE(PG8_SA(1, 0), a3, voffA);
;             PG8_WAIT_V(8); PG8_WAIT_L(0); PG8_BAR; PG8_MMA(1, 0, At, B0); PG8_MMA(1, 1, At, B1); PG8_BAR; PG8_SCHED;
.Ldefer_1700_body:
	s_waitcnt vmcnt(6)
	s_waitcnt lgkmcnt(7)
	s_setprio 1
	s_barrier
	v_mfma_f32_16x16x32_bf16 v[64:67], v[124:127], v[164:167], v[64:67]
	s_waitcnt lgkmcnt(6)
	v_mfma_f32_16x16x32_bf16 v[64:67], v[128:131], v[168:171], v[64:67]
	s_waitcnt lgkmcnt(5)
	v_mfma_f32_16x16x32_bf16 v[48:51], v[128:131], v[176:179], v[48:51]
	s_waitcnt lgkmcnt(4)
	v_mfma_f32_16x16x32_bf16 v[48:51], v[124:127], v[172:175], v[48:51]
	s_waitcnt lgkmcnt(3)
	v_mfma_f32_16x16x32_bf16 v[32:35], v[124:127], v[180:183], v[32:35]
	s_waitcnt lgkmcnt(2)
	v_mfma_f32_16x16x32_bf16 v[32:35], v[128:131], v[184:187], v[32:35]
	s_waitcnt lgkmcnt(1)
	v_mfma_f32_16x16x32_bf16 v[16:19], v[128:131], v[214:217], v[16:19]
	s_waitcnt lgkmcnt(0)
	v_mfma_f32_16x16x32_bf16 v[16:19], v[124:127], v[188:191], v[16:19]
	v_mfma_f32_16x16x32_bf16 v[12:15], v[132:135], v[188:191], v[12:15]
	v_mfma_f32_16x16x32_bf16 v[12:15], v[144:147], v[214:217], v[12:15]
	v_mfma_f32_16x16x32_bf16 v[28:31], v[144:147], v[184:187], v[28:31]
	v_mfma_f32_16x16x32_bf16 v[28:31], v[132:135], v[180:183], v[28:31]
	v_mfma_f32_16x16x32_bf16 v[44:47], v[132:135], v[172:175], v[44:47]
	v_mfma_f32_16x16x32_bf16 v[44:47], v[144:147], v[176:179], v[44:47]
	v_mfma_f32_16x16x32_bf16 v[60:63], v[144:147], v[168:171], v[60:63]
	v_mfma_f32_16x16x32_bf16 v[60:63], v[132:135], v[164:167], v[60:63]
	v_mfma_f32_16x16x32_bf16 v[56:59], v[148:151], v[164:167], v[56:59]
	v_mfma_f32_16x16x32_bf16 v[56:59], v[152:155], v[168:171], v[56:59]
	v_mfma_f32_16x16x32_bf16 v[40:43], v[152:155], v[176:179], v[40:43]
	v_mfma_f32_16x16x32_bf16 v[40:43], v[148:151], v[172:175], v[40:43]
	v_mfma_f32_16x16x32_bf16 v[24:27], v[148:151], v[180:183], v[24:27]
	v_mfma_f32_16x16x32_bf16 v[24:27], v[152:155], v[184:187], v[24:27]
	v_mfma_f32_16x16x32_bf16 v[8:11], v[152:155], v[214:217], v[8:11]
	v_mfma_f32_16x16x32_bf16 v[8:11], v[148:151], v[188:191], v[8:11]
	v_mfma_f32_16x16x32_bf16 v[4:7], v[156:159], v[188:191], v[4:7]
	v_mfma_f32_16x16x32_bf16 v[4:7], v[160:163], v[214:217], v[4:7]
	v_mfma_f32_16x16x32_bf16 v[20:23], v[160:163], v[184:187], v[20:23]
	v_mfma_f32_16x16x32_bf16 v[20:23], v[156:159], v[180:183], v[20:23]
	v_mfma_f32_16x16x32_bf16 v[36:39], v[156:159], v[172:175], v[36:39]
	v_mfma_f32_16x16x32_bf16 v[36:39], v[160:163], v[176:179], v[36:39]
	v_mfma_f32_16x16x32_bf16 v[52:55], v[160:163], v[168:171], v[52:55]
	v_mfma_f32_16x16x32_bf16 v[52:55], v[156:159], v[164:167], v[52:55]
	s_barrier
	s_setprio 0
	s_add_i32 s55, s55, 2
	s_add_u32 s53, s53, 0x100
	s_addc_u32 s54, s54, 0
	s_cmpk_gt_u32 s55, 0xa9
	s_mov_b64 s[22:23], s[24:25]
	s_cbranch_scc0 .LBB0_1700

; #define PG8_STAGE(bufoff, gbase, voff) do { _Pragma("unroll") for (int _i = 0; _i < 2; ++_i) \
;         __builtin_amdgcn_global_load_lds((const unsigned*)((const char*)(gbase) + (voff)[_i]), (PG8_LAS unsigned*)(lds + (bufoff) + ldsw + _i * 8192), 16, 0, 0); } while (0)
; #define PG8_LDA(dst, b, h) do { _Pragma("unroll") for (int m = 0; m < 4; ++m) _Pragma("unroll") for (int k = 0; k < 2; ++k) dst[m][k] = *(const PG8_LAS bf16x8*)(lds + PG8_SA(b, h) + aoff + m * 2048 + k * 1024); } while (0)
; #define PG8_BAR __builtin_amdgcn_s_barrier()
; template <class Epi, class Sched, bool ALIGN_EPI = false, bool SP2 = false, bool I8 = false>
; __device__ __forceinline__ void gemm_phase(PG8_LAS unsigned char* lds, const Gemm g, const Sched& S, const Epi& E) {
;     ...
;         const char* nA = has_next ? (const char*)g.A + (size_t)nxt.pm * tstep : cA; const char* nB = has_next ? (const char*)g.Bt + (size_t)nxt.pn * tstep : cB;
;         for (int t = 0; t < nt; t += 2) {
;             const bool last = (t == nt - 2);
;             const char* a1 = cA + (size_t)(t + 1) * kstep;
;             const char* a2 = last ? nA : cA + (size_t)(t + 2) * kstep; const char* b2 = last ? nB : cB + (size_t)(t + 2) * kstep;
;             const char* a3 = a2 + kstep; const char* b3 = b2 + kstep;
;             if (last && has_next) S.a_ready(nxt);
;             if constexpr (SP2) {
;             PG8_LDB(B0, 0, 0); PG8_LDB(B1, 0, 1); PG8_SCHED; PG8_LDA(At, 0, 0); PG8_STAGE(PG8_SA(1, 1), a1 + hstep, voffA);
;             PG8_WAIT_V(8); PG8_WAIT_L(0); PG8_BAR; PG8_MMA(0, 0, At, B0); PG8_MMA(0, 1, At, B1); PG8_BAR; PG8_SCHED;
;             PG8_LDA(At, 0, 1); PG8_STAGE(PG8_SB(0, 0), b2, voffB); PG8_STAGE(PG8_SB(0, 1), b2 + hstep, voffB); PG8_STAGE(PG8_SA(0, 0), a2, voffA);
;             PG8_WAIT_V(8); PG8_WAIT_L(0); PG8_BAR; PG8_MMA(1, 0, At, B0); PG8_MMA(1, 1, At, B1); PG8_BAR; PG8_SCHED;
;             PG8_LDB(B0, 1, 0); PG8_LDB(B1, 1, 1); PG8_SCHED; PG8_LDA(At, 1, 0); PG8_STAGE(PG8_SA(0, 1), a2 + hstep, voffA);
;             PG8_WAIT_V(8); PG8_WAIT_L(0); PG8_BAR; PG8_MMA(0, 0, At, B0); PG8_MMA(0, 1, At, B1); PG8_BAR; PG8_SCHED;
;             PG8_LDA(At, 1, 1); PG8_STAGE(PG8_SB(1, 0), b3, voffB); PG8_STAGE(PG8_SB(1, 1), b3 + hstep, voffB); PG8_STAGE(PG8_SA(1, 0), a3, voffA);
;             PG8_WAIT_V(8); PG8_WAIT_L(0); PG8_BAR; PG8_MMA(1, 0, At, B0); PG8_MMA(1, 1, At, B1); PG8_BAR; PG8_SCHED;
.LBB0_1842:
	s_ashr_i32 s45, s44, 31
	s_lshl_b64 s[34:35], s[44:45], 20
	s_add_u32 s50, s47, s34
	s_addc_u32 s51, s52, s35
	s_and_b64 s[34:35], s[8:9], exec
	s_cselect_b32 s11, s51, s55
	s_cselect_b32 s13, s50, s54
	s_ashr_i32 s49, s48, 31
	s_lshl_b64 s[34:35], s[48:49], 20
	s_add_u32 s56, s53, s34
	s_addc_u32 s57, s64, s35
	s_and_b64 s[34:35], s[8:9], exec
	s_cselect_b32 s34, s57, s59
	s_cselect_b32 s35, s56, s58
	s_add_u32 s54, s54, 0x80080
	s_addc_u32 s55, s55, 0
	s_add_u32 s45, s58, 0x100
	s_addc_u32 s49, s59, 0
	s_mov_b32 s86, -2
	s_waitcnt lgkmcnt(0)
	s_add_u32 s58, s54, 0xfff80080
	s_addc_u32 s59, s55, -1
	s_add_i32 s87, 0, 0x10000
	s_cmp_eq_u32 s86, 28
	s_cselect_b32 s61, s11, s59
	s_cselect_b32 s60, s13, s58
	s_cselect_b32 s59, s34, s49
	s_cselect_b32 s58, s35, s45
	s_add_i32 vcc_lo, 0, 0x14000
	v_add_u32_e32 v40, s87, v217
	v_add_u32_e32 v160, vcc_lo, v217
	ds_read_b128 v[28:31], v40
	ds_read_b128 v[164:167], v219
	ds_read_b128 v[32:35], v40 offset:1024
	ds_read_b128 v[168:171], v219 offset:1024
	ds_read_b128 v[176:179], v219 offset:3072
	ds_read_b128 v[172:175], v219 offset:2048
	ds_read_b128 v[204:207], v219 offset:4096
	ds_read_b128 v[208:211], v219 offset:5120
	s_add_i32 m0, s65, 0xc000
	ds_read_b128 v[220:223], v219 offset:7168
	ds_read_b128 v[212:215], v219 offset:6144
	ds_read_b128 v[36:39], v40 offset:2048
	ds_read_b128 v[40:43], v40 offset:3072
	ds_read_b128 v[140:143], v160
	ds_read_b128 v[144:147], v160 offset:1024
	ds_read_b128 v[156:159], v160 offset:2048
	ds_read_b128 v[160:163], v160 offset:3072
	global_load_lds_dwordx4 v186, s[54:55]
	s_add_i32 m0, s65, 0xe000
	s_nop 0
	global_load_lds_dwordx4 v188, s[54:55]
	s_waitcnt vmcnt(8)
	s_waitcnt lgkmcnt(14)
	s_setprio 1
	s_barrier
	v_mfma_i32_16x16x64_i8 v[152:155], v[28:31], v[164:167], 0
	s_waitcnt lgkmcnt(12)
	v_mfma_i32_16x16x64_i8 v[152:155], v[32:35], v[168:171], v[152:155]
	s_waitcnt lgkmcnt(11)
	v_mfma_i32_16x16x64_i8 v[128:131], v[32:35], v[176:179], 0
	s_waitcnt lgkmcnt(10)
	v_mfma_i32_16x16x64_i8 v[128:131], v[28:31], v[172:175], v[128:131]
	s_waitcnt lgkmcnt(9)
	v_mfma_i32_16x16x64_i8 v[112:115], v[28:31], v[204:207], 0
	s_waitcnt lgkmcnt(8)
	v_mfma_i32_16x16x64_i8 v[112:115], v[32:35], v[208:211], v[112:115]
	s_waitcnt lgkmcnt(7)
	v_mfma_i32_16x16x64_i8 v[96:99], v[32:35], v[220:223], 0
	s_waitcnt lgkmcnt(6)
	v_mfma_i32_16x16x64_i8 v[96:99], v[28:31], v[212:215], v[96:99]
	s_waitcnt lgkmcnt(5)
	v_mfma_i32_16x16x64_i8 v[92:95], v[36:39], v[212:215], 0
	s_waitcnt lgkmcnt(4)
	v_mfma_i32_16x16x64_i8 v[92:95], v[40:43], v[220:223], v[92:95]
	v_mfma_i32_16x16x64_i8 v[108:111], v[40:43], v[208:211], 0
	v_mfma_i32_16x16x64_i8 v[108:111], v[36:39], v[204:207], v[108:111]
	v_mfma_i32_16x16x64_i8 v[124:127], v[36:39], v[172:175], 0
	v_mfma_i32_16x16x64_i8 v[124:127], v[40:43], v[176:179], v[124:127]
	v_mfma_i32_16x16x64_i8 v[148:151], v[40:43], v[168:171], 0
	v_mfma_i32_16x16x64_i8 v[148:151], v[36:39], v[164:167], v[148:151]
	s_waitcnt lgkmcnt(3)
	v_mfma_i32_16x16x64_i8 v[136:139], v[140:143], v[164:167], 0
	s_waitcnt lgkmcnt(2)
	v_mfma_i32_16x16x64_i8 v[136:139], v[144:147], v[168:171], v[136:139]
	v_mfma_i32_16x16x64_i8 v[120:123], v[144:147], v[176:179], 0
	v_mfma_i32_16x16x64_i8 v[120:123], v[140:143], v[172:175], v[120:123]
	v_mfma_i32_16x16x64_i8 v[104:107], v[140:143], v[204:207], 0
	v_mfma_i32_16x16x64_i8 v[104:107], v[144:147], v[208:211], v[104:107]
	v_mfma_i32_16x16x64_i8 v[88:91], v[144:147], v[220:223], 0
	v_mfma_i32_16x16x64_i8 v[88:91], v[140:143], v[212:215], v[88:91]
	s_waitcnt lgkmcnt(1)
	v_mfma_i32_16x16x64_i8 v[84:87], v[156:159], v[212:215], 0
	s_waitcnt lgkmcnt(0)
	v_mfma_i32_16x16x64_i8 v[84:87], v[160:163], v[220:223], v[84:87]
	v_mfma_i32_16x16x64_i8 v[100:103], v[160:163], v[208:211], 0
	v_mfma_i32_16x16x64_i8 v[100:103], v[156:159], v[204:207], v[100:103]
	v_mfma_i32_16x16x64_i8 v[116:119], v[156:159], v[172:175], 0
	v_mfma_i32_16x16x64_i8 v[116:119], v[160:163], v[176:179], v[116:119]
	v_mfma_i32_16x16x64_i8 v[132:135], v[160:163], v[168:171], 0
	v_mfma_i32_16x16x64_i8 v[132:135], v[156:159], v[164:167], v[132:135]
	s_barrier
	s_setprio 0
	s_add_i32 s87, s87, s46
	v_lshl_add_u64 v[190:191], s[58:59], 0, v[2:3]
	s_mov_b32 m0, s87
	ds_read_b128 v[164:167], v219 offset:16384
	ds_read_b128 v[168:171], v219 offset:17408
	ds_read_b128 v[176:179], v219 offset:19456
	ds_read_b128 v[172:175], v219 offset:18432
	ds_read_b128 v[204:207], v219 offset:20480
	ds_read_b128 v[208:211], v219 offset:21504
	ds_read_b128 v[220:223], v219 offset:23552
	ds_read_b128 v[212:215], v219 offset:22528
	global_load_lds_dwordx4 v[190:191], off
	s_add_i32 m0, s87, 0x2000
	s_add_u32 s96, s58, 0x80000
	v_lshl_add_u64 v[224:225], s[58:59], 0, v[184:185]
	s_addc_u32 s97, s59, 0
	s_add_i32 s87, vcc_lo, s46
	global_load_lds_dwordx4 v[224:225], off
	s_mov_b32 m0, s87
	v_lshl_add_u64 v[228:229], s[60:61], 0, v[182:183]
	global_load_lds_dwordx4 v2, s[96:97]
	s_add_i32 m0, s87, 0x2000
	s_nop 0
	global_load_lds_dwordx4 v184, s[96:97]
	v_lshl_add_u64 v[226:227], s[60:61], 0, v[180:181]
	s_waitcnt vmcnt(6)
	s_waitcnt lgkmcnt(7)
	s_setprio 1
	s_barrier
; #define PG8_STAGE(bufoff, gbase, voff) do { _Pragma("unroll") for (int _i = 0; _i < 2; ++_i) \
;         __builtin_amdgcn_global_load_lds((const unsigned*)((const char*)(gbase) + (voff)[_i]), (PG8_LAS unsigned*)(lds + (bufoff) + ldsw + _i * 8192), 16, 0, 0); } while (0)
; #define PG8_LDA(dst, b, h) do { _Pragma("unroll") for (int m = 0; m < 4; ++m) _Pragma("unroll") for (int k = 0; k < 2; ++k) dst[m][k] = *(const PG8_LAS bf16x8*)(lds + PG8_SA(b, h) + aoff + m * 2048 + k * 1024); } while (0)
; #define PG8_LDB(dst, b, h) do { _Pragma("unroll") for (int n = 0; n < 2; ++n) _Pragma("unroll") for (int k = 0; k < 2; ++k) dst[n][k] = *(const PG8_LAS bf16x8*)(lds + PG8_SB(b, h) + boff + n * 2048 + k * 1024); } while (0)
; #define PG8_WAIT_V(n) asm volatile("s_waitcnt vmcnt(" #n ")" ::: "memory")
; #define PG8_WAIT_L(n) asm volatile("s_waitcnt lgkmcnt(" #n ")" ::: "memory")
; #define PG8_BAR __builtin_amdgcn_s_barrier()
; #define PG8_SCHED __builtin_amdgcn_sched_barrier(0)
; template <class Epi, class Sched, bool ALIGN_EPI = false, bool SP2 = false, bool I8 = false>
; __device__ __forceinline__ void gemm_phase(PG8_LAS unsigned char* lds, const Gemm g, const Sched& S, const Epi& E) {
;     ...
;             if constexpr (SP2) {
;             PG8_LDB(B0, 0, 0); PG8_LDB(B1, 0, 1); PG8_SCHED; PG8_LDA(At, 0, 0); PG8_STAGE(PG8_SA(1, 1), a1 + hstep, voffA);
;             PG8_WAIT_V(8); PG8_WAIT_L(0); PG8_BAR; PG8_MMA(0, 0, At, B0); PG8_MMA(0, 1, At, B1); PG8_BAR; PG8_SCHED;
;             PG8_LDA(At, 0, 1); PG8_STAGE(PG8_SB(0, 0), b2, voffB); PG8_STAGE(PG8_SB(0, 1), b2 + hstep, voffB); PG8_STAGE(PG8_SA(0, 0), a2, voffA);
;             PG8_WAIT_V(8); PG8_WAIT_L(0); PG8_BAR; PG8_MMA(1, 0, At, B0); PG8_MMA(1, 1, At, B1); PG8_BAR; PG8_SCHED;
;             PG8_LDB(B0, 1, 0); PG8_LDB(B1, 1, 1); PG8_SCHED; PG8_LDA(At, 1, 0); PG8_STAGE(PG8_SA(0, 1), a2 + hstep, voffA);
;             PG8_WAIT_V(8); PG8_WAIT_L(0); PG8_BAR; PG8_MMA(0, 0, At, B0); PG8_MMA(0, 1, At, B1); PG8_BAR; PG8_SCHED;
;             PG8_LDA(At, 1, 1); PG8_STAGE(PG8_SB(1, 0), b3, voffB); PG8_STAGE(PG8_SB(1, 1), b3 + hstep, voffB); PG8_STAGE(PG8_SA(1, 0), a3, voffA);
;             PG8_WAIT_V(8); PG8_WAIT_L(0); PG8_BAR; PG8_MMA(1, 0, At, B0); PG8_MMA(1, 1, At, B1); PG8_BAR; PG8_SCHED;
	v_mfma_i32_16x16x64_i8 v[80:83], v[28:31], v[164:167], 0
	s_waitcnt lgkmcnt(6)
	v_mfma_i32_16x16x64_i8 v[80:83], v[32:35], v[168:171], v[80:83]
	s_waitcnt lgkmcnt(5)
	v_mfma_i32_16x16x64_i8 v[64:67], v[32:35], v[176:179], 0
	s_waitcnt lgkmcnt(4)
	v_mfma_i32_16x16x64_i8 v[64:67], v[28:31], v[172:175], v[64:67]
	s_waitcnt lgkmcnt(3)
	v_mfma_i32_16x16x64_i8 v[48:51], v[28:31], v[204:207], 0
	s_waitcnt lgkmcnt(2)
	v_mfma_i32_16x16x64_i8 v[48:51], v[32:35], v[208:211], v[48:51]
	s_waitcnt lgkmcnt(1)
	v_mfma_i32_16x16x64_i8 v[16:19], v[32:35], v[220:223], 0
	s_waitcnt lgkmcnt(0)
	v_mfma_i32_16x16x64_i8 v[16:19], v[28:31], v[212:215], v[16:19]
	v_mfma_i32_16x16x64_i8 v[12:15], v[36:39], v[212:215], 0
	v_mfma_i32_16x16x64_i8 v[12:15], v[40:43], v[220:223], v[12:15]
	v_mfma_i32_16x16x64_i8 v[44:47], v[40:43], v[208:211], 0
	v_mfma_i32_16x16x64_i8 v[44:47], v[36:39], v[204:207], v[44:47]
	v_mfma_i32_16x16x64_i8 v[60:63], v[36:39], v[172:175], 0
	v_mfma_i32_16x16x64_i8 v[60:63], v[40:43], v[176:179], v[60:63]
	v_mfma_i32_16x16x64_i8 v[76:79], v[40:43], v[168:171], 0
	v_mfma_i32_16x16x64_i8 v[76:79], v[36:39], v[164:167], v[76:79]
	v_mfma_i32_16x16x64_i8 v[28:31], v[140:143], v[164:167], 0
	v_mfma_i32_16x16x64_i8 v[28:31], v[144:147], v[168:171], v[28:31]
	v_mfma_i32_16x16x64_i8 v[36:39], v[144:147], v[176:179], 0
	v_mfma_i32_16x16x64_i8 v[36:39], v[140:143], v[172:175], v[36:39]
	v_mfma_i32_16x16x64_i8 v[24:27], v[140:143], v[204:207], 0
	v_mfma_i32_16x16x64_i8 v[24:27], v[144:147], v[208:211], v[24:27]
	v_mfma_i32_16x16x64_i8 v[8:11], v[144:147], v[220:223], 0
	v_mfma_i32_16x16x64_i8 v[8:11], v[140:143], v[212:215], v[8:11]
	v_mfma_i32_16x16x64_i8 v[4:7], v[156:159], v[212:215], 0
	v_mfma_i32_16x16x64_i8 v[4:7], v[160:163], v[220:223], v[4:7]
	v_mfma_i32_16x16x64_i8 v[20:23], v[160:163], v[208:211], 0
	v_mfma_i32_16x16x64_i8 v[20:23], v[156:159], v[204:207], v[20:23]
	v_mfma_i32_16x16x64_i8 v[40:43], v[156:159], v[172:175], 0
	v_mfma_i32_16x16x64_i8 v[40:43], v[160:163], v[176:179], v[40:43]
	v_mfma_i32_16x16x64_i8 v[32:35], v[160:163], v[168:171], 0
	v_mfma_i32_16x16x64_i8 v[32:35], v[156:159], v[164:167], v[32:35]
	s_barrier
	s_setprio 0
	s_mov_b32 m0, s65
	s_nop 0
	global_load_lds_dwordx4 v[226:227], off
	s_mov_b32 m0, s67
	s_nop 0
	global_load_lds_dwordx4 v[228:229], off
	s_add_i32 s87, 0, 0x18000
	s_add_i32 s96, 0, 0x1c000
	v_add_u32_e32 v72, s87, v217
	v_add_u32_e32 v160, s96, v217
	ds_read_b128 v[52:55], v72
	ds_read_b128 v[164:167], v219 offset:32768
	ds_read_b128 v[56:59], v72 offset:1024
	ds_read_b128 v[168:171], v219 offset:33792
	ds_read_b128 v[176:179], v219 offset:35840
	ds_read_b128 v[172:175], v219 offset:34816
	ds_read_b128 v[204:207], v219 offset:36864
	ds_read_b128 v[208:211], v219 offset:37888
	s_add_u32 s60, s60, 0x80000
	s_addc_u32 s61, s61, 0
	s_mov_b32 m0, s72
	ds_read_b128 v[220:223], v219 offset:39936
	ds_read_b128 v[212:215], v219 offset:38912
	ds_read_b128 v[68:71], v72 offset:2048
	ds_read_b128 v[72:75], v72 offset:3072
	ds_read_b128 v[140:143], v160
	ds_read_b128 v[144:147], v160 offset:1024
	ds_read_b128 v[156:159], v160 offset:2048
	ds_read_b128 v[160:163], v160 offset:3072
	global_load_lds_dwordx4 v180, s[60:61]
	s_mov_b32 m0, s73
	s_nop 0
	global_load_lds_dwordx4 v182, s[60:61]
	s_waitcnt vmcnt(8)
	s_waitcnt lgkmcnt(14)
	s_setprio 1
	s_barrier
	v_mfma_i32_16x16x64_i8 v[152:155], v[52:55], v[164:167], v[152:155]
	s_waitcnt lgkmcnt(12)
	v_mfma_i32_16x16x64_i8 v[152:155], v[56:59], v[168:171], v[152:155]
	s_waitcnt lgkmcnt(11)
	v_mfma_i32_16x16x64_i8 v[128:131], v[56:59], v[176:179], v[128:131]
	s_waitcnt lgkmcnt(10)
	v_mfma_i32_16x16x64_i8 v[128:131], v[52:55], v[172:175], v[128:131]
	s_waitcnt lgkmcnt(9)
	v_mfma_i32_16x16x64_i8 v[112:115], v[52:55], v[204:207], v[112:115]
	s_waitcnt lgkmcnt(8)
	v_mfma_i32_16x16x64_i8 v[112:115], v[56:59], v[208:211], v[112:115]
	s_waitcnt lgkmcnt(7)
	v_mfma_i32_16x16x64_i8 v[96:99], v[56:59], v[220:223], v[96:99]
	s_waitcnt lgkmcnt(6)
	v_mfma_i32_16x16x64_i8 v[96:99], v[52:55], v[212:215], v[96:99]
	s_waitcnt lgkmcnt(5)
	v_mfma_i32_16x16x64_i8 v[92:95], v[68:71], v[212:215], v[92:95]
	s_waitcnt lgkmcnt(4)
	v_mfma_i32_16x16x64_i8 v[92:95], v[72:75], v[220:223], v[92:95]
	v_mfma_i32_16x16x64_i8 v[108:111], v[72:75], v[208:211], v[108:111]
	v_mfma_i32_16x16x64_i8 v[108:111], v[68:71], v[204:207], v[108:111]
	v_mfma_i32_16x16x64_i8 v[124:127], v[68:71], v[172:175], v[124:127]
	v_mfma_i32_16x16x64_i8 v[124:127], v[72:75], v[176:179], v[124:127]
	v_mfma_i32_16x16x64_i8 v[148:151], v[72:75], v[168:171], v[148:151]
	v_mfma_i32_16x16x64_i8 v[148:151], v[68:71], v[164:167], v[148:151]
	s_waitcnt lgkmcnt(3)
	v_mfma_i32_16x16x64_i8 v[136:139], v[140:143], v[164:167], v[136:139]
	s_waitcnt lgkmcnt(2)
	v_mfma_i32_16x16x64_i8 v[136:139], v[144:147], v[168:171], v[136:139]
	v_mfma_i32_16x16x64_i8 v[120:123], v[144:147], v[176:179], v[120:123]
	v_mfma_i32_16x16x64_i8 v[120:123], v[140:143], v[172:175], v[120:123]
	v_mfma_i32_16x16x64_i8 v[104:107], v[140:143], v[204:207], v[104:107]
	v_mfma_i32_16x16x64_i8 v[104:107], v[144:147], v[208:211], v[104:107]
	v_mfma_i32_16x16x64_i8 v[88:91], v[144:147], v[220:223], v[88:91]
	v_mfma_i32_16x16x64_i8 v[88:91], v[140:143], v[212:215], v[88:91]
	s_waitcnt lgkmcnt(1)
	v_mfma_i32_16x16x64_i8 v[84:87], v[156:159], v[212:215], v[84:87]
	s_waitcnt lgkmcnt(0)
	v_mfma_i32_16x16x64_i8 v[84:87], v[160:163], v[220:223], v[84:87]
	v_mfma_i32_16x16x64_i8 v[100:103], v[160:163], v[208:211], v[100:103]
	v_mfma_i32_16x16x64_i8 v[100:103], v[156:159], v[204:207], v[100:103]
	v_mfma_i32_16x16x64_i8 v[116:119], v[156:159], v[172:175], v[116:119]
	v_mfma_i32_16x16x64_i8 v[116:119], v[160:163], v[176:179], v[116:119]
	v_mfma_i32_16x16x64_i8 v[132:135], v[160:163], v[168:171], v[132:135]
	v_mfma_i32_16x16x64_i8 v[132:135], v[156:159], v[164:167], v[132:135]
	s_barrier
	s_setprio 0
	s_add_i32 s60, s87, s46
	v_lshl_add_u64 v[190:191], v[190:191], 0, s[84:85]
	s_mov_b32 m0, s60
	ds_read_b128 v[164:167], v219 offset:49152
	ds_read_b128 v[168:171], v219 offset:50176
	ds_read_b128 v[176:179], v219 offset:52224
	ds_read_b128 v[172:175], v219 offset:51200
	ds_read_b128 v[204:207], v219 offset:53248
	ds_read_b128 v[208:211], v219 offset:54272
	ds_read_b128 v[220:223], v219 offset:56320
	ds_read_b128 v[212:215], v219 offset:55296
	global_load_lds_dwordx4 v[190:191], off
	s_add_i32 m0, s60, 0x2000
	s_add_u32 s58, s58, 0x80080
	v_lshl_add_u64 v[190:191], v[224:225], 0, s[84:85]
	s_addc_u32 s59, s59, 0
	s_add_i32 s60, s96, s46
	global_load_lds_dwordx4 v[190:191], off
	s_mov_b32 m0, s60
	s_nop 0
	global_load_lds_dwordx4 v2, s[58:59]
	s_add_i32 m0, s60, 0x2000
	s_nop 0
	global_load_lds_dwordx4 v184, s[58:59]
	s_cmp_eq_u32 s86, 28
	s_cbranch_scc0 .Ldefer_1843_peel
	v_lshl_add_u64 v[190:191], v[226:227], 0, s[84:85]
	s_mov_b32 m0, s28
	s_nop 0
	global_load_lds_dwordx4 v[190:191], off
	v_lshl_add_u64 v[190:191], v[228:229], 0, s[84:85]
	s_mov_b32 m0, s77
	s_nop 0
	global_load_lds_dwordx4 v[190:191], off
; #define PG8_STAGE(bufoff, gbase, voff) do { _Pragma("unroll") for (int _i = 0; _i < 2; ++_i) \
;         __builtin_amdgcn_global_load_lds((const unsigned*)((const char*)(gbase) + (voff)[_i]), (PG8_LAS unsigned*)(lds + (bufoff) + ldsw + _i * 8192), 16, 0, 0); } while (0)
; #define PG8_LDA(dst, b, h) do { _Pragma("unroll") for (int m = 0; m < 4; ++m) _Pragma("unroll") for (int k = 0; k < 2; ++k) dst[m][k] = *(const PG8_LAS bf16x8*)(lds + PG8_SA(b, h) + aoff + m * 2048 + k * 1024); } while (0)
; #define PG8_WAIT_V(n) asm volatile("s_waitcnt vmcnt(" #n ")" ::: "memory")
; #define PG8_WAIT_L(n) asm volatile("s_waitcnt lgkmcnt(" #n ")" ::: "memory")
; #define PG8_BAR __builtin_amdgcn_s_barrier()
; template <class Epi, class Sched, bool ALIGN_EPI = false, bool SP2 = false, bool I8 = false>
; __device__ __forceinline__ void gemm_phase(PG8_LAS unsigned char* lds, const Gemm g, const Sched& S, const Epi& E) {
;     ...
;         for (int t = 0; t < nt; t += 2) {
;             const bool last = (t == nt - 2);
;             const char* a1 = cA + (size_t)(t + 1) * kstep;
;             const char* a2 = last ? nA : cA + (size_t)(t + 2) * kstep; const char* b2 = last ? nB : cB + (size_t)(t + 2) * kstep;
;             const char* a3 = a2 + kstep; const char* b3 = b2 + kstep;
;             if (last && has_next) S.a_ready(nxt);
;             if constexpr (SP2) {
;             PG8_LDB(B0, 0, 0); PG8_LDB(B1, 0, 1); PG8_SCHED; PG8_LDA(At, 0, 0); PG8_STAGE(PG8_SA(1, 1), a1 + hstep, voffA);
;             PG8_WAIT_V(8); PG8_WAIT_L(0); PG8_BAR; PG8_MMA(0, 0, At, B0); PG8_MMA(0, 1, At, B1); PG8_BAR; PG8_SCHED;
;             PG8_LDA(At, 0, 1); PG8_STAGE(PG8_SB(0, 0), b2, voffB); PG8_STAGE(PG8_SB(0, 1), b2 + hstep, voffB); PG8_STAGE(PG8_SA(0, 0), a2, voffA);
;             PG8_WAIT_V(8); PG8_WAIT_L(0); PG8_BAR; PG8_MMA(1, 0, At, B0); PG8_MMA(1, 1, At, B1); PG8_BAR; PG8_SCHED;
;             PG8_LDB(B0, 1, 0); PG8_LDB(B1, 1, 1); PG8_SCHED; PG8_LDA(At, 1, 0); PG8_STAGE(PG8_SA(0, 1), a2 + hstep, voffA);
;             PG8_WAIT_V(8); PG8_WAIT_L(0); PG8_BAR; PG8_MMA(0, 0, At, B0); PG8_MMA(0, 1, At, B1); PG8_BAR; PG8_SCHED;
;             PG8_LDA(At, 1, 1); PG8_STAGE(PG8_SB(1, 0), b3, voffB); PG8_STAGE(PG8_SB(1, 1), b3 + hstep, voffB); PG8_STAGE(PG8_SA(1, 0), a3, voffA);
;             PG8_WAIT_V(8); PG8_WAIT_L(0); PG8_BAR; PG8_MMA(1, 0, At, B0); PG8_MMA(1, 1, At, B1); PG8_BAR; PG8_SCHED;
.Ldefer_1843_peel:
	s_waitcnt vmcnt(6)
	s_waitcnt lgkmcnt(7)
	s_setprio 1
	s_barrier
	v_mfma_i32_16x16x64_i8 v[80:83], v[52:55], v[164:167], v[80:83]
	s_waitcnt lgkmcnt(6)
	v_mfma_i32_16x16x64_i8 v[80:83], v[56:59], v[168:171], v[80:83]
	s_waitcnt lgkmcnt(5)
	v_mfma_i32_16x16x64_i8 v[64:67], v[56:59], v[176:179], v[64:67]
	s_waitcnt lgkmcnt(4)
	v_mfma_i32_16x16x64_i8 v[64:67], v[52:55], v[172:175], v[64:67]
	s_waitcnt lgkmcnt(3)
	v_mfma_i32_16x16x64_i8 v[48:51], v[52:55], v[204:207], v[48:51]
	s_waitcnt lgkmcnt(2)
	v_mfma_i32_16x16x64_i8 v[48:51], v[56:59], v[208:211], v[48:51]
	s_waitcnt lgkmcnt(1)
	v_mfma_i32_16x16x64_i8 v[16:19], v[56:59], v[220:223], v[16:19]
	s_waitcnt lgkmcnt(0)
	v_mfma_i32_16x16x64_i8 v[16:19], v[52:55], v[212:215], v[16:19]
	v_mfma_i32_16x16x64_i8 v[12:15], v[68:71], v[212:215], v[12:15]
	v_mfma_i32_16x16x64_i8 v[12:15], v[72:75], v[220:223], v[12:15]
	v_mfma_i32_16x16x64_i8 v[44:47], v[72:75], v[208:211], v[44:47]
	v_mfma_i32_16x16x64_i8 v[44:47], v[68:71], v[204:207], v[44:47]
	v_mfma_i32_16x16x64_i8 v[60:63], v[68:71], v[172:175], v[60:63]
	v_mfma_i32_16x16x64_i8 v[60:63], v[72:75], v[176:179], v[60:63]
	v_mfma_i32_16x16x64_i8 v[76:79], v[72:75], v[168:171], v[76:79]
	v_mfma_i32_16x16x64_i8 v[76:79], v[68:71], v[164:167], v[76:79]
	v_mfma_i32_16x16x64_i8 v[28:31], v[140:143], v[164:167], v[28:31]
	v_mfma_i32_16x16x64_i8 v[72:75], v[144:147], v[168:171], v[28:31]
	v_mfma_i32_16x16x64_i8 v[28:31], v[144:147], v[176:179], v[36:39]
	v_mfma_i32_16x16x64_i8 v[56:59], v[140:143], v[172:175], v[28:31]
	v_mfma_i32_16x16x64_i8 v[24:27], v[140:143], v[204:207], v[24:27]
	v_mfma_i32_16x16x64_i8 v[24:27], v[144:147], v[208:211], v[24:27]
	v_mfma_i32_16x16x64_i8 v[8:11], v[144:147], v[220:223], v[8:11]
	v_mfma_i32_16x16x64_i8 v[8:11], v[140:143], v[212:215], v[8:11]
	v_mfma_i32_16x16x64_i8 v[4:7], v[156:159], v[212:215], v[4:7]
	v_mfma_i32_16x16x64_i8 v[4:7], v[160:163], v[220:223], v[4:7]
	v_mfma_i32_16x16x64_i8 v[20:23], v[160:163], v[208:211], v[20:23]
	v_mfma_i32_16x16x64_i8 v[20:23], v[156:159], v[204:207], v[20:23]
	v_mfma_i32_16x16x64_i8 v[28:31], v[156:159], v[172:175], v[40:43]
	v_mfma_i32_16x16x64_i8 v[52:55], v[160:163], v[176:179], v[28:31]
	v_mfma_i32_16x16x64_i8 v[28:31], v[160:163], v[168:171], v[32:35]
	v_mfma_i32_16x16x64_i8 v[68:71], v[156:159], v[164:167], v[28:31]
	s_barrier
	s_setprio 0
	s_add_i32 s86, s86, 2
	s_add_u32 s54, s54, 0x100
	s_addc_u32 s55, s55, 0
	s_add_u32 s45, s45, 0x100
	s_addc_u32 s49, s49, 0
	s_cmp_gt_u32 s86, 29
	s_cbranch_scc1 .Lkloop_exit_6
.LBB0_1843:
	s_add_u32 s58, s54, 0xfff80080
	s_addc_u32 s59, s55, -1
	s_add_i32 s87, 0, 0x10000
	s_cmp_eq_u32 s86, 28
	s_cselect_b32 s61, s11, s59
	s_cselect_b32 s60, s13, s58
	s_cselect_b32 s59, s34, s49
	s_cselect_b32 s58, s35, s45
	s_add_i32 vcc_lo, 0, 0x14000
	v_add_u32_e32 v40, s87, v217
	v_add_u32_e32 v160, vcc_lo, v217
	ds_read_b128 v[28:31], v40
	ds_read_b128 v[164:167], v219
	ds_read_b128 v[32:35], v40 offset:1024
	ds_read_b128 v[168:171], v219 offset:1024
	ds_read_b128 v[176:179], v219 offset:3072
	ds_read_b128 v[172:175], v219 offset:2048
	ds_read_b128 v[204:207], v219 offset:4096
	ds_read_b128 v[208:211], v219 offset:5120
	v_lshl_add_u64 v[190:191], v[226:227], 0, s[84:85]
	s_mov_b32 m0, s28
	s_nop 0
	global_load_lds_dwordx4 v[190:191], off
	v_lshl_add_u64 v[190:191], v[228:229], 0, s[84:85]
	s_mov_b32 m0, s77
	s_nop 0
	global_load_lds_dwordx4 v[190:191], off
	s_add_i32 m0, s65, 0xc000
	ds_read_b128 v[220:223], v219 offset:7168
	ds_read_b128 v[212:215], v219 offset:6144
	ds_read_b128 v[36:39], v40 offset:2048
	ds_read_b128 v[40:43], v40 offset:3072
	ds_read_b128 v[140:143], v160
	ds_read_b128 v[144:147], v160 offset:1024
	ds_read_b128 v[156:159], v160 offset:2048
	ds_read_b128 v[160:163], v160 offset:3072
	global_load_lds_dwordx4 v186, s[54:55]
	s_add_i32 m0, s65, 0xe000
	s_nop 0
	global_load_lds_dwordx4 v188, s[54:55]
	s_waitcnt vmcnt(8)
	s_waitcnt lgkmcnt(14)
	s_setprio 1
	s_barrier
	v_mfma_i32_16x16x64_i8 v[152:155], v[28:31], v[164:167], v[152:155]
	s_waitcnt lgkmcnt(12)
	v_mfma_i32_16x16x64_i8 v[152:155], v[32:35], v[168:171], v[152:155]
	s_waitcnt lgkmcnt(11)
	v_mfma_i32_16x16x64_i8 v[128:131], v[32:35], v[176:179], v[128:131]
	s_waitcnt lgkmcnt(10)
	v_mfma_i32_16x16x64_i8 v[128:131], v[28:31], v[172:175], v[128:131]
	s_waitcnt lgkmcnt(9)
	v_mfma_i32_16x16x64_i8 v[112:115], v[28:31], v[204:207], v[112:115]
	s_waitcnt lgkmcnt(8)
	v_mfma_i32_16x16x64_i8 v[112:115], v[32:35], v[208:211], v[112:115]
	s_waitcnt lgkmcnt(7)
	v_mfma_i32_16x16x64_i8 v[96:99], v[32:35], v[220:223], v[96:99]
	s_waitcnt lgkmcnt(6)
	v_mfma_i32_16x16x64_i8 v[96:99], v[28:31], v[212:215], v[96:99]
	s_waitcnt lgkmcnt(5)
	v_mfma_i32_16x16x64_i8 v[92:95], v[36:39], v[212:215], v[92:95]
	s_waitcnt lgkmcnt(4)
	v_mfma_i32_16x16x64_i8 v[92:95], v[40:43], v[220:223], v[92:95]
	v_mfma_i32_16x16x64_i8 v[108:111], v[40:43], v[208:211], v[108:111]
	v_mfma_i32_16x16x64_i8 v[108:111], v[36:39], v[204:207], v[108:111]
	v_mfma_i32_16x16x64_i8 v[124:127], v[36:39], v[172:175], v[124:127]
	v_mfma_i32_16x16x64_i8 v[124:127], v[40:43], v[176:179], v[124:127]
	v_mfma_i32_16x16x64_i8 v[148:151], v[40:43], v[168:171], v[148:151]
	v_mfma_i32_16x16x64_i8 v[148:151], v[36:39], v[164:167], v[148:151]
	s_waitcnt lgkmcnt(3)
	v_mfma_i32_16x16x64_i8 v[136:139], v[140:143], v[164:167], v[136:139]
	s_waitcnt lgkmcnt(2)
	v_mfma_i32_16x16x64_i8 v[136:139], v[144:147], v[168:171], v[136:139]
	v_mfma_i32_16x16x64_i8 v[120:123], v[144:147], v[176:179], v[120:123]
	v_mfma_i32_16x16x64_i8 v[120:123], v[140:143], v[172:175], v[120:123]
	v_mfma_i32_16x16x64_i8 v[104:107], v[140:143], v[204:207], v[104:107]
	v_mfma_i32_16x16x64_i8 v[104:107], v[144:147], v[208:211], v[104:107]
	v_mfma_i32_16x16x64_i8 v[88:91], v[144:147], v[220:223], v[88:91]
	v_mfma_i32_16x16x64_i8 v[88:91], v[140:143], v[212:215], v[88:91]
	s_waitcnt lgkmcnt(1)
	v_mfma_i32_16x16x64_i8 v[84:87], v[156:159], v[212:215], v[84:87]
	s_waitcnt lgkmcnt(0)
	v_mfma_i32_16x16x64_i8 v[84:87], v[160:163], v[220:223], v[84:87]
	v_mfma_i32_16x16x64_i8 v[100:103], v[160:163], v[208:211], v[100:103]
	v_mfma_i32_16x16x64_i8 v[100:103], v[156:159], v[204:207], v[100:103]
	v_mfma_i32_16x16x64_i8 v[116:119], v[156:159], v[172:175], v[116:119]
	v_mfma_i32_16x16x64_i8 v[116:119], v[160:163], v[176:179], v[116:119]
	v_mfma_i32_16x16x64_i8 v[132:135], v[160:163], v[168:171], v[132:135]
	v_mfma_i32_16x16x64_i8 v[132:135], v[156:159], v[164:167], v[132:135]
	s_barrier
; #define PG8_STAGE(bufoff, gbase, voff) do { _Pragma("unroll") for (int _i = 0; _i < 2; ++_i) \
;         __builtin_amdgcn_global_load_lds((const unsigned*)((const char*)(gbase) + (voff)[_i]), (PG8_LAS unsigned*)(lds + (bufoff) + ldsw + _i * 8192), 16, 0, 0); } while (0)
; #define PG8_LDA(dst, b, h) do { _Pragma("unroll") for (int m = 0; m < 4; ++m) _Pragma("unroll") for (int k = 0; k < 2; ++k) dst[m][k] = *(const PG8_LAS bf16x8*)(lds + PG8_SA(b, h) + aoff + m * 2048 + k * 1024); } while (0)
; #define PG8_LDB(dst, b, h) do { _Pragma("unroll") for (int n = 0; n < 2; ++n) _Pragma("unroll") for (int k = 0; k < 2; ++k) dst[n][k] = *(const PG8_LAS bf16x8*)(lds + PG8_SB(b, h) + boff + n * 2048 + k * 1024); } while (0)
; #define PG8_WAIT_V(n) asm volatile("s_waitcnt vmcnt(" #n ")" ::: "memory")
; #define PG8_WAIT_L(n) asm volatile("s_waitcnt lgkmcnt(" #n ")" ::: "memory")
; #define PG8_BAR __builtin_amdgcn_s_barrier()
; #define PG8_SCHED __builtin_amdgcn_sched_barrier(0)
; template <class Epi, class Sched, bool ALIGN_EPI = false, bool SP2 = false, bool I8 = false>
; __device__ __forceinline__ void gemm_phase(PG8_LAS unsigned char* lds, const Gemm g, const Sched& S, const Epi& E) {
;     ...
;             if constexpr (SP2) {
;             PG8_LDB(B0, 0, 0); PG8_LDB(B1, 0, 1); PG8_SCHED; PG8_LDA(At, 0, 0); PG8_STAGE(PG8_SA(1, 1), a1 + hstep, voffA);
;             PG8_WAIT_V(8); PG8_WAIT_L(0); PG8_BAR; PG8_MMA(0, 0, At, B0); PG8_MMA(0, 1, At, B1); PG8_BAR; PG8_SCHED;
;             PG8_LDA(At, 0, 1); PG8_STAGE(PG8_SB(0, 0), b2, voffB); PG8_STAGE(PG8_SB(0, 1), b2 + hstep, voffB); PG8_STAGE(PG8_SA(0, 0), a2, voffA);
;             PG8_WAIT_V(8); PG8_WAIT_L(0); PG8_BAR; PG8_MMA(1, 0, At, B0); PG8_MMA(1, 1, At, B1); PG8_BAR; PG8_SCHED;
;             PG8_LDB(B0, 1, 0); PG8_LDB(B1, 1, 1); PG8_SCHED; PG8_LDA(At, 1, 0); PG8_STAGE(PG8_SA(0, 1), a2 + hstep, voffA);
;             PG8_WAIT_V(8); PG8_WAIT_L(0); PG8_BAR; PG8_MMA(0, 0, At, B0); PG8_MMA(0, 1, At, B1); PG8_BAR; PG8_SCHED;
;             PG8_LDA(At, 1, 1); PG8_STAGE(PG8_SB(1, 0), b3, voffB); PG8_STAGE(PG8_SB(1, 1), b3 + hstep, voffB); PG8_STAGE(PG8_SA(1, 0), a3, voffA);
;             PG8_WAIT_V(8); PG8_WAIT_L(0); PG8_BAR; PG8_MMA(1, 0, At, B0); PG8_MMA(1, 1, At, B1); PG8_BAR; PG8_SCHED;
	s_setprio 0
	s_add_i32 s87, s87, s46
	v_lshl_add_u64 v[190:191], s[58:59], 0, v[2:3]
	s_mov_b32 m0, s87
	ds_read_b128 v[164:167], v219 offset:16384
	ds_read_b128 v[168:171], v219 offset:17408
	ds_read_b128 v[176:179], v219 offset:19456
	ds_read_b128 v[172:175], v219 offset:18432
	ds_read_b128 v[204:207], v219 offset:20480
	ds_read_b128 v[208:211], v219 offset:21504
	ds_read_b128 v[220:223], v219 offset:23552
	ds_read_b128 v[212:215], v219 offset:22528
	global_load_lds_dwordx4 v[190:191], off
	s_add_i32 m0, s87, 0x2000
	s_add_u32 s96, s58, 0x80000
	v_lshl_add_u64 v[224:225], s[58:59], 0, v[184:185]
	s_addc_u32 s97, s59, 0
	s_add_i32 s87, vcc_lo, s46
	global_load_lds_dwordx4 v[224:225], off
	s_mov_b32 m0, s87
	v_lshl_add_u64 v[228:229], s[60:61], 0, v[182:183]
	global_load_lds_dwordx4 v2, s[96:97]
	s_add_i32 m0, s87, 0x2000
	s_nop 0
	global_load_lds_dwordx4 v184, s[96:97]
	v_lshl_add_u64 v[226:227], s[60:61], 0, v[180:181]
	s_waitcnt vmcnt(6)
	s_waitcnt lgkmcnt(7)
	s_setprio 1
	s_barrier
	v_mfma_i32_16x16x64_i8 v[80:83], v[28:31], v[164:167], v[80:83]
	s_waitcnt lgkmcnt(6)
	v_mfma_i32_16x16x64_i8 v[80:83], v[32:35], v[168:171], v[80:83]
	s_waitcnt lgkmcnt(5)
	v_mfma_i32_16x16x64_i8 v[64:67], v[32:35], v[176:179], v[64:67]
	s_waitcnt lgkmcnt(4)
	v_mfma_i32_16x16x64_i8 v[64:67], v[28:31], v[172:175], v[64:67]
	s_waitcnt lgkmcnt(3)
	v_mfma_i32_16x16x64_i8 v[48:51], v[28:31], v[204:207], v[48:51]
	s_waitcnt lgkmcnt(2)
	v_mfma_i32_16x16x64_i8 v[48:51], v[32:35], v[208:211], v[48:51]
	s_waitcnt lgkmcnt(1)
	v_mfma_i32_16x16x64_i8 v[16:19], v[32:35], v[220:223], v[16:19]
	s_waitcnt lgkmcnt(0)
	v_mfma_i32_16x16x64_i8 v[16:19], v[28:31], v[212:215], v[16:19]
	v_mfma_i32_16x16x64_i8 v[12:15], v[36:39], v[212:215], v[12:15]
	v_mfma_i32_16x16x64_i8 v[12:15], v[40:43], v[220:223], v[12:15]
	v_mfma_i32_16x16x64_i8 v[44:47], v[40:43], v[208:211], v[44:47]
	v_mfma_i32_16x16x64_i8 v[44:47], v[36:39], v[204:207], v[44:47]
	v_mfma_i32_16x16x64_i8 v[60:63], v[36:39], v[172:175], v[60:63]
	v_mfma_i32_16x16x64_i8 v[60:63], v[40:43], v[176:179], v[60:63]
	v_mfma_i32_16x16x64_i8 v[76:79], v[40:43], v[168:171], v[76:79]
	v_mfma_i32_16x16x64_i8 v[76:79], v[36:39], v[164:167], v[76:79]
	v_mfma_i32_16x16x64_i8 v[28:31], v[140:143], v[164:167], v[72:75]
	v_mfma_i32_16x16x64_i8 v[28:31], v[144:147], v[168:171], v[28:31]
	v_mfma_i32_16x16x64_i8 v[36:39], v[144:147], v[176:179], v[56:59]
	v_mfma_i32_16x16x64_i8 v[36:39], v[140:143], v[172:175], v[36:39]
	v_mfma_i32_16x16x64_i8 v[24:27], v[140:143], v[204:207], v[24:27]
	v_mfma_i32_16x16x64_i8 v[24:27], v[144:147], v[208:211], v[24:27]
	v_mfma_i32_16x16x64_i8 v[8:11], v[144:147], v[220:223], v[8:11]
	v_mfma_i32_16x16x64_i8 v[8:11], v[140:143], v[212:215], v[8:11]
	v_mfma_i32_16x16x64_i8 v[4:7], v[156:159], v[212:215], v[4:7]
	v_mfma_i32_16x16x64_i8 v[4:7], v[160:163], v[220:223], v[4:7]
	v_mfma_i32_16x16x64_i8 v[20:23], v[160:163], v[208:211], v[20:23]
	v_mfma_i32_16x16x64_i8 v[20:23], v[156:159], v[204:207], v[20:23]
	v_mfma_i32_16x16x64_i8 v[40:43], v[156:159], v[172:175], v[52:55]
	v_mfma_i32_16x16x64_i8 v[40:43], v[160:163], v[176:179], v[40:43]
	v_mfma_i32_16x16x64_i8 v[32:35], v[160:163], v[168:171], v[68:71]
	v_mfma_i32_16x16x64_i8 v[32:35], v[156:159], v[164:167], v[32:35]
	s_barrier
	s_setprio 0
	s_mov_b32 m0, s65
	s_nop 0
	global_load_lds_dwordx4 v[226:227], off
	s_mov_b32 m0, s67
	s_nop 0
	global_load_lds_dwordx4 v[228:229], off
	s_add_i32 s87, 0, 0x18000
	s_add_i32 s96, 0, 0x1c000
	v_add_u32_e32 v72, s87, v217
	v_add_u32_e32 v160, s96, v217
	ds_read_b128 v[52:55], v72
	ds_read_b128 v[164:167], v219 offset:32768
	ds_read_b128 v[56:59], v72 offset:1024
	ds_read_b128 v[168:171], v219 offset:33792
	ds_read_b128 v[176:179], v219 offset:35840
	ds_read_b128 v[172:175], v219 offset:34816
	ds_read_b128 v[204:207], v219 offset:36864
	ds_read_b128 v[208:211], v219 offset:37888
	s_add_u32 s60, s60, 0x80000
	s_addc_u32 s61, s61, 0
	s_mov_b32 m0, s72
	ds_read_b128 v[220:223], v219 offset:39936
	ds_read_b128 v[212:215], v219 offset:38912
	ds_read_b128 v[68:71], v72 offset:2048
	ds_read_b128 v[72:75], v72 offset:3072
	ds_read_b128 v[140:143], v160
	ds_read_b128 v[144:147], v160 offset:1024
	ds_read_b128 v[156:159], v160 offset:2048
	ds_read_b128 v[160:163], v160 offset:3072
	global_load_lds_dwordx4 v180, s[60:61]
	s_mov_b32 m0, s73
	s_nop 0
	global_load_lds_dwordx4 v182, s[60:61]
	s_waitcnt vmcnt(8)
	s_waitcnt lgkmcnt(14)
	s_setprio 1
	s_barrier
; #define PG8_STAGE(bufoff, gbase, voff) do { _Pragma("unroll") for (int _i = 0; _i < 2; ++_i) \
;         __builtin_amdgcn_global_load_lds((const unsigned*)((const char*)(gbase) + (voff)[_i]), (PG8_LAS unsigned*)(lds + (bufoff) + ldsw + _i * 8192), 16, 0, 0); } while (0)
; #define PG8_LDA(dst, b, h) do { _Pragma("unroll") for (int m = 0; m < 4; ++m) _Pragma("unroll") for (int k = 0; k < 2; ++k) dst[m][k] = *(const PG8_LAS bf16x8*)(lds + PG8_SA(b, h) + aoff + m * 2048 + k * 1024); } while (0)
; #define PG8_LDB(dst, b, h) do { _Pragma("unroll") for (int n = 0; n < 2; ++n) _Pragma("unroll") for (int k = 0; k < 2; ++k) dst[n][k] = *(const PG8_LAS bf16x8*)(lds + PG8_SB(b, h) + boff + n * 2048 + k * 1024); } while (0)
; #define PG8_WAIT_V(n) asm volatile("s_waitcnt vmcnt(" #n ")" ::: "memory")
; #define PG8_WAIT_L(n) asm volatile("s_waitcnt lgkmcnt(" #n ")" ::: "memory")
; #define PG8_BAR __builtin_amdgcn_s_barrier()
; #define PG8_SCHED __builtin_amdgcn_sched_barrier(0)
; template <class Epi, class Sched, bool ALIGN_EPI = false, bool SP2 = false, bool I8 = false>
; __device__ __forceinline__ void gemm_phase(PG8_LAS unsigned char* lds, const Gemm g, const Sched& S, const Epi& E) {
;     ...
;             if constexpr (SP2) {
;             PG8_LDB(B0, 0, 0); PG8_LDB(B1, 0, 1); PG8_SCHED; PG8_LDA(At, 0, 0); PG8_STAGE(PG8_SA(1, 1), a1 + hstep, voffA);
;             PG8_WAIT_V(8); PG8_WAIT_L(0); PG8_BAR; PG8_MMA(0, 0, At, B0); PG8_MMA(0, 1, At, B1); PG8_BAR; PG8_SCHED;
;             PG8_LDA(At, 0, 1); PG8_STAGE(PG8_SB(0, 0), b2, voffB); PG8_STAGE(PG8_SB(0, 1), b2 + hstep, voffB); PG8_STAGE(PG8_SA(0, 0), a2, voffA);
;             PG8_WAIT_V(8); PG8_WAIT_L(0); PG8_BAR; PG8_MMA(1, 0, At, B0); PG8_MMA(1, 1, At, B1); PG8_BAR; PG8_SCHED;
;             PG8_LDB(B0, 1, 0); PG8_LDB(B1, 1, 1); PG8_SCHED; PG8_LDA(At, 1, 0); PG8_STAGE(PG8_SA(0, 1), a2 + hstep, voffA);
;             PG8_WAIT_V(8); PG8_WAIT_L(0); PG8_BAR; PG8_MMA(0, 0, At, B0); PG8_MMA(0, 1, At, B1); PG8_BAR; PG8_SCHED;
;             PG8_LDA(At, 1, 1); PG8_STAGE(PG8_SB(1, 0), b3, voffB); PG8_STAGE(PG8_SB(1, 1), b3 + hstep, voffB); PG8_STAGE(PG8_SA(1, 0), a3, voffA);
;             PG8_WAIT_V(8); PG8_WAIT_L(0); PG8_BAR; PG8_MMA(1, 0, At, B0); PG8_MMA(1, 1, At, B1); PG8_BAR; PG8_SCHED;
	v_mfma_i32_16x16x64_i8 v[152:155], v[52:55], v[164:167], v[152:155]
	s_waitcnt lgkmcnt(12)
	v_mfma_i32_16x16x64_i8 v[152:155], v[56:59], v[168:171], v[152:155]
	s_waitcnt lgkmcnt(11)
	v_mfma_i32_16x16x64_i8 v[128:131], v[56:59], v[176:179], v[128:131]
	s_waitcnt lgkmcnt(10)
	v_mfma_i32_16x16x64_i8 v[128:131], v[52:55], v[172:175], v[128:131]
	s_waitcnt lgkmcnt(9)
	v_mfma_i32_16x16x64_i8 v[112:115], v[52:55], v[204:207], v[112:115]
	s_waitcnt lgkmcnt(8)
	v_mfma_i32_16x16x64_i8 v[112:115], v[56:59], v[208:211], v[112:115]
	s_waitcnt lgkmcnt(7)
	v_mfma_i32_16x16x64_i8 v[96:99], v[56:59], v[220:223], v[96:99]
	s_waitcnt lgkmcnt(6)
	v_mfma_i32_16x16x64_i8 v[96:99], v[52:55], v[212:215], v[96:99]
	s_waitcnt lgkmcnt(5)
	v_mfma_i32_16x16x64_i8 v[92:95], v[68:71], v[212:215], v[92:95]
	s_waitcnt lgkmcnt(4)
	v_mfma_i32_16x16x64_i8 v[92:95], v[72:75], v[220:223], v[92:95]
	v_mfma_i32_16x16x64_i8 v[108:111], v[72:75], v[208:211], v[108:111]
	v_mfma_i32_16x16x64_i8 v[108:111], v[68:71], v[204:207], v[108:111]
	v_mfma_i32_16x16x64_i8 v[124:127], v[68:71], v[172:175], v[124:127]
	v_mfma_i32_16x16x64_i8 v[124:127], v[72:75], v[176:179], v[124:127]
	v_mfma_i32_16x16x64_i8 v[148:151], v[72:75], v[168:171], v[148:151]
	v_mfma_i32_16x16x64_i8 v[148:151], v[68:71], v[164:167], v[148:151]
	s_waitcnt lgkmcnt(3)
	v_mfma_i32_16x16x64_i8 v[136:139], v[140:143], v[164:167], v[136:139]
	s_waitcnt lgkmcnt(2)
	v_mfma_i32_16x16x64_i8 v[136:139], v[144:147], v[168:171], v[136:139]
	v_mfma_i32_16x16x64_i8 v[120:123], v[144:147], v[176:179], v[120:123]
	v_mfma_i32_16x16x64_i8 v[120:123], v[140:143], v[172:175], v[120:123]
	v_mfma_i32_16x16x64_i8 v[104:107], v[140:143], v[204:207], v[104:107]
	v_mfma_i32_16x16x64_i8 v[104:107], v[144:147], v[208:211], v[104:107]
	v_mfma_i32_16x16x64_i8 v[88:91], v[144:147], v[220:223], v[88:91]
	v_mfma_i32_16x16x64_i8 v[88:91], v[140:143], v[212:215], v[88:91]
	s_waitcnt lgkmcnt(1)
	v_mfma_i32_16x16x64_i8 v[84:87], v[156:159], v[212:215], v[84:87]
	s_waitcnt lgkmcnt(0)
	v_mfma_i32_16x16x64_i8 v[84:87], v[160:163], v[220:223], v[84:87]
	v_mfma_i32_16x16x64_i8 v[100:103], v[160:163], v[208:211], v[100:103]
	v_mfma_i32_16x16x64_i8 v[100:103], v[156:159], v[204:207], v[100:103]
	v_mfma_i32_16x16x64_i8 v[116:119], v[156:159], v[172:175], v[116:119]
	v_mfma_i32_16x16x64_i8 v[116:119], v[160:163], v[176:179], v[116:119]
	v_mfma_i32_16x16x64_i8 v[132:135], v[160:163], v[168:171], v[132:135]
	v_mfma_i32_16x16x64_i8 v[132:135], v[156:159], v[164:167], v[132:135]
	s_barrier
	s_setprio 0
	s_add_i32 s60, s87, s46
	v_lshl_add_u64 v[190:191], v[190:191], 0, s[84:85]
	s_mov_b32 m0, s60
	ds_read_b128 v[164:167], v219 offset:49152
	ds_read_b128 v[168:171], v219 offset:50176
	ds_read_b128 v[176:179], v219 offset:52224
	ds_read_b128 v[172:175], v219 offset:51200
	ds_read_b128 v[204:207], v219 offset:53248
	ds_read_b128 v[208:211], v219 offset:54272
	ds_read_b128 v[220:223], v219 offset:56320
	ds_read_b128 v[212:215], v219 offset:55296
	global_load_lds_dwordx4 v[190:191], off
	s_add_i32 m0, s60, 0x2000
	s_add_u32 s58, s58, 0x80080
	v_lshl_add_u64 v[190:191], v[224:225], 0, s[84:85]
	s_addc_u32 s59, s59, 0
	s_add_i32 s60, s96, s46
	global_load_lds_dwordx4 v[190:191], off
	s_mov_b32 m0, s60
	s_nop 0
	global_load_lds_dwordx4 v2, s[58:59]
	s_add_i32 m0, s60, 0x2000
	s_nop 0
	global_load_lds_dwordx4 v184, s[58:59]
	s_cmp_eq_u32 s86, 28
	s_cbranch_scc0 .Ldefer_1843_body
	v_lshl_add_u64 v[190:191], v[226:227], 0, s[84:85]
	s_mov_b32 m0, s28
	s_nop 0
	global_load_lds_dwordx4 v[190:191], off
	v_lshl_add_u64 v[190:191], v[228:229], 0, s[84:85]
	s_mov_b32 m0, s77
	s_nop 0
	global_load_lds_dwordx4 v[190:191], off
.Ldefer_1843_body:
	s_waitcnt vmcnt(6)
	s_waitcnt lgkmcnt(7)
	s_setprio 1
	s_barrier
	v_mfma_i32_16x16x64_i8 v[80:83], v[52:55], v[164:167], v[80:83]
	s_waitcnt lgkmcnt(6)
	v_mfma_i32_16x16x64_i8 v[80:83], v[56:59], v[168:171], v[80:83]
	s_waitcnt lgkmcnt(5)
	v_mfma_i32_16x16x64_i8 v[64:67], v[56:59], v[176:179], v[64:67]
	s_waitcnt lgkmcnt(4)
	v_mfma_i32_16x16x64_i8 v[64:67], v[52:55], v[172:175], v[64:67]
	s_waitcnt lgkmcnt(3)
	v_mfma_i32_16x16x64_i8 v[48:51], v[52:55], v[204:207], v[48:51]
	s_waitcnt lgkmcnt(2)
	v_mfma_i32_16x16x64_i8 v[48:51], v[56:59], v[208:211], v[48:51]
	s_waitcnt lgkmcnt(1)
	v_mfma_i32_16x16x64_i8 v[16:19], v[56:59], v[220:223], v[16:19]
	s_waitcnt lgkmcnt(0)
	v_mfma_i32_16x16x64_i8 v[16:19], v[52:55], v[212:215], v[16:19]
	v_mfma_i32_16x16x64_i8 v[12:15], v[68:71], v[212:215], v[12:15]
	v_mfma_i32_16x16x64_i8 v[12:15], v[72:75], v[220:223], v[12:15]
	v_mfma_i32_16x16x64_i8 v[44:47], v[72:75], v[208:211], v[44:47]
	v_mfma_i32_16x16x64_i8 v[44:47], v[68:71], v[204:207], v[44:47]
	v_mfma_i32_16x16x64_i8 v[60:63], v[68:71], v[172:175], v[60:63]
	v_mfma_i32_16x16x64_i8 v[60:63], v[72:75], v[176:179], v[60:63]
	v_mfma_i32_16x16x64_i8 v[76:79], v[72:75], v[168:171], v[76:79]
	v_mfma_i32_16x16x64_i8 v[76:79], v[68:71], v[164:167], v[76:79]
	v_mfma_i32_16x16x64_i8 v[28:31], v[140:143], v[164:167], v[28:31]
	v_mfma_i32_16x16x64_i8 v[72:75], v[144:147], v[168:171], v[28:31]
	v_mfma_i32_16x16x64_i8 v[28:31], v[144:147], v[176:179], v[36:39]
	v_mfma_i32_16x16x64_i8 v[56:59], v[140:143], v[172:175], v[28:31]
	v_mfma_i32_16x16x64_i8 v[24:27], v[140:143], v[204:207], v[24:27]
	v_mfma_i32_16x16x64_i8 v[24:27], v[144:147], v[208:211], v[24:27]
	v_mfma_i32_16x16x64_i8 v[8:11], v[144:147], v[220:223], v[8:11]
	v_mfma_i32_16x16x64_i8 v[8:11], v[140:143], v[212:215], v[8:11]
	v_mfma_i32_16x16x64_i8 v[4:7], v[156:159], v[212:215], v[4:7]
	v_mfma_i32_16x16x64_i8 v[4:7], v[160:163], v[220:223], v[4:7]
	v_mfma_i32_16x16x64_i8 v[20:23], v[160:163], v[208:211], v[20:23]
	v_mfma_i32_16x16x64_i8 v[20:23], v[156:159], v[204:207], v[20:23]
	v_mfma_i32_16x16x64_i8 v[28:31], v[156:159], v[172:175], v[40:43]
	v_mfma_i32_16x16x64_i8 v[52:55], v[160:163], v[176:179], v[28:31]
	v_mfma_i32_16x16x64_i8 v[28:31], v[160:163], v[168:171], v[32:35]
	v_mfma_i32_16x16x64_i8 v[68:71], v[156:159], v[164:167], v[28:31]
	s_barrier
	s_setprio 0
	s_add_i32 s86, s86, 2
	s_add_u32 s54, s54, 0x100
	s_addc_u32 s55, s55, 0
	s_add_u32 s45, s45, 0x100
	s_addc_u32 s49, s49, 0
	s_cmp_gt_u32 s86, 29
	s_cbranch_scc0 .LBB0_1843
